# gather value phase: per-expert coefficient broadcast from a wave-private LDS row (prefetched ds_read, VGPR operand) instead of v_readlane into an SGPR
# baseline (speedup 1.0000x reference)
; DEV int opaque_tid() { int t = (int)threadIdx.x; asm volatile("" : "+v"(t)); return t; }
; __device__ void peer_gather_phase(const Params& P, int l, bool do_store) {
;   const int lane = opaque_tid() & 63, w = opaque_tid() >> 6;
;   const unsigned char* U = P.U8 + (size_t)l * 16384 * 768 + (lane & 31) * 24;
;   const unsigned char* V = P.V8 + (size_t)l * 16384 * 512 + lane * 8;
;   const float* SU = P.SU + l * 16384;
;   const float* SV = P.SV + l * 16384;
;   int nev0, nev1; float ngv0, ngv1; uint4 nxa, nxc;
;   {
;     const int t = blockIdx.x * 4 + w;
;     nev0 = P.EXP[(size_t)t * 128 + lane]; nev1 = P.EXP[(size_t)t * 128 + 64 + lane];
;     ngv0 = P.GATE[(size_t)t * 128 + lane]; ngv1 = P.GATE[(size_t)t * 128 + 64 + lane];
;     const bf16_t* xb = P.XB + (size_t)t * 1024 + lane * 16;
;     nxa = *(const uint4*)xb; nxc = *(const uint4*)(xb + 8);
;   }
.LBB0_14:
	v_readlane_b32 s4, v248, 27
	s_add_i32 s4, s4, 1
	v_readlane_b32 s2, v249, 37
	s_cmp_eq_u32 s4, s2
	v_writelane_b32 v248, s4, 27
	s_cselect_b64 s[4:5], -1, 0
	v_writelane_b32 v248, s4, 32
	s_mov_b64 s[0:1], -1
	s_nop 0
	v_writelane_b32 v248, s5, 33
	v_readlane_b32 s4, v249, 38
	v_readlane_b32 s5, v249, 39
	s_and_b64 vcc, exec, s[4:5]
	s_cbranch_vccz .LBB0_310
	v_readlane_b32 s0, v251, 58
	v_readlane_b32 s1, v251, 59
	s_load_dword s0, s[0:1], 0x0
	s_waitcnt lgkmcnt(0)
	v_writelane_b32 v248, s0, 34
	s_nop 1
	v_writelane_b32 v248, s1, 35
	v_readlane_b32 s0, v249, 40
	s_cmp_lt_i32 s0, 4
	s_mov_b64 s[0:1], -1
	s_cbranch_scc1 .LBB0_65
	v_readlane_b32 s0, v249, 40
	s_cmp_lt_i32 s0, 6
	s_mov_b64 s[0:1], -1
	s_cbranch_scc1 .LBB0_39
	v_readlane_b32 s0, v249, 40
	s_cmp_gt_i32 s0, 6
	s_cbranch_scc0 .LBB0_38
	v_readlane_b32 s0, v251, 60
	v_readlane_b32 s1, v251, 61
	v_mov_b32_e32 v0, v202
	v_mov_b32_e32 v1, v202
	s_andn2_b64 vcc, exec, s[0:1]
	s_cbranch_vccnz .LBB0_38
	v_ashrrev_i32_e32 v73, 6, v1
	v_and_b32_e32 v1, 31, v0
	v_readlane_b32 s0, v249, 41
	v_mul_u32_u24_e32 v176, 24, v1
	v_readlane_b32 s1, v249, 42
	v_and_b32_e32 v72, 63, v0
	v_readlane_b32 s4, v251, 2
	v_lshl_add_u64 v[74:75], s[0:1], 0, v[176:177]
	v_readlane_b32 s0, v249, 43
	v_lshlrev_b32_e32 v176, 3, v72
	v_readlane_b32 s1, v249, 44
	v_readlane_b32 s5, v251, 3
	v_readlane_b32 s6, v251, 4
	v_lshl_add_u64 v[76:77], s[0:1], 0, v[176:177]
	v_readlane_b32 s0, v251, 62
	v_lshlrev_b32_e32 v176, 5, v72
	v_readlane_b32 s7, v251, 5
	v_add_u32_e32 v2, s0, v73
	v_ashrrev_i32_e32 v3, 31, v2
	v_lshlrev_b64 v[4:5], 11, v[2:3]
	v_lshl_add_u64 v[4:5], s[28:29], 0, v[4:5]
	v_lshlrev_b64 v[2:3], 9, v[2:3]
	v_lshl_add_u64 v[4:5], v[4:5], 0, v[176:177]
	v_lshl_or_b32 v2, v72, 2, v2
	global_load_dwordx4 v[64:67], v[4:5], off offset:16
	global_load_dwordx4 v[68:71], v[4:5], off
	v_lshl_add_u64 v[4:5], s[4:5], 0, v[2:3]
	v_lshl_add_u64 v[2:3], s[6:7], 0, v[2:3]
	global_load_dword v93, v[4:5], off offset:256
	global_load_dword v91, v[4:5], off
	global_load_dword v188, v[2:3], off offset:256
	global_load_dword v179, v[2:3], off
	v_readlane_b32 s0, v249, 49
	v_readlane_b32 s4, v248, 32
	v_readlane_b32 s1, v249, 50
	v_readlane_b32 s5, v248, 33
	s_and_b64 s[38:39], s[0:1], s[4:5]
	v_readlane_b32 s0, v248, 1
	v_readlane_b32 s1, v248, 2
	s_and_b64 s[0:1], s[0:1], s[4:5]
	s_xor_b64 s[0:1], s[0:1], -1
	v_writelane_b32 v248, s0, 45
	v_lshl_add_u64 v[78:79], s[28:29], 0, v[176:177]
	v_lshlrev_b32_e32 v176, 6, v72
	v_writelane_b32 v248, s1, 46
	v_readlane_b32 s0, v249, 54
	v_readlane_b32 s1, v249, 55
	v_lshlrev_b32_e32 v0, 5, v0
	v_readlane_b32 s44, v252, 12
	v_lshl_add_u64 v[82:83], s[0:1], 0, v[176:177]
	v_readlane_b32 s0, v249, 56
	v_readlane_b32 s1, v249, 57
	v_lshlrev_b32_e32 v2, 4, v72
	v_and_b32_e32 v0, 0x3e0, v0
	v_readlane_b32 s58, v252, 26
	v_readlane_b32 s59, v252, 27
	v_lshl_add_u64 v[84:85], s[0:1], 0, v[176:177]
	v_readlane_b32 s0, v249, 5
	v_cmp_lt_u32_e64 s[40:41], 31, v72
	v_lshl_add_u64 v[80:81], s[58:59], 0, v[176:177]
	v_lshlrev_b32_e32 v86, 1, v0
	v_lshlrev_b32_e32 v176, 1, v2
	v_mov_b32_e32 v87, v177
	s_mov_b32 s2, s0
	s_movk_i32 s33, 0x300
	v_readlane_b32 s45, v252, 13
	v_readlane_b32 s46, v252, 14
	v_readlane_b32 s47, v252, 15
	v_readlane_b32 s48, v252, 16
	v_readlane_b32 s49, v252, 17
	v_readlane_b32 s50, v252, 18
	v_readlane_b32 s51, v252, 19
	v_readlane_b32 s52, v252, 20
	v_readlane_b32 s53, v252, 21
	v_readlane_b32 s54, v252, 22
	v_readlane_b32 s55, v252, 23
	v_readlane_b32 s56, v252, 24
	v_readlane_b32 s57, v252, 25
	v_readlane_b32 s1, v249, 6
	v_lshrrev_b32_e32 v74, 5, v72
	v_lshlrev_b32_e32 v74, 2, v74
	v_lshl_add_u32 v74, v73, 9, v74
	v_lshlrev_b32_e32 v75, 2, v72
	v_lshl_add_u32 v75, v73, 9, v75
	v_lshlrev_b32_e32 v193, 9, v73
	s_branch .LBB0_21

; __device__ void peer_gather_phase(const Params& P, int l, bool do_store) {
;     ...
;         const int ea = __builtin_amdgcn_readlane(evs, kb + 2 * pr), eb = __builtin_amdgcn_readlane(evs, kb + 2 * pr + 1);
;         const uint2* up = (const uint2*)(U + (size_t)(uphi ? eb : ea) * 768);
;         u6[3 * pr] = up[0]; u6[3 * pr + 1] = up[1]; u6[3 * pr + 2] = up[2];
;     ...
;         v6u_t qv; qv[0] = u6[3 * pr].x; qv[1] = u6[3 * pr].y; qv[2] = u6[3 * pr + 1].x; qv[3] = u6[3 * pr + 1].y; qv[4] = u6[3 * pr + 2].x; qv[5] = u6[3 * pr + 2].y;
;         const v32f_t wv = __builtin_amdgcn_cvt_scalef32_pk32_f32_fp6(qv, 1.0f);
;         f32x2 a2 = f32x2{0.f, 0.f};
; #pragma unroll
;         for (int i = 0; i < 16; ++i) a2 += f32x2{wv[2 * i], wv[2 * i + 1]} * xu[i];
;         float hs = a2.x + a2.y;
;         hs += dpp_row_shr(hs, 1); hs += dpp_row_shr(hs, 2); hs += dpp_row_shr(hs, 4); hs += dpp_row_shr(hs, 8);
;         hs += __builtin_bit_cast(float, __builtin_amdgcn_update_dpp(0, __builtin_bit_cast(int, hs), 0x142, 0xa, 0xf, false));
;         const float da = __builtin_bit_cast(float, __builtin_amdgcn_readlane(__builtin_bit_cast(int, hs), 31));
;         const float db = __builtin_bit_cast(float, __builtin_amdgcn_readlane(__builtin_bit_cast(int, hs), 63));
;         dvec = (lane == kb + 2 * pr) ? da : dvec;
;         dvec = (lane == kb + 2 * pr + 1) ? db : dvec;
.LBB0_22:
	v_readlane_b32 s54, v92, 16
	v_readlane_b32 s55, v92, 17
	s_mul_i32 s0, s54, 0x300
	s_mul_i32 s1, s55, 0x300
	v_add_u32_e32 v167, s0, v195
	s_and_saveexec_b64 s[98:99], s[40:41]
	v_add_u32_e32 v167, s1, v195
	s_mov_b64 exec, s[98:99]
	s_waitcnt vmcnt(32)
	v_cvt_scalef32_pk32_f32_fp6 v[0:31], v[50:55], 1.0
	global_load_dwordx2 v[54:55], v167, s[62:63] offset:16
	global_load_dwordx4 v[50:53], v167, s[62:63]
	v_pk_mul_f32 v[246:247], v[0:1], v[96:97]
	v_pk_mul_f32 v[254:255], v[2:3], v[98:99]
	v_pk_mul_f32 v[160:161], v[4:5], v[100:101]
	v_pk_fma_f32 v[246:247], v[6:7], v[102:103], v[246:247]
	v_pk_fma_f32 v[254:255], v[8:9], v[104:105], v[254:255]
	v_pk_fma_f32 v[160:161], v[10:11], v[106:107], v[160:161]
	v_pk_fma_f32 v[246:247], v[12:13], v[108:109], v[246:247]
	v_pk_fma_f32 v[254:255], v[14:15], v[110:111], v[254:255]
	v_pk_fma_f32 v[160:161], v[16:17], v[112:113], v[160:161]
	v_pk_fma_f32 v[246:247], v[18:19], v[114:115], v[246:247]
	v_pk_fma_f32 v[254:255], v[20:21], v[116:117], v[254:255]
	v_pk_fma_f32 v[160:161], v[22:23], v[118:119], v[160:161]
	v_pk_fma_f32 v[246:247], v[24:25], v[120:121], v[246:247]
	v_pk_fma_f32 v[254:255], v[26:27], v[122:123], v[254:255]
	v_pk_fma_f32 v[160:161], v[28:29], v[124:125], v[160:161]
	v_pk_fma_f32 v[246:247], v[30:31], v[126:127], v[246:247]
	v_pk_add_f32 v[254:255], v[254:255], v[160:161]
	s_nop 0
	v_pk_add_f32 v[246:247], v[246:247], v[254:255]
	s_nop 0
	v_add_f32_e32 v162, v246, v247
	v_readlane_b32 s54, v92, 18
	v_readlane_b32 s55, v92, 19
	s_mul_i32 s0, s54, 0x300
	s_mul_i32 s1, s55, 0x300
	v_add_u32_e32 v167, s0, v195
	s_and_saveexec_b64 s[98:99], s[40:41]
	v_add_u32_e32 v167, s1, v195
	s_mov_b64 exec, s[98:99]
	s_waitcnt vmcnt(32)
	v_cvt_scalef32_pk32_f32_fp6 v[0:31], v[44:49], 1.0
	global_load_dwordx2 v[48:49], v167, s[62:63] offset:16
	global_load_dwordx4 v[44:47], v167, s[62:63]
	v_pk_mul_f32 v[246:247], v[0:1], v[96:97]
	v_pk_mul_f32 v[254:255], v[2:3], v[98:99]
	v_pk_mul_f32 v[160:161], v[4:5], v[100:101]
	v_pk_fma_f32 v[246:247], v[6:7], v[102:103], v[246:247]
	v_pk_fma_f32 v[254:255], v[8:9], v[104:105], v[254:255]
	v_pk_fma_f32 v[160:161], v[10:11], v[106:107], v[160:161]
	v_pk_fma_f32 v[246:247], v[12:13], v[108:109], v[246:247]
	v_pk_fma_f32 v[254:255], v[14:15], v[110:111], v[254:255]
	v_pk_fma_f32 v[160:161], v[16:17], v[112:113], v[160:161]
	v_pk_fma_f32 v[246:247], v[18:19], v[114:115], v[246:247]
	v_pk_fma_f32 v[254:255], v[20:21], v[116:117], v[254:255]
	v_pk_fma_f32 v[160:161], v[22:23], v[118:119], v[160:161]
	v_pk_fma_f32 v[246:247], v[24:25], v[120:121], v[246:247]
	v_pk_fma_f32 v[254:255], v[26:27], v[122:123], v[254:255]
	v_pk_fma_f32 v[160:161], v[28:29], v[124:125], v[160:161]
	v_pk_fma_f32 v[246:247], v[30:31], v[126:127], v[246:247]
	v_pk_add_f32 v[254:255], v[254:255], v[160:161]
	s_nop 0
	v_pk_add_f32 v[246:247], v[246:247], v[254:255]
	s_nop 0
	v_add_f32_e32 v163, v246, v247
	v_readlane_b32 s54, v92, 20
	v_readlane_b32 s55, v92, 21
	s_mul_i32 s0, s54, 0x300
	s_mul_i32 s1, s55, 0x300
	v_add_u32_e32 v167, s0, v195
	s_and_saveexec_b64 s[98:99], s[40:41]
	v_add_u32_e32 v167, s1, v195
	s_mov_b64 exec, s[98:99]
	s_waitcnt vmcnt(32)
	v_cvt_scalef32_pk32_f32_fp6 v[0:31], v[38:43], 1.0
	global_load_dwordx2 v[42:43], v167, s[62:63] offset:16
	global_load_dwordx4 v[38:41], v167, s[62:63]
	v_pk_mul_f32 v[246:247], v[0:1], v[96:97]
	v_pk_mul_f32 v[254:255], v[2:3], v[98:99]
	v_pk_mul_f32 v[160:161], v[4:5], v[100:101]
	v_pk_fma_f32 v[246:247], v[6:7], v[102:103], v[246:247]
	v_pk_fma_f32 v[254:255], v[8:9], v[104:105], v[254:255]
	v_pk_fma_f32 v[160:161], v[10:11], v[106:107], v[160:161]
	v_pk_fma_f32 v[246:247], v[12:13], v[108:109], v[246:247]
	v_pk_fma_f32 v[254:255], v[14:15], v[110:111], v[254:255]
	v_pk_fma_f32 v[160:161], v[16:17], v[112:113], v[160:161]
	v_pk_fma_f32 v[246:247], v[18:19], v[114:115], v[246:247]
	v_pk_fma_f32 v[254:255], v[20:21], v[116:117], v[254:255]
	v_pk_fma_f32 v[160:161], v[22:23], v[118:119], v[160:161]
	v_pk_fma_f32 v[246:247], v[24:25], v[120:121], v[246:247]
	v_pk_fma_f32 v[254:255], v[26:27], v[122:123], v[254:255]
	v_pk_fma_f32 v[160:161], v[28:29], v[124:125], v[160:161]
	v_pk_fma_f32 v[246:247], v[30:31], v[126:127], v[246:247]
	v_pk_add_f32 v[254:255], v[254:255], v[160:161]
	s_nop 0
	v_pk_add_f32 v[246:247], v[246:247], v[254:255]
	s_nop 0
	v_add_f32_e32 v164, v246, v247
	v_readlane_b32 s54, v92, 22
	v_readlane_b32 s55, v92, 23
	s_mul_i32 s0, s54, 0x300
	s_mul_i32 s1, s55, 0x300
	v_add_u32_e32 v167, s0, v195
	s_and_saveexec_b64 s[98:99], s[40:41]
	v_add_u32_e32 v167, s1, v195
	s_mov_b64 exec, s[98:99]
	s_waitcnt vmcnt(32)
; __device__ void peer_gather_phase(const Params& P, int l, bool do_store) {
;     ...
;         const int ea = __builtin_amdgcn_readlane(evs, kb + 2 * pr), eb = __builtin_amdgcn_readlane(evs, kb + 2 * pr + 1);
;         const uint2* up = (const uint2*)(U + (size_t)(uphi ? eb : ea) * 768);
;         u6[3 * pr] = up[0]; u6[3 * pr + 1] = up[1]; u6[3 * pr + 2] = up[2];
;     ...
;         v6u_t qv; qv[0] = u6[3 * pr].x; qv[1] = u6[3 * pr].y; qv[2] = u6[3 * pr + 1].x; qv[3] = u6[3 * pr + 1].y; qv[4] = u6[3 * pr + 2].x; qv[5] = u6[3 * pr + 2].y;
;         const v32f_t wv = __builtin_amdgcn_cvt_scalef32_pk32_f32_fp6(qv, 1.0f);
;         f32x2 a2 = f32x2{0.f, 0.f};
; #pragma unroll
;         for (int i = 0; i < 16; ++i) a2 += f32x2{wv[2 * i], wv[2 * i + 1]} * xu[i];
;         float hs = a2.x + a2.y;
;         hs += dpp_row_shr(hs, 1); hs += dpp_row_shr(hs, 2); hs += dpp_row_shr(hs, 4); hs += dpp_row_shr(hs, 8);
;         hs += __builtin_bit_cast(float, __builtin_amdgcn_update_dpp(0, __builtin_bit_cast(int, hs), 0x142, 0xa, 0xf, false));
;         const float da = __builtin_bit_cast(float, __builtin_amdgcn_readlane(__builtin_bit_cast(int, hs), 31));
;         const float db = __builtin_bit_cast(float, __builtin_amdgcn_readlane(__builtin_bit_cast(int, hs), 63));
;         dvec = (lane == kb + 2 * pr) ? da : dvec;
;         dvec = (lane == kb + 2 * pr + 1) ? db : dvec;
	v_cvt_scalef32_pk32_f32_fp6 v[0:31], v[32:37], 1.0
	global_load_dwordx2 v[36:37], v167, s[62:63] offset:16
	global_load_dwordx4 v[32:35], v167, s[62:63]
	v_pk_mul_f32 v[246:247], v[0:1], v[96:97]
	v_pk_mul_f32 v[254:255], v[2:3], v[98:99]
	v_pk_mul_f32 v[160:161], v[4:5], v[100:101]
	v_pk_fma_f32 v[246:247], v[6:7], v[102:103], v[246:247]
	v_pk_fma_f32 v[254:255], v[8:9], v[104:105], v[254:255]
	v_pk_fma_f32 v[160:161], v[10:11], v[106:107], v[160:161]
	v_pk_fma_f32 v[246:247], v[12:13], v[108:109], v[246:247]
	v_pk_fma_f32 v[254:255], v[14:15], v[110:111], v[254:255]
	v_pk_fma_f32 v[160:161], v[16:17], v[112:113], v[160:161]
	v_pk_fma_f32 v[246:247], v[18:19], v[114:115], v[246:247]
	v_pk_fma_f32 v[254:255], v[20:21], v[116:117], v[254:255]
	v_pk_fma_f32 v[160:161], v[22:23], v[118:119], v[160:161]
	v_pk_fma_f32 v[246:247], v[24:25], v[120:121], v[246:247]
	v_pk_fma_f32 v[254:255], v[26:27], v[122:123], v[254:255]
	v_pk_fma_f32 v[160:161], v[28:29], v[124:125], v[160:161]
	v_pk_fma_f32 v[246:247], v[30:31], v[126:127], v[246:247]
	v_pk_add_f32 v[254:255], v[254:255], v[160:161]
	s_nop 0
	v_pk_add_f32 v[246:247], v[246:247], v[254:255]
	s_nop 0
	v_add_f32_e32 v165, v246, v247
	v_add_f32_dpp v162, v162, v162 row_shr:1 row_mask:0xf bank_mask:0xf bound_ctrl:1
	v_add_f32_dpp v163, v163, v163 row_shr:1 row_mask:0xf bank_mask:0xf bound_ctrl:1
	v_add_f32_dpp v164, v164, v164 row_shr:1 row_mask:0xf bank_mask:0xf bound_ctrl:1
	v_add_f32_dpp v165, v165, v165 row_shr:1 row_mask:0xf bank_mask:0xf bound_ctrl:1
	v_add_f32_dpp v162, v162, v162 row_shr:2 row_mask:0xf bank_mask:0xf bound_ctrl:1
	v_add_f32_dpp v163, v163, v163 row_shr:2 row_mask:0xf bank_mask:0xf bound_ctrl:1
	v_add_f32_dpp v164, v164, v164 row_shr:2 row_mask:0xf bank_mask:0xf bound_ctrl:1
	v_add_f32_dpp v165, v165, v165 row_shr:2 row_mask:0xf bank_mask:0xf bound_ctrl:1
	v_add_f32_dpp v162, v162, v162 row_shr:4 row_mask:0xf bank_mask:0xf bound_ctrl:1
	v_add_f32_dpp v163, v163, v163 row_shr:4 row_mask:0xf bank_mask:0xf bound_ctrl:1
	v_add_f32_dpp v164, v164, v164 row_shr:4 row_mask:0xf bank_mask:0xf bound_ctrl:1
	v_add_f32_dpp v165, v165, v165 row_shr:4 row_mask:0xf bank_mask:0xf bound_ctrl:1
	v_add_f32_dpp v162, v162, v162 row_shr:8 row_mask:0xf bank_mask:0xf bound_ctrl:1
	v_add_f32_dpp v163, v163, v163 row_shr:8 row_mask:0xf bank_mask:0xf bound_ctrl:1
	v_add_f32_dpp v164, v164, v164 row_shr:8 row_mask:0xf bank_mask:0xf bound_ctrl:1
	v_add_f32_dpp v165, v165, v165 row_shr:8 row_mask:0xf bank_mask:0xf bound_ctrl:1
	v_add_f32_dpp v162, v162, v162 row_bcast:15 row_mask:0xa bank_mask:0xf
	v_add_f32_dpp v163, v163, v163 row_bcast:15 row_mask:0xa bank_mask:0xf
	v_add_f32_dpp v164, v164, v164 row_bcast:15 row_mask:0xa bank_mask:0xf
	v_add_f32_dpp v165, v165, v165 row_bcast:15 row_mask:0xa bank_mask:0xf
	s_mov_b64 s[98:99], exec
	s_mov_b32 exec_lo, 0x80000000
	s_mov_b32 exec_hi, 0x80000000
	ds_write_b32 v74, v162
	ds_write_b32 v74, v163 offset:8
	ds_write_b32 v74, v164 offset:16
	ds_write_b32 v74, v165 offset:24
	s_mov_b64 exec, s[98:99]
	v_readlane_b32 s54, v92, 24
	v_readlane_b32 s55, v92, 25
	s_mul_i32 s0, s54, 0x300
	s_mul_i32 s1, s55, 0x300
	v_add_u32_e32 v167, s0, v195
	s_and_saveexec_b64 s[98:99], s[40:41]
	v_add_u32_e32 v167, s1, v195
	s_mov_b64 exec, s[98:99]
	s_waitcnt vmcnt(32)
	v_cvt_scalef32_pk32_f32_fp6 v[0:31], v[196:201], 1.0
	global_load_dwordx2 v[200:201], v167, s[62:63] offset:16
	global_load_dwordx4 v[196:199], v167, s[62:63]
	v_pk_mul_f32 v[246:247], v[0:1], v[96:97]
	v_pk_mul_f32 v[254:255], v[2:3], v[98:99]
	v_pk_mul_f32 v[160:161], v[4:5], v[100:101]
	v_pk_fma_f32 v[246:247], v[6:7], v[102:103], v[246:247]
	v_pk_fma_f32 v[254:255], v[8:9], v[104:105], v[254:255]
	v_pk_fma_f32 v[160:161], v[10:11], v[106:107], v[160:161]
	v_pk_fma_f32 v[246:247], v[12:13], v[108:109], v[246:247]
	v_pk_fma_f32 v[254:255], v[14:15], v[110:111], v[254:255]
	v_pk_fma_f32 v[160:161], v[16:17], v[112:113], v[160:161]
	v_pk_fma_f32 v[246:247], v[18:19], v[114:115], v[246:247]
	v_pk_fma_f32 v[254:255], v[20:21], v[116:117], v[254:255]
	v_pk_fma_f32 v[160:161], v[22:23], v[118:119], v[160:161]
	v_pk_fma_f32 v[246:247], v[24:25], v[120:121], v[246:247]
	v_pk_fma_f32 v[254:255], v[26:27], v[122:123], v[254:255]
	v_pk_fma_f32 v[160:161], v[28:29], v[124:125], v[160:161]
	v_pk_fma_f32 v[246:247], v[30:31], v[126:127], v[246:247]
	v_pk_add_f32 v[254:255], v[254:255], v[160:161]
	s_nop 0
	v_pk_add_f32 v[246:247], v[246:247], v[254:255]
	s_nop 0
	v_add_f32_e32 v162, v246, v247
	v_readlane_b32 s54, v92, 26
	v_readlane_b32 s55, v92, 27
	s_mul_i32 s0, s54, 0x300
	s_mul_i32 s1, s55, 0x300
	v_add_u32_e32 v167, s0, v195
	s_and_saveexec_b64 s[98:99], s[40:41]
	v_add_u32_e32 v167, s1, v195
	s_mov_b64 exec, s[98:99]
	s_waitcnt vmcnt(32)
	v_cvt_scalef32_pk32_f32_fp6 v[0:31], v[228:233], 1.0
	global_load_dwordx2 v[232:233], v167, s[62:63] offset:16
	global_load_dwordx4 v[228:231], v167, s[62:63]
	v_pk_mul_f32 v[246:247], v[0:1], v[96:97]
	v_pk_mul_f32 v[254:255], v[2:3], v[98:99]
	v_pk_mul_f32 v[160:161], v[4:5], v[100:101]
	v_pk_fma_f32 v[246:247], v[6:7], v[102:103], v[246:247]
	v_pk_fma_f32 v[254:255], v[8:9], v[104:105], v[254:255]
	v_pk_fma_f32 v[160:161], v[10:11], v[106:107], v[160:161]
	v_pk_fma_f32 v[246:247], v[12:13], v[108:109], v[246:247]
	v_pk_fma_f32 v[254:255], v[14:15], v[110:111], v[254:255]
	v_pk_fma_f32 v[160:161], v[16:17], v[112:113], v[160:161]
	v_pk_fma_f32 v[246:247], v[18:19], v[114:115], v[246:247]
	v_pk_fma_f32 v[254:255], v[20:21], v[116:117], v[254:255]
	v_pk_fma_f32 v[160:161], v[22:23], v[118:119], v[160:161]
	v_pk_fma_f32 v[246:247], v[24:25], v[120:121], v[246:247]
	v_pk_fma_f32 v[254:255], v[26:27], v[122:123], v[254:255]
	v_pk_fma_f32 v[160:161], v[28:29], v[124:125], v[160:161]
	v_pk_fma_f32 v[246:247], v[30:31], v[126:127], v[246:247]
	v_pk_add_f32 v[254:255], v[254:255], v[160:161]
	s_nop 0
	v_pk_add_f32 v[246:247], v[246:247], v[254:255]
	s_nop 0
	v_add_f32_e32 v163, v246, v247
	v_readlane_b32 s54, v92, 28
	v_readlane_b32 s55, v92, 29
	s_mul_i32 s0, s54, 0x300
	s_mul_i32 s1, s55, 0x300
	v_add_u32_e32 v167, s0, v195
	s_and_saveexec_b64 s[98:99], s[40:41]
	v_add_u32_e32 v167, s1, v195
	s_mov_b64 exec, s[98:99]
	s_waitcnt vmcnt(32)
; __device__ void peer_gather_phase(const Params& P, int l, bool do_store) {
;     ...
;         const int ea = __builtin_amdgcn_readlane(evs, kb + 2 * pr), eb = __builtin_amdgcn_readlane(evs, kb + 2 * pr + 1);
;         const uint2* up = (const uint2*)(U + (size_t)(uphi ? eb : ea) * 768);
;         u6[3 * pr] = up[0]; u6[3 * pr + 1] = up[1]; u6[3 * pr + 2] = up[2];
;     ...
;         v6u_t qv; qv[0] = u6[3 * pr].x; qv[1] = u6[3 * pr].y; qv[2] = u6[3 * pr + 1].x; qv[3] = u6[3 * pr + 1].y; qv[4] = u6[3 * pr + 2].x; qv[5] = u6[3 * pr + 2].y;
;         const v32f_t wv = __builtin_amdgcn_cvt_scalef32_pk32_f32_fp6(qv, 1.0f);
;         f32x2 a2 = f32x2{0.f, 0.f};
; #pragma unroll
;         for (int i = 0; i < 16; ++i) a2 += f32x2{wv[2 * i], wv[2 * i + 1]} * xu[i];
;         float hs = a2.x + a2.y;
;         hs += dpp_row_shr(hs, 1); hs += dpp_row_shr(hs, 2); hs += dpp_row_shr(hs, 4); hs += dpp_row_shr(hs, 8);
;         hs += __builtin_bit_cast(float, __builtin_amdgcn_update_dpp(0, __builtin_bit_cast(int, hs), 0x142, 0xa, 0xf, false));
;         const float da = __builtin_bit_cast(float, __builtin_amdgcn_readlane(__builtin_bit_cast(int, hs), 31));
;         const float db = __builtin_bit_cast(float, __builtin_amdgcn_readlane(__builtin_bit_cast(int, hs), 63));
;         dvec = (lane == kb + 2 * pr) ? da : dvec;
;         dvec = (lane == kb + 2 * pr + 1) ? db : dvec;
	v_cvt_scalef32_pk32_f32_fp6 v[0:31], v[234:239], 1.0
	global_load_dwordx2 v[238:239], v167, s[62:63] offset:16
	global_load_dwordx4 v[234:237], v167, s[62:63]
	v_pk_mul_f32 v[246:247], v[0:1], v[96:97]
	v_pk_mul_f32 v[254:255], v[2:3], v[98:99]
	v_pk_mul_f32 v[160:161], v[4:5], v[100:101]
	v_pk_fma_f32 v[246:247], v[6:7], v[102:103], v[246:247]
	v_pk_fma_f32 v[254:255], v[8:9], v[104:105], v[254:255]
	v_pk_fma_f32 v[160:161], v[10:11], v[106:107], v[160:161]
	v_pk_fma_f32 v[246:247], v[12:13], v[108:109], v[246:247]
	v_pk_fma_f32 v[254:255], v[14:15], v[110:111], v[254:255]
	v_pk_fma_f32 v[160:161], v[16:17], v[112:113], v[160:161]
	v_pk_fma_f32 v[246:247], v[18:19], v[114:115], v[246:247]
	v_pk_fma_f32 v[254:255], v[20:21], v[116:117], v[254:255]
	v_pk_fma_f32 v[160:161], v[22:23], v[118:119], v[160:161]
	v_pk_fma_f32 v[246:247], v[24:25], v[120:121], v[246:247]
	v_pk_fma_f32 v[254:255], v[26:27], v[122:123], v[254:255]
	v_pk_fma_f32 v[160:161], v[28:29], v[124:125], v[160:161]
	v_pk_fma_f32 v[246:247], v[30:31], v[126:127], v[246:247]
	v_pk_add_f32 v[254:255], v[254:255], v[160:161]
	s_nop 0
	v_pk_add_f32 v[246:247], v[246:247], v[254:255]
	s_nop 0
	v_add_f32_e32 v164, v246, v247
	v_readlane_b32 s54, v92, 30
	v_readlane_b32 s55, v92, 31
	s_mul_i32 s0, s54, 0x300
	s_mul_i32 s1, s55, 0x300
	v_add_u32_e32 v167, s0, v195
	s_and_saveexec_b64 s[98:99], s[40:41]
	v_add_u32_e32 v167, s1, v195
	s_mov_b64 exec, s[98:99]
	s_waitcnt vmcnt(32)
	v_cvt_scalef32_pk32_f32_fp6 v[0:31], v[240:245], 1.0
	global_load_dwordx2 v[244:245], v167, s[62:63] offset:16
	global_load_dwordx4 v[240:243], v167, s[62:63]
	v_pk_mul_f32 v[246:247], v[0:1], v[96:97]
	v_pk_mul_f32 v[254:255], v[2:3], v[98:99]
	v_pk_mul_f32 v[160:161], v[4:5], v[100:101]
	v_pk_fma_f32 v[246:247], v[6:7], v[102:103], v[246:247]
	v_pk_fma_f32 v[254:255], v[8:9], v[104:105], v[254:255]
	v_pk_fma_f32 v[160:161], v[10:11], v[106:107], v[160:161]
	v_pk_fma_f32 v[246:247], v[12:13], v[108:109], v[246:247]
	v_pk_fma_f32 v[254:255], v[14:15], v[110:111], v[254:255]
	v_pk_fma_f32 v[160:161], v[16:17], v[112:113], v[160:161]
	v_pk_fma_f32 v[246:247], v[18:19], v[114:115], v[246:247]
	v_pk_fma_f32 v[254:255], v[20:21], v[116:117], v[254:255]
	v_pk_fma_f32 v[160:161], v[22:23], v[118:119], v[160:161]
	v_pk_fma_f32 v[246:247], v[24:25], v[120:121], v[246:247]
	v_pk_fma_f32 v[254:255], v[26:27], v[122:123], v[254:255]
	v_pk_fma_f32 v[160:161], v[28:29], v[124:125], v[160:161]
	v_pk_fma_f32 v[246:247], v[30:31], v[126:127], v[246:247]
	v_pk_add_f32 v[254:255], v[254:255], v[160:161]
	s_nop 0
	v_pk_add_f32 v[246:247], v[246:247], v[254:255]
	s_nop 0
	v_add_f32_e32 v165, v246, v247
	v_add_f32_dpp v162, v162, v162 row_shr:1 row_mask:0xf bank_mask:0xf bound_ctrl:1
	v_add_f32_dpp v163, v163, v163 row_shr:1 row_mask:0xf bank_mask:0xf bound_ctrl:1
	v_add_f32_dpp v164, v164, v164 row_shr:1 row_mask:0xf bank_mask:0xf bound_ctrl:1
	v_add_f32_dpp v165, v165, v165 row_shr:1 row_mask:0xf bank_mask:0xf bound_ctrl:1
	v_add_f32_dpp v162, v162, v162 row_shr:2 row_mask:0xf bank_mask:0xf bound_ctrl:1
	v_add_f32_dpp v163, v163, v163 row_shr:2 row_mask:0xf bank_mask:0xf bound_ctrl:1
	v_add_f32_dpp v164, v164, v164 row_shr:2 row_mask:0xf bank_mask:0xf bound_ctrl:1
	v_add_f32_dpp v165, v165, v165 row_shr:2 row_mask:0xf bank_mask:0xf bound_ctrl:1
	v_add_f32_dpp v162, v162, v162 row_shr:4 row_mask:0xf bank_mask:0xf bound_ctrl:1
	v_add_f32_dpp v163, v163, v163 row_shr:4 row_mask:0xf bank_mask:0xf bound_ctrl:1
	v_add_f32_dpp v164, v164, v164 row_shr:4 row_mask:0xf bank_mask:0xf bound_ctrl:1
	v_add_f32_dpp v165, v165, v165 row_shr:4 row_mask:0xf bank_mask:0xf bound_ctrl:1
	v_add_f32_dpp v162, v162, v162 row_shr:8 row_mask:0xf bank_mask:0xf bound_ctrl:1
	v_add_f32_dpp v163, v163, v163 row_shr:8 row_mask:0xf bank_mask:0xf bound_ctrl:1
	v_add_f32_dpp v164, v164, v164 row_shr:8 row_mask:0xf bank_mask:0xf bound_ctrl:1
	v_add_f32_dpp v165, v165, v165 row_shr:8 row_mask:0xf bank_mask:0xf bound_ctrl:1
	v_add_f32_dpp v162, v162, v162 row_bcast:15 row_mask:0xa bank_mask:0xf
	v_add_f32_dpp v163, v163, v163 row_bcast:15 row_mask:0xa bank_mask:0xf
	v_add_f32_dpp v164, v164, v164 row_bcast:15 row_mask:0xa bank_mask:0xf
	v_add_f32_dpp v165, v165, v165 row_bcast:15 row_mask:0xa bank_mask:0xf
	s_mov_b64 s[98:99], exec
	s_mov_b32 exec_lo, 0x80000000
	s_mov_b32 exec_hi, 0x80000000
	ds_write_b32 v74, v162 offset:32
	ds_write_b32 v74, v163 offset:40
	ds_write_b32 v74, v164 offset:48
	ds_write_b32 v74, v165 offset:56
	s_mov_b64 exec, s[98:99]
	v_readlane_b32 s54, v92, 32
	v_readlane_b32 s55, v92, 33
	s_mul_i32 s0, s54, 0x300
	s_mul_i32 s1, s55, 0x300
	v_add_u32_e32 v167, s0, v195
	s_and_saveexec_b64 s[98:99], s[40:41]
	v_add_u32_e32 v167, s1, v195
	s_mov_b64 exec, s[98:99]
	s_waitcnt vmcnt(14)
	v_cvt_scalef32_pk32_f32_fp6 v[0:31], v[50:55], 1.0
	global_load_dwordx2 v[54:55], v167, s[62:63] offset:16
	global_load_dwordx4 v[50:53], v167, s[62:63]
	v_pk_mul_f32 v[246:247], v[0:1], v[96:97]
	v_pk_mul_f32 v[254:255], v[2:3], v[98:99]
	v_pk_mul_f32 v[160:161], v[4:5], v[100:101]
	v_pk_fma_f32 v[246:247], v[6:7], v[102:103], v[246:247]
	v_pk_fma_f32 v[254:255], v[8:9], v[104:105], v[254:255]
	v_pk_fma_f32 v[160:161], v[10:11], v[106:107], v[160:161]
	v_pk_fma_f32 v[246:247], v[12:13], v[108:109], v[246:247]
	v_pk_fma_f32 v[254:255], v[14:15], v[110:111], v[254:255]
	v_pk_fma_f32 v[160:161], v[16:17], v[112:113], v[160:161]
	v_pk_fma_f32 v[246:247], v[18:19], v[114:115], v[246:247]
	v_pk_fma_f32 v[254:255], v[20:21], v[116:117], v[254:255]
	v_pk_fma_f32 v[160:161], v[22:23], v[118:119], v[160:161]
	v_pk_fma_f32 v[246:247], v[24:25], v[120:121], v[246:247]
	v_pk_fma_f32 v[254:255], v[26:27], v[122:123], v[254:255]
	v_pk_fma_f32 v[160:161], v[28:29], v[124:125], v[160:161]
	v_pk_fma_f32 v[246:247], v[30:31], v[126:127], v[246:247]
	v_pk_add_f32 v[254:255], v[254:255], v[160:161]
	s_nop 0
	v_pk_add_f32 v[246:247], v[246:247], v[254:255]
	s_nop 0
	v_add_f32_e32 v162, v246, v247
	v_readlane_b32 s54, v92, 34
	v_readlane_b32 s55, v92, 35
	s_mul_i32 s0, s54, 0x300
	s_mul_i32 s1, s55, 0x300
	v_add_u32_e32 v167, s0, v195
	s_and_saveexec_b64 s[98:99], s[40:41]
	v_add_u32_e32 v167, s1, v195
	s_mov_b64 exec, s[98:99]
	s_waitcnt vmcnt(14)
; __device__ void peer_gather_phase(const Params& P, int l, bool do_store) {
;     ...
;         const int ea = __builtin_amdgcn_readlane(evs, kb + 2 * pr), eb = __builtin_amdgcn_readlane(evs, kb + 2 * pr + 1);
;         const uint2* up = (const uint2*)(U + (size_t)(uphi ? eb : ea) * 768);
;         u6[3 * pr] = up[0]; u6[3 * pr + 1] = up[1]; u6[3 * pr + 2] = up[2];
;     ...
;         v6u_t qv; qv[0] = u6[3 * pr].x; qv[1] = u6[3 * pr].y; qv[2] = u6[3 * pr + 1].x; qv[3] = u6[3 * pr + 1].y; qv[4] = u6[3 * pr + 2].x; qv[5] = u6[3 * pr + 2].y;
;         const v32f_t wv = __builtin_amdgcn_cvt_scalef32_pk32_f32_fp6(qv, 1.0f);
;         f32x2 a2 = f32x2{0.f, 0.f};
; #pragma unroll
;         for (int i = 0; i < 16; ++i) a2 += f32x2{wv[2 * i], wv[2 * i + 1]} * xu[i];
;         float hs = a2.x + a2.y;
;         hs += dpp_row_shr(hs, 1); hs += dpp_row_shr(hs, 2); hs += dpp_row_shr(hs, 4); hs += dpp_row_shr(hs, 8);
;         hs += __builtin_bit_cast(float, __builtin_amdgcn_update_dpp(0, __builtin_bit_cast(int, hs), 0x142, 0xa, 0xf, false));
;         const float da = __builtin_bit_cast(float, __builtin_amdgcn_readlane(__builtin_bit_cast(int, hs), 31));
;         const float db = __builtin_bit_cast(float, __builtin_amdgcn_readlane(__builtin_bit_cast(int, hs), 63));
;         dvec = (lane == kb + 2 * pr) ? da : dvec;
;         dvec = (lane == kb + 2 * pr + 1) ? db : dvec;
	v_cvt_scalef32_pk32_f32_fp6 v[0:31], v[44:49], 1.0
	global_load_dwordx2 v[48:49], v167, s[62:63] offset:16
	global_load_dwordx4 v[44:47], v167, s[62:63]
	v_pk_mul_f32 v[246:247], v[0:1], v[96:97]
	v_pk_mul_f32 v[254:255], v[2:3], v[98:99]
	v_pk_mul_f32 v[160:161], v[4:5], v[100:101]
	v_pk_fma_f32 v[246:247], v[6:7], v[102:103], v[246:247]
	v_pk_fma_f32 v[254:255], v[8:9], v[104:105], v[254:255]
	v_pk_fma_f32 v[160:161], v[10:11], v[106:107], v[160:161]
	v_pk_fma_f32 v[246:247], v[12:13], v[108:109], v[246:247]
	v_pk_fma_f32 v[254:255], v[14:15], v[110:111], v[254:255]
	v_pk_fma_f32 v[160:161], v[16:17], v[112:113], v[160:161]
	v_pk_fma_f32 v[246:247], v[18:19], v[114:115], v[246:247]
	v_pk_fma_f32 v[254:255], v[20:21], v[116:117], v[254:255]
	v_pk_fma_f32 v[160:161], v[22:23], v[118:119], v[160:161]
	v_pk_fma_f32 v[246:247], v[24:25], v[120:121], v[246:247]
	v_pk_fma_f32 v[254:255], v[26:27], v[122:123], v[254:255]
	v_pk_fma_f32 v[160:161], v[28:29], v[124:125], v[160:161]
	v_pk_fma_f32 v[246:247], v[30:31], v[126:127], v[246:247]
	v_pk_add_f32 v[254:255], v[254:255], v[160:161]
	s_nop 0
	v_pk_add_f32 v[246:247], v[246:247], v[254:255]
	s_nop 0
	v_add_f32_e32 v163, v246, v247
	v_readlane_b32 s54, v92, 36
	v_readlane_b32 s55, v92, 37
	s_mul_i32 s0, s54, 0x300
	s_mul_i32 s1, s55, 0x300
	v_add_u32_e32 v167, s0, v195
	s_and_saveexec_b64 s[98:99], s[40:41]
	v_add_u32_e32 v167, s1, v195
	s_mov_b64 exec, s[98:99]
	s_waitcnt vmcnt(14)
	v_cvt_scalef32_pk32_f32_fp6 v[0:31], v[38:43], 1.0
	global_load_dwordx2 v[42:43], v167, s[62:63] offset:16
	global_load_dwordx4 v[38:41], v167, s[62:63]
	v_pk_mul_f32 v[246:247], v[0:1], v[96:97]
	v_pk_mul_f32 v[254:255], v[2:3], v[98:99]
	v_pk_mul_f32 v[160:161], v[4:5], v[100:101]
	v_pk_fma_f32 v[246:247], v[6:7], v[102:103], v[246:247]
	v_pk_fma_f32 v[254:255], v[8:9], v[104:105], v[254:255]
	v_pk_fma_f32 v[160:161], v[10:11], v[106:107], v[160:161]
	v_pk_fma_f32 v[246:247], v[12:13], v[108:109], v[246:247]
	v_pk_fma_f32 v[254:255], v[14:15], v[110:111], v[254:255]
	v_pk_fma_f32 v[160:161], v[16:17], v[112:113], v[160:161]
	v_pk_fma_f32 v[246:247], v[18:19], v[114:115], v[246:247]
	v_pk_fma_f32 v[254:255], v[20:21], v[116:117], v[254:255]
	v_pk_fma_f32 v[160:161], v[22:23], v[118:119], v[160:161]
	v_pk_fma_f32 v[246:247], v[24:25], v[120:121], v[246:247]
	v_pk_fma_f32 v[254:255], v[26:27], v[122:123], v[254:255]
	v_pk_fma_f32 v[160:161], v[28:29], v[124:125], v[160:161]
	v_pk_fma_f32 v[246:247], v[30:31], v[126:127], v[246:247]
	v_pk_add_f32 v[254:255], v[254:255], v[160:161]
	s_nop 0
	v_pk_add_f32 v[246:247], v[246:247], v[254:255]
	s_nop 0
	v_add_f32_e32 v164, v246, v247
	v_readlane_b32 s54, v92, 38
	v_readlane_b32 s55, v92, 39
	s_mul_i32 s0, s54, 0x300
	s_mul_i32 s1, s55, 0x300
	v_add_u32_e32 v167, s0, v195
	s_and_saveexec_b64 s[98:99], s[40:41]
	v_add_u32_e32 v167, s1, v195
	s_mov_b64 exec, s[98:99]
	s_waitcnt vmcnt(14)
	v_cvt_scalef32_pk32_f32_fp6 v[0:31], v[32:37], 1.0
	global_load_dwordx2 v[36:37], v167, s[62:63] offset:16
	global_load_dwordx4 v[32:35], v167, s[62:63]
	v_pk_mul_f32 v[246:247], v[0:1], v[96:97]
	v_pk_mul_f32 v[254:255], v[2:3], v[98:99]
	v_pk_mul_f32 v[160:161], v[4:5], v[100:101]
	v_pk_fma_f32 v[246:247], v[6:7], v[102:103], v[246:247]
	v_pk_fma_f32 v[254:255], v[8:9], v[104:105], v[254:255]
	v_pk_fma_f32 v[160:161], v[10:11], v[106:107], v[160:161]
	v_pk_fma_f32 v[246:247], v[12:13], v[108:109], v[246:247]
	v_pk_fma_f32 v[254:255], v[14:15], v[110:111], v[254:255]
	v_pk_fma_f32 v[160:161], v[16:17], v[112:113], v[160:161]
	v_pk_fma_f32 v[246:247], v[18:19], v[114:115], v[246:247]
	v_pk_fma_f32 v[254:255], v[20:21], v[116:117], v[254:255]
	v_pk_fma_f32 v[160:161], v[22:23], v[118:119], v[160:161]
	v_pk_fma_f32 v[246:247], v[24:25], v[120:121], v[246:247]
	v_pk_fma_f32 v[254:255], v[26:27], v[122:123], v[254:255]
	v_pk_fma_f32 v[160:161], v[28:29], v[124:125], v[160:161]
	v_pk_fma_f32 v[246:247], v[30:31], v[126:127], v[246:247]
	v_pk_add_f32 v[254:255], v[254:255], v[160:161]
	s_nop 0
	v_pk_add_f32 v[246:247], v[246:247], v[254:255]
	s_nop 0
	v_add_f32_e32 v165, v246, v247
	v_add_f32_dpp v162, v162, v162 row_shr:1 row_mask:0xf bank_mask:0xf bound_ctrl:1
	v_add_f32_dpp v163, v163, v163 row_shr:1 row_mask:0xf bank_mask:0xf bound_ctrl:1
	v_add_f32_dpp v164, v164, v164 row_shr:1 row_mask:0xf bank_mask:0xf bound_ctrl:1
	v_add_f32_dpp v165, v165, v165 row_shr:1 row_mask:0xf bank_mask:0xf bound_ctrl:1
	v_add_f32_dpp v162, v162, v162 row_shr:2 row_mask:0xf bank_mask:0xf bound_ctrl:1
	v_add_f32_dpp v163, v163, v163 row_shr:2 row_mask:0xf bank_mask:0xf bound_ctrl:1
	v_add_f32_dpp v164, v164, v164 row_shr:2 row_mask:0xf bank_mask:0xf bound_ctrl:1
	v_add_f32_dpp v165, v165, v165 row_shr:2 row_mask:0xf bank_mask:0xf bound_ctrl:1
	v_add_f32_dpp v162, v162, v162 row_shr:4 row_mask:0xf bank_mask:0xf bound_ctrl:1
	v_add_f32_dpp v163, v163, v163 row_shr:4 row_mask:0xf bank_mask:0xf bound_ctrl:1
	v_add_f32_dpp v164, v164, v164 row_shr:4 row_mask:0xf bank_mask:0xf bound_ctrl:1
	v_add_f32_dpp v165, v165, v165 row_shr:4 row_mask:0xf bank_mask:0xf bound_ctrl:1
	v_add_f32_dpp v162, v162, v162 row_shr:8 row_mask:0xf bank_mask:0xf bound_ctrl:1
	v_add_f32_dpp v163, v163, v163 row_shr:8 row_mask:0xf bank_mask:0xf bound_ctrl:1
	v_add_f32_dpp v164, v164, v164 row_shr:8 row_mask:0xf bank_mask:0xf bound_ctrl:1
	v_add_f32_dpp v165, v165, v165 row_shr:8 row_mask:0xf bank_mask:0xf bound_ctrl:1
	v_add_f32_dpp v162, v162, v162 row_bcast:15 row_mask:0xa bank_mask:0xf
	v_add_f32_dpp v163, v163, v163 row_bcast:15 row_mask:0xa bank_mask:0xf
	v_add_f32_dpp v164, v164, v164 row_bcast:15 row_mask:0xa bank_mask:0xf
	v_add_f32_dpp v165, v165, v165 row_bcast:15 row_mask:0xa bank_mask:0xf
	s_mov_b64 s[98:99], exec
	s_mov_b32 exec_lo, 0x80000000
	s_mov_b32 exec_hi, 0x80000000
	ds_write_b32 v74, v162 offset:64
	ds_write_b32 v74, v163 offset:72
	ds_write_b32 v74, v164 offset:80
	ds_write_b32 v74, v165 offset:88
	s_mov_b64 exec, s[98:99]
	v_readlane_b32 s54, v92, 40
	v_readlane_b32 s55, v92, 41
	s_mul_i32 s0, s54, 0x300
	s_mul_i32 s1, s55, 0x300
	v_add_u32_e32 v167, s0, v195
	s_and_saveexec_b64 s[98:99], s[40:41]
	v_add_u32_e32 v167, s1, v195
	s_mov_b64 exec, s[98:99]
	s_waitcnt vmcnt(14)
; __device__ void peer_gather_phase(const Params& P, int l, bool do_store) {
;     ...
;         const int ea = __builtin_amdgcn_readlane(evs, kb + 2 * pr), eb = __builtin_amdgcn_readlane(evs, kb + 2 * pr + 1);
;         const uint2* up = (const uint2*)(U + (size_t)(uphi ? eb : ea) * 768);
;         u6[3 * pr] = up[0]; u6[3 * pr + 1] = up[1]; u6[3 * pr + 2] = up[2];
;     ...
;         v6u_t qv; qv[0] = u6[3 * pr].x; qv[1] = u6[3 * pr].y; qv[2] = u6[3 * pr + 1].x; qv[3] = u6[3 * pr + 1].y; qv[4] = u6[3 * pr + 2].x; qv[5] = u6[3 * pr + 2].y;
;         const v32f_t wv = __builtin_amdgcn_cvt_scalef32_pk32_f32_fp6(qv, 1.0f);
;         f32x2 a2 = f32x2{0.f, 0.f};
; #pragma unroll
;         for (int i = 0; i < 16; ++i) a2 += f32x2{wv[2 * i], wv[2 * i + 1]} * xu[i];
;         float hs = a2.x + a2.y;
;         hs += dpp_row_shr(hs, 1); hs += dpp_row_shr(hs, 2); hs += dpp_row_shr(hs, 4); hs += dpp_row_shr(hs, 8);
;         hs += __builtin_bit_cast(float, __builtin_amdgcn_update_dpp(0, __builtin_bit_cast(int, hs), 0x142, 0xa, 0xf, false));
;         const float da = __builtin_bit_cast(float, __builtin_amdgcn_readlane(__builtin_bit_cast(int, hs), 31));
;         const float db = __builtin_bit_cast(float, __builtin_amdgcn_readlane(__builtin_bit_cast(int, hs), 63));
;         dvec = (lane == kb + 2 * pr) ? da : dvec;
;         dvec = (lane == kb + 2 * pr + 1) ? db : dvec;
	v_cvt_scalef32_pk32_f32_fp6 v[0:31], v[196:201], 1.0
	global_load_dwordx2 v[200:201], v167, s[62:63] offset:16
	global_load_dwordx4 v[196:199], v167, s[62:63]
	v_pk_mul_f32 v[246:247], v[0:1], v[96:97]
	v_pk_mul_f32 v[254:255], v[2:3], v[98:99]
	v_pk_mul_f32 v[160:161], v[4:5], v[100:101]
	v_pk_fma_f32 v[246:247], v[6:7], v[102:103], v[246:247]
	v_pk_fma_f32 v[254:255], v[8:9], v[104:105], v[254:255]
	v_pk_fma_f32 v[160:161], v[10:11], v[106:107], v[160:161]
	v_pk_fma_f32 v[246:247], v[12:13], v[108:109], v[246:247]
	v_pk_fma_f32 v[254:255], v[14:15], v[110:111], v[254:255]
	v_pk_fma_f32 v[160:161], v[16:17], v[112:113], v[160:161]
	v_pk_fma_f32 v[246:247], v[18:19], v[114:115], v[246:247]
	v_pk_fma_f32 v[254:255], v[20:21], v[116:117], v[254:255]
	v_pk_fma_f32 v[160:161], v[22:23], v[118:119], v[160:161]
	v_pk_fma_f32 v[246:247], v[24:25], v[120:121], v[246:247]
	v_pk_fma_f32 v[254:255], v[26:27], v[122:123], v[254:255]
	v_pk_fma_f32 v[160:161], v[28:29], v[124:125], v[160:161]
	v_pk_fma_f32 v[246:247], v[30:31], v[126:127], v[246:247]
	v_pk_add_f32 v[254:255], v[254:255], v[160:161]
	s_nop 0
	v_pk_add_f32 v[246:247], v[246:247], v[254:255]
	s_nop 0
	v_add_f32_e32 v162, v246, v247
	v_readlane_b32 s54, v92, 42
	v_readlane_b32 s55, v92, 43
	s_mul_i32 s0, s54, 0x300
	s_mul_i32 s1, s55, 0x300
	v_add_u32_e32 v167, s0, v195
	s_and_saveexec_b64 s[98:99], s[40:41]
	v_add_u32_e32 v167, s1, v195
	s_mov_b64 exec, s[98:99]
	s_waitcnt vmcnt(14)
	v_cvt_scalef32_pk32_f32_fp6 v[0:31], v[228:233], 1.0
	global_load_dwordx2 v[232:233], v167, s[62:63] offset:16
	global_load_dwordx4 v[228:231], v167, s[62:63]
	v_pk_mul_f32 v[246:247], v[0:1], v[96:97]
	v_pk_mul_f32 v[254:255], v[2:3], v[98:99]
	v_pk_mul_f32 v[160:161], v[4:5], v[100:101]
	v_pk_fma_f32 v[246:247], v[6:7], v[102:103], v[246:247]
	v_pk_fma_f32 v[254:255], v[8:9], v[104:105], v[254:255]
	v_pk_fma_f32 v[160:161], v[10:11], v[106:107], v[160:161]
	v_pk_fma_f32 v[246:247], v[12:13], v[108:109], v[246:247]
	v_pk_fma_f32 v[254:255], v[14:15], v[110:111], v[254:255]
	v_pk_fma_f32 v[160:161], v[16:17], v[112:113], v[160:161]
	v_pk_fma_f32 v[246:247], v[18:19], v[114:115], v[246:247]
	v_pk_fma_f32 v[254:255], v[20:21], v[116:117], v[254:255]
	v_pk_fma_f32 v[160:161], v[22:23], v[118:119], v[160:161]
	v_pk_fma_f32 v[246:247], v[24:25], v[120:121], v[246:247]
	v_pk_fma_f32 v[254:255], v[26:27], v[122:123], v[254:255]
	v_pk_fma_f32 v[160:161], v[28:29], v[124:125], v[160:161]
	v_pk_fma_f32 v[246:247], v[30:31], v[126:127], v[246:247]
	v_pk_add_f32 v[254:255], v[254:255], v[160:161]
	s_nop 0
	v_pk_add_f32 v[246:247], v[246:247], v[254:255]
	s_nop 0
	v_add_f32_e32 v163, v246, v247
	v_readlane_b32 s54, v92, 44
	v_readlane_b32 s55, v92, 45
	s_mul_i32 s0, s54, 0x300
	s_mul_i32 s1, s55, 0x300
	v_add_u32_e32 v167, s0, v195
	s_and_saveexec_b64 s[98:99], s[40:41]
	v_add_u32_e32 v167, s1, v195
	s_mov_b64 exec, s[98:99]
	s_waitcnt vmcnt(14)
	v_cvt_scalef32_pk32_f32_fp6 v[0:31], v[234:239], 1.0
	global_load_dwordx2 v[238:239], v167, s[62:63] offset:16
	global_load_dwordx4 v[234:237], v167, s[62:63]
	v_pk_mul_f32 v[246:247], v[0:1], v[96:97]
	v_pk_mul_f32 v[254:255], v[2:3], v[98:99]
	v_pk_mul_f32 v[160:161], v[4:5], v[100:101]
	v_pk_fma_f32 v[246:247], v[6:7], v[102:103], v[246:247]
	v_pk_fma_f32 v[254:255], v[8:9], v[104:105], v[254:255]
	v_pk_fma_f32 v[160:161], v[10:11], v[106:107], v[160:161]
	v_pk_fma_f32 v[246:247], v[12:13], v[108:109], v[246:247]
	v_pk_fma_f32 v[254:255], v[14:15], v[110:111], v[254:255]
	v_pk_fma_f32 v[160:161], v[16:17], v[112:113], v[160:161]
	v_pk_fma_f32 v[246:247], v[18:19], v[114:115], v[246:247]
	v_pk_fma_f32 v[254:255], v[20:21], v[116:117], v[254:255]
	v_pk_fma_f32 v[160:161], v[22:23], v[118:119], v[160:161]
	v_pk_fma_f32 v[246:247], v[24:25], v[120:121], v[246:247]
	v_pk_fma_f32 v[254:255], v[26:27], v[122:123], v[254:255]
	v_pk_fma_f32 v[160:161], v[28:29], v[124:125], v[160:161]
	v_pk_fma_f32 v[246:247], v[30:31], v[126:127], v[246:247]
	v_pk_add_f32 v[254:255], v[254:255], v[160:161]
	s_nop 0
	v_pk_add_f32 v[246:247], v[246:247], v[254:255]
	s_nop 0
	v_add_f32_e32 v164, v246, v247
	v_readlane_b32 s54, v92, 46
	v_readlane_b32 s55, v92, 47
	s_mul_i32 s0, s54, 0x300
	s_mul_i32 s1, s55, 0x300
	v_add_u32_e32 v167, s0, v195
	s_and_saveexec_b64 s[98:99], s[40:41]
	v_add_u32_e32 v167, s1, v195
	s_mov_b64 exec, s[98:99]
	s_waitcnt vmcnt(14)
; __device__ void peer_gather_phase(const Params& P, int l, bool do_store) {
;     ...
;         const int ea = __builtin_amdgcn_readlane(evs, kb + 2 * pr), eb = __builtin_amdgcn_readlane(evs, kb + 2 * pr + 1);
;         const uint2* up = (const uint2*)(U + (size_t)(uphi ? eb : ea) * 768);
;         u6[3 * pr] = up[0]; u6[3 * pr + 1] = up[1]; u6[3 * pr + 2] = up[2];
;         v8[2 * pr] = *(const uint2*)(V + (size_t)ea * 512);
;         v8[2 * pr + 1] = *(const uint2*)(V + (size_t)eb * 512);
;       }
;     };
;     auto compute_batch = [&](const uint2 (&u6)[12], const uint2 (&v8)[8], int bt) {
;       const int kb = (bt & 7) * 8;
;       float dvec = 0.f;
; #pragma unroll
;       for (int pr = 0; pr < 4; ++pr) {
;         v6u_t qv; qv[0] = u6[3 * pr].x; qv[1] = u6[3 * pr].y; qv[2] = u6[3 * pr + 1].x; qv[3] = u6[3 * pr + 1].y; qv[4] = u6[3 * pr + 2].x; qv[5] = u6[3 * pr + 2].y;
;         const v32f_t wv = __builtin_amdgcn_cvt_scalef32_pk32_f32_fp6(qv, 1.0f);
;         f32x2 a2 = f32x2{0.f, 0.f};
; #pragma unroll
;         for (int i = 0; i < 16; ++i) a2 += f32x2{wv[2 * i], wv[2 * i + 1]} * xu[i];
;         float hs = a2.x + a2.y;
;         hs += dpp_row_shr(hs, 1); hs += dpp_row_shr(hs, 2); hs += dpp_row_shr(hs, 4); hs += dpp_row_shr(hs, 8);
;         hs += __builtin_bit_cast(float, __builtin_amdgcn_update_dpp(0, __builtin_bit_cast(int, hs), 0x142, 0xa, 0xf, false));
;         const float da = __builtin_bit_cast(float, __builtin_amdgcn_readlane(__builtin_bit_cast(int, hs), 31));
;         const float db = __builtin_bit_cast(float, __builtin_amdgcn_readlane(__builtin_bit_cast(int, hs), 63));
;         dvec = (lane == kb + 2 * pr) ? da : dvec;
;         dvec = (lane == kb + 2 * pr + 1) ? db : dvec;
	v_cvt_scalef32_pk32_f32_fp6 v[0:31], v[240:245], 1.0
	global_load_dwordx2 v[244:245], v167, s[62:63] offset:16
	global_load_dwordx4 v[240:243], v167, s[62:63]
	v_pk_mul_f32 v[246:247], v[0:1], v[96:97]
	v_pk_mul_f32 v[254:255], v[2:3], v[98:99]
	v_pk_mul_f32 v[160:161], v[4:5], v[100:101]
	v_pk_fma_f32 v[246:247], v[6:7], v[102:103], v[246:247]
	v_pk_fma_f32 v[254:255], v[8:9], v[104:105], v[254:255]
	v_pk_fma_f32 v[160:161], v[10:11], v[106:107], v[160:161]
	v_pk_fma_f32 v[246:247], v[12:13], v[108:109], v[246:247]
	v_pk_fma_f32 v[254:255], v[14:15], v[110:111], v[254:255]
	v_pk_fma_f32 v[160:161], v[16:17], v[112:113], v[160:161]
	v_pk_fma_f32 v[246:247], v[18:19], v[114:115], v[246:247]
	v_pk_fma_f32 v[254:255], v[20:21], v[116:117], v[254:255]
	v_pk_fma_f32 v[160:161], v[22:23], v[118:119], v[160:161]
	v_pk_fma_f32 v[246:247], v[24:25], v[120:121], v[246:247]
	v_pk_fma_f32 v[254:255], v[26:27], v[122:123], v[254:255]
	v_pk_fma_f32 v[160:161], v[28:29], v[124:125], v[160:161]
	v_pk_fma_f32 v[246:247], v[30:31], v[126:127], v[246:247]
	v_pk_add_f32 v[254:255], v[254:255], v[160:161]
	s_nop 0
	v_pk_add_f32 v[246:247], v[246:247], v[254:255]
	s_nop 0
	v_add_f32_e32 v165, v246, v247
	v_add_f32_dpp v162, v162, v162 row_shr:1 row_mask:0xf bank_mask:0xf bound_ctrl:1
	v_add_f32_dpp v163, v163, v163 row_shr:1 row_mask:0xf bank_mask:0xf bound_ctrl:1
	v_add_f32_dpp v164, v164, v164 row_shr:1 row_mask:0xf bank_mask:0xf bound_ctrl:1
	v_add_f32_dpp v165, v165, v165 row_shr:1 row_mask:0xf bank_mask:0xf bound_ctrl:1
	v_add_f32_dpp v162, v162, v162 row_shr:2 row_mask:0xf bank_mask:0xf bound_ctrl:1
	v_add_f32_dpp v163, v163, v163 row_shr:2 row_mask:0xf bank_mask:0xf bound_ctrl:1
	v_add_f32_dpp v164, v164, v164 row_shr:2 row_mask:0xf bank_mask:0xf bound_ctrl:1
	v_add_f32_dpp v165, v165, v165 row_shr:2 row_mask:0xf bank_mask:0xf bound_ctrl:1
	v_add_f32_dpp v162, v162, v162 row_shr:4 row_mask:0xf bank_mask:0xf bound_ctrl:1
	v_add_f32_dpp v163, v163, v163 row_shr:4 row_mask:0xf bank_mask:0xf bound_ctrl:1
	v_add_f32_dpp v164, v164, v164 row_shr:4 row_mask:0xf bank_mask:0xf bound_ctrl:1
	v_add_f32_dpp v165, v165, v165 row_shr:4 row_mask:0xf bank_mask:0xf bound_ctrl:1
	v_add_f32_dpp v162, v162, v162 row_shr:8 row_mask:0xf bank_mask:0xf bound_ctrl:1
	v_add_f32_dpp v163, v163, v163 row_shr:8 row_mask:0xf bank_mask:0xf bound_ctrl:1
	v_add_f32_dpp v164, v164, v164 row_shr:8 row_mask:0xf bank_mask:0xf bound_ctrl:1
	v_add_f32_dpp v165, v165, v165 row_shr:8 row_mask:0xf bank_mask:0xf bound_ctrl:1
	v_add_f32_dpp v162, v162, v162 row_bcast:15 row_mask:0xa bank_mask:0xf
	v_add_f32_dpp v163, v163, v163 row_bcast:15 row_mask:0xa bank_mask:0xf
	v_add_f32_dpp v164, v164, v164 row_bcast:15 row_mask:0xa bank_mask:0xf
	v_add_f32_dpp v165, v165, v165 row_bcast:15 row_mask:0xa bank_mask:0xf
	s_mov_b64 s[98:99], exec
	s_mov_b32 exec_lo, 0x80000000
	s_mov_b32 exec_hi, 0x80000000
	ds_write_b32 v74, v162 offset:96
	ds_write_b32 v74, v163 offset:104
	ds_write_b32 v74, v164 offset:112
	ds_write_b32 v74, v165 offset:120
	s_mov_b64 exec, s[98:99]
	v_readlane_b32 s54, v92, 48
	v_readlane_b32 s55, v92, 49
	s_mul_i32 s0, s54, 0x300
	s_mul_i32 s1, s55, 0x300
	v_add_u32_e32 v167, s0, v195
	s_and_saveexec_b64 s[98:99], s[40:41]
	v_add_u32_e32 v167, s1, v195
	s_mov_b64 exec, s[98:99]
	s_waitcnt vmcnt(14)
	v_cvt_scalef32_pk32_f32_fp6 v[0:31], v[50:55], 1.0
	global_load_dwordx2 v[54:55], v167, s[62:63] offset:16
	global_load_dwordx4 v[50:53], v167, s[62:63]
	v_pk_mul_f32 v[246:247], v[0:1], v[96:97]
	v_pk_mul_f32 v[254:255], v[2:3], v[98:99]
	v_pk_mul_f32 v[160:161], v[4:5], v[100:101]
	v_pk_fma_f32 v[246:247], v[6:7], v[102:103], v[246:247]
	v_pk_fma_f32 v[254:255], v[8:9], v[104:105], v[254:255]
	v_pk_fma_f32 v[160:161], v[10:11], v[106:107], v[160:161]
	v_pk_fma_f32 v[246:247], v[12:13], v[108:109], v[246:247]
	v_pk_fma_f32 v[254:255], v[14:15], v[110:111], v[254:255]
	v_pk_fma_f32 v[160:161], v[16:17], v[112:113], v[160:161]
	v_pk_fma_f32 v[246:247], v[18:19], v[114:115], v[246:247]
	v_pk_fma_f32 v[254:255], v[20:21], v[116:117], v[254:255]
	v_pk_fma_f32 v[160:161], v[22:23], v[118:119], v[160:161]
	v_pk_fma_f32 v[246:247], v[24:25], v[120:121], v[246:247]
	v_pk_fma_f32 v[254:255], v[26:27], v[122:123], v[254:255]
	v_pk_fma_f32 v[160:161], v[28:29], v[124:125], v[160:161]
	v_pk_fma_f32 v[246:247], v[30:31], v[126:127], v[246:247]
	v_pk_add_f32 v[254:255], v[254:255], v[160:161]
	s_nop 0
	v_pk_add_f32 v[246:247], v[246:247], v[254:255]
	s_nop 0
	v_add_f32_e32 v162, v246, v247
	v_readlane_b32 s54, v92, 50
	v_readlane_b32 s55, v92, 51
	s_mul_i32 s0, s54, 0x300
	s_mul_i32 s1, s55, 0x300
	v_add_u32_e32 v167, s0, v195
	s_and_saveexec_b64 s[98:99], s[40:41]
	v_add_u32_e32 v167, s1, v195
	s_mov_b64 exec, s[98:99]
	s_waitcnt vmcnt(14)
	v_cvt_scalef32_pk32_f32_fp6 v[0:31], v[44:49], 1.0
	global_load_dwordx2 v[48:49], v167, s[62:63] offset:16
	global_load_dwordx4 v[44:47], v167, s[62:63]
	v_pk_mul_f32 v[246:247], v[0:1], v[96:97]
	v_pk_mul_f32 v[254:255], v[2:3], v[98:99]
	v_pk_mul_f32 v[160:161], v[4:5], v[100:101]
	v_pk_fma_f32 v[246:247], v[6:7], v[102:103], v[246:247]
	v_pk_fma_f32 v[254:255], v[8:9], v[104:105], v[254:255]
	v_pk_fma_f32 v[160:161], v[10:11], v[106:107], v[160:161]
	v_pk_fma_f32 v[246:247], v[12:13], v[108:109], v[246:247]
	v_pk_fma_f32 v[254:255], v[14:15], v[110:111], v[254:255]
	v_pk_fma_f32 v[160:161], v[16:17], v[112:113], v[160:161]
	v_pk_fma_f32 v[246:247], v[18:19], v[114:115], v[246:247]
	v_pk_fma_f32 v[254:255], v[20:21], v[116:117], v[254:255]
	v_pk_fma_f32 v[160:161], v[22:23], v[118:119], v[160:161]
	v_pk_fma_f32 v[246:247], v[24:25], v[120:121], v[246:247]
	v_pk_fma_f32 v[254:255], v[26:27], v[122:123], v[254:255]
	v_pk_fma_f32 v[160:161], v[28:29], v[124:125], v[160:161]
	v_pk_fma_f32 v[246:247], v[30:31], v[126:127], v[246:247]
	v_pk_add_f32 v[254:255], v[254:255], v[160:161]
	s_nop 0
	v_pk_add_f32 v[246:247], v[246:247], v[254:255]
	s_nop 0
	v_add_f32_e32 v163, v246, v247
	v_readlane_b32 s54, v92, 52
	v_readlane_b32 s55, v92, 53
	s_mul_i32 s0, s54, 0x300
	s_mul_i32 s1, s55, 0x300
	v_add_u32_e32 v167, s0, v195
	s_and_saveexec_b64 s[98:99], s[40:41]
	v_add_u32_e32 v167, s1, v195
	s_mov_b64 exec, s[98:99]
	s_waitcnt vmcnt(14)
; __device__ void peer_gather_phase(const Params& P, int l, bool do_store) {
;     ...
;         const int ea = __builtin_amdgcn_readlane(evs, kb + 2 * pr), eb = __builtin_amdgcn_readlane(evs, kb + 2 * pr + 1);
;         const uint2* up = (const uint2*)(U + (size_t)(uphi ? eb : ea) * 768);
;         u6[3 * pr] = up[0]; u6[3 * pr + 1] = up[1]; u6[3 * pr + 2] = up[2];
;         v8[2 * pr] = *(const uint2*)(V + (size_t)ea * 512);
;         v8[2 * pr + 1] = *(const uint2*)(V + (size_t)eb * 512);
;       }
;     };
;     auto compute_batch = [&](const uint2 (&u6)[12], const uint2 (&v8)[8], int bt) {
;       const int kb = (bt & 7) * 8;
;       float dvec = 0.f;
; #pragma unroll
;       for (int pr = 0; pr < 4; ++pr) {
;         v6u_t qv; qv[0] = u6[3 * pr].x; qv[1] = u6[3 * pr].y; qv[2] = u6[3 * pr + 1].x; qv[3] = u6[3 * pr + 1].y; qv[4] = u6[3 * pr + 2].x; qv[5] = u6[3 * pr + 2].y;
;         const v32f_t wv = __builtin_amdgcn_cvt_scalef32_pk32_f32_fp6(qv, 1.0f);
;         f32x2 a2 = f32x2{0.f, 0.f};
; #pragma unroll
;         for (int i = 0; i < 16; ++i) a2 += f32x2{wv[2 * i], wv[2 * i + 1]} * xu[i];
;         float hs = a2.x + a2.y;
;         hs += dpp_row_shr(hs, 1); hs += dpp_row_shr(hs, 2); hs += dpp_row_shr(hs, 4); hs += dpp_row_shr(hs, 8);
;         hs += __builtin_bit_cast(float, __builtin_amdgcn_update_dpp(0, __builtin_bit_cast(int, hs), 0x142, 0xa, 0xf, false));
;         const float da = __builtin_bit_cast(float, __builtin_amdgcn_readlane(__builtin_bit_cast(int, hs), 31));
;         const float db = __builtin_bit_cast(float, __builtin_amdgcn_readlane(__builtin_bit_cast(int, hs), 63));
;         dvec = (lane == kb + 2 * pr) ? da : dvec;
;         dvec = (lane == kb + 2 * pr + 1) ? db : dvec;
	v_cvt_scalef32_pk32_f32_fp6 v[0:31], v[38:43], 1.0
	global_load_dwordx2 v[42:43], v167, s[62:63] offset:16
	global_load_dwordx4 v[38:41], v167, s[62:63]
	v_pk_mul_f32 v[246:247], v[0:1], v[96:97]
	v_pk_mul_f32 v[254:255], v[2:3], v[98:99]
	v_pk_mul_f32 v[160:161], v[4:5], v[100:101]
	v_pk_fma_f32 v[246:247], v[6:7], v[102:103], v[246:247]
	v_pk_fma_f32 v[254:255], v[8:9], v[104:105], v[254:255]
	v_pk_fma_f32 v[160:161], v[10:11], v[106:107], v[160:161]
	v_pk_fma_f32 v[246:247], v[12:13], v[108:109], v[246:247]
	v_pk_fma_f32 v[254:255], v[14:15], v[110:111], v[254:255]
	v_pk_fma_f32 v[160:161], v[16:17], v[112:113], v[160:161]
	v_pk_fma_f32 v[246:247], v[18:19], v[114:115], v[246:247]
	v_pk_fma_f32 v[254:255], v[20:21], v[116:117], v[254:255]
	v_pk_fma_f32 v[160:161], v[22:23], v[118:119], v[160:161]
	v_pk_fma_f32 v[246:247], v[24:25], v[120:121], v[246:247]
	v_pk_fma_f32 v[254:255], v[26:27], v[122:123], v[254:255]
	v_pk_fma_f32 v[160:161], v[28:29], v[124:125], v[160:161]
	v_pk_fma_f32 v[246:247], v[30:31], v[126:127], v[246:247]
	v_pk_add_f32 v[254:255], v[254:255], v[160:161]
	s_nop 0
	v_pk_add_f32 v[246:247], v[246:247], v[254:255]
	s_nop 0
	v_add_f32_e32 v164, v246, v247
	v_readlane_b32 s54, v92, 54
	v_readlane_b32 s55, v92, 55
	s_mul_i32 s0, s54, 0x300
	s_mul_i32 s1, s55, 0x300
	v_add_u32_e32 v167, s0, v195
	s_and_saveexec_b64 s[98:99], s[40:41]
	v_add_u32_e32 v167, s1, v195
	s_mov_b64 exec, s[98:99]
	s_waitcnt vmcnt(14)
	v_cvt_scalef32_pk32_f32_fp6 v[0:31], v[32:37], 1.0
	global_load_dwordx2 v[36:37], v167, s[62:63] offset:16
	global_load_dwordx4 v[32:35], v167, s[62:63]
	v_pk_mul_f32 v[246:247], v[0:1], v[96:97]
	v_pk_mul_f32 v[254:255], v[2:3], v[98:99]
	v_pk_mul_f32 v[160:161], v[4:5], v[100:101]
	v_pk_fma_f32 v[246:247], v[6:7], v[102:103], v[246:247]
	v_pk_fma_f32 v[254:255], v[8:9], v[104:105], v[254:255]
	v_pk_fma_f32 v[160:161], v[10:11], v[106:107], v[160:161]
	v_pk_fma_f32 v[246:247], v[12:13], v[108:109], v[246:247]
	v_pk_fma_f32 v[254:255], v[14:15], v[110:111], v[254:255]
	v_pk_fma_f32 v[160:161], v[16:17], v[112:113], v[160:161]
	v_pk_fma_f32 v[246:247], v[18:19], v[114:115], v[246:247]
	v_pk_fma_f32 v[254:255], v[20:21], v[116:117], v[254:255]
	v_pk_fma_f32 v[160:161], v[22:23], v[118:119], v[160:161]
	v_pk_fma_f32 v[246:247], v[24:25], v[120:121], v[246:247]
	v_pk_fma_f32 v[254:255], v[26:27], v[122:123], v[254:255]
	v_pk_fma_f32 v[160:161], v[28:29], v[124:125], v[160:161]
	v_pk_fma_f32 v[246:247], v[30:31], v[126:127], v[246:247]
	v_pk_add_f32 v[254:255], v[254:255], v[160:161]
	s_nop 0
	v_pk_add_f32 v[246:247], v[246:247], v[254:255]
	s_nop 0
	v_add_f32_e32 v165, v246, v247
	v_add_f32_dpp v162, v162, v162 row_shr:1 row_mask:0xf bank_mask:0xf bound_ctrl:1
	v_add_f32_dpp v163, v163, v163 row_shr:1 row_mask:0xf bank_mask:0xf bound_ctrl:1
	v_add_f32_dpp v164, v164, v164 row_shr:1 row_mask:0xf bank_mask:0xf bound_ctrl:1
	v_add_f32_dpp v165, v165, v165 row_shr:1 row_mask:0xf bank_mask:0xf bound_ctrl:1
	v_add_f32_dpp v162, v162, v162 row_shr:2 row_mask:0xf bank_mask:0xf bound_ctrl:1
	v_add_f32_dpp v163, v163, v163 row_shr:2 row_mask:0xf bank_mask:0xf bound_ctrl:1
	v_add_f32_dpp v164, v164, v164 row_shr:2 row_mask:0xf bank_mask:0xf bound_ctrl:1
	v_add_f32_dpp v165, v165, v165 row_shr:2 row_mask:0xf bank_mask:0xf bound_ctrl:1
	v_add_f32_dpp v162, v162, v162 row_shr:4 row_mask:0xf bank_mask:0xf bound_ctrl:1
	v_add_f32_dpp v163, v163, v163 row_shr:4 row_mask:0xf bank_mask:0xf bound_ctrl:1
	v_add_f32_dpp v164, v164, v164 row_shr:4 row_mask:0xf bank_mask:0xf bound_ctrl:1
	v_add_f32_dpp v165, v165, v165 row_shr:4 row_mask:0xf bank_mask:0xf bound_ctrl:1
	v_add_f32_dpp v162, v162, v162 row_shr:8 row_mask:0xf bank_mask:0xf bound_ctrl:1
	v_add_f32_dpp v163, v163, v163 row_shr:8 row_mask:0xf bank_mask:0xf bound_ctrl:1
	v_add_f32_dpp v164, v164, v164 row_shr:8 row_mask:0xf bank_mask:0xf bound_ctrl:1
	v_add_f32_dpp v165, v165, v165 row_shr:8 row_mask:0xf bank_mask:0xf bound_ctrl:1
	v_add_f32_dpp v162, v162, v162 row_bcast:15 row_mask:0xa bank_mask:0xf
	v_add_f32_dpp v163, v163, v163 row_bcast:15 row_mask:0xa bank_mask:0xf
	v_add_f32_dpp v164, v164, v164 row_bcast:15 row_mask:0xa bank_mask:0xf
	v_add_f32_dpp v165, v165, v165 row_bcast:15 row_mask:0xa bank_mask:0xf
	s_mov_b64 s[98:99], exec
	s_mov_b32 exec_lo, 0x80000000
	s_mov_b32 exec_hi, 0x80000000
	ds_write_b32 v74, v162 offset:128
	ds_write_b32 v74, v163 offset:136
	ds_write_b32 v74, v164 offset:144
	ds_write_b32 v74, v165 offset:152
	s_mov_b64 exec, s[98:99]
	v_readlane_b32 s54, v92, 56
	v_readlane_b32 s55, v92, 57
	s_mul_i32 s0, s54, 0x300
	s_mul_i32 s1, s55, 0x300
	v_add_u32_e32 v167, s0, v195
	s_and_saveexec_b64 s[98:99], s[40:41]
	v_add_u32_e32 v167, s1, v195
	s_mov_b64 exec, s[98:99]
	s_waitcnt vmcnt(14)
	v_cvt_scalef32_pk32_f32_fp6 v[0:31], v[196:201], 1.0
	global_load_dwordx2 v[200:201], v167, s[62:63] offset:16
	global_load_dwordx4 v[196:199], v167, s[62:63]
	v_pk_mul_f32 v[246:247], v[0:1], v[96:97]
	v_pk_mul_f32 v[254:255], v[2:3], v[98:99]
	v_pk_mul_f32 v[160:161], v[4:5], v[100:101]
	v_pk_fma_f32 v[246:247], v[6:7], v[102:103], v[246:247]
	v_pk_fma_f32 v[254:255], v[8:9], v[104:105], v[254:255]
	v_pk_fma_f32 v[160:161], v[10:11], v[106:107], v[160:161]
	v_pk_fma_f32 v[246:247], v[12:13], v[108:109], v[246:247]
	v_pk_fma_f32 v[254:255], v[14:15], v[110:111], v[254:255]
	v_pk_fma_f32 v[160:161], v[16:17], v[112:113], v[160:161]
	v_pk_fma_f32 v[246:247], v[18:19], v[114:115], v[246:247]
	v_pk_fma_f32 v[254:255], v[20:21], v[116:117], v[254:255]
	v_pk_fma_f32 v[160:161], v[22:23], v[118:119], v[160:161]
	v_pk_fma_f32 v[246:247], v[24:25], v[120:121], v[246:247]
	v_pk_fma_f32 v[254:255], v[26:27], v[122:123], v[254:255]
	v_pk_fma_f32 v[160:161], v[28:29], v[124:125], v[160:161]
	v_pk_fma_f32 v[246:247], v[30:31], v[126:127], v[246:247]
	v_pk_add_f32 v[254:255], v[254:255], v[160:161]
	s_nop 0
	v_pk_add_f32 v[246:247], v[246:247], v[254:255]
	s_nop 0
	v_add_f32_e32 v162, v246, v247
	v_readlane_b32 s54, v92, 58
	v_readlane_b32 s55, v92, 59
	s_mul_i32 s0, s54, 0x300
	s_mul_i32 s1, s55, 0x300
	v_add_u32_e32 v167, s0, v195
	s_and_saveexec_b64 s[98:99], s[40:41]
	v_add_u32_e32 v167, s1, v195
	s_mov_b64 exec, s[98:99]
	s_waitcnt vmcnt(14)
; __device__ void peer_gather_phase(const Params& P, int l, bool do_store) {
;     ...
;         const int ea = __builtin_amdgcn_readlane(evs, kb + 2 * pr), eb = __builtin_amdgcn_readlane(evs, kb + 2 * pr + 1);
;         const uint2* up = (const uint2*)(U + (size_t)(uphi ? eb : ea) * 768);
;         u6[3 * pr] = up[0]; u6[3 * pr + 1] = up[1]; u6[3 * pr + 2] = up[2];
;         v8[2 * pr] = *(const uint2*)(V + (size_t)ea * 512);
;         v8[2 * pr + 1] = *(const uint2*)(V + (size_t)eb * 512);
;       }
;     };
;     auto compute_batch = [&](const uint2 (&u6)[12], const uint2 (&v8)[8], int bt) {
;       const int kb = (bt & 7) * 8;
;       float dvec = 0.f;
; #pragma unroll
;       for (int pr = 0; pr < 4; ++pr) {
;         v6u_t qv; qv[0] = u6[3 * pr].x; qv[1] = u6[3 * pr].y; qv[2] = u6[3 * pr + 1].x; qv[3] = u6[3 * pr + 1].y; qv[4] = u6[3 * pr + 2].x; qv[5] = u6[3 * pr + 2].y;
;         const v32f_t wv = __builtin_amdgcn_cvt_scalef32_pk32_f32_fp6(qv, 1.0f);
;         f32x2 a2 = f32x2{0.f, 0.f};
; #pragma unroll
;         for (int i = 0; i < 16; ++i) a2 += f32x2{wv[2 * i], wv[2 * i + 1]} * xu[i];
;         float hs = a2.x + a2.y;
;         hs += dpp_row_shr(hs, 1); hs += dpp_row_shr(hs, 2); hs += dpp_row_shr(hs, 4); hs += dpp_row_shr(hs, 8);
;         hs += __builtin_bit_cast(float, __builtin_amdgcn_update_dpp(0, __builtin_bit_cast(int, hs), 0x142, 0xa, 0xf, false));
;         const float da = __builtin_bit_cast(float, __builtin_amdgcn_readlane(__builtin_bit_cast(int, hs), 31));
;         const float db = __builtin_bit_cast(float, __builtin_amdgcn_readlane(__builtin_bit_cast(int, hs), 63));
;         dvec = (lane == kb + 2 * pr) ? da : dvec;
;         dvec = (lane == kb + 2 * pr + 1) ? db : dvec;
	v_cvt_scalef32_pk32_f32_fp6 v[0:31], v[228:233], 1.0
	global_load_dwordx2 v[232:233], v167, s[62:63] offset:16
	global_load_dwordx4 v[228:231], v167, s[62:63]
	v_pk_mul_f32 v[246:247], v[0:1], v[96:97]
	v_pk_mul_f32 v[254:255], v[2:3], v[98:99]
	v_pk_mul_f32 v[160:161], v[4:5], v[100:101]
	v_pk_fma_f32 v[246:247], v[6:7], v[102:103], v[246:247]
	v_pk_fma_f32 v[254:255], v[8:9], v[104:105], v[254:255]
	v_pk_fma_f32 v[160:161], v[10:11], v[106:107], v[160:161]
	v_pk_fma_f32 v[246:247], v[12:13], v[108:109], v[246:247]
	v_pk_fma_f32 v[254:255], v[14:15], v[110:111], v[254:255]
	v_pk_fma_f32 v[160:161], v[16:17], v[112:113], v[160:161]
	v_pk_fma_f32 v[246:247], v[18:19], v[114:115], v[246:247]
	v_pk_fma_f32 v[254:255], v[20:21], v[116:117], v[254:255]
	v_pk_fma_f32 v[160:161], v[22:23], v[118:119], v[160:161]
	v_pk_fma_f32 v[246:247], v[24:25], v[120:121], v[246:247]
	v_pk_fma_f32 v[254:255], v[26:27], v[122:123], v[254:255]
	v_pk_fma_f32 v[160:161], v[28:29], v[124:125], v[160:161]
	v_pk_fma_f32 v[246:247], v[30:31], v[126:127], v[246:247]
	v_pk_add_f32 v[254:255], v[254:255], v[160:161]
	s_nop 0
	v_pk_add_f32 v[246:247], v[246:247], v[254:255]
	s_nop 0
	v_add_f32_e32 v163, v246, v247
	v_readlane_b32 s54, v92, 60
	v_readlane_b32 s55, v92, 61
	s_mul_i32 s0, s54, 0x300
	s_mul_i32 s1, s55, 0x300
	v_add_u32_e32 v167, s0, v195
	s_and_saveexec_b64 s[98:99], s[40:41]
	v_add_u32_e32 v167, s1, v195
	s_mov_b64 exec, s[98:99]
	s_waitcnt vmcnt(14)
	v_cvt_scalef32_pk32_f32_fp6 v[0:31], v[234:239], 1.0
	global_load_dwordx2 v[238:239], v167, s[62:63] offset:16
	global_load_dwordx4 v[234:237], v167, s[62:63]
	v_pk_mul_f32 v[246:247], v[0:1], v[96:97]
	v_pk_mul_f32 v[254:255], v[2:3], v[98:99]
	v_pk_mul_f32 v[160:161], v[4:5], v[100:101]
	v_pk_fma_f32 v[246:247], v[6:7], v[102:103], v[246:247]
	v_pk_fma_f32 v[254:255], v[8:9], v[104:105], v[254:255]
	v_pk_fma_f32 v[160:161], v[10:11], v[106:107], v[160:161]
	v_pk_fma_f32 v[246:247], v[12:13], v[108:109], v[246:247]
	v_pk_fma_f32 v[254:255], v[14:15], v[110:111], v[254:255]
	v_pk_fma_f32 v[160:161], v[16:17], v[112:113], v[160:161]
	v_pk_fma_f32 v[246:247], v[18:19], v[114:115], v[246:247]
	v_pk_fma_f32 v[254:255], v[20:21], v[116:117], v[254:255]
	v_pk_fma_f32 v[160:161], v[22:23], v[118:119], v[160:161]
	v_pk_fma_f32 v[246:247], v[24:25], v[120:121], v[246:247]
	v_pk_fma_f32 v[254:255], v[26:27], v[122:123], v[254:255]
	v_pk_fma_f32 v[160:161], v[28:29], v[124:125], v[160:161]
	v_pk_fma_f32 v[246:247], v[30:31], v[126:127], v[246:247]
	v_pk_add_f32 v[254:255], v[254:255], v[160:161]
	s_nop 0
	v_pk_add_f32 v[246:247], v[246:247], v[254:255]
	s_nop 0
	v_add_f32_e32 v164, v246, v247
	v_readlane_b32 s54, v92, 62
	v_readlane_b32 s55, v92, 63
	s_mul_i32 s0, s54, 0x300
	s_mul_i32 s1, s55, 0x300
	v_add_u32_e32 v167, s0, v195
	s_and_saveexec_b64 s[98:99], s[40:41]
	v_add_u32_e32 v167, s1, v195
	s_mov_b64 exec, s[98:99]
	s_waitcnt vmcnt(14)
	v_cvt_scalef32_pk32_f32_fp6 v[0:31], v[240:245], 1.0
	global_load_dwordx2 v[244:245], v167, s[62:63] offset:16
	global_load_dwordx4 v[240:243], v167, s[62:63]
	v_pk_mul_f32 v[246:247], v[0:1], v[96:97]
	v_pk_mul_f32 v[254:255], v[2:3], v[98:99]
	v_pk_mul_f32 v[160:161], v[4:5], v[100:101]
	v_pk_fma_f32 v[246:247], v[6:7], v[102:103], v[246:247]
	v_pk_fma_f32 v[254:255], v[8:9], v[104:105], v[254:255]
	v_pk_fma_f32 v[160:161], v[10:11], v[106:107], v[160:161]
	v_pk_fma_f32 v[246:247], v[12:13], v[108:109], v[246:247]
	v_pk_fma_f32 v[254:255], v[14:15], v[110:111], v[254:255]
	v_pk_fma_f32 v[160:161], v[16:17], v[112:113], v[160:161]
	v_pk_fma_f32 v[246:247], v[18:19], v[114:115], v[246:247]
	v_pk_fma_f32 v[254:255], v[20:21], v[116:117], v[254:255]
	v_pk_fma_f32 v[160:161], v[22:23], v[118:119], v[160:161]
	v_pk_fma_f32 v[246:247], v[24:25], v[120:121], v[246:247]
	v_pk_fma_f32 v[254:255], v[26:27], v[122:123], v[254:255]
	v_pk_fma_f32 v[160:161], v[28:29], v[124:125], v[160:161]
	v_pk_fma_f32 v[246:247], v[30:31], v[126:127], v[246:247]
	v_pk_add_f32 v[254:255], v[254:255], v[160:161]
	s_nop 0
	v_pk_add_f32 v[246:247], v[246:247], v[254:255]
	s_nop 0
	v_add_f32_e32 v165, v246, v247
	v_add_f32_dpp v162, v162, v162 row_shr:1 row_mask:0xf bank_mask:0xf bound_ctrl:1
	v_add_f32_dpp v163, v163, v163 row_shr:1 row_mask:0xf bank_mask:0xf bound_ctrl:1
	v_add_f32_dpp v164, v164, v164 row_shr:1 row_mask:0xf bank_mask:0xf bound_ctrl:1
	v_add_f32_dpp v165, v165, v165 row_shr:1 row_mask:0xf bank_mask:0xf bound_ctrl:1
	v_add_f32_dpp v162, v162, v162 row_shr:2 row_mask:0xf bank_mask:0xf bound_ctrl:1
	v_add_f32_dpp v163, v163, v163 row_shr:2 row_mask:0xf bank_mask:0xf bound_ctrl:1
	v_add_f32_dpp v164, v164, v164 row_shr:2 row_mask:0xf bank_mask:0xf bound_ctrl:1
	v_add_f32_dpp v165, v165, v165 row_shr:2 row_mask:0xf bank_mask:0xf bound_ctrl:1
	v_add_f32_dpp v162, v162, v162 row_shr:4 row_mask:0xf bank_mask:0xf bound_ctrl:1
	v_add_f32_dpp v163, v163, v163 row_shr:4 row_mask:0xf bank_mask:0xf bound_ctrl:1
	v_add_f32_dpp v164, v164, v164 row_shr:4 row_mask:0xf bank_mask:0xf bound_ctrl:1
	v_add_f32_dpp v165, v165, v165 row_shr:4 row_mask:0xf bank_mask:0xf bound_ctrl:1
	v_add_f32_dpp v162, v162, v162 row_shr:8 row_mask:0xf bank_mask:0xf bound_ctrl:1
	v_add_f32_dpp v163, v163, v163 row_shr:8 row_mask:0xf bank_mask:0xf bound_ctrl:1
	v_add_f32_dpp v164, v164, v164 row_shr:8 row_mask:0xf bank_mask:0xf bound_ctrl:1
	v_add_f32_dpp v165, v165, v165 row_shr:8 row_mask:0xf bank_mask:0xf bound_ctrl:1
	v_add_f32_dpp v162, v162, v162 row_bcast:15 row_mask:0xa bank_mask:0xf
	v_add_f32_dpp v163, v163, v163 row_bcast:15 row_mask:0xa bank_mask:0xf
	v_add_f32_dpp v164, v164, v164 row_bcast:15 row_mask:0xa bank_mask:0xf
	v_add_f32_dpp v165, v165, v165 row_bcast:15 row_mask:0xa bank_mask:0xf
	s_mov_b64 s[98:99], exec
	s_mov_b32 exec_lo, 0x80000000
	s_mov_b32 exec_hi, 0x80000000
	ds_write_b32 v74, v162 offset:160
	ds_write_b32 v74, v163 offset:168
	ds_write_b32 v74, v164 offset:176
	ds_write_b32 v74, v165 offset:184
	s_mov_b64 exec, s[98:99]
	v_readlane_b32 s54, v90, 0
	v_readlane_b32 s55, v90, 1
	s_mul_i32 s0, s54, 0x300
	s_mul_i32 s1, s55, 0x300
	v_add_u32_e32 v167, s0, v195
	s_and_saveexec_b64 s[98:99], s[40:41]
	v_add_u32_e32 v167, s1, v195
	s_mov_b64 exec, s[98:99]
	s_waitcnt vmcnt(14)
; __device__ void peer_gather_phase(const Params& P, int l, bool do_store) {
;     ...
;         const int ea = __builtin_amdgcn_readlane(evs, kb + 2 * pr), eb = __builtin_amdgcn_readlane(evs, kb + 2 * pr + 1);
;         const uint2* up = (const uint2*)(U + (size_t)(uphi ? eb : ea) * 768);
;         u6[3 * pr] = up[0]; u6[3 * pr + 1] = up[1]; u6[3 * pr + 2] = up[2];
;         v8[2 * pr] = *(const uint2*)(V + (size_t)ea * 512);
;         v8[2 * pr + 1] = *(const uint2*)(V + (size_t)eb * 512);
;       }
;     };
;     auto compute_batch = [&](const uint2 (&u6)[12], const uint2 (&v8)[8], int bt) {
;       const int kb = (bt & 7) * 8;
;       float dvec = 0.f;
; #pragma unroll
;       for (int pr = 0; pr < 4; ++pr) {
;         v6u_t qv; qv[0] = u6[3 * pr].x; qv[1] = u6[3 * pr].y; qv[2] = u6[3 * pr + 1].x; qv[3] = u6[3 * pr + 1].y; qv[4] = u6[3 * pr + 2].x; qv[5] = u6[3 * pr + 2].y;
;         const v32f_t wv = __builtin_amdgcn_cvt_scalef32_pk32_f32_fp6(qv, 1.0f);
;         f32x2 a2 = f32x2{0.f, 0.f};
; #pragma unroll
;         for (int i = 0; i < 16; ++i) a2 += f32x2{wv[2 * i], wv[2 * i + 1]} * xu[i];
;         float hs = a2.x + a2.y;
;         hs += dpp_row_shr(hs, 1); hs += dpp_row_shr(hs, 2); hs += dpp_row_shr(hs, 4); hs += dpp_row_shr(hs, 8);
;         hs += __builtin_bit_cast(float, __builtin_amdgcn_update_dpp(0, __builtin_bit_cast(int, hs), 0x142, 0xa, 0xf, false));
;         const float da = __builtin_bit_cast(float, __builtin_amdgcn_readlane(__builtin_bit_cast(int, hs), 31));
;         const float db = __builtin_bit_cast(float, __builtin_amdgcn_readlane(__builtin_bit_cast(int, hs), 63));
;         dvec = (lane == kb + 2 * pr) ? da : dvec;
;         dvec = (lane == kb + 2 * pr + 1) ? db : dvec;
	v_cvt_scalef32_pk32_f32_fp6 v[0:31], v[50:55], 1.0
	global_load_dwordx2 v[54:55], v167, s[62:63] offset:16
	global_load_dwordx4 v[50:53], v167, s[62:63]
	v_pk_mul_f32 v[246:247], v[0:1], v[96:97]
	v_pk_mul_f32 v[254:255], v[2:3], v[98:99]
	v_pk_mul_f32 v[160:161], v[4:5], v[100:101]
	v_pk_fma_f32 v[246:247], v[6:7], v[102:103], v[246:247]
	v_pk_fma_f32 v[254:255], v[8:9], v[104:105], v[254:255]
	v_pk_fma_f32 v[160:161], v[10:11], v[106:107], v[160:161]
	v_pk_fma_f32 v[246:247], v[12:13], v[108:109], v[246:247]
	v_pk_fma_f32 v[254:255], v[14:15], v[110:111], v[254:255]
	v_pk_fma_f32 v[160:161], v[16:17], v[112:113], v[160:161]
	v_pk_fma_f32 v[246:247], v[18:19], v[114:115], v[246:247]
	v_pk_fma_f32 v[254:255], v[20:21], v[116:117], v[254:255]
	v_pk_fma_f32 v[160:161], v[22:23], v[118:119], v[160:161]
	v_pk_fma_f32 v[246:247], v[24:25], v[120:121], v[246:247]
	v_pk_fma_f32 v[254:255], v[26:27], v[122:123], v[254:255]
	v_pk_fma_f32 v[160:161], v[28:29], v[124:125], v[160:161]
	v_pk_fma_f32 v[246:247], v[30:31], v[126:127], v[246:247]
	v_pk_add_f32 v[254:255], v[254:255], v[160:161]
	s_nop 0
	v_pk_add_f32 v[246:247], v[246:247], v[254:255]
	s_nop 0
	v_add_f32_e32 v162, v246, v247
	v_readlane_b32 s54, v90, 2
	v_readlane_b32 s55, v90, 3
	s_mul_i32 s0, s54, 0x300
	s_mul_i32 s1, s55, 0x300
	v_add_u32_e32 v167, s0, v195
	s_and_saveexec_b64 s[98:99], s[40:41]
	v_add_u32_e32 v167, s1, v195
	s_mov_b64 exec, s[98:99]
	s_waitcnt vmcnt(14)
	v_cvt_scalef32_pk32_f32_fp6 v[0:31], v[44:49], 1.0
	global_load_dwordx2 v[48:49], v167, s[62:63] offset:16
	global_load_dwordx4 v[44:47], v167, s[62:63]
	v_pk_mul_f32 v[246:247], v[0:1], v[96:97]
	v_pk_mul_f32 v[254:255], v[2:3], v[98:99]
	v_pk_mul_f32 v[160:161], v[4:5], v[100:101]
	v_pk_fma_f32 v[246:247], v[6:7], v[102:103], v[246:247]
	v_pk_fma_f32 v[254:255], v[8:9], v[104:105], v[254:255]
	v_pk_fma_f32 v[160:161], v[10:11], v[106:107], v[160:161]
	v_pk_fma_f32 v[246:247], v[12:13], v[108:109], v[246:247]
	v_pk_fma_f32 v[254:255], v[14:15], v[110:111], v[254:255]
	v_pk_fma_f32 v[160:161], v[16:17], v[112:113], v[160:161]
	v_pk_fma_f32 v[246:247], v[18:19], v[114:115], v[246:247]
	v_pk_fma_f32 v[254:255], v[20:21], v[116:117], v[254:255]
	v_pk_fma_f32 v[160:161], v[22:23], v[118:119], v[160:161]
	v_pk_fma_f32 v[246:247], v[24:25], v[120:121], v[246:247]
	v_pk_fma_f32 v[254:255], v[26:27], v[122:123], v[254:255]
	v_pk_fma_f32 v[160:161], v[28:29], v[124:125], v[160:161]
	v_pk_fma_f32 v[246:247], v[30:31], v[126:127], v[246:247]
	v_pk_add_f32 v[254:255], v[254:255], v[160:161]
	s_nop 0
	v_pk_add_f32 v[246:247], v[246:247], v[254:255]
	s_nop 0
	v_add_f32_e32 v163, v246, v247
	v_readlane_b32 s54, v90, 4
	v_readlane_b32 s55, v90, 5
	s_mul_i32 s0, s54, 0x300
	s_mul_i32 s1, s55, 0x300
	v_add_u32_e32 v167, s0, v195
	s_and_saveexec_b64 s[98:99], s[40:41]
	v_add_u32_e32 v167, s1, v195
	s_mov_b64 exec, s[98:99]
	s_waitcnt vmcnt(14)
	v_cvt_scalef32_pk32_f32_fp6 v[0:31], v[38:43], 1.0
	global_load_dwordx2 v[42:43], v167, s[62:63] offset:16
	global_load_dwordx4 v[38:41], v167, s[62:63]
	v_pk_mul_f32 v[246:247], v[0:1], v[96:97]
	v_pk_mul_f32 v[254:255], v[2:3], v[98:99]
	v_pk_mul_f32 v[160:161], v[4:5], v[100:101]
	v_pk_fma_f32 v[246:247], v[6:7], v[102:103], v[246:247]
	v_pk_fma_f32 v[254:255], v[8:9], v[104:105], v[254:255]
	v_pk_fma_f32 v[160:161], v[10:11], v[106:107], v[160:161]
	v_pk_fma_f32 v[246:247], v[12:13], v[108:109], v[246:247]
	v_pk_fma_f32 v[254:255], v[14:15], v[110:111], v[254:255]
	v_pk_fma_f32 v[160:161], v[16:17], v[112:113], v[160:161]
	v_pk_fma_f32 v[246:247], v[18:19], v[114:115], v[246:247]
	v_pk_fma_f32 v[254:255], v[20:21], v[116:117], v[254:255]
	v_pk_fma_f32 v[160:161], v[22:23], v[118:119], v[160:161]
	v_pk_fma_f32 v[246:247], v[24:25], v[120:121], v[246:247]
	v_pk_fma_f32 v[254:255], v[26:27], v[122:123], v[254:255]
	v_pk_fma_f32 v[160:161], v[28:29], v[124:125], v[160:161]
	v_pk_fma_f32 v[246:247], v[30:31], v[126:127], v[246:247]
	v_pk_add_f32 v[254:255], v[254:255], v[160:161]
	s_nop 0
	v_pk_add_f32 v[246:247], v[246:247], v[254:255]
	s_nop 0
	v_add_f32_e32 v164, v246, v247
	v_readlane_b32 s54, v90, 6
	v_readlane_b32 s55, v90, 7
	s_mul_i32 s0, s54, 0x300
	s_mul_i32 s1, s55, 0x300
	v_add_u32_e32 v167, s0, v195
	s_and_saveexec_b64 s[98:99], s[40:41]
	v_add_u32_e32 v167, s1, v195
	s_mov_b64 exec, s[98:99]
	s_waitcnt vmcnt(14)
; __device__ void peer_gather_phase(const Params& P, int l, bool do_store) {
;     ...
;         const int ea = __builtin_amdgcn_readlane(evs, kb + 2 * pr), eb = __builtin_amdgcn_readlane(evs, kb + 2 * pr + 1);
;         const uint2* up = (const uint2*)(U + (size_t)(uphi ? eb : ea) * 768);
;         u6[3 * pr] = up[0]; u6[3 * pr + 1] = up[1]; u6[3 * pr + 2] = up[2];
;         v8[2 * pr] = *(const uint2*)(V + (size_t)ea * 512);
;         v8[2 * pr + 1] = *(const uint2*)(V + (size_t)eb * 512);
;       }
;     };
;     auto compute_batch = [&](const uint2 (&u6)[12], const uint2 (&v8)[8], int bt) {
;       const int kb = (bt & 7) * 8;
;       float dvec = 0.f;
; #pragma unroll
;       for (int pr = 0; pr < 4; ++pr) {
;         v6u_t qv; qv[0] = u6[3 * pr].x; qv[1] = u6[3 * pr].y; qv[2] = u6[3 * pr + 1].x; qv[3] = u6[3 * pr + 1].y; qv[4] = u6[3 * pr + 2].x; qv[5] = u6[3 * pr + 2].y;
;         const v32f_t wv = __builtin_amdgcn_cvt_scalef32_pk32_f32_fp6(qv, 1.0f);
;         f32x2 a2 = f32x2{0.f, 0.f};
; #pragma unroll
;         for (int i = 0; i < 16; ++i) a2 += f32x2{wv[2 * i], wv[2 * i + 1]} * xu[i];
;         float hs = a2.x + a2.y;
;         hs += dpp_row_shr(hs, 1); hs += dpp_row_shr(hs, 2); hs += dpp_row_shr(hs, 4); hs += dpp_row_shr(hs, 8);
;         hs += __builtin_bit_cast(float, __builtin_amdgcn_update_dpp(0, __builtin_bit_cast(int, hs), 0x142, 0xa, 0xf, false));
;         const float da = __builtin_bit_cast(float, __builtin_amdgcn_readlane(__builtin_bit_cast(int, hs), 31));
;         const float db = __builtin_bit_cast(float, __builtin_amdgcn_readlane(__builtin_bit_cast(int, hs), 63));
;         dvec = (lane == kb + 2 * pr) ? da : dvec;
;         dvec = (lane == kb + 2 * pr + 1) ? db : dvec;
	v_cvt_scalef32_pk32_f32_fp6 v[0:31], v[32:37], 1.0
	global_load_dwordx2 v[36:37], v167, s[62:63] offset:16
	global_load_dwordx4 v[32:35], v167, s[62:63]
	v_pk_mul_f32 v[246:247], v[0:1], v[96:97]
	v_pk_mul_f32 v[254:255], v[2:3], v[98:99]
	v_pk_mul_f32 v[160:161], v[4:5], v[100:101]
	v_pk_fma_f32 v[246:247], v[6:7], v[102:103], v[246:247]
	v_pk_fma_f32 v[254:255], v[8:9], v[104:105], v[254:255]
	v_pk_fma_f32 v[160:161], v[10:11], v[106:107], v[160:161]
	v_pk_fma_f32 v[246:247], v[12:13], v[108:109], v[246:247]
	v_pk_fma_f32 v[254:255], v[14:15], v[110:111], v[254:255]
	v_pk_fma_f32 v[160:161], v[16:17], v[112:113], v[160:161]
	v_pk_fma_f32 v[246:247], v[18:19], v[114:115], v[246:247]
	v_pk_fma_f32 v[254:255], v[20:21], v[116:117], v[254:255]
	v_pk_fma_f32 v[160:161], v[22:23], v[118:119], v[160:161]
	v_pk_fma_f32 v[246:247], v[24:25], v[120:121], v[246:247]
	v_pk_fma_f32 v[254:255], v[26:27], v[122:123], v[254:255]
	v_pk_fma_f32 v[160:161], v[28:29], v[124:125], v[160:161]
	v_pk_fma_f32 v[246:247], v[30:31], v[126:127], v[246:247]
	v_pk_add_f32 v[254:255], v[254:255], v[160:161]
	s_nop 0
	v_pk_add_f32 v[246:247], v[246:247], v[254:255]
	s_nop 0
	v_add_f32_e32 v165, v246, v247
	v_add_f32_dpp v162, v162, v162 row_shr:1 row_mask:0xf bank_mask:0xf bound_ctrl:1
	v_add_f32_dpp v163, v163, v163 row_shr:1 row_mask:0xf bank_mask:0xf bound_ctrl:1
	v_add_f32_dpp v164, v164, v164 row_shr:1 row_mask:0xf bank_mask:0xf bound_ctrl:1
	v_add_f32_dpp v165, v165, v165 row_shr:1 row_mask:0xf bank_mask:0xf bound_ctrl:1
	v_add_f32_dpp v162, v162, v162 row_shr:2 row_mask:0xf bank_mask:0xf bound_ctrl:1
	v_add_f32_dpp v163, v163, v163 row_shr:2 row_mask:0xf bank_mask:0xf bound_ctrl:1
	v_add_f32_dpp v164, v164, v164 row_shr:2 row_mask:0xf bank_mask:0xf bound_ctrl:1
	v_add_f32_dpp v165, v165, v165 row_shr:2 row_mask:0xf bank_mask:0xf bound_ctrl:1
	v_add_f32_dpp v162, v162, v162 row_shr:4 row_mask:0xf bank_mask:0xf bound_ctrl:1
	v_add_f32_dpp v163, v163, v163 row_shr:4 row_mask:0xf bank_mask:0xf bound_ctrl:1
	v_add_f32_dpp v164, v164, v164 row_shr:4 row_mask:0xf bank_mask:0xf bound_ctrl:1
	v_add_f32_dpp v165, v165, v165 row_shr:4 row_mask:0xf bank_mask:0xf bound_ctrl:1
	v_add_f32_dpp v162, v162, v162 row_shr:8 row_mask:0xf bank_mask:0xf bound_ctrl:1
	v_add_f32_dpp v163, v163, v163 row_shr:8 row_mask:0xf bank_mask:0xf bound_ctrl:1
	v_add_f32_dpp v164, v164, v164 row_shr:8 row_mask:0xf bank_mask:0xf bound_ctrl:1
	v_add_f32_dpp v165, v165, v165 row_shr:8 row_mask:0xf bank_mask:0xf bound_ctrl:1
	v_add_f32_dpp v162, v162, v162 row_bcast:15 row_mask:0xa bank_mask:0xf
	v_add_f32_dpp v163, v163, v163 row_bcast:15 row_mask:0xa bank_mask:0xf
	v_add_f32_dpp v164, v164, v164 row_bcast:15 row_mask:0xa bank_mask:0xf
	v_add_f32_dpp v165, v165, v165 row_bcast:15 row_mask:0xa bank_mask:0xf
	s_mov_b64 s[98:99], exec
	s_mov_b32 exec_lo, 0x80000000
	s_mov_b32 exec_hi, 0x80000000
	ds_write_b32 v74, v162 offset:192
	ds_write_b32 v74, v163 offset:200
	ds_write_b32 v74, v164 offset:208
	ds_write_b32 v74, v165 offset:216
	s_mov_b64 exec, s[98:99]
	v_readlane_b32 s54, v90, 8
	v_readlane_b32 s55, v90, 9
	s_mul_i32 s0, s54, 0x300
	s_mul_i32 s1, s55, 0x300
	v_add_u32_e32 v167, s0, v195
	s_and_saveexec_b64 s[98:99], s[40:41]
	v_add_u32_e32 v167, s1, v195
	s_mov_b64 exec, s[98:99]
	s_waitcnt vmcnt(14)
	v_cvt_scalef32_pk32_f32_fp6 v[0:31], v[196:201], 1.0
	global_load_dwordx2 v[200:201], v167, s[62:63] offset:16
	global_load_dwordx4 v[196:199], v167, s[62:63]
	v_pk_mul_f32 v[246:247], v[0:1], v[96:97]
	v_pk_mul_f32 v[254:255], v[2:3], v[98:99]
	v_pk_mul_f32 v[160:161], v[4:5], v[100:101]
	v_pk_fma_f32 v[246:247], v[6:7], v[102:103], v[246:247]
	v_pk_fma_f32 v[254:255], v[8:9], v[104:105], v[254:255]
	v_pk_fma_f32 v[160:161], v[10:11], v[106:107], v[160:161]
	v_pk_fma_f32 v[246:247], v[12:13], v[108:109], v[246:247]
	v_pk_fma_f32 v[254:255], v[14:15], v[110:111], v[254:255]
	v_pk_fma_f32 v[160:161], v[16:17], v[112:113], v[160:161]
	v_pk_fma_f32 v[246:247], v[18:19], v[114:115], v[246:247]
	v_pk_fma_f32 v[254:255], v[20:21], v[116:117], v[254:255]
	v_pk_fma_f32 v[160:161], v[22:23], v[118:119], v[160:161]
	v_pk_fma_f32 v[246:247], v[24:25], v[120:121], v[246:247]
	v_pk_fma_f32 v[254:255], v[26:27], v[122:123], v[254:255]
	v_pk_fma_f32 v[160:161], v[28:29], v[124:125], v[160:161]
	v_pk_fma_f32 v[246:247], v[30:31], v[126:127], v[246:247]
	v_pk_add_f32 v[254:255], v[254:255], v[160:161]
	s_nop 0
	v_pk_add_f32 v[246:247], v[246:247], v[254:255]
	s_nop 0
	v_add_f32_e32 v162, v246, v247
	v_readlane_b32 s54, v90, 10
	v_readlane_b32 s55, v90, 11
	s_mul_i32 s0, s54, 0x300
	s_mul_i32 s1, s55, 0x300
	v_add_u32_e32 v167, s0, v195
	s_and_saveexec_b64 s[98:99], s[40:41]
	v_add_u32_e32 v167, s1, v195
	s_mov_b64 exec, s[98:99]
	s_waitcnt vmcnt(14)
	v_cvt_scalef32_pk32_f32_fp6 v[0:31], v[228:233], 1.0
	global_load_dwordx2 v[232:233], v167, s[62:63] offset:16
	global_load_dwordx4 v[228:231], v167, s[62:63]
	v_pk_mul_f32 v[246:247], v[0:1], v[96:97]
	v_pk_mul_f32 v[254:255], v[2:3], v[98:99]
	v_pk_mul_f32 v[160:161], v[4:5], v[100:101]
	v_pk_fma_f32 v[246:247], v[6:7], v[102:103], v[246:247]
	v_pk_fma_f32 v[254:255], v[8:9], v[104:105], v[254:255]
	v_pk_fma_f32 v[160:161], v[10:11], v[106:107], v[160:161]
	v_pk_fma_f32 v[246:247], v[12:13], v[108:109], v[246:247]
	v_pk_fma_f32 v[254:255], v[14:15], v[110:111], v[254:255]
	v_pk_fma_f32 v[160:161], v[16:17], v[112:113], v[160:161]
	v_pk_fma_f32 v[246:247], v[18:19], v[114:115], v[246:247]
	v_pk_fma_f32 v[254:255], v[20:21], v[116:117], v[254:255]
	v_pk_fma_f32 v[160:161], v[22:23], v[118:119], v[160:161]
	v_pk_fma_f32 v[246:247], v[24:25], v[120:121], v[246:247]
	v_pk_fma_f32 v[254:255], v[26:27], v[122:123], v[254:255]
	v_pk_fma_f32 v[160:161], v[28:29], v[124:125], v[160:161]
	v_pk_fma_f32 v[246:247], v[30:31], v[126:127], v[246:247]
	v_pk_add_f32 v[254:255], v[254:255], v[160:161]
	s_nop 0
	v_pk_add_f32 v[246:247], v[246:247], v[254:255]
	s_nop 0
	v_add_f32_e32 v163, v246, v247
	v_readlane_b32 s54, v90, 12
	v_readlane_b32 s55, v90, 13
	s_mul_i32 s0, s54, 0x300
	s_mul_i32 s1, s55, 0x300
	v_add_u32_e32 v167, s0, v195
	s_and_saveexec_b64 s[98:99], s[40:41]
	v_add_u32_e32 v167, s1, v195
	s_mov_b64 exec, s[98:99]
	s_waitcnt vmcnt(14)
; __device__ void peer_gather_phase(const Params& P, int l, bool do_store) {
;     ...
;         v6u_t qv; qv[0] = u6[3 * pr].x; qv[1] = u6[3 * pr].y; qv[2] = u6[3 * pr + 1].x; qv[3] = u6[3 * pr + 1].y; qv[4] = u6[3 * pr + 2].x; qv[5] = u6[3 * pr + 2].y;
;         const v32f_t wv = __builtin_amdgcn_cvt_scalef32_pk32_f32_fp6(qv, 1.0f);
;         f32x2 a2 = f32x2{0.f, 0.f};
; #pragma unroll
;         for (int i = 0; i < 16; ++i) a2 += f32x2{wv[2 * i], wv[2 * i + 1]} * xu[i];
;         float hs = a2.x + a2.y;
;         hs += dpp_row_shr(hs, 1); hs += dpp_row_shr(hs, 2); hs += dpp_row_shr(hs, 4); hs += dpp_row_shr(hs, 8);
;         hs += __builtin_bit_cast(float, __builtin_amdgcn_update_dpp(0, __builtin_bit_cast(int, hs), 0x142, 0xa, 0xf, false));
;         const float da = __builtin_bit_cast(float, __builtin_amdgcn_readlane(__builtin_bit_cast(int, hs), 31));
;         const float db = __builtin_bit_cast(float, __builtin_amdgcn_readlane(__builtin_bit_cast(int, hs), 63));
;         dvec = (lane == kb + 2 * pr) ? da : dvec;
;         dvec = (lane == kb + 2 * pr + 1) ? db : dvec;
;       }
;       const float sux = (bt < 8) ? sux0 : sux1;
;       const float gsx = (bt < 8) ? gsx0 : gsx1;
;       const float avec = gelu_t(dvec * sux) * gsx;
; #pragma unroll
;       for (int j = 0; j < 8; ++j) {
;         const float a = __builtin_bit_cast(float, __builtin_amdgcn_readlane(__builtin_bit_cast(int, avec), kb + j));
;         const f32x2 aa = f32x2{a, a};
	v_cvt_scalef32_pk32_f32_fp6 v[0:31], v[234:239], 1.0
	global_load_dwordx2 v[238:239], v167, s[62:63] offset:16
	global_load_dwordx4 v[234:237], v167, s[62:63]
	v_pk_mul_f32 v[246:247], v[0:1], v[96:97]
	v_pk_mul_f32 v[254:255], v[2:3], v[98:99]
	v_pk_mul_f32 v[160:161], v[4:5], v[100:101]
	v_pk_fma_f32 v[246:247], v[6:7], v[102:103], v[246:247]
	v_pk_fma_f32 v[254:255], v[8:9], v[104:105], v[254:255]
	v_pk_fma_f32 v[160:161], v[10:11], v[106:107], v[160:161]
	v_pk_fma_f32 v[246:247], v[12:13], v[108:109], v[246:247]
	v_pk_fma_f32 v[254:255], v[14:15], v[110:111], v[254:255]
	v_pk_fma_f32 v[160:161], v[16:17], v[112:113], v[160:161]
	v_pk_fma_f32 v[246:247], v[18:19], v[114:115], v[246:247]
	v_pk_fma_f32 v[254:255], v[20:21], v[116:117], v[254:255]
	v_pk_fma_f32 v[160:161], v[22:23], v[118:119], v[160:161]
	v_pk_fma_f32 v[246:247], v[24:25], v[120:121], v[246:247]
	v_pk_fma_f32 v[254:255], v[26:27], v[122:123], v[254:255]
	v_pk_fma_f32 v[160:161], v[28:29], v[124:125], v[160:161]
	v_pk_fma_f32 v[246:247], v[30:31], v[126:127], v[246:247]
	v_pk_add_f32 v[254:255], v[254:255], v[160:161]
	s_nop 0
	v_pk_add_f32 v[246:247], v[246:247], v[254:255]
	s_nop 0
	v_add_f32_e32 v164, v246, v247
	v_readlane_b32 s54, v90, 14
	v_readlane_b32 s55, v90, 15
	s_mul_i32 s0, s54, 0x300
	s_mul_i32 s1, s55, 0x300
	v_add_u32_e32 v167, s0, v195
	s_and_saveexec_b64 s[98:99], s[40:41]
	v_add_u32_e32 v167, s1, v195
	s_mov_b64 exec, s[98:99]
	s_waitcnt vmcnt(14)
	v_cvt_scalef32_pk32_f32_fp6 v[0:31], v[240:245], 1.0
	global_load_dwordx2 v[244:245], v167, s[62:63] offset:16
	global_load_dwordx4 v[240:243], v167, s[62:63]
	v_pk_mul_f32 v[246:247], v[0:1], v[96:97]
	v_pk_mul_f32 v[254:255], v[2:3], v[98:99]
	v_pk_mul_f32 v[160:161], v[4:5], v[100:101]
	v_pk_fma_f32 v[246:247], v[6:7], v[102:103], v[246:247]
	v_pk_fma_f32 v[254:255], v[8:9], v[104:105], v[254:255]
	v_pk_fma_f32 v[160:161], v[10:11], v[106:107], v[160:161]
	v_pk_fma_f32 v[246:247], v[12:13], v[108:109], v[246:247]
	v_pk_fma_f32 v[254:255], v[14:15], v[110:111], v[254:255]
	v_pk_fma_f32 v[160:161], v[16:17], v[112:113], v[160:161]
	v_pk_fma_f32 v[246:247], v[18:19], v[114:115], v[246:247]
	v_pk_fma_f32 v[254:255], v[20:21], v[116:117], v[254:255]
	v_pk_fma_f32 v[160:161], v[22:23], v[118:119], v[160:161]
	v_pk_fma_f32 v[246:247], v[24:25], v[120:121], v[246:247]
	v_pk_fma_f32 v[254:255], v[26:27], v[122:123], v[254:255]
	v_pk_fma_f32 v[160:161], v[28:29], v[124:125], v[160:161]
	v_pk_fma_f32 v[246:247], v[30:31], v[126:127], v[246:247]
	v_pk_add_f32 v[254:255], v[254:255], v[160:161]
	s_nop 0
	v_pk_add_f32 v[246:247], v[246:247], v[254:255]
	s_nop 0
	v_add_f32_e32 v165, v246, v247
	v_add_f32_dpp v162, v162, v162 row_shr:1 row_mask:0xf bank_mask:0xf bound_ctrl:1
	v_add_f32_dpp v163, v163, v163 row_shr:1 row_mask:0xf bank_mask:0xf bound_ctrl:1
	v_add_f32_dpp v164, v164, v164 row_shr:1 row_mask:0xf bank_mask:0xf bound_ctrl:1
	v_add_f32_dpp v165, v165, v165 row_shr:1 row_mask:0xf bank_mask:0xf bound_ctrl:1
	v_add_f32_dpp v162, v162, v162 row_shr:2 row_mask:0xf bank_mask:0xf bound_ctrl:1
	v_add_f32_dpp v163, v163, v163 row_shr:2 row_mask:0xf bank_mask:0xf bound_ctrl:1
	v_add_f32_dpp v164, v164, v164 row_shr:2 row_mask:0xf bank_mask:0xf bound_ctrl:1
	v_add_f32_dpp v165, v165, v165 row_shr:2 row_mask:0xf bank_mask:0xf bound_ctrl:1
	v_add_f32_dpp v162, v162, v162 row_shr:4 row_mask:0xf bank_mask:0xf bound_ctrl:1
	v_add_f32_dpp v163, v163, v163 row_shr:4 row_mask:0xf bank_mask:0xf bound_ctrl:1
	v_add_f32_dpp v164, v164, v164 row_shr:4 row_mask:0xf bank_mask:0xf bound_ctrl:1
	v_add_f32_dpp v165, v165, v165 row_shr:4 row_mask:0xf bank_mask:0xf bound_ctrl:1
	v_add_f32_dpp v162, v162, v162 row_shr:8 row_mask:0xf bank_mask:0xf bound_ctrl:1
	v_add_f32_dpp v163, v163, v163 row_shr:8 row_mask:0xf bank_mask:0xf bound_ctrl:1
	v_add_f32_dpp v164, v164, v164 row_shr:8 row_mask:0xf bank_mask:0xf bound_ctrl:1
	v_add_f32_dpp v165, v165, v165 row_shr:8 row_mask:0xf bank_mask:0xf bound_ctrl:1
	v_add_f32_dpp v162, v162, v162 row_bcast:15 row_mask:0xa bank_mask:0xf
	v_add_f32_dpp v163, v163, v163 row_bcast:15 row_mask:0xa bank_mask:0xf
	v_add_f32_dpp v164, v164, v164 row_bcast:15 row_mask:0xa bank_mask:0xf
	v_add_f32_dpp v165, v165, v165 row_bcast:15 row_mask:0xa bank_mask:0xf
	s_mov_b64 s[98:99], exec
	s_mov_b32 exec_lo, 0x80000000
	s_mov_b32 exec_hi, 0x80000000
	ds_write_b32 v74, v162 offset:224
	ds_write_b32 v74, v163 offset:232
	ds_write_b32 v74, v164 offset:240
	ds_write_b32 v74, v165 offset:248
	s_mov_b64 exec, s[98:99]
	ds_read_b32 v166, v75
	s_waitcnt lgkmcnt(0)
	v_mul_f32_e32 v0, v189, v166
	v_mul_f32_e32 v1, 0x3d372713, v0
	v_mul_f32_e32 v1, v0, v1
	v_fma_f32 v1, v0, v1, v0
	v_mul_f32_e32 v1, 0x3f4c422a, v1
	v_add_f32_e32 v1, v1, v1
	v_mul_f32_e32 v1, 0x3fb8aa3b, v1
	v_exp_f32_e32 v1, v1
	v_mul_f32_e32 v0, 0.5, v0
	v_add_f32_e32 v1, 1.0, v1
	v_div_scale_f32 v2, s[0:1], v1, v1, 2.0
	v_rcp_f32_e32 v3, v2
	s_nop 0
	v_fma_f32 v4, -v2, v3, 1.0
	v_fmac_f32_e32 v3, v4, v3
	v_div_scale_f32 v4, vcc, 2.0, v1, 2.0
	v_mul_f32_e32 v5, v4, v3
	v_fma_f32 v6, -v2, v5, v4
	v_fmac_f32_e32 v5, v6, v3
	v_fma_f32 v2, -v2, v5, v4
	v_div_fmas_f32 v2, v2, v3, v5
	v_div_fixup_f32 v1, v2, v1, 2.0
	v_sub_f32_e32 v1, 1.0, v1
	v_add_f32_e32 v1, 1.0, v1
	v_mul_f32_e32 v0, v0, v1
	v_mul_f32_e32 v167, v191, v0
	ds_write_b32 v75, v167 offset:256
	ds_read_b32 v76, v193 offset:256
	ds_read_b32 v194, v193 offset:260
	s_waitcnt vmcnt(48)
; __device__ void peer_gather_phase(const Params& P, int l, bool do_store) {
;     ...
;         v8[2 * pr] = *(const uint2*)(V + (size_t)ea * 512);
;         v8[2 * pr + 1] = *(const uint2*)(V + (size_t)eb * 512);
;     ...
; #pragma unroll
;       for (int j = 0; j < 8; ++j) {
;         const float a = __builtin_bit_cast(float, __builtin_amdgcn_readlane(__builtin_bit_cast(int, avec), kb + j));
;         const f32x2 aa = f32x2{a, a};
;         y[0] += aa * __builtin_amdgcn_cvt_scalef32_pk_f32_fp4(v8[j].x, 1.0f, 0); y[1] += aa * __builtin_amdgcn_cvt_scalef32_pk_f32_fp4(v8[j].x, 1.0f, 1);
;         y[2] += aa * __builtin_amdgcn_cvt_scalef32_pk_f32_fp4(v8[j].x, 1.0f, 2); y[3] += aa * __builtin_amdgcn_cvt_scalef32_pk_f32_fp4(v8[j].x, 1.0f, 3);
;         y[4] += aa * __builtin_amdgcn_cvt_scalef32_pk_f32_fp4(v8[j].y, 1.0f, 0); y[5] += aa * __builtin_amdgcn_cvt_scalef32_pk_f32_fp4(v8[j].y, 1.0f, 1);
;         y[6] += aa * __builtin_amdgcn_cvt_scalef32_pk_f32_fp4(v8[j].y, 1.0f, 2); y[7] += aa * __builtin_amdgcn_cvt_scalef32_pk_f32_fp4(v8[j].y, 1.0f, 3);
;       }
	v_cvt_scalef32_pk_f32_fp4 v[0:1], v144, 1.0
	v_cvt_scalef32_pk_f32_fp4 v[2:3], v144, 1.0 op_sel:[1,0,0]
	v_cvt_scalef32_pk_f32_fp4 v[4:5], v144, 1.0 op_sel:[0,1,0]
	v_cvt_scalef32_pk_f32_fp4 v[6:7], v144, 1.0 op_sel:[1,1,0]
	v_cvt_scalef32_pk_f32_fp4 v[8:9], v145, 1.0
	v_cvt_scalef32_pk_f32_fp4 v[10:11], v145, 1.0 op_sel:[1,0,0]
	v_cvt_scalef32_pk_f32_fp4 v[12:13], v145, 1.0 op_sel:[0,1,0]
	v_cvt_scalef32_pk_f32_fp4 v[14:15], v145, 1.0 op_sel:[1,1,0]
	v_readlane_b32 s54, v92, 16
	s_lshl_b32 s56, s54, 9
	s_add_u32 s56, s64, s56
	s_addc_u32 s57, s65, 0
	global_load_dwordx2 v[144:145], v227, s[56:57]
	s_waitcnt lgkmcnt(1)
	v_pk_fma_f32 v[130:131], v[0:1], v[76:77], v[130:131] op_sel_hi:[1,0,1]
	v_pk_fma_f32 v[138:139], v[2:3], v[76:77], v[138:139] op_sel_hi:[1,0,1]
	v_pk_fma_f32 v[140:141], v[4:5], v[76:77], v[140:141] op_sel_hi:[1,0,1]
	v_pk_fma_f32 v[142:143], v[6:7], v[76:77], v[142:143] op_sel_hi:[1,0,1]
	v_pk_fma_f32 v[128:129], v[8:9], v[76:77], v[128:129] op_sel_hi:[1,0,1]
	v_pk_fma_f32 v[132:133], v[10:11], v[76:77], v[132:133] op_sel_hi:[1,0,1]
	v_pk_fma_f32 v[134:135], v[12:13], v[76:77], v[134:135] op_sel_hi:[1,0,1]
	v_pk_fma_f32 v[136:137], v[14:15], v[76:77], v[136:137] op_sel_hi:[1,0,1]
	ds_read_b32 v76, v193 offset:264
	s_waitcnt vmcnt(48)
	v_cvt_scalef32_pk_f32_fp4 v[0:1], v146, 1.0
	v_cvt_scalef32_pk_f32_fp4 v[2:3], v146, 1.0 op_sel:[1,0,0]
	v_cvt_scalef32_pk_f32_fp4 v[4:5], v146, 1.0 op_sel:[0,1,0]
	v_cvt_scalef32_pk_f32_fp4 v[6:7], v146, 1.0 op_sel:[1,1,0]
	v_cvt_scalef32_pk_f32_fp4 v[8:9], v147, 1.0
	v_cvt_scalef32_pk_f32_fp4 v[10:11], v147, 1.0 op_sel:[1,0,0]
	v_cvt_scalef32_pk_f32_fp4 v[12:13], v147, 1.0 op_sel:[0,1,0]
	v_cvt_scalef32_pk_f32_fp4 v[14:15], v147, 1.0 op_sel:[1,1,0]
	v_readlane_b32 s54, v92, 17
	s_lshl_b32 s56, s54, 9
	s_add_u32 s56, s64, s56
	s_addc_u32 s57, s65, 0
	global_load_dwordx2 v[146:147], v227, s[56:57]
	s_waitcnt lgkmcnt(1)
	v_pk_fma_f32 v[130:131], v[0:1], v[194:195], v[130:131] op_sel_hi:[1,0,1]
	v_pk_fma_f32 v[138:139], v[2:3], v[194:195], v[138:139] op_sel_hi:[1,0,1]
	v_pk_fma_f32 v[140:141], v[4:5], v[194:195], v[140:141] op_sel_hi:[1,0,1]
	v_pk_fma_f32 v[142:143], v[6:7], v[194:195], v[142:143] op_sel_hi:[1,0,1]
	v_pk_fma_f32 v[128:129], v[8:9], v[194:195], v[128:129] op_sel_hi:[1,0,1]
	v_pk_fma_f32 v[132:133], v[10:11], v[194:195], v[132:133] op_sel_hi:[1,0,1]
	v_pk_fma_f32 v[134:135], v[12:13], v[194:195], v[134:135] op_sel_hi:[1,0,1]
	v_pk_fma_f32 v[136:137], v[14:15], v[194:195], v[136:137] op_sel_hi:[1,0,1]
	ds_read_b32 v194, v193 offset:268
	s_waitcnt vmcnt(48)
	v_cvt_scalef32_pk_f32_fp4 v[0:1], v148, 1.0
	v_cvt_scalef32_pk_f32_fp4 v[2:3], v148, 1.0 op_sel:[1,0,0]
	v_cvt_scalef32_pk_f32_fp4 v[4:5], v148, 1.0 op_sel:[0,1,0]
	v_cvt_scalef32_pk_f32_fp4 v[6:7], v148, 1.0 op_sel:[1,1,0]
	v_cvt_scalef32_pk_f32_fp4 v[8:9], v149, 1.0
	v_cvt_scalef32_pk_f32_fp4 v[10:11], v149, 1.0 op_sel:[1,0,0]
	v_cvt_scalef32_pk_f32_fp4 v[12:13], v149, 1.0 op_sel:[0,1,0]
	v_cvt_scalef32_pk_f32_fp4 v[14:15], v149, 1.0 op_sel:[1,1,0]
	v_readlane_b32 s54, v92, 18
	s_lshl_b32 s56, s54, 9
	s_add_u32 s56, s64, s56
	s_addc_u32 s57, s65, 0
	global_load_dwordx2 v[148:149], v227, s[56:57]
	s_waitcnt lgkmcnt(1)
	v_pk_fma_f32 v[130:131], v[0:1], v[76:77], v[130:131] op_sel_hi:[1,0,1]
	v_pk_fma_f32 v[138:139], v[2:3], v[76:77], v[138:139] op_sel_hi:[1,0,1]
	v_pk_fma_f32 v[140:141], v[4:5], v[76:77], v[140:141] op_sel_hi:[1,0,1]
	v_pk_fma_f32 v[142:143], v[6:7], v[76:77], v[142:143] op_sel_hi:[1,0,1]
	v_pk_fma_f32 v[128:129], v[8:9], v[76:77], v[128:129] op_sel_hi:[1,0,1]
	v_pk_fma_f32 v[132:133], v[10:11], v[76:77], v[132:133] op_sel_hi:[1,0,1]
	v_pk_fma_f32 v[134:135], v[12:13], v[76:77], v[134:135] op_sel_hi:[1,0,1]
	v_pk_fma_f32 v[136:137], v[14:15], v[76:77], v[136:137] op_sel_hi:[1,0,1]
	ds_read_b32 v76, v193 offset:272
	s_waitcnt vmcnt(48)
	v_cvt_scalef32_pk_f32_fp4 v[0:1], v150, 1.0
	v_cvt_scalef32_pk_f32_fp4 v[2:3], v150, 1.0 op_sel:[1,0,0]
	v_cvt_scalef32_pk_f32_fp4 v[4:5], v150, 1.0 op_sel:[0,1,0]
	v_cvt_scalef32_pk_f32_fp4 v[6:7], v150, 1.0 op_sel:[1,1,0]
	v_cvt_scalef32_pk_f32_fp4 v[8:9], v151, 1.0
	v_cvt_scalef32_pk_f32_fp4 v[10:11], v151, 1.0 op_sel:[1,0,0]
	v_cvt_scalef32_pk_f32_fp4 v[12:13], v151, 1.0 op_sel:[0,1,0]
	v_cvt_scalef32_pk_f32_fp4 v[14:15], v151, 1.0 op_sel:[1,1,0]
	v_readlane_b32 s54, v92, 19
	s_lshl_b32 s56, s54, 9
	s_add_u32 s56, s64, s56
	s_addc_u32 s57, s65, 0
	global_load_dwordx2 v[150:151], v227, s[56:57]
	s_waitcnt lgkmcnt(1)
	v_pk_fma_f32 v[130:131], v[0:1], v[194:195], v[130:131] op_sel_hi:[1,0,1]
	v_pk_fma_f32 v[138:139], v[2:3], v[194:195], v[138:139] op_sel_hi:[1,0,1]
	v_pk_fma_f32 v[140:141], v[4:5], v[194:195], v[140:141] op_sel_hi:[1,0,1]
	v_pk_fma_f32 v[142:143], v[6:7], v[194:195], v[142:143] op_sel_hi:[1,0,1]
	v_pk_fma_f32 v[128:129], v[8:9], v[194:195], v[128:129] op_sel_hi:[1,0,1]
	v_pk_fma_f32 v[132:133], v[10:11], v[194:195], v[132:133] op_sel_hi:[1,0,1]
	v_pk_fma_f32 v[134:135], v[12:13], v[194:195], v[134:135] op_sel_hi:[1,0,1]
	v_pk_fma_f32 v[136:137], v[14:15], v[194:195], v[136:137] op_sel_hi:[1,0,1]
	ds_read_b32 v194, v193 offset:276
	s_waitcnt vmcnt(48)
	v_cvt_scalef32_pk_f32_fp4 v[0:1], v152, 1.0
	v_cvt_scalef32_pk_f32_fp4 v[2:3], v152, 1.0 op_sel:[1,0,0]
	v_cvt_scalef32_pk_f32_fp4 v[4:5], v152, 1.0 op_sel:[0,1,0]
	v_cvt_scalef32_pk_f32_fp4 v[6:7], v152, 1.0 op_sel:[1,1,0]
	v_cvt_scalef32_pk_f32_fp4 v[8:9], v153, 1.0
	v_cvt_scalef32_pk_f32_fp4 v[10:11], v153, 1.0 op_sel:[1,0,0]
	v_cvt_scalef32_pk_f32_fp4 v[12:13], v153, 1.0 op_sel:[0,1,0]
	v_cvt_scalef32_pk_f32_fp4 v[14:15], v153, 1.0 op_sel:[1,1,0]
	v_readlane_b32 s54, v92, 20
	s_lshl_b32 s56, s54, 9
	s_add_u32 s56, s64, s56
	s_addc_u32 s57, s65, 0
	global_load_dwordx2 v[152:153], v227, s[56:57]
	s_waitcnt lgkmcnt(1)
; __device__ void peer_gather_phase(const Params& P, int l, bool do_store) {
;     ...
;         v8[2 * pr] = *(const uint2*)(V + (size_t)ea * 512);
;         v8[2 * pr + 1] = *(const uint2*)(V + (size_t)eb * 512);
;     ...
; #pragma unroll
;       for (int j = 0; j < 8; ++j) {
;         const float a = __builtin_bit_cast(float, __builtin_amdgcn_readlane(__builtin_bit_cast(int, avec), kb + j));
;         const f32x2 aa = f32x2{a, a};
;         y[0] += aa * __builtin_amdgcn_cvt_scalef32_pk_f32_fp4(v8[j].x, 1.0f, 0); y[1] += aa * __builtin_amdgcn_cvt_scalef32_pk_f32_fp4(v8[j].x, 1.0f, 1);
;         y[2] += aa * __builtin_amdgcn_cvt_scalef32_pk_f32_fp4(v8[j].x, 1.0f, 2); y[3] += aa * __builtin_amdgcn_cvt_scalef32_pk_f32_fp4(v8[j].x, 1.0f, 3);
;         y[4] += aa * __builtin_amdgcn_cvt_scalef32_pk_f32_fp4(v8[j].y, 1.0f, 0); y[5] += aa * __builtin_amdgcn_cvt_scalef32_pk_f32_fp4(v8[j].y, 1.0f, 1);
;         y[6] += aa * __builtin_amdgcn_cvt_scalef32_pk_f32_fp4(v8[j].y, 1.0f, 2); y[7] += aa * __builtin_amdgcn_cvt_scalef32_pk_f32_fp4(v8[j].y, 1.0f, 3);
;       }
	v_pk_fma_f32 v[130:131], v[0:1], v[76:77], v[130:131] op_sel_hi:[1,0,1]
	v_pk_fma_f32 v[138:139], v[2:3], v[76:77], v[138:139] op_sel_hi:[1,0,1]
	v_pk_fma_f32 v[140:141], v[4:5], v[76:77], v[140:141] op_sel_hi:[1,0,1]
	v_pk_fma_f32 v[142:143], v[6:7], v[76:77], v[142:143] op_sel_hi:[1,0,1]
	v_pk_fma_f32 v[128:129], v[8:9], v[76:77], v[128:129] op_sel_hi:[1,0,1]
	v_pk_fma_f32 v[132:133], v[10:11], v[76:77], v[132:133] op_sel_hi:[1,0,1]
	v_pk_fma_f32 v[134:135], v[12:13], v[76:77], v[134:135] op_sel_hi:[1,0,1]
	v_pk_fma_f32 v[136:137], v[14:15], v[76:77], v[136:137] op_sel_hi:[1,0,1]
	ds_read_b32 v76, v193 offset:280
	s_waitcnt vmcnt(48)
	v_cvt_scalef32_pk_f32_fp4 v[0:1], v154, 1.0
	v_cvt_scalef32_pk_f32_fp4 v[2:3], v154, 1.0 op_sel:[1,0,0]
	v_cvt_scalef32_pk_f32_fp4 v[4:5], v154, 1.0 op_sel:[0,1,0]
	v_cvt_scalef32_pk_f32_fp4 v[6:7], v154, 1.0 op_sel:[1,1,0]
	v_cvt_scalef32_pk_f32_fp4 v[8:9], v155, 1.0
	v_cvt_scalef32_pk_f32_fp4 v[10:11], v155, 1.0 op_sel:[1,0,0]
	v_cvt_scalef32_pk_f32_fp4 v[12:13], v155, 1.0 op_sel:[0,1,0]
	v_cvt_scalef32_pk_f32_fp4 v[14:15], v155, 1.0 op_sel:[1,1,0]
	v_readlane_b32 s54, v92, 21
	s_lshl_b32 s56, s54, 9
	s_add_u32 s56, s64, s56
	s_addc_u32 s57, s65, 0
	global_load_dwordx2 v[154:155], v227, s[56:57]
	s_waitcnt lgkmcnt(1)
	v_pk_fma_f32 v[130:131], v[0:1], v[194:195], v[130:131] op_sel_hi:[1,0,1]
	v_pk_fma_f32 v[138:139], v[2:3], v[194:195], v[138:139] op_sel_hi:[1,0,1]
	v_pk_fma_f32 v[140:141], v[4:5], v[194:195], v[140:141] op_sel_hi:[1,0,1]
	v_pk_fma_f32 v[142:143], v[6:7], v[194:195], v[142:143] op_sel_hi:[1,0,1]
	v_pk_fma_f32 v[128:129], v[8:9], v[194:195], v[128:129] op_sel_hi:[1,0,1]
	v_pk_fma_f32 v[132:133], v[10:11], v[194:195], v[132:133] op_sel_hi:[1,0,1]
	v_pk_fma_f32 v[134:135], v[12:13], v[194:195], v[134:135] op_sel_hi:[1,0,1]
	v_pk_fma_f32 v[136:137], v[14:15], v[194:195], v[136:137] op_sel_hi:[1,0,1]
	ds_read_b32 v194, v193 offset:284
	s_waitcnt vmcnt(48)
	v_cvt_scalef32_pk_f32_fp4 v[0:1], v156, 1.0
	v_cvt_scalef32_pk_f32_fp4 v[2:3], v156, 1.0 op_sel:[1,0,0]
	v_cvt_scalef32_pk_f32_fp4 v[4:5], v156, 1.0 op_sel:[0,1,0]
	v_cvt_scalef32_pk_f32_fp4 v[6:7], v156, 1.0 op_sel:[1,1,0]
	v_cvt_scalef32_pk_f32_fp4 v[8:9], v157, 1.0
	v_cvt_scalef32_pk_f32_fp4 v[10:11], v157, 1.0 op_sel:[1,0,0]
	v_cvt_scalef32_pk_f32_fp4 v[12:13], v157, 1.0 op_sel:[0,1,0]
	v_cvt_scalef32_pk_f32_fp4 v[14:15], v157, 1.0 op_sel:[1,1,0]
	v_readlane_b32 s54, v92, 22
	s_lshl_b32 s56, s54, 9
	s_add_u32 s56, s64, s56
	s_addc_u32 s57, s65, 0
	global_load_dwordx2 v[156:157], v227, s[56:57]
	s_waitcnt lgkmcnt(1)
	v_pk_fma_f32 v[130:131], v[0:1], v[76:77], v[130:131] op_sel_hi:[1,0,1]
	v_pk_fma_f32 v[138:139], v[2:3], v[76:77], v[138:139] op_sel_hi:[1,0,1]
	v_pk_fma_f32 v[140:141], v[4:5], v[76:77], v[140:141] op_sel_hi:[1,0,1]
	v_pk_fma_f32 v[142:143], v[6:7], v[76:77], v[142:143] op_sel_hi:[1,0,1]
	v_pk_fma_f32 v[128:129], v[8:9], v[76:77], v[128:129] op_sel_hi:[1,0,1]
	v_pk_fma_f32 v[132:133], v[10:11], v[76:77], v[132:133] op_sel_hi:[1,0,1]
	v_pk_fma_f32 v[134:135], v[12:13], v[76:77], v[134:135] op_sel_hi:[1,0,1]
	v_pk_fma_f32 v[136:137], v[14:15], v[76:77], v[136:137] op_sel_hi:[1,0,1]
	ds_read_b32 v76, v193 offset:288
	s_waitcnt vmcnt(48)
	v_cvt_scalef32_pk_f32_fp4 v[0:1], v158, 1.0
	v_cvt_scalef32_pk_f32_fp4 v[2:3], v158, 1.0 op_sel:[1,0,0]
	v_cvt_scalef32_pk_f32_fp4 v[4:5], v158, 1.0 op_sel:[0,1,0]
	v_cvt_scalef32_pk_f32_fp4 v[6:7], v158, 1.0 op_sel:[1,1,0]
	v_cvt_scalef32_pk_f32_fp4 v[8:9], v159, 1.0
	v_cvt_scalef32_pk_f32_fp4 v[10:11], v159, 1.0 op_sel:[1,0,0]
	v_cvt_scalef32_pk_f32_fp4 v[12:13], v159, 1.0 op_sel:[0,1,0]
	v_cvt_scalef32_pk_f32_fp4 v[14:15], v159, 1.0 op_sel:[1,1,0]
	v_readlane_b32 s54, v92, 23
	s_lshl_b32 s56, s54, 9
	s_add_u32 s56, s64, s56
	s_addc_u32 s57, s65, 0
	global_load_dwordx2 v[158:159], v227, s[56:57]
	s_waitcnt lgkmcnt(1)
	v_pk_fma_f32 v[130:131], v[0:1], v[194:195], v[130:131] op_sel_hi:[1,0,1]
	v_pk_fma_f32 v[138:139], v[2:3], v[194:195], v[138:139] op_sel_hi:[1,0,1]
	v_pk_fma_f32 v[140:141], v[4:5], v[194:195], v[140:141] op_sel_hi:[1,0,1]
	v_pk_fma_f32 v[142:143], v[6:7], v[194:195], v[142:143] op_sel_hi:[1,0,1]
	v_pk_fma_f32 v[128:129], v[8:9], v[194:195], v[128:129] op_sel_hi:[1,0,1]
	v_pk_fma_f32 v[132:133], v[10:11], v[194:195], v[132:133] op_sel_hi:[1,0,1]
	v_pk_fma_f32 v[134:135], v[12:13], v[194:195], v[134:135] op_sel_hi:[1,0,1]
	v_pk_fma_f32 v[136:137], v[14:15], v[194:195], v[136:137] op_sel_hi:[1,0,1]
	ds_read_b32 v194, v193 offset:292
	s_waitcnt vmcnt(48)
	v_cvt_scalef32_pk_f32_fp4 v[0:1], v168, 1.0
	v_cvt_scalef32_pk_f32_fp4 v[2:3], v168, 1.0 op_sel:[1,0,0]
	v_cvt_scalef32_pk_f32_fp4 v[4:5], v168, 1.0 op_sel:[0,1,0]
	v_cvt_scalef32_pk_f32_fp4 v[6:7], v168, 1.0 op_sel:[1,1,0]
	v_cvt_scalef32_pk_f32_fp4 v[8:9], v169, 1.0
	v_cvt_scalef32_pk_f32_fp4 v[10:11], v169, 1.0 op_sel:[1,0,0]
	v_cvt_scalef32_pk_f32_fp4 v[12:13], v169, 1.0 op_sel:[0,1,0]
	v_cvt_scalef32_pk_f32_fp4 v[14:15], v169, 1.0 op_sel:[1,1,0]
	v_readlane_b32 s54, v92, 24
	s_lshl_b32 s56, s54, 9
	s_add_u32 s56, s64, s56
	s_addc_u32 s57, s65, 0
	global_load_dwordx2 v[168:169], v227, s[56:57]
	s_waitcnt lgkmcnt(1)
	v_pk_fma_f32 v[130:131], v[0:1], v[76:77], v[130:131] op_sel_hi:[1,0,1]
	v_pk_fma_f32 v[138:139], v[2:3], v[76:77], v[138:139] op_sel_hi:[1,0,1]
	v_pk_fma_f32 v[140:141], v[4:5], v[76:77], v[140:141] op_sel_hi:[1,0,1]
	v_pk_fma_f32 v[142:143], v[6:7], v[76:77], v[142:143] op_sel_hi:[1,0,1]
	v_pk_fma_f32 v[128:129], v[8:9], v[76:77], v[128:129] op_sel_hi:[1,0,1]
	v_pk_fma_f32 v[132:133], v[10:11], v[76:77], v[132:133] op_sel_hi:[1,0,1]
	v_pk_fma_f32 v[134:135], v[12:13], v[76:77], v[134:135] op_sel_hi:[1,0,1]
	v_pk_fma_f32 v[136:137], v[14:15], v[76:77], v[136:137] op_sel_hi:[1,0,1]
	ds_read_b32 v76, v193 offset:296
	s_waitcnt vmcnt(48)
; __device__ void peer_gather_phase(const Params& P, int l, bool do_store) {
;     ...
;         v8[2 * pr] = *(const uint2*)(V + (size_t)ea * 512);
;         v8[2 * pr + 1] = *(const uint2*)(V + (size_t)eb * 512);
;     ...
; #pragma unroll
;       for (int j = 0; j < 8; ++j) {
;         const float a = __builtin_bit_cast(float, __builtin_amdgcn_readlane(__builtin_bit_cast(int, avec), kb + j));
;         const f32x2 aa = f32x2{a, a};
;         y[0] += aa * __builtin_amdgcn_cvt_scalef32_pk_f32_fp4(v8[j].x, 1.0f, 0); y[1] += aa * __builtin_amdgcn_cvt_scalef32_pk_f32_fp4(v8[j].x, 1.0f, 1);
;         y[2] += aa * __builtin_amdgcn_cvt_scalef32_pk_f32_fp4(v8[j].x, 1.0f, 2); y[3] += aa * __builtin_amdgcn_cvt_scalef32_pk_f32_fp4(v8[j].x, 1.0f, 3);
;         y[4] += aa * __builtin_amdgcn_cvt_scalef32_pk_f32_fp4(v8[j].y, 1.0f, 0); y[5] += aa * __builtin_amdgcn_cvt_scalef32_pk_f32_fp4(v8[j].y, 1.0f, 1);
;         y[6] += aa * __builtin_amdgcn_cvt_scalef32_pk_f32_fp4(v8[j].y, 1.0f, 2); y[7] += aa * __builtin_amdgcn_cvt_scalef32_pk_f32_fp4(v8[j].y, 1.0f, 3);
;       }
	v_cvt_scalef32_pk_f32_fp4 v[0:1], v170, 1.0
	v_cvt_scalef32_pk_f32_fp4 v[2:3], v170, 1.0 op_sel:[1,0,0]
	v_cvt_scalef32_pk_f32_fp4 v[4:5], v170, 1.0 op_sel:[0,1,0]
	v_cvt_scalef32_pk_f32_fp4 v[6:7], v170, 1.0 op_sel:[1,1,0]
	v_cvt_scalef32_pk_f32_fp4 v[8:9], v171, 1.0
	v_cvt_scalef32_pk_f32_fp4 v[10:11], v171, 1.0 op_sel:[1,0,0]
	v_cvt_scalef32_pk_f32_fp4 v[12:13], v171, 1.0 op_sel:[0,1,0]
	v_cvt_scalef32_pk_f32_fp4 v[14:15], v171, 1.0 op_sel:[1,1,0]
	v_readlane_b32 s54, v92, 25
	s_lshl_b32 s56, s54, 9
	s_add_u32 s56, s64, s56
	s_addc_u32 s57, s65, 0
	global_load_dwordx2 v[170:171], v227, s[56:57]
	s_waitcnt lgkmcnt(1)
	v_pk_fma_f32 v[130:131], v[0:1], v[194:195], v[130:131] op_sel_hi:[1,0,1]
	v_pk_fma_f32 v[138:139], v[2:3], v[194:195], v[138:139] op_sel_hi:[1,0,1]
	v_pk_fma_f32 v[140:141], v[4:5], v[194:195], v[140:141] op_sel_hi:[1,0,1]
	v_pk_fma_f32 v[142:143], v[6:7], v[194:195], v[142:143] op_sel_hi:[1,0,1]
	v_pk_fma_f32 v[128:129], v[8:9], v[194:195], v[128:129] op_sel_hi:[1,0,1]
	v_pk_fma_f32 v[132:133], v[10:11], v[194:195], v[132:133] op_sel_hi:[1,0,1]
	v_pk_fma_f32 v[134:135], v[12:13], v[194:195], v[134:135] op_sel_hi:[1,0,1]
	v_pk_fma_f32 v[136:137], v[14:15], v[194:195], v[136:137] op_sel_hi:[1,0,1]
	ds_read_b32 v194, v193 offset:300
	s_waitcnt vmcnt(48)
	v_cvt_scalef32_pk_f32_fp4 v[0:1], v172, 1.0
	v_cvt_scalef32_pk_f32_fp4 v[2:3], v172, 1.0 op_sel:[1,0,0]
	v_cvt_scalef32_pk_f32_fp4 v[4:5], v172, 1.0 op_sel:[0,1,0]
	v_cvt_scalef32_pk_f32_fp4 v[6:7], v172, 1.0 op_sel:[1,1,0]
	v_cvt_scalef32_pk_f32_fp4 v[8:9], v173, 1.0
	v_cvt_scalef32_pk_f32_fp4 v[10:11], v173, 1.0 op_sel:[1,0,0]
	v_cvt_scalef32_pk_f32_fp4 v[12:13], v173, 1.0 op_sel:[0,1,0]
	v_cvt_scalef32_pk_f32_fp4 v[14:15], v173, 1.0 op_sel:[1,1,0]
	v_readlane_b32 s54, v92, 26
	s_lshl_b32 s56, s54, 9
	s_add_u32 s56, s64, s56
	s_addc_u32 s57, s65, 0
	global_load_dwordx2 v[172:173], v227, s[56:57]
	s_waitcnt lgkmcnt(1)
	v_pk_fma_f32 v[130:131], v[0:1], v[76:77], v[130:131] op_sel_hi:[1,0,1]
	v_pk_fma_f32 v[138:139], v[2:3], v[76:77], v[138:139] op_sel_hi:[1,0,1]
	v_pk_fma_f32 v[140:141], v[4:5], v[76:77], v[140:141] op_sel_hi:[1,0,1]
	v_pk_fma_f32 v[142:143], v[6:7], v[76:77], v[142:143] op_sel_hi:[1,0,1]
	v_pk_fma_f32 v[128:129], v[8:9], v[76:77], v[128:129] op_sel_hi:[1,0,1]
	v_pk_fma_f32 v[132:133], v[10:11], v[76:77], v[132:133] op_sel_hi:[1,0,1]
	v_pk_fma_f32 v[134:135], v[12:13], v[76:77], v[134:135] op_sel_hi:[1,0,1]
	v_pk_fma_f32 v[136:137], v[14:15], v[76:77], v[136:137] op_sel_hi:[1,0,1]
	ds_read_b32 v76, v193 offset:304
	s_waitcnt vmcnt(48)
	v_cvt_scalef32_pk_f32_fp4 v[0:1], v174, 1.0
	v_cvt_scalef32_pk_f32_fp4 v[2:3], v174, 1.0 op_sel:[1,0,0]
	v_cvt_scalef32_pk_f32_fp4 v[4:5], v174, 1.0 op_sel:[0,1,0]
	v_cvt_scalef32_pk_f32_fp4 v[6:7], v174, 1.0 op_sel:[1,1,0]
	v_cvt_scalef32_pk_f32_fp4 v[8:9], v175, 1.0
	v_cvt_scalef32_pk_f32_fp4 v[10:11], v175, 1.0 op_sel:[1,0,0]
	v_cvt_scalef32_pk_f32_fp4 v[12:13], v175, 1.0 op_sel:[0,1,0]
	v_cvt_scalef32_pk_f32_fp4 v[14:15], v175, 1.0 op_sel:[1,1,0]
	v_readlane_b32 s54, v92, 27
	s_lshl_b32 s56, s54, 9
	s_add_u32 s56, s64, s56
	s_addc_u32 s57, s65, 0
	global_load_dwordx2 v[174:175], v227, s[56:57]
	s_waitcnt lgkmcnt(1)
	v_pk_fma_f32 v[130:131], v[0:1], v[194:195], v[130:131] op_sel_hi:[1,0,1]
	v_pk_fma_f32 v[138:139], v[2:3], v[194:195], v[138:139] op_sel_hi:[1,0,1]
	v_pk_fma_f32 v[140:141], v[4:5], v[194:195], v[140:141] op_sel_hi:[1,0,1]
	v_pk_fma_f32 v[142:143], v[6:7], v[194:195], v[142:143] op_sel_hi:[1,0,1]
	v_pk_fma_f32 v[128:129], v[8:9], v[194:195], v[128:129] op_sel_hi:[1,0,1]
	v_pk_fma_f32 v[132:133], v[10:11], v[194:195], v[132:133] op_sel_hi:[1,0,1]
	v_pk_fma_f32 v[134:135], v[12:13], v[194:195], v[134:135] op_sel_hi:[1,0,1]
	v_pk_fma_f32 v[136:137], v[14:15], v[194:195], v[136:137] op_sel_hi:[1,0,1]
	ds_read_b32 v194, v193 offset:308
	s_waitcnt vmcnt(48)
	v_cvt_scalef32_pk_f32_fp4 v[0:1], v180, 1.0
	v_cvt_scalef32_pk_f32_fp4 v[2:3], v180, 1.0 op_sel:[1,0,0]
	v_cvt_scalef32_pk_f32_fp4 v[4:5], v180, 1.0 op_sel:[0,1,0]
	v_cvt_scalef32_pk_f32_fp4 v[6:7], v180, 1.0 op_sel:[1,1,0]
	v_cvt_scalef32_pk_f32_fp4 v[8:9], v181, 1.0
	v_cvt_scalef32_pk_f32_fp4 v[10:11], v181, 1.0 op_sel:[1,0,0]
	v_cvt_scalef32_pk_f32_fp4 v[12:13], v181, 1.0 op_sel:[0,1,0]
	v_cvt_scalef32_pk_f32_fp4 v[14:15], v181, 1.0 op_sel:[1,1,0]
	v_readlane_b32 s54, v92, 28
	s_lshl_b32 s56, s54, 9
	s_add_u32 s56, s64, s56
	s_addc_u32 s57, s65, 0
	global_load_dwordx2 v[180:181], v227, s[56:57]
	s_waitcnt lgkmcnt(1)
	v_pk_fma_f32 v[130:131], v[0:1], v[76:77], v[130:131] op_sel_hi:[1,0,1]
	v_pk_fma_f32 v[138:139], v[2:3], v[76:77], v[138:139] op_sel_hi:[1,0,1]
	v_pk_fma_f32 v[140:141], v[4:5], v[76:77], v[140:141] op_sel_hi:[1,0,1]
	v_pk_fma_f32 v[142:143], v[6:7], v[76:77], v[142:143] op_sel_hi:[1,0,1]
	v_pk_fma_f32 v[128:129], v[8:9], v[76:77], v[128:129] op_sel_hi:[1,0,1]
	v_pk_fma_f32 v[132:133], v[10:11], v[76:77], v[132:133] op_sel_hi:[1,0,1]
	v_pk_fma_f32 v[134:135], v[12:13], v[76:77], v[134:135] op_sel_hi:[1,0,1]
	v_pk_fma_f32 v[136:137], v[14:15], v[76:77], v[136:137] op_sel_hi:[1,0,1]
	ds_read_b32 v76, v193 offset:312
	s_waitcnt vmcnt(48)
	v_cvt_scalef32_pk_f32_fp4 v[0:1], v182, 1.0
	v_cvt_scalef32_pk_f32_fp4 v[2:3], v182, 1.0 op_sel:[1,0,0]
	v_cvt_scalef32_pk_f32_fp4 v[4:5], v182, 1.0 op_sel:[0,1,0]
	v_cvt_scalef32_pk_f32_fp4 v[6:7], v182, 1.0 op_sel:[1,1,0]
	v_cvt_scalef32_pk_f32_fp4 v[8:9], v183, 1.0
	v_cvt_scalef32_pk_f32_fp4 v[10:11], v183, 1.0 op_sel:[1,0,0]
	v_cvt_scalef32_pk_f32_fp4 v[12:13], v183, 1.0 op_sel:[0,1,0]
	v_cvt_scalef32_pk_f32_fp4 v[14:15], v183, 1.0 op_sel:[1,1,0]
	v_readlane_b32 s54, v92, 29
	s_lshl_b32 s56, s54, 9
	s_add_u32 s56, s64, s56
	s_addc_u32 s57, s65, 0
	global_load_dwordx2 v[182:183], v227, s[56:57]
	s_waitcnt lgkmcnt(1)
; __device__ void peer_gather_phase(const Params& P, int l, bool do_store) {
;     ...
;         v8[2 * pr] = *(const uint2*)(V + (size_t)ea * 512);
;         v8[2 * pr + 1] = *(const uint2*)(V + (size_t)eb * 512);
;     ...
; #pragma unroll
;       for (int j = 0; j < 8; ++j) {
;         const float a = __builtin_bit_cast(float, __builtin_amdgcn_readlane(__builtin_bit_cast(int, avec), kb + j));
;         const f32x2 aa = f32x2{a, a};
;         y[0] += aa * __builtin_amdgcn_cvt_scalef32_pk_f32_fp4(v8[j].x, 1.0f, 0); y[1] += aa * __builtin_amdgcn_cvt_scalef32_pk_f32_fp4(v8[j].x, 1.0f, 1);
;         y[2] += aa * __builtin_amdgcn_cvt_scalef32_pk_f32_fp4(v8[j].x, 1.0f, 2); y[3] += aa * __builtin_amdgcn_cvt_scalef32_pk_f32_fp4(v8[j].x, 1.0f, 3);
;         y[4] += aa * __builtin_amdgcn_cvt_scalef32_pk_f32_fp4(v8[j].y, 1.0f, 0); y[5] += aa * __builtin_amdgcn_cvt_scalef32_pk_f32_fp4(v8[j].y, 1.0f, 1);
;         y[6] += aa * __builtin_amdgcn_cvt_scalef32_pk_f32_fp4(v8[j].y, 1.0f, 2); y[7] += aa * __builtin_amdgcn_cvt_scalef32_pk_f32_fp4(v8[j].y, 1.0f, 3);
;       }
	v_pk_fma_f32 v[130:131], v[0:1], v[194:195], v[130:131] op_sel_hi:[1,0,1]
	v_pk_fma_f32 v[138:139], v[2:3], v[194:195], v[138:139] op_sel_hi:[1,0,1]
	v_pk_fma_f32 v[140:141], v[4:5], v[194:195], v[140:141] op_sel_hi:[1,0,1]
	v_pk_fma_f32 v[142:143], v[6:7], v[194:195], v[142:143] op_sel_hi:[1,0,1]
	v_pk_fma_f32 v[128:129], v[8:9], v[194:195], v[128:129] op_sel_hi:[1,0,1]
	v_pk_fma_f32 v[132:133], v[10:11], v[194:195], v[132:133] op_sel_hi:[1,0,1]
	v_pk_fma_f32 v[134:135], v[12:13], v[194:195], v[134:135] op_sel_hi:[1,0,1]
	v_pk_fma_f32 v[136:137], v[14:15], v[194:195], v[136:137] op_sel_hi:[1,0,1]
	ds_read_b32 v194, v193 offset:316
	s_waitcnt vmcnt(48)
	v_cvt_scalef32_pk_f32_fp4 v[0:1], v184, 1.0
	v_cvt_scalef32_pk_f32_fp4 v[2:3], v184, 1.0 op_sel:[1,0,0]
	v_cvt_scalef32_pk_f32_fp4 v[4:5], v184, 1.0 op_sel:[0,1,0]
	v_cvt_scalef32_pk_f32_fp4 v[6:7], v184, 1.0 op_sel:[1,1,0]
	v_cvt_scalef32_pk_f32_fp4 v[8:9], v185, 1.0
	v_cvt_scalef32_pk_f32_fp4 v[10:11], v185, 1.0 op_sel:[1,0,0]
	v_cvt_scalef32_pk_f32_fp4 v[12:13], v185, 1.0 op_sel:[0,1,0]
	v_cvt_scalef32_pk_f32_fp4 v[14:15], v185, 1.0 op_sel:[1,1,0]
	v_readlane_b32 s54, v92, 30
	s_lshl_b32 s56, s54, 9
	s_add_u32 s56, s64, s56
	s_addc_u32 s57, s65, 0
	global_load_dwordx2 v[184:185], v227, s[56:57]
	s_waitcnt lgkmcnt(1)
	v_pk_fma_f32 v[130:131], v[0:1], v[76:77], v[130:131] op_sel_hi:[1,0,1]
	v_pk_fma_f32 v[138:139], v[2:3], v[76:77], v[138:139] op_sel_hi:[1,0,1]
	v_pk_fma_f32 v[140:141], v[4:5], v[76:77], v[140:141] op_sel_hi:[1,0,1]
	v_pk_fma_f32 v[142:143], v[6:7], v[76:77], v[142:143] op_sel_hi:[1,0,1]
	v_pk_fma_f32 v[128:129], v[8:9], v[76:77], v[128:129] op_sel_hi:[1,0,1]
	v_pk_fma_f32 v[132:133], v[10:11], v[76:77], v[132:133] op_sel_hi:[1,0,1]
	v_pk_fma_f32 v[134:135], v[12:13], v[76:77], v[134:135] op_sel_hi:[1,0,1]
	v_pk_fma_f32 v[136:137], v[14:15], v[76:77], v[136:137] op_sel_hi:[1,0,1]
	ds_read_b32 v76, v193 offset:320
	s_waitcnt vmcnt(48)
	v_cvt_scalef32_pk_f32_fp4 v[0:1], v186, 1.0
	v_cvt_scalef32_pk_f32_fp4 v[2:3], v186, 1.0 op_sel:[1,0,0]
	v_cvt_scalef32_pk_f32_fp4 v[4:5], v186, 1.0 op_sel:[0,1,0]
	v_cvt_scalef32_pk_f32_fp4 v[6:7], v186, 1.0 op_sel:[1,1,0]
	v_cvt_scalef32_pk_f32_fp4 v[8:9], v187, 1.0
	v_cvt_scalef32_pk_f32_fp4 v[10:11], v187, 1.0 op_sel:[1,0,0]
	v_cvt_scalef32_pk_f32_fp4 v[12:13], v187, 1.0 op_sel:[0,1,0]
	v_cvt_scalef32_pk_f32_fp4 v[14:15], v187, 1.0 op_sel:[1,1,0]
	v_readlane_b32 s54, v92, 31
	s_lshl_b32 s56, s54, 9
	s_add_u32 s56, s64, s56
	s_addc_u32 s57, s65, 0
	global_load_dwordx2 v[186:187], v227, s[56:57]
	s_waitcnt lgkmcnt(1)
	v_pk_fma_f32 v[130:131], v[0:1], v[194:195], v[130:131] op_sel_hi:[1,0,1]
	v_pk_fma_f32 v[138:139], v[2:3], v[194:195], v[138:139] op_sel_hi:[1,0,1]
	v_pk_fma_f32 v[140:141], v[4:5], v[194:195], v[140:141] op_sel_hi:[1,0,1]
	v_pk_fma_f32 v[142:143], v[6:7], v[194:195], v[142:143] op_sel_hi:[1,0,1]
	v_pk_fma_f32 v[128:129], v[8:9], v[194:195], v[128:129] op_sel_hi:[1,0,1]
	v_pk_fma_f32 v[132:133], v[10:11], v[194:195], v[132:133] op_sel_hi:[1,0,1]
	v_pk_fma_f32 v[134:135], v[12:13], v[194:195], v[134:135] op_sel_hi:[1,0,1]
	v_pk_fma_f32 v[136:137], v[14:15], v[194:195], v[136:137] op_sel_hi:[1,0,1]
	ds_read_b32 v194, v193 offset:324
	s_waitcnt vmcnt(15)
	v_cvt_scalef32_pk_f32_fp4 v[0:1], v144, 1.0
	v_cvt_scalef32_pk_f32_fp4 v[2:3], v144, 1.0 op_sel:[1,0,0]
	v_cvt_scalef32_pk_f32_fp4 v[4:5], v144, 1.0 op_sel:[0,1,0]
	v_cvt_scalef32_pk_f32_fp4 v[6:7], v144, 1.0 op_sel:[1,1,0]
	v_cvt_scalef32_pk_f32_fp4 v[8:9], v145, 1.0
	v_cvt_scalef32_pk_f32_fp4 v[10:11], v145, 1.0 op_sel:[1,0,0]
	v_cvt_scalef32_pk_f32_fp4 v[12:13], v145, 1.0 op_sel:[0,1,0]
	v_cvt_scalef32_pk_f32_fp4 v[14:15], v145, 1.0 op_sel:[1,1,0]
	v_readlane_b32 s54, v92, 32
	s_lshl_b32 s56, s54, 9
	s_add_u32 s56, s64, s56
	s_addc_u32 s57, s65, 0
	global_load_dwordx2 v[144:145], v227, s[56:57]
	s_waitcnt lgkmcnt(1)
	v_pk_fma_f32 v[130:131], v[0:1], v[76:77], v[130:131] op_sel_hi:[1,0,1]
	v_pk_fma_f32 v[138:139], v[2:3], v[76:77], v[138:139] op_sel_hi:[1,0,1]
	v_pk_fma_f32 v[140:141], v[4:5], v[76:77], v[140:141] op_sel_hi:[1,0,1]
	v_pk_fma_f32 v[142:143], v[6:7], v[76:77], v[142:143] op_sel_hi:[1,0,1]
	v_pk_fma_f32 v[128:129], v[8:9], v[76:77], v[128:129] op_sel_hi:[1,0,1]
	v_pk_fma_f32 v[132:133], v[10:11], v[76:77], v[132:133] op_sel_hi:[1,0,1]
	v_pk_fma_f32 v[134:135], v[12:13], v[76:77], v[134:135] op_sel_hi:[1,0,1]
	v_pk_fma_f32 v[136:137], v[14:15], v[76:77], v[136:137] op_sel_hi:[1,0,1]
	ds_read_b32 v76, v193 offset:328
	s_waitcnt vmcnt(15)
	v_cvt_scalef32_pk_f32_fp4 v[0:1], v146, 1.0
	v_cvt_scalef32_pk_f32_fp4 v[2:3], v146, 1.0 op_sel:[1,0,0]
	v_cvt_scalef32_pk_f32_fp4 v[4:5], v146, 1.0 op_sel:[0,1,0]
	v_cvt_scalef32_pk_f32_fp4 v[6:7], v146, 1.0 op_sel:[1,1,0]
	v_cvt_scalef32_pk_f32_fp4 v[8:9], v147, 1.0
	v_cvt_scalef32_pk_f32_fp4 v[10:11], v147, 1.0 op_sel:[1,0,0]
	v_cvt_scalef32_pk_f32_fp4 v[12:13], v147, 1.0 op_sel:[0,1,0]
	v_cvt_scalef32_pk_f32_fp4 v[14:15], v147, 1.0 op_sel:[1,1,0]
	v_readlane_b32 s54, v92, 33
	s_lshl_b32 s56, s54, 9
	s_add_u32 s56, s64, s56
	s_addc_u32 s57, s65, 0
	global_load_dwordx2 v[146:147], v227, s[56:57]
	s_waitcnt lgkmcnt(1)
	v_pk_fma_f32 v[130:131], v[0:1], v[194:195], v[130:131] op_sel_hi:[1,0,1]
	v_pk_fma_f32 v[138:139], v[2:3], v[194:195], v[138:139] op_sel_hi:[1,0,1]
	v_pk_fma_f32 v[140:141], v[4:5], v[194:195], v[140:141] op_sel_hi:[1,0,1]
	v_pk_fma_f32 v[142:143], v[6:7], v[194:195], v[142:143] op_sel_hi:[1,0,1]
	v_pk_fma_f32 v[128:129], v[8:9], v[194:195], v[128:129] op_sel_hi:[1,0,1]
	v_pk_fma_f32 v[132:133], v[10:11], v[194:195], v[132:133] op_sel_hi:[1,0,1]
	v_pk_fma_f32 v[134:135], v[12:13], v[194:195], v[134:135] op_sel_hi:[1,0,1]
	v_pk_fma_f32 v[136:137], v[14:15], v[194:195], v[136:137] op_sel_hi:[1,0,1]
	ds_read_b32 v194, v193 offset:332
	s_waitcnt vmcnt(15)
; __device__ void peer_gather_phase(const Params& P, int l, bool do_store) {
;     ...
;         v8[2 * pr] = *(const uint2*)(V + (size_t)ea * 512);
;         v8[2 * pr + 1] = *(const uint2*)(V + (size_t)eb * 512);
;     ...
; #pragma unroll
;       for (int j = 0; j < 8; ++j) {
;         const float a = __builtin_bit_cast(float, __builtin_amdgcn_readlane(__builtin_bit_cast(int, avec), kb + j));
;         const f32x2 aa = f32x2{a, a};
;         y[0] += aa * __builtin_amdgcn_cvt_scalef32_pk_f32_fp4(v8[j].x, 1.0f, 0); y[1] += aa * __builtin_amdgcn_cvt_scalef32_pk_f32_fp4(v8[j].x, 1.0f, 1);
;         y[2] += aa * __builtin_amdgcn_cvt_scalef32_pk_f32_fp4(v8[j].x, 1.0f, 2); y[3] += aa * __builtin_amdgcn_cvt_scalef32_pk_f32_fp4(v8[j].x, 1.0f, 3);
;         y[4] += aa * __builtin_amdgcn_cvt_scalef32_pk_f32_fp4(v8[j].y, 1.0f, 0); y[5] += aa * __builtin_amdgcn_cvt_scalef32_pk_f32_fp4(v8[j].y, 1.0f, 1);
;         y[6] += aa * __builtin_amdgcn_cvt_scalef32_pk_f32_fp4(v8[j].y, 1.0f, 2); y[7] += aa * __builtin_amdgcn_cvt_scalef32_pk_f32_fp4(v8[j].y, 1.0f, 3);
;       }
	v_cvt_scalef32_pk_f32_fp4 v[0:1], v148, 1.0
	v_cvt_scalef32_pk_f32_fp4 v[2:3], v148, 1.0 op_sel:[1,0,0]
	v_cvt_scalef32_pk_f32_fp4 v[4:5], v148, 1.0 op_sel:[0,1,0]
	v_cvt_scalef32_pk_f32_fp4 v[6:7], v148, 1.0 op_sel:[1,1,0]
	v_cvt_scalef32_pk_f32_fp4 v[8:9], v149, 1.0
	v_cvt_scalef32_pk_f32_fp4 v[10:11], v149, 1.0 op_sel:[1,0,0]
	v_cvt_scalef32_pk_f32_fp4 v[12:13], v149, 1.0 op_sel:[0,1,0]
	v_cvt_scalef32_pk_f32_fp4 v[14:15], v149, 1.0 op_sel:[1,1,0]
	v_readlane_b32 s54, v92, 34
	s_lshl_b32 s56, s54, 9
	s_add_u32 s56, s64, s56
	s_addc_u32 s57, s65, 0
	global_load_dwordx2 v[148:149], v227, s[56:57]
	s_waitcnt lgkmcnt(1)
	v_pk_fma_f32 v[130:131], v[0:1], v[76:77], v[130:131] op_sel_hi:[1,0,1]
	v_pk_fma_f32 v[138:139], v[2:3], v[76:77], v[138:139] op_sel_hi:[1,0,1]
	v_pk_fma_f32 v[140:141], v[4:5], v[76:77], v[140:141] op_sel_hi:[1,0,1]
	v_pk_fma_f32 v[142:143], v[6:7], v[76:77], v[142:143] op_sel_hi:[1,0,1]
	v_pk_fma_f32 v[128:129], v[8:9], v[76:77], v[128:129] op_sel_hi:[1,0,1]
	v_pk_fma_f32 v[132:133], v[10:11], v[76:77], v[132:133] op_sel_hi:[1,0,1]
	v_pk_fma_f32 v[134:135], v[12:13], v[76:77], v[134:135] op_sel_hi:[1,0,1]
	v_pk_fma_f32 v[136:137], v[14:15], v[76:77], v[136:137] op_sel_hi:[1,0,1]
	ds_read_b32 v76, v193 offset:336
	s_waitcnt vmcnt(15)
	v_cvt_scalef32_pk_f32_fp4 v[0:1], v150, 1.0
	v_cvt_scalef32_pk_f32_fp4 v[2:3], v150, 1.0 op_sel:[1,0,0]
	v_cvt_scalef32_pk_f32_fp4 v[4:5], v150, 1.0 op_sel:[0,1,0]
	v_cvt_scalef32_pk_f32_fp4 v[6:7], v150, 1.0 op_sel:[1,1,0]
	v_cvt_scalef32_pk_f32_fp4 v[8:9], v151, 1.0
	v_cvt_scalef32_pk_f32_fp4 v[10:11], v151, 1.0 op_sel:[1,0,0]
	v_cvt_scalef32_pk_f32_fp4 v[12:13], v151, 1.0 op_sel:[0,1,0]
	v_cvt_scalef32_pk_f32_fp4 v[14:15], v151, 1.0 op_sel:[1,1,0]
	v_readlane_b32 s54, v92, 35
	s_lshl_b32 s56, s54, 9
	s_add_u32 s56, s64, s56
	s_addc_u32 s57, s65, 0
	global_load_dwordx2 v[150:151], v227, s[56:57]
	s_waitcnt lgkmcnt(1)
	v_pk_fma_f32 v[130:131], v[0:1], v[194:195], v[130:131] op_sel_hi:[1,0,1]
	v_pk_fma_f32 v[138:139], v[2:3], v[194:195], v[138:139] op_sel_hi:[1,0,1]
	v_pk_fma_f32 v[140:141], v[4:5], v[194:195], v[140:141] op_sel_hi:[1,0,1]
	v_pk_fma_f32 v[142:143], v[6:7], v[194:195], v[142:143] op_sel_hi:[1,0,1]
	v_pk_fma_f32 v[128:129], v[8:9], v[194:195], v[128:129] op_sel_hi:[1,0,1]
	v_pk_fma_f32 v[132:133], v[10:11], v[194:195], v[132:133] op_sel_hi:[1,0,1]
	v_pk_fma_f32 v[134:135], v[12:13], v[194:195], v[134:135] op_sel_hi:[1,0,1]
	v_pk_fma_f32 v[136:137], v[14:15], v[194:195], v[136:137] op_sel_hi:[1,0,1]
	ds_read_b32 v194, v193 offset:340
	s_waitcnt vmcnt(15)
	v_cvt_scalef32_pk_f32_fp4 v[0:1], v152, 1.0
	v_cvt_scalef32_pk_f32_fp4 v[2:3], v152, 1.0 op_sel:[1,0,0]
	v_cvt_scalef32_pk_f32_fp4 v[4:5], v152, 1.0 op_sel:[0,1,0]
	v_cvt_scalef32_pk_f32_fp4 v[6:7], v152, 1.0 op_sel:[1,1,0]
	v_cvt_scalef32_pk_f32_fp4 v[8:9], v153, 1.0
	v_cvt_scalef32_pk_f32_fp4 v[10:11], v153, 1.0 op_sel:[1,0,0]
	v_cvt_scalef32_pk_f32_fp4 v[12:13], v153, 1.0 op_sel:[0,1,0]
	v_cvt_scalef32_pk_f32_fp4 v[14:15], v153, 1.0 op_sel:[1,1,0]
	v_readlane_b32 s54, v92, 36
	s_lshl_b32 s56, s54, 9
	s_add_u32 s56, s64, s56
	s_addc_u32 s57, s65, 0
	global_load_dwordx2 v[152:153], v227, s[56:57]
	s_waitcnt lgkmcnt(1)
	v_pk_fma_f32 v[130:131], v[0:1], v[76:77], v[130:131] op_sel_hi:[1,0,1]
	v_pk_fma_f32 v[138:139], v[2:3], v[76:77], v[138:139] op_sel_hi:[1,0,1]
	v_pk_fma_f32 v[140:141], v[4:5], v[76:77], v[140:141] op_sel_hi:[1,0,1]
	v_pk_fma_f32 v[142:143], v[6:7], v[76:77], v[142:143] op_sel_hi:[1,0,1]
	v_pk_fma_f32 v[128:129], v[8:9], v[76:77], v[128:129] op_sel_hi:[1,0,1]
	v_pk_fma_f32 v[132:133], v[10:11], v[76:77], v[132:133] op_sel_hi:[1,0,1]
	v_pk_fma_f32 v[134:135], v[12:13], v[76:77], v[134:135] op_sel_hi:[1,0,1]
	v_pk_fma_f32 v[136:137], v[14:15], v[76:77], v[136:137] op_sel_hi:[1,0,1]
	ds_read_b32 v76, v193 offset:344
	s_waitcnt vmcnt(15)
	v_cvt_scalef32_pk_f32_fp4 v[0:1], v154, 1.0
	v_cvt_scalef32_pk_f32_fp4 v[2:3], v154, 1.0 op_sel:[1,0,0]
	v_cvt_scalef32_pk_f32_fp4 v[4:5], v154, 1.0 op_sel:[0,1,0]
	v_cvt_scalef32_pk_f32_fp4 v[6:7], v154, 1.0 op_sel:[1,1,0]
	v_cvt_scalef32_pk_f32_fp4 v[8:9], v155, 1.0
	v_cvt_scalef32_pk_f32_fp4 v[10:11], v155, 1.0 op_sel:[1,0,0]
	v_cvt_scalef32_pk_f32_fp4 v[12:13], v155, 1.0 op_sel:[0,1,0]
	v_cvt_scalef32_pk_f32_fp4 v[14:15], v155, 1.0 op_sel:[1,1,0]
	v_readlane_b32 s54, v92, 37
	s_lshl_b32 s56, s54, 9
	s_add_u32 s56, s64, s56
	s_addc_u32 s57, s65, 0
	global_load_dwordx2 v[154:155], v227, s[56:57]
	s_waitcnt lgkmcnt(1)
	v_pk_fma_f32 v[130:131], v[0:1], v[194:195], v[130:131] op_sel_hi:[1,0,1]
	v_pk_fma_f32 v[138:139], v[2:3], v[194:195], v[138:139] op_sel_hi:[1,0,1]
	v_pk_fma_f32 v[140:141], v[4:5], v[194:195], v[140:141] op_sel_hi:[1,0,1]
	v_pk_fma_f32 v[142:143], v[6:7], v[194:195], v[142:143] op_sel_hi:[1,0,1]
	v_pk_fma_f32 v[128:129], v[8:9], v[194:195], v[128:129] op_sel_hi:[1,0,1]
	v_pk_fma_f32 v[132:133], v[10:11], v[194:195], v[132:133] op_sel_hi:[1,0,1]
	v_pk_fma_f32 v[134:135], v[12:13], v[194:195], v[134:135] op_sel_hi:[1,0,1]
	v_pk_fma_f32 v[136:137], v[14:15], v[194:195], v[136:137] op_sel_hi:[1,0,1]
	ds_read_b32 v194, v193 offset:348
	s_waitcnt vmcnt(15)
	v_cvt_scalef32_pk_f32_fp4 v[0:1], v156, 1.0
	v_cvt_scalef32_pk_f32_fp4 v[2:3], v156, 1.0 op_sel:[1,0,0]
	v_cvt_scalef32_pk_f32_fp4 v[4:5], v156, 1.0 op_sel:[0,1,0]
	v_cvt_scalef32_pk_f32_fp4 v[6:7], v156, 1.0 op_sel:[1,1,0]
	v_cvt_scalef32_pk_f32_fp4 v[8:9], v157, 1.0
	v_cvt_scalef32_pk_f32_fp4 v[10:11], v157, 1.0 op_sel:[1,0,0]
	v_cvt_scalef32_pk_f32_fp4 v[12:13], v157, 1.0 op_sel:[0,1,0]
	v_cvt_scalef32_pk_f32_fp4 v[14:15], v157, 1.0 op_sel:[1,1,0]
	v_readlane_b32 s54, v92, 38
	s_lshl_b32 s56, s54, 9
	s_add_u32 s56, s64, s56
	s_addc_u32 s57, s65, 0
	global_load_dwordx2 v[156:157], v227, s[56:57]
	s_waitcnt lgkmcnt(1)
; __device__ void peer_gather_phase(const Params& P, int l, bool do_store) {
;     ...
;         v8[2 * pr] = *(const uint2*)(V + (size_t)ea * 512);
;         v8[2 * pr + 1] = *(const uint2*)(V + (size_t)eb * 512);
;     ...
; #pragma unroll
;       for (int j = 0; j < 8; ++j) {
;         const float a = __builtin_bit_cast(float, __builtin_amdgcn_readlane(__builtin_bit_cast(int, avec), kb + j));
;         const f32x2 aa = f32x2{a, a};
;         y[0] += aa * __builtin_amdgcn_cvt_scalef32_pk_f32_fp4(v8[j].x, 1.0f, 0); y[1] += aa * __builtin_amdgcn_cvt_scalef32_pk_f32_fp4(v8[j].x, 1.0f, 1);
;         y[2] += aa * __builtin_amdgcn_cvt_scalef32_pk_f32_fp4(v8[j].x, 1.0f, 2); y[3] += aa * __builtin_amdgcn_cvt_scalef32_pk_f32_fp4(v8[j].x, 1.0f, 3);
;         y[4] += aa * __builtin_amdgcn_cvt_scalef32_pk_f32_fp4(v8[j].y, 1.0f, 0); y[5] += aa * __builtin_amdgcn_cvt_scalef32_pk_f32_fp4(v8[j].y, 1.0f, 1);
;         y[6] += aa * __builtin_amdgcn_cvt_scalef32_pk_f32_fp4(v8[j].y, 1.0f, 2); y[7] += aa * __builtin_amdgcn_cvt_scalef32_pk_f32_fp4(v8[j].y, 1.0f, 3);
;       }
	v_pk_fma_f32 v[130:131], v[0:1], v[76:77], v[130:131] op_sel_hi:[1,0,1]
	v_pk_fma_f32 v[138:139], v[2:3], v[76:77], v[138:139] op_sel_hi:[1,0,1]
	v_pk_fma_f32 v[140:141], v[4:5], v[76:77], v[140:141] op_sel_hi:[1,0,1]
	v_pk_fma_f32 v[142:143], v[6:7], v[76:77], v[142:143] op_sel_hi:[1,0,1]
	v_pk_fma_f32 v[128:129], v[8:9], v[76:77], v[128:129] op_sel_hi:[1,0,1]
	v_pk_fma_f32 v[132:133], v[10:11], v[76:77], v[132:133] op_sel_hi:[1,0,1]
	v_pk_fma_f32 v[134:135], v[12:13], v[76:77], v[134:135] op_sel_hi:[1,0,1]
	v_pk_fma_f32 v[136:137], v[14:15], v[76:77], v[136:137] op_sel_hi:[1,0,1]
	ds_read_b32 v76, v193 offset:352
	s_waitcnt vmcnt(15)
	v_cvt_scalef32_pk_f32_fp4 v[0:1], v158, 1.0
	v_cvt_scalef32_pk_f32_fp4 v[2:3], v158, 1.0 op_sel:[1,0,0]
	v_cvt_scalef32_pk_f32_fp4 v[4:5], v158, 1.0 op_sel:[0,1,0]
	v_cvt_scalef32_pk_f32_fp4 v[6:7], v158, 1.0 op_sel:[1,1,0]
	v_cvt_scalef32_pk_f32_fp4 v[8:9], v159, 1.0
	v_cvt_scalef32_pk_f32_fp4 v[10:11], v159, 1.0 op_sel:[1,0,0]
	v_cvt_scalef32_pk_f32_fp4 v[12:13], v159, 1.0 op_sel:[0,1,0]
	v_cvt_scalef32_pk_f32_fp4 v[14:15], v159, 1.0 op_sel:[1,1,0]
	v_readlane_b32 s54, v92, 39
	s_lshl_b32 s56, s54, 9
	s_add_u32 s56, s64, s56
	s_addc_u32 s57, s65, 0
	global_load_dwordx2 v[158:159], v227, s[56:57]
	s_waitcnt lgkmcnt(1)
	v_pk_fma_f32 v[130:131], v[0:1], v[194:195], v[130:131] op_sel_hi:[1,0,1]
	v_pk_fma_f32 v[138:139], v[2:3], v[194:195], v[138:139] op_sel_hi:[1,0,1]
	v_pk_fma_f32 v[140:141], v[4:5], v[194:195], v[140:141] op_sel_hi:[1,0,1]
	v_pk_fma_f32 v[142:143], v[6:7], v[194:195], v[142:143] op_sel_hi:[1,0,1]
	v_pk_fma_f32 v[128:129], v[8:9], v[194:195], v[128:129] op_sel_hi:[1,0,1]
	v_pk_fma_f32 v[132:133], v[10:11], v[194:195], v[132:133] op_sel_hi:[1,0,1]
	v_pk_fma_f32 v[134:135], v[12:13], v[194:195], v[134:135] op_sel_hi:[1,0,1]
	v_pk_fma_f32 v[136:137], v[14:15], v[194:195], v[136:137] op_sel_hi:[1,0,1]
	ds_read_b32 v194, v193 offset:356
	s_waitcnt vmcnt(15)
	v_cvt_scalef32_pk_f32_fp4 v[0:1], v168, 1.0
	v_cvt_scalef32_pk_f32_fp4 v[2:3], v168, 1.0 op_sel:[1,0,0]
	v_cvt_scalef32_pk_f32_fp4 v[4:5], v168, 1.0 op_sel:[0,1,0]
	v_cvt_scalef32_pk_f32_fp4 v[6:7], v168, 1.0 op_sel:[1,1,0]
	v_cvt_scalef32_pk_f32_fp4 v[8:9], v169, 1.0
	v_cvt_scalef32_pk_f32_fp4 v[10:11], v169, 1.0 op_sel:[1,0,0]
	v_cvt_scalef32_pk_f32_fp4 v[12:13], v169, 1.0 op_sel:[0,1,0]
	v_cvt_scalef32_pk_f32_fp4 v[14:15], v169, 1.0 op_sel:[1,1,0]
	v_readlane_b32 s54, v92, 40
	s_lshl_b32 s56, s54, 9
	s_add_u32 s56, s64, s56
	s_addc_u32 s57, s65, 0
	global_load_dwordx2 v[168:169], v227, s[56:57]
	s_waitcnt lgkmcnt(1)
	v_pk_fma_f32 v[130:131], v[0:1], v[76:77], v[130:131] op_sel_hi:[1,0,1]
	v_pk_fma_f32 v[138:139], v[2:3], v[76:77], v[138:139] op_sel_hi:[1,0,1]
	v_pk_fma_f32 v[140:141], v[4:5], v[76:77], v[140:141] op_sel_hi:[1,0,1]
	v_pk_fma_f32 v[142:143], v[6:7], v[76:77], v[142:143] op_sel_hi:[1,0,1]
	v_pk_fma_f32 v[128:129], v[8:9], v[76:77], v[128:129] op_sel_hi:[1,0,1]
	v_pk_fma_f32 v[132:133], v[10:11], v[76:77], v[132:133] op_sel_hi:[1,0,1]
	v_pk_fma_f32 v[134:135], v[12:13], v[76:77], v[134:135] op_sel_hi:[1,0,1]
	v_pk_fma_f32 v[136:137], v[14:15], v[76:77], v[136:137] op_sel_hi:[1,0,1]
	ds_read_b32 v76, v193 offset:360
	s_waitcnt vmcnt(15)
	v_cvt_scalef32_pk_f32_fp4 v[0:1], v170, 1.0
	v_cvt_scalef32_pk_f32_fp4 v[2:3], v170, 1.0 op_sel:[1,0,0]
	v_cvt_scalef32_pk_f32_fp4 v[4:5], v170, 1.0 op_sel:[0,1,0]
	v_cvt_scalef32_pk_f32_fp4 v[6:7], v170, 1.0 op_sel:[1,1,0]
	v_cvt_scalef32_pk_f32_fp4 v[8:9], v171, 1.0
	v_cvt_scalef32_pk_f32_fp4 v[10:11], v171, 1.0 op_sel:[1,0,0]
	v_cvt_scalef32_pk_f32_fp4 v[12:13], v171, 1.0 op_sel:[0,1,0]
	v_cvt_scalef32_pk_f32_fp4 v[14:15], v171, 1.0 op_sel:[1,1,0]
	v_readlane_b32 s54, v92, 41
	s_lshl_b32 s56, s54, 9
	s_add_u32 s56, s64, s56
	s_addc_u32 s57, s65, 0
	global_load_dwordx2 v[170:171], v227, s[56:57]
	s_waitcnt lgkmcnt(1)
	v_pk_fma_f32 v[130:131], v[0:1], v[194:195], v[130:131] op_sel_hi:[1,0,1]
	v_pk_fma_f32 v[138:139], v[2:3], v[194:195], v[138:139] op_sel_hi:[1,0,1]
	v_pk_fma_f32 v[140:141], v[4:5], v[194:195], v[140:141] op_sel_hi:[1,0,1]
	v_pk_fma_f32 v[142:143], v[6:7], v[194:195], v[142:143] op_sel_hi:[1,0,1]
	v_pk_fma_f32 v[128:129], v[8:9], v[194:195], v[128:129] op_sel_hi:[1,0,1]
	v_pk_fma_f32 v[132:133], v[10:11], v[194:195], v[132:133] op_sel_hi:[1,0,1]
	v_pk_fma_f32 v[134:135], v[12:13], v[194:195], v[134:135] op_sel_hi:[1,0,1]
	v_pk_fma_f32 v[136:137], v[14:15], v[194:195], v[136:137] op_sel_hi:[1,0,1]
	ds_read_b32 v194, v193 offset:364
	s_waitcnt vmcnt(15)
	v_cvt_scalef32_pk_f32_fp4 v[0:1], v172, 1.0
	v_cvt_scalef32_pk_f32_fp4 v[2:3], v172, 1.0 op_sel:[1,0,0]
	v_cvt_scalef32_pk_f32_fp4 v[4:5], v172, 1.0 op_sel:[0,1,0]
	v_cvt_scalef32_pk_f32_fp4 v[6:7], v172, 1.0 op_sel:[1,1,0]
	v_cvt_scalef32_pk_f32_fp4 v[8:9], v173, 1.0
	v_cvt_scalef32_pk_f32_fp4 v[10:11], v173, 1.0 op_sel:[1,0,0]
	v_cvt_scalef32_pk_f32_fp4 v[12:13], v173, 1.0 op_sel:[0,1,0]
	v_cvt_scalef32_pk_f32_fp4 v[14:15], v173, 1.0 op_sel:[1,1,0]
	v_readlane_b32 s54, v92, 42
	s_lshl_b32 s56, s54, 9
	s_add_u32 s56, s64, s56
	s_addc_u32 s57, s65, 0
	global_load_dwordx2 v[172:173], v227, s[56:57]
	s_waitcnt lgkmcnt(1)
	v_pk_fma_f32 v[130:131], v[0:1], v[76:77], v[130:131] op_sel_hi:[1,0,1]
	v_pk_fma_f32 v[138:139], v[2:3], v[76:77], v[138:139] op_sel_hi:[1,0,1]
	v_pk_fma_f32 v[140:141], v[4:5], v[76:77], v[140:141] op_sel_hi:[1,0,1]
	v_pk_fma_f32 v[142:143], v[6:7], v[76:77], v[142:143] op_sel_hi:[1,0,1]
	v_pk_fma_f32 v[128:129], v[8:9], v[76:77], v[128:129] op_sel_hi:[1,0,1]
	v_pk_fma_f32 v[132:133], v[10:11], v[76:77], v[132:133] op_sel_hi:[1,0,1]
	v_pk_fma_f32 v[134:135], v[12:13], v[76:77], v[134:135] op_sel_hi:[1,0,1]
	v_pk_fma_f32 v[136:137], v[14:15], v[76:77], v[136:137] op_sel_hi:[1,0,1]
	ds_read_b32 v76, v193 offset:368
	s_waitcnt vmcnt(15)
; __device__ void peer_gather_phase(const Params& P, int l, bool do_store) {
;     ...
;         v8[2 * pr] = *(const uint2*)(V + (size_t)ea * 512);
;         v8[2 * pr + 1] = *(const uint2*)(V + (size_t)eb * 512);
;     ...
; #pragma unroll
;       for (int j = 0; j < 8; ++j) {
;         const float a = __builtin_bit_cast(float, __builtin_amdgcn_readlane(__builtin_bit_cast(int, avec), kb + j));
;         const f32x2 aa = f32x2{a, a};
;         y[0] += aa * __builtin_amdgcn_cvt_scalef32_pk_f32_fp4(v8[j].x, 1.0f, 0); y[1] += aa * __builtin_amdgcn_cvt_scalef32_pk_f32_fp4(v8[j].x, 1.0f, 1);
;         y[2] += aa * __builtin_amdgcn_cvt_scalef32_pk_f32_fp4(v8[j].x, 1.0f, 2); y[3] += aa * __builtin_amdgcn_cvt_scalef32_pk_f32_fp4(v8[j].x, 1.0f, 3);
;         y[4] += aa * __builtin_amdgcn_cvt_scalef32_pk_f32_fp4(v8[j].y, 1.0f, 0); y[5] += aa * __builtin_amdgcn_cvt_scalef32_pk_f32_fp4(v8[j].y, 1.0f, 1);
;         y[6] += aa * __builtin_amdgcn_cvt_scalef32_pk_f32_fp4(v8[j].y, 1.0f, 2); y[7] += aa * __builtin_amdgcn_cvt_scalef32_pk_f32_fp4(v8[j].y, 1.0f, 3);
;       }
	v_cvt_scalef32_pk_f32_fp4 v[0:1], v174, 1.0
	v_cvt_scalef32_pk_f32_fp4 v[2:3], v174, 1.0 op_sel:[1,0,0]
	v_cvt_scalef32_pk_f32_fp4 v[4:5], v174, 1.0 op_sel:[0,1,0]
	v_cvt_scalef32_pk_f32_fp4 v[6:7], v174, 1.0 op_sel:[1,1,0]
	v_cvt_scalef32_pk_f32_fp4 v[8:9], v175, 1.0
	v_cvt_scalef32_pk_f32_fp4 v[10:11], v175, 1.0 op_sel:[1,0,0]
	v_cvt_scalef32_pk_f32_fp4 v[12:13], v175, 1.0 op_sel:[0,1,0]
	v_cvt_scalef32_pk_f32_fp4 v[14:15], v175, 1.0 op_sel:[1,1,0]
	v_readlane_b32 s54, v92, 43
	s_lshl_b32 s56, s54, 9
	s_add_u32 s56, s64, s56
	s_addc_u32 s57, s65, 0
	global_load_dwordx2 v[174:175], v227, s[56:57]
	s_waitcnt lgkmcnt(1)
	v_pk_fma_f32 v[130:131], v[0:1], v[194:195], v[130:131] op_sel_hi:[1,0,1]
	v_pk_fma_f32 v[138:139], v[2:3], v[194:195], v[138:139] op_sel_hi:[1,0,1]
	v_pk_fma_f32 v[140:141], v[4:5], v[194:195], v[140:141] op_sel_hi:[1,0,1]
	v_pk_fma_f32 v[142:143], v[6:7], v[194:195], v[142:143] op_sel_hi:[1,0,1]
	v_pk_fma_f32 v[128:129], v[8:9], v[194:195], v[128:129] op_sel_hi:[1,0,1]
	v_pk_fma_f32 v[132:133], v[10:11], v[194:195], v[132:133] op_sel_hi:[1,0,1]
	v_pk_fma_f32 v[134:135], v[12:13], v[194:195], v[134:135] op_sel_hi:[1,0,1]
	v_pk_fma_f32 v[136:137], v[14:15], v[194:195], v[136:137] op_sel_hi:[1,0,1]
	ds_read_b32 v194, v193 offset:372
	s_waitcnt vmcnt(15)
	v_cvt_scalef32_pk_f32_fp4 v[0:1], v180, 1.0
	v_cvt_scalef32_pk_f32_fp4 v[2:3], v180, 1.0 op_sel:[1,0,0]
	v_cvt_scalef32_pk_f32_fp4 v[4:5], v180, 1.0 op_sel:[0,1,0]
	v_cvt_scalef32_pk_f32_fp4 v[6:7], v180, 1.0 op_sel:[1,1,0]
	v_cvt_scalef32_pk_f32_fp4 v[8:9], v181, 1.0
	v_cvt_scalef32_pk_f32_fp4 v[10:11], v181, 1.0 op_sel:[1,0,0]
	v_cvt_scalef32_pk_f32_fp4 v[12:13], v181, 1.0 op_sel:[0,1,0]
	v_cvt_scalef32_pk_f32_fp4 v[14:15], v181, 1.0 op_sel:[1,1,0]
	v_readlane_b32 s54, v92, 44
	s_lshl_b32 s56, s54, 9
	s_add_u32 s56, s64, s56
	s_addc_u32 s57, s65, 0
	global_load_dwordx2 v[180:181], v227, s[56:57]
	s_waitcnt lgkmcnt(1)
	v_pk_fma_f32 v[130:131], v[0:1], v[76:77], v[130:131] op_sel_hi:[1,0,1]
	v_pk_fma_f32 v[138:139], v[2:3], v[76:77], v[138:139] op_sel_hi:[1,0,1]
	v_pk_fma_f32 v[140:141], v[4:5], v[76:77], v[140:141] op_sel_hi:[1,0,1]
	v_pk_fma_f32 v[142:143], v[6:7], v[76:77], v[142:143] op_sel_hi:[1,0,1]
	v_pk_fma_f32 v[128:129], v[8:9], v[76:77], v[128:129] op_sel_hi:[1,0,1]
	v_pk_fma_f32 v[132:133], v[10:11], v[76:77], v[132:133] op_sel_hi:[1,0,1]
	v_pk_fma_f32 v[134:135], v[12:13], v[76:77], v[134:135] op_sel_hi:[1,0,1]
	v_pk_fma_f32 v[136:137], v[14:15], v[76:77], v[136:137] op_sel_hi:[1,0,1]
	ds_read_b32 v76, v193 offset:376
	s_waitcnt vmcnt(15)
	v_cvt_scalef32_pk_f32_fp4 v[0:1], v182, 1.0
	v_cvt_scalef32_pk_f32_fp4 v[2:3], v182, 1.0 op_sel:[1,0,0]
	v_cvt_scalef32_pk_f32_fp4 v[4:5], v182, 1.0 op_sel:[0,1,0]
	v_cvt_scalef32_pk_f32_fp4 v[6:7], v182, 1.0 op_sel:[1,1,0]
	v_cvt_scalef32_pk_f32_fp4 v[8:9], v183, 1.0
	v_cvt_scalef32_pk_f32_fp4 v[10:11], v183, 1.0 op_sel:[1,0,0]
	v_cvt_scalef32_pk_f32_fp4 v[12:13], v183, 1.0 op_sel:[0,1,0]
	v_cvt_scalef32_pk_f32_fp4 v[14:15], v183, 1.0 op_sel:[1,1,0]
	v_readlane_b32 s54, v92, 45
	s_lshl_b32 s56, s54, 9
	s_add_u32 s56, s64, s56
	s_addc_u32 s57, s65, 0
	global_load_dwordx2 v[182:183], v227, s[56:57]
	s_waitcnt lgkmcnt(1)
	v_pk_fma_f32 v[130:131], v[0:1], v[194:195], v[130:131] op_sel_hi:[1,0,1]
	v_pk_fma_f32 v[138:139], v[2:3], v[194:195], v[138:139] op_sel_hi:[1,0,1]
	v_pk_fma_f32 v[140:141], v[4:5], v[194:195], v[140:141] op_sel_hi:[1,0,1]
	v_pk_fma_f32 v[142:143], v[6:7], v[194:195], v[142:143] op_sel_hi:[1,0,1]
	v_pk_fma_f32 v[128:129], v[8:9], v[194:195], v[128:129] op_sel_hi:[1,0,1]
	v_pk_fma_f32 v[132:133], v[10:11], v[194:195], v[132:133] op_sel_hi:[1,0,1]
	v_pk_fma_f32 v[134:135], v[12:13], v[194:195], v[134:135] op_sel_hi:[1,0,1]
	v_pk_fma_f32 v[136:137], v[14:15], v[194:195], v[136:137] op_sel_hi:[1,0,1]
	ds_read_b32 v194, v193 offset:380
	s_waitcnt vmcnt(15)
	v_cvt_scalef32_pk_f32_fp4 v[0:1], v184, 1.0
	v_cvt_scalef32_pk_f32_fp4 v[2:3], v184, 1.0 op_sel:[1,0,0]
	v_cvt_scalef32_pk_f32_fp4 v[4:5], v184, 1.0 op_sel:[0,1,0]
	v_cvt_scalef32_pk_f32_fp4 v[6:7], v184, 1.0 op_sel:[1,1,0]
	v_cvt_scalef32_pk_f32_fp4 v[8:9], v185, 1.0
	v_cvt_scalef32_pk_f32_fp4 v[10:11], v185, 1.0 op_sel:[1,0,0]
	v_cvt_scalef32_pk_f32_fp4 v[12:13], v185, 1.0 op_sel:[0,1,0]
	v_cvt_scalef32_pk_f32_fp4 v[14:15], v185, 1.0 op_sel:[1,1,0]
	v_readlane_b32 s54, v92, 46
	s_lshl_b32 s56, s54, 9
	s_add_u32 s56, s64, s56
	s_addc_u32 s57, s65, 0
	global_load_dwordx2 v[184:185], v227, s[56:57]
	s_waitcnt lgkmcnt(1)
	v_pk_fma_f32 v[130:131], v[0:1], v[76:77], v[130:131] op_sel_hi:[1,0,1]
	v_pk_fma_f32 v[138:139], v[2:3], v[76:77], v[138:139] op_sel_hi:[1,0,1]
	v_pk_fma_f32 v[140:141], v[4:5], v[76:77], v[140:141] op_sel_hi:[1,0,1]
	v_pk_fma_f32 v[142:143], v[6:7], v[76:77], v[142:143] op_sel_hi:[1,0,1]
	v_pk_fma_f32 v[128:129], v[8:9], v[76:77], v[128:129] op_sel_hi:[1,0,1]
	v_pk_fma_f32 v[132:133], v[10:11], v[76:77], v[132:133] op_sel_hi:[1,0,1]
	v_pk_fma_f32 v[134:135], v[12:13], v[76:77], v[134:135] op_sel_hi:[1,0,1]
	v_pk_fma_f32 v[136:137], v[14:15], v[76:77], v[136:137] op_sel_hi:[1,0,1]
	ds_read_b32 v76, v193 offset:384
	s_waitcnt vmcnt(15)
	v_cvt_scalef32_pk_f32_fp4 v[0:1], v186, 1.0
	v_cvt_scalef32_pk_f32_fp4 v[2:3], v186, 1.0 op_sel:[1,0,0]
	v_cvt_scalef32_pk_f32_fp4 v[4:5], v186, 1.0 op_sel:[0,1,0]
	v_cvt_scalef32_pk_f32_fp4 v[6:7], v186, 1.0 op_sel:[1,1,0]
	v_cvt_scalef32_pk_f32_fp4 v[8:9], v187, 1.0
	v_cvt_scalef32_pk_f32_fp4 v[10:11], v187, 1.0 op_sel:[1,0,0]
	v_cvt_scalef32_pk_f32_fp4 v[12:13], v187, 1.0 op_sel:[0,1,0]
	v_cvt_scalef32_pk_f32_fp4 v[14:15], v187, 1.0 op_sel:[1,1,0]
	v_readlane_b32 s54, v92, 47
	s_lshl_b32 s56, s54, 9
	s_add_u32 s56, s64, s56
	s_addc_u32 s57, s65, 0
	global_load_dwordx2 v[186:187], v227, s[56:57]
	s_waitcnt lgkmcnt(1)
; __device__ void peer_gather_phase(const Params& P, int l, bool do_store) {
;     ...
;         v8[2 * pr] = *(const uint2*)(V + (size_t)ea * 512);
;         v8[2 * pr + 1] = *(const uint2*)(V + (size_t)eb * 512);
;     ...
; #pragma unroll
;       for (int j = 0; j < 8; ++j) {
;         const float a = __builtin_bit_cast(float, __builtin_amdgcn_readlane(__builtin_bit_cast(int, avec), kb + j));
;         const f32x2 aa = f32x2{a, a};
;         y[0] += aa * __builtin_amdgcn_cvt_scalef32_pk_f32_fp4(v8[j].x, 1.0f, 0); y[1] += aa * __builtin_amdgcn_cvt_scalef32_pk_f32_fp4(v8[j].x, 1.0f, 1);
;         y[2] += aa * __builtin_amdgcn_cvt_scalef32_pk_f32_fp4(v8[j].x, 1.0f, 2); y[3] += aa * __builtin_amdgcn_cvt_scalef32_pk_f32_fp4(v8[j].x, 1.0f, 3);
;         y[4] += aa * __builtin_amdgcn_cvt_scalef32_pk_f32_fp4(v8[j].y, 1.0f, 0); y[5] += aa * __builtin_amdgcn_cvt_scalef32_pk_f32_fp4(v8[j].y, 1.0f, 1);
;         y[6] += aa * __builtin_amdgcn_cvt_scalef32_pk_f32_fp4(v8[j].y, 1.0f, 2); y[7] += aa * __builtin_amdgcn_cvt_scalef32_pk_f32_fp4(v8[j].y, 1.0f, 3);
;       }
	v_pk_fma_f32 v[130:131], v[0:1], v[194:195], v[130:131] op_sel_hi:[1,0,1]
	v_pk_fma_f32 v[138:139], v[2:3], v[194:195], v[138:139] op_sel_hi:[1,0,1]
	v_pk_fma_f32 v[140:141], v[4:5], v[194:195], v[140:141] op_sel_hi:[1,0,1]
	v_pk_fma_f32 v[142:143], v[6:7], v[194:195], v[142:143] op_sel_hi:[1,0,1]
	v_pk_fma_f32 v[128:129], v[8:9], v[194:195], v[128:129] op_sel_hi:[1,0,1]
	v_pk_fma_f32 v[132:133], v[10:11], v[194:195], v[132:133] op_sel_hi:[1,0,1]
	v_pk_fma_f32 v[134:135], v[12:13], v[194:195], v[134:135] op_sel_hi:[1,0,1]
	v_pk_fma_f32 v[136:137], v[14:15], v[194:195], v[136:137] op_sel_hi:[1,0,1]
	ds_read_b32 v194, v193 offset:388
	s_waitcnt vmcnt(15)
	v_cvt_scalef32_pk_f32_fp4 v[0:1], v144, 1.0
	v_cvt_scalef32_pk_f32_fp4 v[2:3], v144, 1.0 op_sel:[1,0,0]
	v_cvt_scalef32_pk_f32_fp4 v[4:5], v144, 1.0 op_sel:[0,1,0]
	v_cvt_scalef32_pk_f32_fp4 v[6:7], v144, 1.0 op_sel:[1,1,0]
	v_cvt_scalef32_pk_f32_fp4 v[8:9], v145, 1.0
	v_cvt_scalef32_pk_f32_fp4 v[10:11], v145, 1.0 op_sel:[1,0,0]
	v_cvt_scalef32_pk_f32_fp4 v[12:13], v145, 1.0 op_sel:[0,1,0]
	v_cvt_scalef32_pk_f32_fp4 v[14:15], v145, 1.0 op_sel:[1,1,0]
	v_readlane_b32 s54, v92, 48
	s_lshl_b32 s56, s54, 9
	s_add_u32 s56, s64, s56
	s_addc_u32 s57, s65, 0
	global_load_dwordx2 v[144:145], v227, s[56:57]
	s_waitcnt lgkmcnt(1)
	v_pk_fma_f32 v[130:131], v[0:1], v[76:77], v[130:131] op_sel_hi:[1,0,1]
	v_pk_fma_f32 v[138:139], v[2:3], v[76:77], v[138:139] op_sel_hi:[1,0,1]
	v_pk_fma_f32 v[140:141], v[4:5], v[76:77], v[140:141] op_sel_hi:[1,0,1]
	v_pk_fma_f32 v[142:143], v[6:7], v[76:77], v[142:143] op_sel_hi:[1,0,1]
	v_pk_fma_f32 v[128:129], v[8:9], v[76:77], v[128:129] op_sel_hi:[1,0,1]
	v_pk_fma_f32 v[132:133], v[10:11], v[76:77], v[132:133] op_sel_hi:[1,0,1]
	v_pk_fma_f32 v[134:135], v[12:13], v[76:77], v[134:135] op_sel_hi:[1,0,1]
	v_pk_fma_f32 v[136:137], v[14:15], v[76:77], v[136:137] op_sel_hi:[1,0,1]
	ds_read_b32 v76, v193 offset:392
	s_waitcnt vmcnt(15)
	v_cvt_scalef32_pk_f32_fp4 v[0:1], v146, 1.0
	v_cvt_scalef32_pk_f32_fp4 v[2:3], v146, 1.0 op_sel:[1,0,0]
	v_cvt_scalef32_pk_f32_fp4 v[4:5], v146, 1.0 op_sel:[0,1,0]
	v_cvt_scalef32_pk_f32_fp4 v[6:7], v146, 1.0 op_sel:[1,1,0]
	v_cvt_scalef32_pk_f32_fp4 v[8:9], v147, 1.0
	v_cvt_scalef32_pk_f32_fp4 v[10:11], v147, 1.0 op_sel:[1,0,0]
	v_cvt_scalef32_pk_f32_fp4 v[12:13], v147, 1.0 op_sel:[0,1,0]
	v_cvt_scalef32_pk_f32_fp4 v[14:15], v147, 1.0 op_sel:[1,1,0]
	v_readlane_b32 s54, v92, 49
	s_lshl_b32 s56, s54, 9
	s_add_u32 s56, s64, s56
	s_addc_u32 s57, s65, 0
	global_load_dwordx2 v[146:147], v227, s[56:57]
	s_waitcnt lgkmcnt(1)
	v_pk_fma_f32 v[130:131], v[0:1], v[194:195], v[130:131] op_sel_hi:[1,0,1]
	v_pk_fma_f32 v[138:139], v[2:3], v[194:195], v[138:139] op_sel_hi:[1,0,1]
	v_pk_fma_f32 v[140:141], v[4:5], v[194:195], v[140:141] op_sel_hi:[1,0,1]
	v_pk_fma_f32 v[142:143], v[6:7], v[194:195], v[142:143] op_sel_hi:[1,0,1]
	v_pk_fma_f32 v[128:129], v[8:9], v[194:195], v[128:129] op_sel_hi:[1,0,1]
	v_pk_fma_f32 v[132:133], v[10:11], v[194:195], v[132:133] op_sel_hi:[1,0,1]
	v_pk_fma_f32 v[134:135], v[12:13], v[194:195], v[134:135] op_sel_hi:[1,0,1]
	v_pk_fma_f32 v[136:137], v[14:15], v[194:195], v[136:137] op_sel_hi:[1,0,1]
	ds_read_b32 v194, v193 offset:396
	s_waitcnt vmcnt(15)
	v_cvt_scalef32_pk_f32_fp4 v[0:1], v148, 1.0
	v_cvt_scalef32_pk_f32_fp4 v[2:3], v148, 1.0 op_sel:[1,0,0]
	v_cvt_scalef32_pk_f32_fp4 v[4:5], v148, 1.0 op_sel:[0,1,0]
	v_cvt_scalef32_pk_f32_fp4 v[6:7], v148, 1.0 op_sel:[1,1,0]
	v_cvt_scalef32_pk_f32_fp4 v[8:9], v149, 1.0
	v_cvt_scalef32_pk_f32_fp4 v[10:11], v149, 1.0 op_sel:[1,0,0]
	v_cvt_scalef32_pk_f32_fp4 v[12:13], v149, 1.0 op_sel:[0,1,0]
	v_cvt_scalef32_pk_f32_fp4 v[14:15], v149, 1.0 op_sel:[1,1,0]
	v_readlane_b32 s54, v92, 50
	s_lshl_b32 s56, s54, 9
	s_add_u32 s56, s64, s56
	s_addc_u32 s57, s65, 0
	global_load_dwordx2 v[148:149], v227, s[56:57]
	s_waitcnt lgkmcnt(1)
	v_pk_fma_f32 v[130:131], v[0:1], v[76:77], v[130:131] op_sel_hi:[1,0,1]
	v_pk_fma_f32 v[138:139], v[2:3], v[76:77], v[138:139] op_sel_hi:[1,0,1]
	v_pk_fma_f32 v[140:141], v[4:5], v[76:77], v[140:141] op_sel_hi:[1,0,1]
	v_pk_fma_f32 v[142:143], v[6:7], v[76:77], v[142:143] op_sel_hi:[1,0,1]
	v_pk_fma_f32 v[128:129], v[8:9], v[76:77], v[128:129] op_sel_hi:[1,0,1]
	v_pk_fma_f32 v[132:133], v[10:11], v[76:77], v[132:133] op_sel_hi:[1,0,1]
	v_pk_fma_f32 v[134:135], v[12:13], v[76:77], v[134:135] op_sel_hi:[1,0,1]
	v_pk_fma_f32 v[136:137], v[14:15], v[76:77], v[136:137] op_sel_hi:[1,0,1]
	ds_read_b32 v76, v193 offset:400
	s_waitcnt vmcnt(15)
	v_cvt_scalef32_pk_f32_fp4 v[0:1], v150, 1.0
	v_cvt_scalef32_pk_f32_fp4 v[2:3], v150, 1.0 op_sel:[1,0,0]
	v_cvt_scalef32_pk_f32_fp4 v[4:5], v150, 1.0 op_sel:[0,1,0]
	v_cvt_scalef32_pk_f32_fp4 v[6:7], v150, 1.0 op_sel:[1,1,0]
	v_cvt_scalef32_pk_f32_fp4 v[8:9], v151, 1.0
	v_cvt_scalef32_pk_f32_fp4 v[10:11], v151, 1.0 op_sel:[1,0,0]
	v_cvt_scalef32_pk_f32_fp4 v[12:13], v151, 1.0 op_sel:[0,1,0]
	v_cvt_scalef32_pk_f32_fp4 v[14:15], v151, 1.0 op_sel:[1,1,0]
	v_readlane_b32 s54, v92, 51
	s_lshl_b32 s56, s54, 9
	s_add_u32 s56, s64, s56
	s_addc_u32 s57, s65, 0
	global_load_dwordx2 v[150:151], v227, s[56:57]
	s_waitcnt lgkmcnt(1)
	v_pk_fma_f32 v[130:131], v[0:1], v[194:195], v[130:131] op_sel_hi:[1,0,1]
	v_pk_fma_f32 v[138:139], v[2:3], v[194:195], v[138:139] op_sel_hi:[1,0,1]
	v_pk_fma_f32 v[140:141], v[4:5], v[194:195], v[140:141] op_sel_hi:[1,0,1]
	v_pk_fma_f32 v[142:143], v[6:7], v[194:195], v[142:143] op_sel_hi:[1,0,1]
	v_pk_fma_f32 v[128:129], v[8:9], v[194:195], v[128:129] op_sel_hi:[1,0,1]
	v_pk_fma_f32 v[132:133], v[10:11], v[194:195], v[132:133] op_sel_hi:[1,0,1]
	v_pk_fma_f32 v[134:135], v[12:13], v[194:195], v[134:135] op_sel_hi:[1,0,1]
	v_pk_fma_f32 v[136:137], v[14:15], v[194:195], v[136:137] op_sel_hi:[1,0,1]
	ds_read_b32 v194, v193 offset:404
	s_waitcnt vmcnt(15)
; __device__ void peer_gather_phase(const Params& P, int l, bool do_store) {
;     ...
;         v8[2 * pr] = *(const uint2*)(V + (size_t)ea * 512);
;         v8[2 * pr + 1] = *(const uint2*)(V + (size_t)eb * 512);
;     ...
; #pragma unroll
;       for (int j = 0; j < 8; ++j) {
;         const float a = __builtin_bit_cast(float, __builtin_amdgcn_readlane(__builtin_bit_cast(int, avec), kb + j));
;         const f32x2 aa = f32x2{a, a};
;         y[0] += aa * __builtin_amdgcn_cvt_scalef32_pk_f32_fp4(v8[j].x, 1.0f, 0); y[1] += aa * __builtin_amdgcn_cvt_scalef32_pk_f32_fp4(v8[j].x, 1.0f, 1);
;         y[2] += aa * __builtin_amdgcn_cvt_scalef32_pk_f32_fp4(v8[j].x, 1.0f, 2); y[3] += aa * __builtin_amdgcn_cvt_scalef32_pk_f32_fp4(v8[j].x, 1.0f, 3);
;         y[4] += aa * __builtin_amdgcn_cvt_scalef32_pk_f32_fp4(v8[j].y, 1.0f, 0); y[5] += aa * __builtin_amdgcn_cvt_scalef32_pk_f32_fp4(v8[j].y, 1.0f, 1);
;         y[6] += aa * __builtin_amdgcn_cvt_scalef32_pk_f32_fp4(v8[j].y, 1.0f, 2); y[7] += aa * __builtin_amdgcn_cvt_scalef32_pk_f32_fp4(v8[j].y, 1.0f, 3);
;       }
	v_cvt_scalef32_pk_f32_fp4 v[0:1], v152, 1.0
	v_cvt_scalef32_pk_f32_fp4 v[2:3], v152, 1.0 op_sel:[1,0,0]
	v_cvt_scalef32_pk_f32_fp4 v[4:5], v152, 1.0 op_sel:[0,1,0]
	v_cvt_scalef32_pk_f32_fp4 v[6:7], v152, 1.0 op_sel:[1,1,0]
	v_cvt_scalef32_pk_f32_fp4 v[8:9], v153, 1.0
	v_cvt_scalef32_pk_f32_fp4 v[10:11], v153, 1.0 op_sel:[1,0,0]
	v_cvt_scalef32_pk_f32_fp4 v[12:13], v153, 1.0 op_sel:[0,1,0]
	v_cvt_scalef32_pk_f32_fp4 v[14:15], v153, 1.0 op_sel:[1,1,0]
	v_readlane_b32 s54, v92, 52
	s_lshl_b32 s56, s54, 9
	s_add_u32 s56, s64, s56
	s_addc_u32 s57, s65, 0
	global_load_dwordx2 v[152:153], v227, s[56:57]
	s_waitcnt lgkmcnt(1)
	v_pk_fma_f32 v[130:131], v[0:1], v[76:77], v[130:131] op_sel_hi:[1,0,1]
	v_pk_fma_f32 v[138:139], v[2:3], v[76:77], v[138:139] op_sel_hi:[1,0,1]
	v_pk_fma_f32 v[140:141], v[4:5], v[76:77], v[140:141] op_sel_hi:[1,0,1]
	v_pk_fma_f32 v[142:143], v[6:7], v[76:77], v[142:143] op_sel_hi:[1,0,1]
	v_pk_fma_f32 v[128:129], v[8:9], v[76:77], v[128:129] op_sel_hi:[1,0,1]
	v_pk_fma_f32 v[132:133], v[10:11], v[76:77], v[132:133] op_sel_hi:[1,0,1]
	v_pk_fma_f32 v[134:135], v[12:13], v[76:77], v[134:135] op_sel_hi:[1,0,1]
	v_pk_fma_f32 v[136:137], v[14:15], v[76:77], v[136:137] op_sel_hi:[1,0,1]
	ds_read_b32 v76, v193 offset:408
	s_waitcnt vmcnt(15)
	v_cvt_scalef32_pk_f32_fp4 v[0:1], v154, 1.0
	v_cvt_scalef32_pk_f32_fp4 v[2:3], v154, 1.0 op_sel:[1,0,0]
	v_cvt_scalef32_pk_f32_fp4 v[4:5], v154, 1.0 op_sel:[0,1,0]
	v_cvt_scalef32_pk_f32_fp4 v[6:7], v154, 1.0 op_sel:[1,1,0]
	v_cvt_scalef32_pk_f32_fp4 v[8:9], v155, 1.0
	v_cvt_scalef32_pk_f32_fp4 v[10:11], v155, 1.0 op_sel:[1,0,0]
	v_cvt_scalef32_pk_f32_fp4 v[12:13], v155, 1.0 op_sel:[0,1,0]
	v_cvt_scalef32_pk_f32_fp4 v[14:15], v155, 1.0 op_sel:[1,1,0]
	v_readlane_b32 s54, v92, 53
	s_lshl_b32 s56, s54, 9
	s_add_u32 s56, s64, s56
	s_addc_u32 s57, s65, 0
	global_load_dwordx2 v[154:155], v227, s[56:57]
	s_waitcnt lgkmcnt(1)
	v_pk_fma_f32 v[130:131], v[0:1], v[194:195], v[130:131] op_sel_hi:[1,0,1]
	v_pk_fma_f32 v[138:139], v[2:3], v[194:195], v[138:139] op_sel_hi:[1,0,1]
	v_pk_fma_f32 v[140:141], v[4:5], v[194:195], v[140:141] op_sel_hi:[1,0,1]
	v_pk_fma_f32 v[142:143], v[6:7], v[194:195], v[142:143] op_sel_hi:[1,0,1]
	v_pk_fma_f32 v[128:129], v[8:9], v[194:195], v[128:129] op_sel_hi:[1,0,1]
	v_pk_fma_f32 v[132:133], v[10:11], v[194:195], v[132:133] op_sel_hi:[1,0,1]
	v_pk_fma_f32 v[134:135], v[12:13], v[194:195], v[134:135] op_sel_hi:[1,0,1]
	v_pk_fma_f32 v[136:137], v[14:15], v[194:195], v[136:137] op_sel_hi:[1,0,1]
	ds_read_b32 v194, v193 offset:412
	s_waitcnt vmcnt(15)
	v_cvt_scalef32_pk_f32_fp4 v[0:1], v156, 1.0
	v_cvt_scalef32_pk_f32_fp4 v[2:3], v156, 1.0 op_sel:[1,0,0]
	v_cvt_scalef32_pk_f32_fp4 v[4:5], v156, 1.0 op_sel:[0,1,0]
	v_cvt_scalef32_pk_f32_fp4 v[6:7], v156, 1.0 op_sel:[1,1,0]
	v_cvt_scalef32_pk_f32_fp4 v[8:9], v157, 1.0
	v_cvt_scalef32_pk_f32_fp4 v[10:11], v157, 1.0 op_sel:[1,0,0]
	v_cvt_scalef32_pk_f32_fp4 v[12:13], v157, 1.0 op_sel:[0,1,0]
	v_cvt_scalef32_pk_f32_fp4 v[14:15], v157, 1.0 op_sel:[1,1,0]
	v_readlane_b32 s54, v92, 54
	s_lshl_b32 s56, s54, 9
	s_add_u32 s56, s64, s56
	s_addc_u32 s57, s65, 0
	global_load_dwordx2 v[156:157], v227, s[56:57]
	s_waitcnt lgkmcnt(1)
	v_pk_fma_f32 v[130:131], v[0:1], v[76:77], v[130:131] op_sel_hi:[1,0,1]
	v_pk_fma_f32 v[138:139], v[2:3], v[76:77], v[138:139] op_sel_hi:[1,0,1]
	v_pk_fma_f32 v[140:141], v[4:5], v[76:77], v[140:141] op_sel_hi:[1,0,1]
	v_pk_fma_f32 v[142:143], v[6:7], v[76:77], v[142:143] op_sel_hi:[1,0,1]
	v_pk_fma_f32 v[128:129], v[8:9], v[76:77], v[128:129] op_sel_hi:[1,0,1]
	v_pk_fma_f32 v[132:133], v[10:11], v[76:77], v[132:133] op_sel_hi:[1,0,1]
	v_pk_fma_f32 v[134:135], v[12:13], v[76:77], v[134:135] op_sel_hi:[1,0,1]
	v_pk_fma_f32 v[136:137], v[14:15], v[76:77], v[136:137] op_sel_hi:[1,0,1]
	ds_read_b32 v76, v193 offset:416
	s_waitcnt vmcnt(15)
	v_cvt_scalef32_pk_f32_fp4 v[0:1], v158, 1.0
	v_cvt_scalef32_pk_f32_fp4 v[2:3], v158, 1.0 op_sel:[1,0,0]
	v_cvt_scalef32_pk_f32_fp4 v[4:5], v158, 1.0 op_sel:[0,1,0]
	v_cvt_scalef32_pk_f32_fp4 v[6:7], v158, 1.0 op_sel:[1,1,0]
	v_cvt_scalef32_pk_f32_fp4 v[8:9], v159, 1.0
	v_cvt_scalef32_pk_f32_fp4 v[10:11], v159, 1.0 op_sel:[1,0,0]
	v_cvt_scalef32_pk_f32_fp4 v[12:13], v159, 1.0 op_sel:[0,1,0]
	v_cvt_scalef32_pk_f32_fp4 v[14:15], v159, 1.0 op_sel:[1,1,0]
	v_readlane_b32 s54, v92, 55
	s_lshl_b32 s56, s54, 9
	s_add_u32 s56, s64, s56
	s_addc_u32 s57, s65, 0
	global_load_dwordx2 v[158:159], v227, s[56:57]
	s_waitcnt lgkmcnt(1)
	v_pk_fma_f32 v[130:131], v[0:1], v[194:195], v[130:131] op_sel_hi:[1,0,1]
	v_pk_fma_f32 v[138:139], v[2:3], v[194:195], v[138:139] op_sel_hi:[1,0,1]
	v_pk_fma_f32 v[140:141], v[4:5], v[194:195], v[140:141] op_sel_hi:[1,0,1]
	v_pk_fma_f32 v[142:143], v[6:7], v[194:195], v[142:143] op_sel_hi:[1,0,1]
	v_pk_fma_f32 v[128:129], v[8:9], v[194:195], v[128:129] op_sel_hi:[1,0,1]
	v_pk_fma_f32 v[132:133], v[10:11], v[194:195], v[132:133] op_sel_hi:[1,0,1]
	v_pk_fma_f32 v[134:135], v[12:13], v[194:195], v[134:135] op_sel_hi:[1,0,1]
	v_pk_fma_f32 v[136:137], v[14:15], v[194:195], v[136:137] op_sel_hi:[1,0,1]
	ds_read_b32 v194, v193 offset:420
	s_waitcnt vmcnt(15)
	v_cvt_scalef32_pk_f32_fp4 v[0:1], v168, 1.0
	v_cvt_scalef32_pk_f32_fp4 v[2:3], v168, 1.0 op_sel:[1,0,0]
	v_cvt_scalef32_pk_f32_fp4 v[4:5], v168, 1.0 op_sel:[0,1,0]
	v_cvt_scalef32_pk_f32_fp4 v[6:7], v168, 1.0 op_sel:[1,1,0]
	v_cvt_scalef32_pk_f32_fp4 v[8:9], v169, 1.0
	v_cvt_scalef32_pk_f32_fp4 v[10:11], v169, 1.0 op_sel:[1,0,0]
	v_cvt_scalef32_pk_f32_fp4 v[12:13], v169, 1.0 op_sel:[0,1,0]
	v_cvt_scalef32_pk_f32_fp4 v[14:15], v169, 1.0 op_sel:[1,1,0]
	v_readlane_b32 s54, v92, 56
	s_lshl_b32 s56, s54, 9
	s_add_u32 s56, s64, s56
	s_addc_u32 s57, s65, 0
	global_load_dwordx2 v[168:169], v227, s[56:57]
	s_waitcnt lgkmcnt(1)
; __device__ void peer_gather_phase(const Params& P, int l, bool do_store) {
;     ...
;         v8[2 * pr] = *(const uint2*)(V + (size_t)ea * 512);
;         v8[2 * pr + 1] = *(const uint2*)(V + (size_t)eb * 512);
;     ...
; #pragma unroll
;       for (int j = 0; j < 8; ++j) {
;         const float a = __builtin_bit_cast(float, __builtin_amdgcn_readlane(__builtin_bit_cast(int, avec), kb + j));
;         const f32x2 aa = f32x2{a, a};
;         y[0] += aa * __builtin_amdgcn_cvt_scalef32_pk_f32_fp4(v8[j].x, 1.0f, 0); y[1] += aa * __builtin_amdgcn_cvt_scalef32_pk_f32_fp4(v8[j].x, 1.0f, 1);
;         y[2] += aa * __builtin_amdgcn_cvt_scalef32_pk_f32_fp4(v8[j].x, 1.0f, 2); y[3] += aa * __builtin_amdgcn_cvt_scalef32_pk_f32_fp4(v8[j].x, 1.0f, 3);
;         y[4] += aa * __builtin_amdgcn_cvt_scalef32_pk_f32_fp4(v8[j].y, 1.0f, 0); y[5] += aa * __builtin_amdgcn_cvt_scalef32_pk_f32_fp4(v8[j].y, 1.0f, 1);
;         y[6] += aa * __builtin_amdgcn_cvt_scalef32_pk_f32_fp4(v8[j].y, 1.0f, 2); y[7] += aa * __builtin_amdgcn_cvt_scalef32_pk_f32_fp4(v8[j].y, 1.0f, 3);
;       }
	v_pk_fma_f32 v[130:131], v[0:1], v[76:77], v[130:131] op_sel_hi:[1,0,1]
	v_pk_fma_f32 v[138:139], v[2:3], v[76:77], v[138:139] op_sel_hi:[1,0,1]
	v_pk_fma_f32 v[140:141], v[4:5], v[76:77], v[140:141] op_sel_hi:[1,0,1]
	v_pk_fma_f32 v[142:143], v[6:7], v[76:77], v[142:143] op_sel_hi:[1,0,1]
	v_pk_fma_f32 v[128:129], v[8:9], v[76:77], v[128:129] op_sel_hi:[1,0,1]
	v_pk_fma_f32 v[132:133], v[10:11], v[76:77], v[132:133] op_sel_hi:[1,0,1]
	v_pk_fma_f32 v[134:135], v[12:13], v[76:77], v[134:135] op_sel_hi:[1,0,1]
	v_pk_fma_f32 v[136:137], v[14:15], v[76:77], v[136:137] op_sel_hi:[1,0,1]
	ds_read_b32 v76, v193 offset:424
	s_waitcnt vmcnt(15)
	v_cvt_scalef32_pk_f32_fp4 v[0:1], v170, 1.0
	v_cvt_scalef32_pk_f32_fp4 v[2:3], v170, 1.0 op_sel:[1,0,0]
	v_cvt_scalef32_pk_f32_fp4 v[4:5], v170, 1.0 op_sel:[0,1,0]
	v_cvt_scalef32_pk_f32_fp4 v[6:7], v170, 1.0 op_sel:[1,1,0]
	v_cvt_scalef32_pk_f32_fp4 v[8:9], v171, 1.0
	v_cvt_scalef32_pk_f32_fp4 v[10:11], v171, 1.0 op_sel:[1,0,0]
	v_cvt_scalef32_pk_f32_fp4 v[12:13], v171, 1.0 op_sel:[0,1,0]
	v_cvt_scalef32_pk_f32_fp4 v[14:15], v171, 1.0 op_sel:[1,1,0]
	v_readlane_b32 s54, v92, 57
	s_lshl_b32 s56, s54, 9
	s_add_u32 s56, s64, s56
	s_addc_u32 s57, s65, 0
	global_load_dwordx2 v[170:171], v227, s[56:57]
	s_waitcnt lgkmcnt(1)
	v_pk_fma_f32 v[130:131], v[0:1], v[194:195], v[130:131] op_sel_hi:[1,0,1]
	v_pk_fma_f32 v[138:139], v[2:3], v[194:195], v[138:139] op_sel_hi:[1,0,1]
	v_pk_fma_f32 v[140:141], v[4:5], v[194:195], v[140:141] op_sel_hi:[1,0,1]
	v_pk_fma_f32 v[142:143], v[6:7], v[194:195], v[142:143] op_sel_hi:[1,0,1]
	v_pk_fma_f32 v[128:129], v[8:9], v[194:195], v[128:129] op_sel_hi:[1,0,1]
	v_pk_fma_f32 v[132:133], v[10:11], v[194:195], v[132:133] op_sel_hi:[1,0,1]
	v_pk_fma_f32 v[134:135], v[12:13], v[194:195], v[134:135] op_sel_hi:[1,0,1]
	v_pk_fma_f32 v[136:137], v[14:15], v[194:195], v[136:137] op_sel_hi:[1,0,1]
	ds_read_b32 v194, v193 offset:428
	s_waitcnt vmcnt(15)
	v_cvt_scalef32_pk_f32_fp4 v[0:1], v172, 1.0
	v_cvt_scalef32_pk_f32_fp4 v[2:3], v172, 1.0 op_sel:[1,0,0]
	v_cvt_scalef32_pk_f32_fp4 v[4:5], v172, 1.0 op_sel:[0,1,0]
	v_cvt_scalef32_pk_f32_fp4 v[6:7], v172, 1.0 op_sel:[1,1,0]
	v_cvt_scalef32_pk_f32_fp4 v[8:9], v173, 1.0
	v_cvt_scalef32_pk_f32_fp4 v[10:11], v173, 1.0 op_sel:[1,0,0]
	v_cvt_scalef32_pk_f32_fp4 v[12:13], v173, 1.0 op_sel:[0,1,0]
	v_cvt_scalef32_pk_f32_fp4 v[14:15], v173, 1.0 op_sel:[1,1,0]
	v_readlane_b32 s54, v92, 58
	s_lshl_b32 s56, s54, 9
	s_add_u32 s56, s64, s56
	s_addc_u32 s57, s65, 0
	global_load_dwordx2 v[172:173], v227, s[56:57]
	s_waitcnt lgkmcnt(1)
	v_pk_fma_f32 v[130:131], v[0:1], v[76:77], v[130:131] op_sel_hi:[1,0,1]
	v_pk_fma_f32 v[138:139], v[2:3], v[76:77], v[138:139] op_sel_hi:[1,0,1]
	v_pk_fma_f32 v[140:141], v[4:5], v[76:77], v[140:141] op_sel_hi:[1,0,1]
	v_pk_fma_f32 v[142:143], v[6:7], v[76:77], v[142:143] op_sel_hi:[1,0,1]
	v_pk_fma_f32 v[128:129], v[8:9], v[76:77], v[128:129] op_sel_hi:[1,0,1]
	v_pk_fma_f32 v[132:133], v[10:11], v[76:77], v[132:133] op_sel_hi:[1,0,1]
	v_pk_fma_f32 v[134:135], v[12:13], v[76:77], v[134:135] op_sel_hi:[1,0,1]
	v_pk_fma_f32 v[136:137], v[14:15], v[76:77], v[136:137] op_sel_hi:[1,0,1]
	ds_read_b32 v76, v193 offset:432
	s_waitcnt vmcnt(15)
	v_cvt_scalef32_pk_f32_fp4 v[0:1], v174, 1.0
	v_cvt_scalef32_pk_f32_fp4 v[2:3], v174, 1.0 op_sel:[1,0,0]
	v_cvt_scalef32_pk_f32_fp4 v[4:5], v174, 1.0 op_sel:[0,1,0]
	v_cvt_scalef32_pk_f32_fp4 v[6:7], v174, 1.0 op_sel:[1,1,0]
	v_cvt_scalef32_pk_f32_fp4 v[8:9], v175, 1.0
	v_cvt_scalef32_pk_f32_fp4 v[10:11], v175, 1.0 op_sel:[1,0,0]
	v_cvt_scalef32_pk_f32_fp4 v[12:13], v175, 1.0 op_sel:[0,1,0]
	v_cvt_scalef32_pk_f32_fp4 v[14:15], v175, 1.0 op_sel:[1,1,0]
	v_readlane_b32 s54, v92, 59
	s_lshl_b32 s56, s54, 9
	s_add_u32 s56, s64, s56
	s_addc_u32 s57, s65, 0
	global_load_dwordx2 v[174:175], v227, s[56:57]
	s_waitcnt lgkmcnt(1)
	v_pk_fma_f32 v[130:131], v[0:1], v[194:195], v[130:131] op_sel_hi:[1,0,1]
	v_pk_fma_f32 v[138:139], v[2:3], v[194:195], v[138:139] op_sel_hi:[1,0,1]
	v_pk_fma_f32 v[140:141], v[4:5], v[194:195], v[140:141] op_sel_hi:[1,0,1]
	v_pk_fma_f32 v[142:143], v[6:7], v[194:195], v[142:143] op_sel_hi:[1,0,1]
	v_pk_fma_f32 v[128:129], v[8:9], v[194:195], v[128:129] op_sel_hi:[1,0,1]
	v_pk_fma_f32 v[132:133], v[10:11], v[194:195], v[132:133] op_sel_hi:[1,0,1]
	v_pk_fma_f32 v[134:135], v[12:13], v[194:195], v[134:135] op_sel_hi:[1,0,1]
	v_pk_fma_f32 v[136:137], v[14:15], v[194:195], v[136:137] op_sel_hi:[1,0,1]
	ds_read_b32 v194, v193 offset:436
	s_waitcnt vmcnt(15)
	v_cvt_scalef32_pk_f32_fp4 v[0:1], v180, 1.0
	v_cvt_scalef32_pk_f32_fp4 v[2:3], v180, 1.0 op_sel:[1,0,0]
	v_cvt_scalef32_pk_f32_fp4 v[4:5], v180, 1.0 op_sel:[0,1,0]
	v_cvt_scalef32_pk_f32_fp4 v[6:7], v180, 1.0 op_sel:[1,1,0]
	v_cvt_scalef32_pk_f32_fp4 v[8:9], v181, 1.0
	v_cvt_scalef32_pk_f32_fp4 v[10:11], v181, 1.0 op_sel:[1,0,0]
	v_cvt_scalef32_pk_f32_fp4 v[12:13], v181, 1.0 op_sel:[0,1,0]
	v_cvt_scalef32_pk_f32_fp4 v[14:15], v181, 1.0 op_sel:[1,1,0]
	v_readlane_b32 s54, v92, 60
	s_lshl_b32 s56, s54, 9
	s_add_u32 s56, s64, s56
	s_addc_u32 s57, s65, 0
	global_load_dwordx2 v[180:181], v227, s[56:57]
	s_waitcnt lgkmcnt(1)
	v_pk_fma_f32 v[130:131], v[0:1], v[76:77], v[130:131] op_sel_hi:[1,0,1]
	v_pk_fma_f32 v[138:139], v[2:3], v[76:77], v[138:139] op_sel_hi:[1,0,1]
	v_pk_fma_f32 v[140:141], v[4:5], v[76:77], v[140:141] op_sel_hi:[1,0,1]
	v_pk_fma_f32 v[142:143], v[6:7], v[76:77], v[142:143] op_sel_hi:[1,0,1]
	v_pk_fma_f32 v[128:129], v[8:9], v[76:77], v[128:129] op_sel_hi:[1,0,1]
	v_pk_fma_f32 v[132:133], v[10:11], v[76:77], v[132:133] op_sel_hi:[1,0,1]
	v_pk_fma_f32 v[134:135], v[12:13], v[76:77], v[134:135] op_sel_hi:[1,0,1]
	v_pk_fma_f32 v[136:137], v[14:15], v[76:77], v[136:137] op_sel_hi:[1,0,1]
	ds_read_b32 v76, v193 offset:440
	s_waitcnt vmcnt(15)
; __device__ void peer_gather_phase(const Params& P, int l, bool do_store) {
;     ...
;         v8[2 * pr] = *(const uint2*)(V + (size_t)ea * 512);
;         v8[2 * pr + 1] = *(const uint2*)(V + (size_t)eb * 512);
;     ...
;       for (int j = 0; j < 8; ++j) {
;         const float a = __builtin_bit_cast(float, __builtin_amdgcn_readlane(__builtin_bit_cast(int, avec), kb + j));
;         const f32x2 aa = f32x2{a, a};
;         y[0] += aa * __builtin_amdgcn_cvt_scalef32_pk_f32_fp4(v8[j].x, 1.0f, 0); y[1] += aa * __builtin_amdgcn_cvt_scalef32_pk_f32_fp4(v8[j].x, 1.0f, 1);
;         y[2] += aa * __builtin_amdgcn_cvt_scalef32_pk_f32_fp4(v8[j].x, 1.0f, 2); y[3] += aa * __builtin_amdgcn_cvt_scalef32_pk_f32_fp4(v8[j].x, 1.0f, 3);
;         y[4] += aa * __builtin_amdgcn_cvt_scalef32_pk_f32_fp4(v8[j].y, 1.0f, 0); y[5] += aa * __builtin_amdgcn_cvt_scalef32_pk_f32_fp4(v8[j].y, 1.0f, 1);
;         y[6] += aa * __builtin_amdgcn_cvt_scalef32_pk_f32_fp4(v8[j].y, 1.0f, 2); y[7] += aa * __builtin_amdgcn_cvt_scalef32_pk_f32_fp4(v8[j].y, 1.0f, 3);
;       }
	v_cvt_scalef32_pk_f32_fp4 v[0:1], v182, 1.0
	v_cvt_scalef32_pk_f32_fp4 v[2:3], v182, 1.0 op_sel:[1,0,0]
	v_cvt_scalef32_pk_f32_fp4 v[4:5], v182, 1.0 op_sel:[0,1,0]
	v_cvt_scalef32_pk_f32_fp4 v[6:7], v182, 1.0 op_sel:[1,1,0]
	v_cvt_scalef32_pk_f32_fp4 v[8:9], v183, 1.0
	v_cvt_scalef32_pk_f32_fp4 v[10:11], v183, 1.0 op_sel:[1,0,0]
	v_cvt_scalef32_pk_f32_fp4 v[12:13], v183, 1.0 op_sel:[0,1,0]
	v_cvt_scalef32_pk_f32_fp4 v[14:15], v183, 1.0 op_sel:[1,1,0]
	v_readlane_b32 s54, v92, 61
	s_lshl_b32 s56, s54, 9
	s_add_u32 s56, s64, s56
	s_addc_u32 s57, s65, 0
	global_load_dwordx2 v[182:183], v227, s[56:57]
	s_waitcnt lgkmcnt(1)
	v_pk_fma_f32 v[130:131], v[0:1], v[194:195], v[130:131] op_sel_hi:[1,0,1]
	v_pk_fma_f32 v[138:139], v[2:3], v[194:195], v[138:139] op_sel_hi:[1,0,1]
	v_pk_fma_f32 v[140:141], v[4:5], v[194:195], v[140:141] op_sel_hi:[1,0,1]
	v_pk_fma_f32 v[142:143], v[6:7], v[194:195], v[142:143] op_sel_hi:[1,0,1]
	v_pk_fma_f32 v[128:129], v[8:9], v[194:195], v[128:129] op_sel_hi:[1,0,1]
	v_pk_fma_f32 v[132:133], v[10:11], v[194:195], v[132:133] op_sel_hi:[1,0,1]
	v_pk_fma_f32 v[134:135], v[12:13], v[194:195], v[134:135] op_sel_hi:[1,0,1]
	v_pk_fma_f32 v[136:137], v[14:15], v[194:195], v[136:137] op_sel_hi:[1,0,1]
	ds_read_b32 v194, v193 offset:444
	s_waitcnt vmcnt(15)
	v_cvt_scalef32_pk_f32_fp4 v[0:1], v184, 1.0
	v_cvt_scalef32_pk_f32_fp4 v[2:3], v184, 1.0 op_sel:[1,0,0]
	v_cvt_scalef32_pk_f32_fp4 v[4:5], v184, 1.0 op_sel:[0,1,0]
	v_cvt_scalef32_pk_f32_fp4 v[6:7], v184, 1.0 op_sel:[1,1,0]
	v_cvt_scalef32_pk_f32_fp4 v[8:9], v185, 1.0
	v_cvt_scalef32_pk_f32_fp4 v[10:11], v185, 1.0 op_sel:[1,0,0]
	v_cvt_scalef32_pk_f32_fp4 v[12:13], v185, 1.0 op_sel:[0,1,0]
	v_cvt_scalef32_pk_f32_fp4 v[14:15], v185, 1.0 op_sel:[1,1,0]
	v_readlane_b32 s54, v92, 62
	s_lshl_b32 s56, s54, 9
	s_add_u32 s56, s64, s56
	s_addc_u32 s57, s65, 0
	global_load_dwordx2 v[184:185], v227, s[56:57]
	s_waitcnt lgkmcnt(1)
	v_pk_fma_f32 v[130:131], v[0:1], v[76:77], v[130:131] op_sel_hi:[1,0,1]
	v_pk_fma_f32 v[138:139], v[2:3], v[76:77], v[138:139] op_sel_hi:[1,0,1]
	v_pk_fma_f32 v[140:141], v[4:5], v[76:77], v[140:141] op_sel_hi:[1,0,1]
	v_pk_fma_f32 v[142:143], v[6:7], v[76:77], v[142:143] op_sel_hi:[1,0,1]
	v_pk_fma_f32 v[128:129], v[8:9], v[76:77], v[128:129] op_sel_hi:[1,0,1]
	v_pk_fma_f32 v[132:133], v[10:11], v[76:77], v[132:133] op_sel_hi:[1,0,1]
	v_pk_fma_f32 v[134:135], v[12:13], v[76:77], v[134:135] op_sel_hi:[1,0,1]
	v_pk_fma_f32 v[136:137], v[14:15], v[76:77], v[136:137] op_sel_hi:[1,0,1]
	ds_read_b32 v76, v193 offset:448
	s_waitcnt vmcnt(15)
	v_cvt_scalef32_pk_f32_fp4 v[0:1], v186, 1.0
	v_cvt_scalef32_pk_f32_fp4 v[2:3], v186, 1.0 op_sel:[1,0,0]
	v_cvt_scalef32_pk_f32_fp4 v[4:5], v186, 1.0 op_sel:[0,1,0]
	v_cvt_scalef32_pk_f32_fp4 v[6:7], v186, 1.0 op_sel:[1,1,0]
	v_cvt_scalef32_pk_f32_fp4 v[8:9], v187, 1.0
	v_cvt_scalef32_pk_f32_fp4 v[10:11], v187, 1.0 op_sel:[1,0,0]
	v_cvt_scalef32_pk_f32_fp4 v[12:13], v187, 1.0 op_sel:[0,1,0]
	v_cvt_scalef32_pk_f32_fp4 v[14:15], v187, 1.0 op_sel:[1,1,0]
	v_readlane_b32 s54, v92, 63
	s_lshl_b32 s56, s54, 9
	s_add_u32 s56, s64, s56
	s_addc_u32 s57, s65, 0
	global_load_dwordx2 v[186:187], v227, s[56:57]
	s_waitcnt lgkmcnt(1)
	v_pk_fma_f32 v[130:131], v[0:1], v[194:195], v[130:131] op_sel_hi:[1,0,1]
	v_pk_fma_f32 v[138:139], v[2:3], v[194:195], v[138:139] op_sel_hi:[1,0,1]
	v_pk_fma_f32 v[140:141], v[4:5], v[194:195], v[140:141] op_sel_hi:[1,0,1]
	v_pk_fma_f32 v[142:143], v[6:7], v[194:195], v[142:143] op_sel_hi:[1,0,1]
	v_pk_fma_f32 v[128:129], v[8:9], v[194:195], v[128:129] op_sel_hi:[1,0,1]
	v_pk_fma_f32 v[132:133], v[10:11], v[194:195], v[132:133] op_sel_hi:[1,0,1]
	v_pk_fma_f32 v[134:135], v[12:13], v[194:195], v[134:135] op_sel_hi:[1,0,1]
	v_pk_fma_f32 v[136:137], v[14:15], v[194:195], v[136:137] op_sel_hi:[1,0,1]
	ds_read_b32 v194, v193 offset:452
	s_waitcnt vmcnt(15)
	v_cvt_scalef32_pk_f32_fp4 v[0:1], v144, 1.0
	v_cvt_scalef32_pk_f32_fp4 v[2:3], v144, 1.0 op_sel:[1,0,0]
	v_cvt_scalef32_pk_f32_fp4 v[4:5], v144, 1.0 op_sel:[0,1,0]
	v_cvt_scalef32_pk_f32_fp4 v[6:7], v144, 1.0 op_sel:[1,1,0]
	v_cvt_scalef32_pk_f32_fp4 v[8:9], v145, 1.0
	v_cvt_scalef32_pk_f32_fp4 v[10:11], v145, 1.0 op_sel:[1,0,0]
	v_cvt_scalef32_pk_f32_fp4 v[12:13], v145, 1.0 op_sel:[0,1,0]
	v_cvt_scalef32_pk_f32_fp4 v[14:15], v145, 1.0 op_sel:[1,1,0]
	v_readlane_b32 s54, v90, 0
	s_lshl_b32 s56, s54, 9
	s_add_u32 s56, s64, s56
	s_addc_u32 s57, s65, 0
	global_load_dwordx2 v[144:145], v227, s[56:57]
	s_waitcnt lgkmcnt(1)
	v_pk_fma_f32 v[130:131], v[0:1], v[76:77], v[130:131] op_sel_hi:[1,0,1]
	v_pk_fma_f32 v[138:139], v[2:3], v[76:77], v[138:139] op_sel_hi:[1,0,1]
	v_pk_fma_f32 v[140:141], v[4:5], v[76:77], v[140:141] op_sel_hi:[1,0,1]
	v_pk_fma_f32 v[142:143], v[6:7], v[76:77], v[142:143] op_sel_hi:[1,0,1]
	v_pk_fma_f32 v[128:129], v[8:9], v[76:77], v[128:129] op_sel_hi:[1,0,1]
	v_pk_fma_f32 v[132:133], v[10:11], v[76:77], v[132:133] op_sel_hi:[1,0,1]
	v_pk_fma_f32 v[134:135], v[12:13], v[76:77], v[134:135] op_sel_hi:[1,0,1]
	v_pk_fma_f32 v[136:137], v[14:15], v[76:77], v[136:137] op_sel_hi:[1,0,1]
	ds_read_b32 v76, v193 offset:456
	s_waitcnt vmcnt(15)
	v_cvt_scalef32_pk_f32_fp4 v[0:1], v146, 1.0
	v_cvt_scalef32_pk_f32_fp4 v[2:3], v146, 1.0 op_sel:[1,0,0]
	v_cvt_scalef32_pk_f32_fp4 v[4:5], v146, 1.0 op_sel:[0,1,0]
	v_cvt_scalef32_pk_f32_fp4 v[6:7], v146, 1.0 op_sel:[1,1,0]
	v_cvt_scalef32_pk_f32_fp4 v[8:9], v147, 1.0
	v_cvt_scalef32_pk_f32_fp4 v[10:11], v147, 1.0 op_sel:[1,0,0]
	v_cvt_scalef32_pk_f32_fp4 v[12:13], v147, 1.0 op_sel:[0,1,0]
	v_cvt_scalef32_pk_f32_fp4 v[14:15], v147, 1.0 op_sel:[1,1,0]
	v_readlane_b32 s54, v90, 1
	s_lshl_b32 s56, s54, 9
	s_add_u32 s56, s64, s56
	s_addc_u32 s57, s65, 0
	global_load_dwordx2 v[146:147], v227, s[56:57]
	s_waitcnt lgkmcnt(1)
; __device__ void peer_gather_phase(const Params& P, int l, bool do_store) {
;     ...
;         v8[2 * pr] = *(const uint2*)(V + (size_t)ea * 512);
;         v8[2 * pr + 1] = *(const uint2*)(V + (size_t)eb * 512);
;     ...
;       for (int j = 0; j < 8; ++j) {
;         const float a = __builtin_bit_cast(float, __builtin_amdgcn_readlane(__builtin_bit_cast(int, avec), kb + j));
;         const f32x2 aa = f32x2{a, a};
;         y[0] += aa * __builtin_amdgcn_cvt_scalef32_pk_f32_fp4(v8[j].x, 1.0f, 0); y[1] += aa * __builtin_amdgcn_cvt_scalef32_pk_f32_fp4(v8[j].x, 1.0f, 1);
;         y[2] += aa * __builtin_amdgcn_cvt_scalef32_pk_f32_fp4(v8[j].x, 1.0f, 2); y[3] += aa * __builtin_amdgcn_cvt_scalef32_pk_f32_fp4(v8[j].x, 1.0f, 3);
;         y[4] += aa * __builtin_amdgcn_cvt_scalef32_pk_f32_fp4(v8[j].y, 1.0f, 0); y[5] += aa * __builtin_amdgcn_cvt_scalef32_pk_f32_fp4(v8[j].y, 1.0f, 1);
;         y[6] += aa * __builtin_amdgcn_cvt_scalef32_pk_f32_fp4(v8[j].y, 1.0f, 2); y[7] += aa * __builtin_amdgcn_cvt_scalef32_pk_f32_fp4(v8[j].y, 1.0f, 3);
;       }
	v_pk_fma_f32 v[130:131], v[0:1], v[194:195], v[130:131] op_sel_hi:[1,0,1]
	v_pk_fma_f32 v[138:139], v[2:3], v[194:195], v[138:139] op_sel_hi:[1,0,1]
	v_pk_fma_f32 v[140:141], v[4:5], v[194:195], v[140:141] op_sel_hi:[1,0,1]
	v_pk_fma_f32 v[142:143], v[6:7], v[194:195], v[142:143] op_sel_hi:[1,0,1]
	v_pk_fma_f32 v[128:129], v[8:9], v[194:195], v[128:129] op_sel_hi:[1,0,1]
	v_pk_fma_f32 v[132:133], v[10:11], v[194:195], v[132:133] op_sel_hi:[1,0,1]
	v_pk_fma_f32 v[134:135], v[12:13], v[194:195], v[134:135] op_sel_hi:[1,0,1]
	v_pk_fma_f32 v[136:137], v[14:15], v[194:195], v[136:137] op_sel_hi:[1,0,1]
	ds_read_b32 v194, v193 offset:460
	s_waitcnt vmcnt(15)
	v_cvt_scalef32_pk_f32_fp4 v[0:1], v148, 1.0
	v_cvt_scalef32_pk_f32_fp4 v[2:3], v148, 1.0 op_sel:[1,0,0]
	v_cvt_scalef32_pk_f32_fp4 v[4:5], v148, 1.0 op_sel:[0,1,0]
	v_cvt_scalef32_pk_f32_fp4 v[6:7], v148, 1.0 op_sel:[1,1,0]
	v_cvt_scalef32_pk_f32_fp4 v[8:9], v149, 1.0
	v_cvt_scalef32_pk_f32_fp4 v[10:11], v149, 1.0 op_sel:[1,0,0]
	v_cvt_scalef32_pk_f32_fp4 v[12:13], v149, 1.0 op_sel:[0,1,0]
	v_cvt_scalef32_pk_f32_fp4 v[14:15], v149, 1.0 op_sel:[1,1,0]
	v_readlane_b32 s54, v90, 2
	s_lshl_b32 s56, s54, 9
	s_add_u32 s56, s64, s56
	s_addc_u32 s57, s65, 0
	global_load_dwordx2 v[148:149], v227, s[56:57]
	s_waitcnt lgkmcnt(1)
	v_pk_fma_f32 v[130:131], v[0:1], v[76:77], v[130:131] op_sel_hi:[1,0,1]
	v_pk_fma_f32 v[138:139], v[2:3], v[76:77], v[138:139] op_sel_hi:[1,0,1]
	v_pk_fma_f32 v[140:141], v[4:5], v[76:77], v[140:141] op_sel_hi:[1,0,1]
	v_pk_fma_f32 v[142:143], v[6:7], v[76:77], v[142:143] op_sel_hi:[1,0,1]
	v_pk_fma_f32 v[128:129], v[8:9], v[76:77], v[128:129] op_sel_hi:[1,0,1]
	v_pk_fma_f32 v[132:133], v[10:11], v[76:77], v[132:133] op_sel_hi:[1,0,1]
	v_pk_fma_f32 v[134:135], v[12:13], v[76:77], v[134:135] op_sel_hi:[1,0,1]
	v_pk_fma_f32 v[136:137], v[14:15], v[76:77], v[136:137] op_sel_hi:[1,0,1]
	ds_read_b32 v76, v193 offset:464
	s_waitcnt vmcnt(15)
	v_cvt_scalef32_pk_f32_fp4 v[0:1], v150, 1.0
	v_cvt_scalef32_pk_f32_fp4 v[2:3], v150, 1.0 op_sel:[1,0,0]
	v_cvt_scalef32_pk_f32_fp4 v[4:5], v150, 1.0 op_sel:[0,1,0]
	v_cvt_scalef32_pk_f32_fp4 v[6:7], v150, 1.0 op_sel:[1,1,0]
	v_cvt_scalef32_pk_f32_fp4 v[8:9], v151, 1.0
	v_cvt_scalef32_pk_f32_fp4 v[10:11], v151, 1.0 op_sel:[1,0,0]
	v_cvt_scalef32_pk_f32_fp4 v[12:13], v151, 1.0 op_sel:[0,1,0]
	v_cvt_scalef32_pk_f32_fp4 v[14:15], v151, 1.0 op_sel:[1,1,0]
	v_readlane_b32 s54, v90, 3
	s_lshl_b32 s56, s54, 9
	s_add_u32 s56, s64, s56
	s_addc_u32 s57, s65, 0
	global_load_dwordx2 v[150:151], v227, s[56:57]
	s_waitcnt lgkmcnt(1)
	v_pk_fma_f32 v[130:131], v[0:1], v[194:195], v[130:131] op_sel_hi:[1,0,1]
	v_pk_fma_f32 v[138:139], v[2:3], v[194:195], v[138:139] op_sel_hi:[1,0,1]
	v_pk_fma_f32 v[140:141], v[4:5], v[194:195], v[140:141] op_sel_hi:[1,0,1]
	v_pk_fma_f32 v[142:143], v[6:7], v[194:195], v[142:143] op_sel_hi:[1,0,1]
	v_pk_fma_f32 v[128:129], v[8:9], v[194:195], v[128:129] op_sel_hi:[1,0,1]
	v_pk_fma_f32 v[132:133], v[10:11], v[194:195], v[132:133] op_sel_hi:[1,0,1]
	v_pk_fma_f32 v[134:135], v[12:13], v[194:195], v[134:135] op_sel_hi:[1,0,1]
	v_pk_fma_f32 v[136:137], v[14:15], v[194:195], v[136:137] op_sel_hi:[1,0,1]
	ds_read_b32 v194, v193 offset:468
	s_waitcnt vmcnt(15)
	v_cvt_scalef32_pk_f32_fp4 v[0:1], v152, 1.0
	v_cvt_scalef32_pk_f32_fp4 v[2:3], v152, 1.0 op_sel:[1,0,0]
	v_cvt_scalef32_pk_f32_fp4 v[4:5], v152, 1.0 op_sel:[0,1,0]
	v_cvt_scalef32_pk_f32_fp4 v[6:7], v152, 1.0 op_sel:[1,1,0]
	v_cvt_scalef32_pk_f32_fp4 v[8:9], v153, 1.0
	v_cvt_scalef32_pk_f32_fp4 v[10:11], v153, 1.0 op_sel:[1,0,0]
	v_cvt_scalef32_pk_f32_fp4 v[12:13], v153, 1.0 op_sel:[0,1,0]
	v_cvt_scalef32_pk_f32_fp4 v[14:15], v153, 1.0 op_sel:[1,1,0]
	v_readlane_b32 s54, v90, 4
	s_lshl_b32 s56, s54, 9
	s_add_u32 s56, s64, s56
	s_addc_u32 s57, s65, 0
	global_load_dwordx2 v[152:153], v227, s[56:57]
	s_waitcnt lgkmcnt(1)
	v_pk_fma_f32 v[130:131], v[0:1], v[76:77], v[130:131] op_sel_hi:[1,0,1]
	v_pk_fma_f32 v[138:139], v[2:3], v[76:77], v[138:139] op_sel_hi:[1,0,1]
	v_pk_fma_f32 v[140:141], v[4:5], v[76:77], v[140:141] op_sel_hi:[1,0,1]
	v_pk_fma_f32 v[142:143], v[6:7], v[76:77], v[142:143] op_sel_hi:[1,0,1]
	v_pk_fma_f32 v[128:129], v[8:9], v[76:77], v[128:129] op_sel_hi:[1,0,1]
	v_pk_fma_f32 v[132:133], v[10:11], v[76:77], v[132:133] op_sel_hi:[1,0,1]
	v_pk_fma_f32 v[134:135], v[12:13], v[76:77], v[134:135] op_sel_hi:[1,0,1]
	v_pk_fma_f32 v[136:137], v[14:15], v[76:77], v[136:137] op_sel_hi:[1,0,1]
	ds_read_b32 v76, v193 offset:472
	s_waitcnt vmcnt(15)
	v_cvt_scalef32_pk_f32_fp4 v[0:1], v154, 1.0
	v_cvt_scalef32_pk_f32_fp4 v[2:3], v154, 1.0 op_sel:[1,0,0]
	v_cvt_scalef32_pk_f32_fp4 v[4:5], v154, 1.0 op_sel:[0,1,0]
	v_cvt_scalef32_pk_f32_fp4 v[6:7], v154, 1.0 op_sel:[1,1,0]
	v_cvt_scalef32_pk_f32_fp4 v[8:9], v155, 1.0
	v_cvt_scalef32_pk_f32_fp4 v[10:11], v155, 1.0 op_sel:[1,0,0]
	v_cvt_scalef32_pk_f32_fp4 v[12:13], v155, 1.0 op_sel:[0,1,0]
	v_cvt_scalef32_pk_f32_fp4 v[14:15], v155, 1.0 op_sel:[1,1,0]
	v_readlane_b32 s54, v90, 5
	s_lshl_b32 s56, s54, 9
	s_add_u32 s56, s64, s56
	s_addc_u32 s57, s65, 0
	global_load_dwordx2 v[154:155], v227, s[56:57]
	s_waitcnt lgkmcnt(1)
	v_pk_fma_f32 v[130:131], v[0:1], v[194:195], v[130:131] op_sel_hi:[1,0,1]
	v_pk_fma_f32 v[138:139], v[2:3], v[194:195], v[138:139] op_sel_hi:[1,0,1]
	v_pk_fma_f32 v[140:141], v[4:5], v[194:195], v[140:141] op_sel_hi:[1,0,1]
	v_pk_fma_f32 v[142:143], v[6:7], v[194:195], v[142:143] op_sel_hi:[1,0,1]
	v_pk_fma_f32 v[128:129], v[8:9], v[194:195], v[128:129] op_sel_hi:[1,0,1]
	v_pk_fma_f32 v[132:133], v[10:11], v[194:195], v[132:133] op_sel_hi:[1,0,1]
	v_pk_fma_f32 v[134:135], v[12:13], v[194:195], v[134:135] op_sel_hi:[1,0,1]
	v_pk_fma_f32 v[136:137], v[14:15], v[194:195], v[136:137] op_sel_hi:[1,0,1]
	ds_read_b32 v194, v193 offset:476
	s_waitcnt vmcnt(15)
; __device__ void peer_gather_phase(const Params& P, int l, bool do_store) {
;     ...
;         v8[2 * pr] = *(const uint2*)(V + (size_t)ea * 512);
;         v8[2 * pr + 1] = *(const uint2*)(V + (size_t)eb * 512);
;     ...
;       for (int j = 0; j < 8; ++j) {
;         const float a = __builtin_bit_cast(float, __builtin_amdgcn_readlane(__builtin_bit_cast(int, avec), kb + j));
;         const f32x2 aa = f32x2{a, a};
;         y[0] += aa * __builtin_amdgcn_cvt_scalef32_pk_f32_fp4(v8[j].x, 1.0f, 0); y[1] += aa * __builtin_amdgcn_cvt_scalef32_pk_f32_fp4(v8[j].x, 1.0f, 1);
;         y[2] += aa * __builtin_amdgcn_cvt_scalef32_pk_f32_fp4(v8[j].x, 1.0f, 2); y[3] += aa * __builtin_amdgcn_cvt_scalef32_pk_f32_fp4(v8[j].x, 1.0f, 3);
;         y[4] += aa * __builtin_amdgcn_cvt_scalef32_pk_f32_fp4(v8[j].y, 1.0f, 0); y[5] += aa * __builtin_amdgcn_cvt_scalef32_pk_f32_fp4(v8[j].y, 1.0f, 1);
;         y[6] += aa * __builtin_amdgcn_cvt_scalef32_pk_f32_fp4(v8[j].y, 1.0f, 2); y[7] += aa * __builtin_amdgcn_cvt_scalef32_pk_f32_fp4(v8[j].y, 1.0f, 3);
;       }
	v_cvt_scalef32_pk_f32_fp4 v[0:1], v156, 1.0
	v_cvt_scalef32_pk_f32_fp4 v[2:3], v156, 1.0 op_sel:[1,0,0]
	v_cvt_scalef32_pk_f32_fp4 v[4:5], v156, 1.0 op_sel:[0,1,0]
	v_cvt_scalef32_pk_f32_fp4 v[6:7], v156, 1.0 op_sel:[1,1,0]
	v_cvt_scalef32_pk_f32_fp4 v[8:9], v157, 1.0
	v_cvt_scalef32_pk_f32_fp4 v[10:11], v157, 1.0 op_sel:[1,0,0]
	v_cvt_scalef32_pk_f32_fp4 v[12:13], v157, 1.0 op_sel:[0,1,0]
	v_cvt_scalef32_pk_f32_fp4 v[14:15], v157, 1.0 op_sel:[1,1,0]
	v_readlane_b32 s54, v90, 6
	s_lshl_b32 s56, s54, 9
	s_add_u32 s56, s64, s56
	s_addc_u32 s57, s65, 0
	global_load_dwordx2 v[156:157], v227, s[56:57]
	s_waitcnt lgkmcnt(1)
	v_pk_fma_f32 v[130:131], v[0:1], v[76:77], v[130:131] op_sel_hi:[1,0,1]
	v_pk_fma_f32 v[138:139], v[2:3], v[76:77], v[138:139] op_sel_hi:[1,0,1]
	v_pk_fma_f32 v[140:141], v[4:5], v[76:77], v[140:141] op_sel_hi:[1,0,1]
	v_pk_fma_f32 v[142:143], v[6:7], v[76:77], v[142:143] op_sel_hi:[1,0,1]
	v_pk_fma_f32 v[128:129], v[8:9], v[76:77], v[128:129] op_sel_hi:[1,0,1]
	v_pk_fma_f32 v[132:133], v[10:11], v[76:77], v[132:133] op_sel_hi:[1,0,1]
	v_pk_fma_f32 v[134:135], v[12:13], v[76:77], v[134:135] op_sel_hi:[1,0,1]
	v_pk_fma_f32 v[136:137], v[14:15], v[76:77], v[136:137] op_sel_hi:[1,0,1]
	ds_read_b32 v76, v193 offset:480
	s_waitcnt vmcnt(15)
	v_cvt_scalef32_pk_f32_fp4 v[0:1], v158, 1.0
	v_cvt_scalef32_pk_f32_fp4 v[2:3], v158, 1.0 op_sel:[1,0,0]
	v_cvt_scalef32_pk_f32_fp4 v[4:5], v158, 1.0 op_sel:[0,1,0]
	v_cvt_scalef32_pk_f32_fp4 v[6:7], v158, 1.0 op_sel:[1,1,0]
	v_cvt_scalef32_pk_f32_fp4 v[8:9], v159, 1.0
	v_cvt_scalef32_pk_f32_fp4 v[10:11], v159, 1.0 op_sel:[1,0,0]
	v_cvt_scalef32_pk_f32_fp4 v[12:13], v159, 1.0 op_sel:[0,1,0]
	v_cvt_scalef32_pk_f32_fp4 v[14:15], v159, 1.0 op_sel:[1,1,0]
	v_readlane_b32 s54, v90, 7
	s_lshl_b32 s56, s54, 9
	s_add_u32 s56, s64, s56
	s_addc_u32 s57, s65, 0
	global_load_dwordx2 v[158:159], v227, s[56:57]
	s_waitcnt lgkmcnt(1)
	v_pk_fma_f32 v[130:131], v[0:1], v[194:195], v[130:131] op_sel_hi:[1,0,1]
	v_pk_fma_f32 v[138:139], v[2:3], v[194:195], v[138:139] op_sel_hi:[1,0,1]
	v_pk_fma_f32 v[140:141], v[4:5], v[194:195], v[140:141] op_sel_hi:[1,0,1]
	v_pk_fma_f32 v[142:143], v[6:7], v[194:195], v[142:143] op_sel_hi:[1,0,1]
	v_pk_fma_f32 v[128:129], v[8:9], v[194:195], v[128:129] op_sel_hi:[1,0,1]
	v_pk_fma_f32 v[132:133], v[10:11], v[194:195], v[132:133] op_sel_hi:[1,0,1]
	v_pk_fma_f32 v[134:135], v[12:13], v[194:195], v[134:135] op_sel_hi:[1,0,1]
	v_pk_fma_f32 v[136:137], v[14:15], v[194:195], v[136:137] op_sel_hi:[1,0,1]
	ds_read_b32 v194, v193 offset:484
	s_waitcnt vmcnt(15)
	v_cvt_scalef32_pk_f32_fp4 v[0:1], v168, 1.0
	v_cvt_scalef32_pk_f32_fp4 v[2:3], v168, 1.0 op_sel:[1,0,0]
	v_cvt_scalef32_pk_f32_fp4 v[4:5], v168, 1.0 op_sel:[0,1,0]
	v_cvt_scalef32_pk_f32_fp4 v[6:7], v168, 1.0 op_sel:[1,1,0]
	v_cvt_scalef32_pk_f32_fp4 v[8:9], v169, 1.0
	v_cvt_scalef32_pk_f32_fp4 v[10:11], v169, 1.0 op_sel:[1,0,0]
	v_cvt_scalef32_pk_f32_fp4 v[12:13], v169, 1.0 op_sel:[0,1,0]
	v_cvt_scalef32_pk_f32_fp4 v[14:15], v169, 1.0 op_sel:[1,1,0]
	v_readlane_b32 s54, v90, 8
	s_lshl_b32 s56, s54, 9
	s_add_u32 s56, s64, s56
	s_addc_u32 s57, s65, 0
	global_load_dwordx2 v[168:169], v227, s[56:57]
	s_waitcnt lgkmcnt(1)
	v_pk_fma_f32 v[130:131], v[0:1], v[76:77], v[130:131] op_sel_hi:[1,0,1]
	v_pk_fma_f32 v[138:139], v[2:3], v[76:77], v[138:139] op_sel_hi:[1,0,1]
	v_pk_fma_f32 v[140:141], v[4:5], v[76:77], v[140:141] op_sel_hi:[1,0,1]
	v_pk_fma_f32 v[142:143], v[6:7], v[76:77], v[142:143] op_sel_hi:[1,0,1]
	v_pk_fma_f32 v[128:129], v[8:9], v[76:77], v[128:129] op_sel_hi:[1,0,1]
	v_pk_fma_f32 v[132:133], v[10:11], v[76:77], v[132:133] op_sel_hi:[1,0,1]
	v_pk_fma_f32 v[134:135], v[12:13], v[76:77], v[134:135] op_sel_hi:[1,0,1]
	v_pk_fma_f32 v[136:137], v[14:15], v[76:77], v[136:137] op_sel_hi:[1,0,1]
	ds_read_b32 v76, v193 offset:488
	s_waitcnt vmcnt(15)
	v_cvt_scalef32_pk_f32_fp4 v[0:1], v170, 1.0
	v_cvt_scalef32_pk_f32_fp4 v[2:3], v170, 1.0 op_sel:[1,0,0]
	v_cvt_scalef32_pk_f32_fp4 v[4:5], v170, 1.0 op_sel:[0,1,0]
	v_cvt_scalef32_pk_f32_fp4 v[6:7], v170, 1.0 op_sel:[1,1,0]
	v_cvt_scalef32_pk_f32_fp4 v[8:9], v171, 1.0
	v_cvt_scalef32_pk_f32_fp4 v[10:11], v171, 1.0 op_sel:[1,0,0]
	v_cvt_scalef32_pk_f32_fp4 v[12:13], v171, 1.0 op_sel:[0,1,0]
	v_cvt_scalef32_pk_f32_fp4 v[14:15], v171, 1.0 op_sel:[1,1,0]
	v_readlane_b32 s54, v90, 9
	s_lshl_b32 s56, s54, 9
	s_add_u32 s56, s64, s56
	s_addc_u32 s57, s65, 0
	global_load_dwordx2 v[170:171], v227, s[56:57]
	s_waitcnt lgkmcnt(1)
	v_pk_fma_f32 v[130:131], v[0:1], v[194:195], v[130:131] op_sel_hi:[1,0,1]
	v_pk_fma_f32 v[138:139], v[2:3], v[194:195], v[138:139] op_sel_hi:[1,0,1]
	v_pk_fma_f32 v[140:141], v[4:5], v[194:195], v[140:141] op_sel_hi:[1,0,1]
	v_pk_fma_f32 v[142:143], v[6:7], v[194:195], v[142:143] op_sel_hi:[1,0,1]
	v_pk_fma_f32 v[128:129], v[8:9], v[194:195], v[128:129] op_sel_hi:[1,0,1]
	v_pk_fma_f32 v[132:133], v[10:11], v[194:195], v[132:133] op_sel_hi:[1,0,1]
	v_pk_fma_f32 v[134:135], v[12:13], v[194:195], v[134:135] op_sel_hi:[1,0,1]
	v_pk_fma_f32 v[136:137], v[14:15], v[194:195], v[136:137] op_sel_hi:[1,0,1]
	ds_read_b32 v194, v193 offset:492
	s_waitcnt vmcnt(15)
	v_cvt_scalef32_pk_f32_fp4 v[0:1], v172, 1.0
	v_cvt_scalef32_pk_f32_fp4 v[2:3], v172, 1.0 op_sel:[1,0,0]
	v_cvt_scalef32_pk_f32_fp4 v[4:5], v172, 1.0 op_sel:[0,1,0]
	v_cvt_scalef32_pk_f32_fp4 v[6:7], v172, 1.0 op_sel:[1,1,0]
	v_cvt_scalef32_pk_f32_fp4 v[8:9], v173, 1.0
	v_cvt_scalef32_pk_f32_fp4 v[10:11], v173, 1.0 op_sel:[1,0,0]
	v_cvt_scalef32_pk_f32_fp4 v[12:13], v173, 1.0 op_sel:[0,1,0]
	v_cvt_scalef32_pk_f32_fp4 v[14:15], v173, 1.0 op_sel:[1,1,0]
	v_readlane_b32 s54, v90, 10
	s_lshl_b32 s56, s54, 9
	s_add_u32 s56, s64, s56
	s_addc_u32 s57, s65, 0
	global_load_dwordx2 v[172:173], v227, s[56:57]
	s_waitcnt lgkmcnt(1)
; __device__ void peer_gather_phase(const Params& P, int l, bool do_store) {
;     ...
;         v8[2 * pr] = *(const uint2*)(V + (size_t)ea * 512);
;         v8[2 * pr + 1] = *(const uint2*)(V + (size_t)eb * 512);
;     ...
;       for (int j = 0; j < 8; ++j) {
;         const float a = __builtin_bit_cast(float, __builtin_amdgcn_readlane(__builtin_bit_cast(int, avec), kb + j));
;         const f32x2 aa = f32x2{a, a};
;         y[0] += aa * __builtin_amdgcn_cvt_scalef32_pk_f32_fp4(v8[j].x, 1.0f, 0); y[1] += aa * __builtin_amdgcn_cvt_scalef32_pk_f32_fp4(v8[j].x, 1.0f, 1);
;         y[2] += aa * __builtin_amdgcn_cvt_scalef32_pk_f32_fp4(v8[j].x, 1.0f, 2); y[3] += aa * __builtin_amdgcn_cvt_scalef32_pk_f32_fp4(v8[j].x, 1.0f, 3);
;         y[4] += aa * __builtin_amdgcn_cvt_scalef32_pk_f32_fp4(v8[j].y, 1.0f, 0); y[5] += aa * __builtin_amdgcn_cvt_scalef32_pk_f32_fp4(v8[j].y, 1.0f, 1);
;         y[6] += aa * __builtin_amdgcn_cvt_scalef32_pk_f32_fp4(v8[j].y, 1.0f, 2); y[7] += aa * __builtin_amdgcn_cvt_scalef32_pk_f32_fp4(v8[j].y, 1.0f, 3);
;       }
	v_pk_fma_f32 v[130:131], v[0:1], v[76:77], v[130:131] op_sel_hi:[1,0,1]
	v_pk_fma_f32 v[138:139], v[2:3], v[76:77], v[138:139] op_sel_hi:[1,0,1]
	v_pk_fma_f32 v[140:141], v[4:5], v[76:77], v[140:141] op_sel_hi:[1,0,1]
	v_pk_fma_f32 v[142:143], v[6:7], v[76:77], v[142:143] op_sel_hi:[1,0,1]
	v_pk_fma_f32 v[128:129], v[8:9], v[76:77], v[128:129] op_sel_hi:[1,0,1]
	v_pk_fma_f32 v[132:133], v[10:11], v[76:77], v[132:133] op_sel_hi:[1,0,1]
	v_pk_fma_f32 v[134:135], v[12:13], v[76:77], v[134:135] op_sel_hi:[1,0,1]
	v_pk_fma_f32 v[136:137], v[14:15], v[76:77], v[136:137] op_sel_hi:[1,0,1]
	ds_read_b32 v76, v193 offset:496
	s_waitcnt vmcnt(15)
	v_cvt_scalef32_pk_f32_fp4 v[0:1], v174, 1.0
	v_cvt_scalef32_pk_f32_fp4 v[2:3], v174, 1.0 op_sel:[1,0,0]
	v_cvt_scalef32_pk_f32_fp4 v[4:5], v174, 1.0 op_sel:[0,1,0]
	v_cvt_scalef32_pk_f32_fp4 v[6:7], v174, 1.0 op_sel:[1,1,0]
	v_cvt_scalef32_pk_f32_fp4 v[8:9], v175, 1.0
	v_cvt_scalef32_pk_f32_fp4 v[10:11], v175, 1.0 op_sel:[1,0,0]
	v_cvt_scalef32_pk_f32_fp4 v[12:13], v175, 1.0 op_sel:[0,1,0]
	v_cvt_scalef32_pk_f32_fp4 v[14:15], v175, 1.0 op_sel:[1,1,0]
	v_readlane_b32 s54, v90, 11
	s_lshl_b32 s56, s54, 9
	s_add_u32 s56, s64, s56
	s_addc_u32 s57, s65, 0
	global_load_dwordx2 v[174:175], v227, s[56:57]
	s_waitcnt lgkmcnt(1)
	v_pk_fma_f32 v[130:131], v[0:1], v[194:195], v[130:131] op_sel_hi:[1,0,1]
	v_pk_fma_f32 v[138:139], v[2:3], v[194:195], v[138:139] op_sel_hi:[1,0,1]
	v_pk_fma_f32 v[140:141], v[4:5], v[194:195], v[140:141] op_sel_hi:[1,0,1]
	v_pk_fma_f32 v[142:143], v[6:7], v[194:195], v[142:143] op_sel_hi:[1,0,1]
	v_pk_fma_f32 v[128:129], v[8:9], v[194:195], v[128:129] op_sel_hi:[1,0,1]
	v_pk_fma_f32 v[132:133], v[10:11], v[194:195], v[132:133] op_sel_hi:[1,0,1]
	v_pk_fma_f32 v[134:135], v[12:13], v[194:195], v[134:135] op_sel_hi:[1,0,1]
	v_pk_fma_f32 v[136:137], v[14:15], v[194:195], v[136:137] op_sel_hi:[1,0,1]
	ds_read_b32 v194, v193 offset:500
	s_waitcnt vmcnt(15)
	v_cvt_scalef32_pk_f32_fp4 v[0:1], v180, 1.0
	v_cvt_scalef32_pk_f32_fp4 v[2:3], v180, 1.0 op_sel:[1,0,0]
	v_cvt_scalef32_pk_f32_fp4 v[4:5], v180, 1.0 op_sel:[0,1,0]
	v_cvt_scalef32_pk_f32_fp4 v[6:7], v180, 1.0 op_sel:[1,1,0]
	v_cvt_scalef32_pk_f32_fp4 v[8:9], v181, 1.0
	v_cvt_scalef32_pk_f32_fp4 v[10:11], v181, 1.0 op_sel:[1,0,0]
	v_cvt_scalef32_pk_f32_fp4 v[12:13], v181, 1.0 op_sel:[0,1,0]
	v_cvt_scalef32_pk_f32_fp4 v[14:15], v181, 1.0 op_sel:[1,1,0]
	v_readlane_b32 s54, v90, 12
	s_lshl_b32 s56, s54, 9
	s_add_u32 s56, s64, s56
	s_addc_u32 s57, s65, 0
	global_load_dwordx2 v[180:181], v227, s[56:57]
	s_waitcnt lgkmcnt(1)
	v_pk_fma_f32 v[130:131], v[0:1], v[76:77], v[130:131] op_sel_hi:[1,0,1]
	v_pk_fma_f32 v[138:139], v[2:3], v[76:77], v[138:139] op_sel_hi:[1,0,1]
	v_pk_fma_f32 v[140:141], v[4:5], v[76:77], v[140:141] op_sel_hi:[1,0,1]
	v_pk_fma_f32 v[142:143], v[6:7], v[76:77], v[142:143] op_sel_hi:[1,0,1]
	v_pk_fma_f32 v[128:129], v[8:9], v[76:77], v[128:129] op_sel_hi:[1,0,1]
	v_pk_fma_f32 v[132:133], v[10:11], v[76:77], v[132:133] op_sel_hi:[1,0,1]
	v_pk_fma_f32 v[134:135], v[12:13], v[76:77], v[134:135] op_sel_hi:[1,0,1]
	v_pk_fma_f32 v[136:137], v[14:15], v[76:77], v[136:137] op_sel_hi:[1,0,1]
	ds_read_b32 v76, v193 offset:504
	s_waitcnt vmcnt(15)
	v_cvt_scalef32_pk_f32_fp4 v[0:1], v182, 1.0
	v_cvt_scalef32_pk_f32_fp4 v[2:3], v182, 1.0 op_sel:[1,0,0]
	v_cvt_scalef32_pk_f32_fp4 v[4:5], v182, 1.0 op_sel:[0,1,0]
	v_cvt_scalef32_pk_f32_fp4 v[6:7], v182, 1.0 op_sel:[1,1,0]
	v_cvt_scalef32_pk_f32_fp4 v[8:9], v183, 1.0
	v_cvt_scalef32_pk_f32_fp4 v[10:11], v183, 1.0 op_sel:[1,0,0]
	v_cvt_scalef32_pk_f32_fp4 v[12:13], v183, 1.0 op_sel:[0,1,0]
	v_cvt_scalef32_pk_f32_fp4 v[14:15], v183, 1.0 op_sel:[1,1,0]
	v_readlane_b32 s54, v90, 13
	s_lshl_b32 s56, s54, 9
	s_add_u32 s56, s64, s56
	s_addc_u32 s57, s65, 0
	global_load_dwordx2 v[182:183], v227, s[56:57]
	s_waitcnt lgkmcnt(1)
	v_pk_fma_f32 v[130:131], v[0:1], v[194:195], v[130:131] op_sel_hi:[1,0,1]
	v_pk_fma_f32 v[138:139], v[2:3], v[194:195], v[138:139] op_sel_hi:[1,0,1]
	v_pk_fma_f32 v[140:141], v[4:5], v[194:195], v[140:141] op_sel_hi:[1,0,1]
	v_pk_fma_f32 v[142:143], v[6:7], v[194:195], v[142:143] op_sel_hi:[1,0,1]
	v_pk_fma_f32 v[128:129], v[8:9], v[194:195], v[128:129] op_sel_hi:[1,0,1]
	v_pk_fma_f32 v[132:133], v[10:11], v[194:195], v[132:133] op_sel_hi:[1,0,1]
	v_pk_fma_f32 v[134:135], v[12:13], v[194:195], v[134:135] op_sel_hi:[1,0,1]
	v_pk_fma_f32 v[136:137], v[14:15], v[194:195], v[136:137] op_sel_hi:[1,0,1]
	ds_read_b32 v194, v193 offset:508
	s_waitcnt vmcnt(15)
	v_cvt_scalef32_pk_f32_fp4 v[0:1], v184, 1.0
	v_cvt_scalef32_pk_f32_fp4 v[2:3], v184, 1.0 op_sel:[1,0,0]
	v_cvt_scalef32_pk_f32_fp4 v[4:5], v184, 1.0 op_sel:[0,1,0]
	v_cvt_scalef32_pk_f32_fp4 v[6:7], v184, 1.0 op_sel:[1,1,0]
	v_cvt_scalef32_pk_f32_fp4 v[8:9], v185, 1.0
	v_cvt_scalef32_pk_f32_fp4 v[10:11], v185, 1.0 op_sel:[1,0,0]
	v_cvt_scalef32_pk_f32_fp4 v[12:13], v185, 1.0 op_sel:[0,1,0]
	v_cvt_scalef32_pk_f32_fp4 v[14:15], v185, 1.0 op_sel:[1,1,0]
	v_readlane_b32 s54, v90, 14
	s_lshl_b32 s56, s54, 9
	s_add_u32 s56, s64, s56
	s_addc_u32 s57, s65, 0
	global_load_dwordx2 v[184:185], v227, s[56:57]
	s_waitcnt lgkmcnt(1)
	v_pk_fma_f32 v[130:131], v[0:1], v[76:77], v[130:131] op_sel_hi:[1,0,1]
	v_pk_fma_f32 v[138:139], v[2:3], v[76:77], v[138:139] op_sel_hi:[1,0,1]
	v_pk_fma_f32 v[140:141], v[4:5], v[76:77], v[140:141] op_sel_hi:[1,0,1]
	v_pk_fma_f32 v[142:143], v[6:7], v[76:77], v[142:143] op_sel_hi:[1,0,1]
	v_pk_fma_f32 v[128:129], v[8:9], v[76:77], v[128:129] op_sel_hi:[1,0,1]
	v_pk_fma_f32 v[132:133], v[10:11], v[76:77], v[132:133] op_sel_hi:[1,0,1]
	v_pk_fma_f32 v[134:135], v[12:13], v[76:77], v[134:135] op_sel_hi:[1,0,1]
	v_pk_fma_f32 v[136:137], v[14:15], v[76:77], v[136:137] op_sel_hi:[1,0,1]
	s_waitcnt vmcnt(15)
; __device__ void peer_gather_phase(const Params& P, int l, bool do_store) {
;     ...
;         const uint2* up = (const uint2*)(U + (size_t)(uphi ? eb : ea) * 768);
;         u6[3 * pr] = up[0]; u6[3 * pr + 1] = up[1]; u6[3 * pr + 2] = up[2];
;     ...
;         v6u_t qv; qv[0] = u6[3 * pr].x; qv[1] = u6[3 * pr].y; qv[2] = u6[3 * pr + 1].x; qv[3] = u6[3 * pr + 1].y; qv[4] = u6[3 * pr + 2].x; qv[5] = u6[3 * pr + 2].y;
;         const v32f_t wv = __builtin_amdgcn_cvt_scalef32_pk32_f32_fp6(qv, 1.0f);
;         f32x2 a2 = f32x2{0.f, 0.f};
; #pragma unroll
;         for (int i = 0; i < 16; ++i) a2 += f32x2{wv[2 * i], wv[2 * i + 1]} * xu[i];
;     ...
;       for (int j = 0; j < 8; ++j) {
;         const float a = __builtin_bit_cast(float, __builtin_amdgcn_readlane(__builtin_bit_cast(int, avec), kb + j));
;         const f32x2 aa = f32x2{a, a};
;         y[0] += aa * __builtin_amdgcn_cvt_scalef32_pk_f32_fp4(v8[j].x, 1.0f, 0); y[1] += aa * __builtin_amdgcn_cvt_scalef32_pk_f32_fp4(v8[j].x, 1.0f, 1);
;         y[2] += aa * __builtin_amdgcn_cvt_scalef32_pk_f32_fp4(v8[j].x, 1.0f, 2); y[3] += aa * __builtin_amdgcn_cvt_scalef32_pk_f32_fp4(v8[j].x, 1.0f, 3);
;         y[4] += aa * __builtin_amdgcn_cvt_scalef32_pk_f32_fp4(v8[j].y, 1.0f, 0); y[5] += aa * __builtin_amdgcn_cvt_scalef32_pk_f32_fp4(v8[j].y, 1.0f, 1);
;         y[6] += aa * __builtin_amdgcn_cvt_scalef32_pk_f32_fp4(v8[j].y, 1.0f, 2); y[7] += aa * __builtin_amdgcn_cvt_scalef32_pk_f32_fp4(v8[j].y, 1.0f, 3);
;       }
	v_cvt_scalef32_pk_f32_fp4 v[0:1], v186, 1.0
	v_cvt_scalef32_pk_f32_fp4 v[2:3], v186, 1.0 op_sel:[1,0,0]
	v_cvt_scalef32_pk_f32_fp4 v[4:5], v186, 1.0 op_sel:[0,1,0]
	v_cvt_scalef32_pk_f32_fp4 v[6:7], v186, 1.0 op_sel:[1,1,0]
	v_cvt_scalef32_pk_f32_fp4 v[8:9], v187, 1.0
	v_cvt_scalef32_pk_f32_fp4 v[10:11], v187, 1.0 op_sel:[1,0,0]
	v_cvt_scalef32_pk_f32_fp4 v[12:13], v187, 1.0 op_sel:[0,1,0]
	v_cvt_scalef32_pk_f32_fp4 v[14:15], v187, 1.0 op_sel:[1,1,0]
	v_readlane_b32 s54, v90, 15
	s_lshl_b32 s56, s54, 9
	s_add_u32 s56, s64, s56
	s_addc_u32 s57, s65, 0
	global_load_dwordx2 v[186:187], v227, s[56:57]
	s_waitcnt lgkmcnt(0)
	v_pk_fma_f32 v[130:131], v[0:1], v[194:195], v[130:131] op_sel_hi:[1,0,1]
	v_pk_fma_f32 v[138:139], v[2:3], v[194:195], v[138:139] op_sel_hi:[1,0,1]
	v_pk_fma_f32 v[140:141], v[4:5], v[194:195], v[140:141] op_sel_hi:[1,0,1]
	v_pk_fma_f32 v[142:143], v[6:7], v[194:195], v[142:143] op_sel_hi:[1,0,1]
	v_pk_fma_f32 v[128:129], v[8:9], v[194:195], v[128:129] op_sel_hi:[1,0,1]
	v_pk_fma_f32 v[132:133], v[10:11], v[194:195], v[132:133] op_sel_hi:[1,0,1]
	v_pk_fma_f32 v[134:135], v[12:13], v[194:195], v[134:135] op_sel_hi:[1,0,1]
	v_pk_fma_f32 v[136:137], v[14:15], v[194:195], v[136:137] op_sel_hi:[1,0,1]
	v_readlane_b32 s54, v90, 16
	v_readlane_b32 s55, v90, 17
	s_mul_i32 s0, s54, 0x300
	s_mul_i32 s1, s55, 0x300
	v_add_u32_e32 v167, s0, v195
	s_and_saveexec_b64 s[98:99], s[40:41]
	v_add_u32_e32 v167, s1, v195
	s_mov_b64 exec, s[98:99]
	s_waitcnt vmcnt(48)
	v_cvt_scalef32_pk32_f32_fp6 v[0:31], v[50:55], 1.0
	global_load_dwordx2 v[54:55], v167, s[62:63] offset:16
	global_load_dwordx4 v[50:53], v167, s[62:63]
	v_pk_mul_f32 v[246:247], v[0:1], v[96:97]
	v_pk_mul_f32 v[254:255], v[2:3], v[98:99]
	v_pk_mul_f32 v[160:161], v[4:5], v[100:101]
	v_pk_fma_f32 v[246:247], v[6:7], v[102:103], v[246:247]
	v_pk_fma_f32 v[254:255], v[8:9], v[104:105], v[254:255]
	v_pk_fma_f32 v[160:161], v[10:11], v[106:107], v[160:161]
	v_pk_fma_f32 v[246:247], v[12:13], v[108:109], v[246:247]
	v_pk_fma_f32 v[254:255], v[14:15], v[110:111], v[254:255]
	v_pk_fma_f32 v[160:161], v[16:17], v[112:113], v[160:161]
	v_pk_fma_f32 v[246:247], v[18:19], v[114:115], v[246:247]
	v_pk_fma_f32 v[254:255], v[20:21], v[116:117], v[254:255]
	v_pk_fma_f32 v[160:161], v[22:23], v[118:119], v[160:161]
	v_pk_fma_f32 v[246:247], v[24:25], v[120:121], v[246:247]
	v_pk_fma_f32 v[254:255], v[26:27], v[122:123], v[254:255]
	v_pk_fma_f32 v[160:161], v[28:29], v[124:125], v[160:161]
	v_pk_fma_f32 v[246:247], v[30:31], v[126:127], v[246:247]
	v_pk_add_f32 v[254:255], v[254:255], v[160:161]
	s_nop 0
	v_pk_add_f32 v[246:247], v[246:247], v[254:255]
	s_nop 0
	v_add_f32_e32 v162, v246, v247
	v_readlane_b32 s54, v90, 18
	v_readlane_b32 s55, v90, 19
	s_mul_i32 s0, s54, 0x300
	s_mul_i32 s1, s55, 0x300
	v_add_u32_e32 v167, s0, v195
	s_and_saveexec_b64 s[98:99], s[40:41]
	v_add_u32_e32 v167, s1, v195
	s_mov_b64 exec, s[98:99]
	s_waitcnt vmcnt(48)
	v_cvt_scalef32_pk32_f32_fp6 v[0:31], v[44:49], 1.0
	global_load_dwordx2 v[48:49], v167, s[62:63] offset:16
	global_load_dwordx4 v[44:47], v167, s[62:63]
	v_pk_mul_f32 v[246:247], v[0:1], v[96:97]
	v_pk_mul_f32 v[254:255], v[2:3], v[98:99]
	v_pk_mul_f32 v[160:161], v[4:5], v[100:101]
	v_pk_fma_f32 v[246:247], v[6:7], v[102:103], v[246:247]
	v_pk_fma_f32 v[254:255], v[8:9], v[104:105], v[254:255]
	v_pk_fma_f32 v[160:161], v[10:11], v[106:107], v[160:161]
	v_pk_fma_f32 v[246:247], v[12:13], v[108:109], v[246:247]
	v_pk_fma_f32 v[254:255], v[14:15], v[110:111], v[254:255]
	v_pk_fma_f32 v[160:161], v[16:17], v[112:113], v[160:161]
	v_pk_fma_f32 v[246:247], v[18:19], v[114:115], v[246:247]
	v_pk_fma_f32 v[254:255], v[20:21], v[116:117], v[254:255]
	v_pk_fma_f32 v[160:161], v[22:23], v[118:119], v[160:161]
	v_pk_fma_f32 v[246:247], v[24:25], v[120:121], v[246:247]
	v_pk_fma_f32 v[254:255], v[26:27], v[122:123], v[254:255]
	v_pk_fma_f32 v[160:161], v[28:29], v[124:125], v[160:161]
	v_pk_fma_f32 v[246:247], v[30:31], v[126:127], v[246:247]
	v_pk_add_f32 v[254:255], v[254:255], v[160:161]
	s_nop 0
	v_pk_add_f32 v[246:247], v[246:247], v[254:255]
	s_nop 0
	v_add_f32_e32 v163, v246, v247
	v_readlane_b32 s54, v90, 20
	v_readlane_b32 s55, v90, 21
	s_mul_i32 s0, s54, 0x300
	s_mul_i32 s1, s55, 0x300
	v_add_u32_e32 v167, s0, v195
	s_and_saveexec_b64 s[98:99], s[40:41]
	v_add_u32_e32 v167, s1, v195
	s_mov_b64 exec, s[98:99]
	s_waitcnt vmcnt(48)
	v_cvt_scalef32_pk32_f32_fp6 v[0:31], v[38:43], 1.0
	global_load_dwordx2 v[42:43], v167, s[62:63] offset:16
	global_load_dwordx4 v[38:41], v167, s[62:63]
	v_pk_mul_f32 v[246:247], v[0:1], v[96:97]
	v_pk_mul_f32 v[254:255], v[2:3], v[98:99]
	v_pk_mul_f32 v[160:161], v[4:5], v[100:101]
	v_pk_fma_f32 v[246:247], v[6:7], v[102:103], v[246:247]
	v_pk_fma_f32 v[254:255], v[8:9], v[104:105], v[254:255]
	v_pk_fma_f32 v[160:161], v[10:11], v[106:107], v[160:161]
	v_pk_fma_f32 v[246:247], v[12:13], v[108:109], v[246:247]
	v_pk_fma_f32 v[254:255], v[14:15], v[110:111], v[254:255]
	v_pk_fma_f32 v[160:161], v[16:17], v[112:113], v[160:161]
	v_pk_fma_f32 v[246:247], v[18:19], v[114:115], v[246:247]
	v_pk_fma_f32 v[254:255], v[20:21], v[116:117], v[254:255]
	v_pk_fma_f32 v[160:161], v[22:23], v[118:119], v[160:161]
	v_pk_fma_f32 v[246:247], v[24:25], v[120:121], v[246:247]
	v_pk_fma_f32 v[254:255], v[26:27], v[122:123], v[254:255]
	v_pk_fma_f32 v[160:161], v[28:29], v[124:125], v[160:161]
	v_pk_fma_f32 v[246:247], v[30:31], v[126:127], v[246:247]
	v_pk_add_f32 v[254:255], v[254:255], v[160:161]
	s_nop 0
	v_pk_add_f32 v[246:247], v[246:247], v[254:255]
	s_nop 0
	v_add_f32_e32 v164, v246, v247
	v_readlane_b32 s54, v90, 22
	v_readlane_b32 s55, v90, 23
	s_mul_i32 s0, s54, 0x300
	s_mul_i32 s1, s55, 0x300
	v_add_u32_e32 v167, s0, v195
	s_and_saveexec_b64 s[98:99], s[40:41]
	v_add_u32_e32 v167, s1, v195
	s_mov_b64 exec, s[98:99]
	s_waitcnt vmcnt(48)
; __device__ void peer_gather_phase(const Params& P, int l, bool do_store) {
;     ...
;         v6u_t qv; qv[0] = u6[3 * pr].x; qv[1] = u6[3 * pr].y; qv[2] = u6[3 * pr + 1].x; qv[3] = u6[3 * pr + 1].y; qv[4] = u6[3 * pr + 2].x; qv[5] = u6[3 * pr + 2].y;
;         const v32f_t wv = __builtin_amdgcn_cvt_scalef32_pk32_f32_fp6(qv, 1.0f);
;         f32x2 a2 = f32x2{0.f, 0.f};
; #pragma unroll
;         for (int i = 0; i < 16; ++i) a2 += f32x2{wv[2 * i], wv[2 * i + 1]} * xu[i];
;         float hs = a2.x + a2.y;
;         hs += dpp_row_shr(hs, 1); hs += dpp_row_shr(hs, 2); hs += dpp_row_shr(hs, 4); hs += dpp_row_shr(hs, 8);
;         hs += __builtin_bit_cast(float, __builtin_amdgcn_update_dpp(0, __builtin_bit_cast(int, hs), 0x142, 0xa, 0xf, false));
;         const float da = __builtin_bit_cast(float, __builtin_amdgcn_readlane(__builtin_bit_cast(int, hs), 31));
;         const float db = __builtin_bit_cast(float, __builtin_amdgcn_readlane(__builtin_bit_cast(int, hs), 63));
;         dvec = (lane == kb + 2 * pr) ? da : dvec;
;         dvec = (lane == kb + 2 * pr + 1) ? db : dvec;
	v_cvt_scalef32_pk32_f32_fp6 v[0:31], v[32:37], 1.0
	global_load_dwordx2 v[36:37], v167, s[62:63] offset:16
	global_load_dwordx4 v[32:35], v167, s[62:63]
	v_pk_mul_f32 v[246:247], v[0:1], v[96:97]
	v_pk_mul_f32 v[254:255], v[2:3], v[98:99]
	v_pk_mul_f32 v[160:161], v[4:5], v[100:101]
	v_pk_fma_f32 v[246:247], v[6:7], v[102:103], v[246:247]
	v_pk_fma_f32 v[254:255], v[8:9], v[104:105], v[254:255]
	v_pk_fma_f32 v[160:161], v[10:11], v[106:107], v[160:161]
	v_pk_fma_f32 v[246:247], v[12:13], v[108:109], v[246:247]
	v_pk_fma_f32 v[254:255], v[14:15], v[110:111], v[254:255]
	v_pk_fma_f32 v[160:161], v[16:17], v[112:113], v[160:161]
	v_pk_fma_f32 v[246:247], v[18:19], v[114:115], v[246:247]
	v_pk_fma_f32 v[254:255], v[20:21], v[116:117], v[254:255]
	v_pk_fma_f32 v[160:161], v[22:23], v[118:119], v[160:161]
	v_pk_fma_f32 v[246:247], v[24:25], v[120:121], v[246:247]
	v_pk_fma_f32 v[254:255], v[26:27], v[122:123], v[254:255]
	v_pk_fma_f32 v[160:161], v[28:29], v[124:125], v[160:161]
	v_pk_fma_f32 v[246:247], v[30:31], v[126:127], v[246:247]
	v_pk_add_f32 v[254:255], v[254:255], v[160:161]
	s_nop 0
	v_pk_add_f32 v[246:247], v[246:247], v[254:255]
	s_nop 0
	v_add_f32_e32 v165, v246, v247
	v_add_f32_dpp v162, v162, v162 row_shr:1 row_mask:0xf bank_mask:0xf bound_ctrl:1
	v_add_f32_dpp v163, v163, v163 row_shr:1 row_mask:0xf bank_mask:0xf bound_ctrl:1
	v_add_f32_dpp v164, v164, v164 row_shr:1 row_mask:0xf bank_mask:0xf bound_ctrl:1
	v_add_f32_dpp v165, v165, v165 row_shr:1 row_mask:0xf bank_mask:0xf bound_ctrl:1
	v_add_f32_dpp v162, v162, v162 row_shr:2 row_mask:0xf bank_mask:0xf bound_ctrl:1
	v_add_f32_dpp v163, v163, v163 row_shr:2 row_mask:0xf bank_mask:0xf bound_ctrl:1
	v_add_f32_dpp v164, v164, v164 row_shr:2 row_mask:0xf bank_mask:0xf bound_ctrl:1
	v_add_f32_dpp v165, v165, v165 row_shr:2 row_mask:0xf bank_mask:0xf bound_ctrl:1
	v_add_f32_dpp v162, v162, v162 row_shr:4 row_mask:0xf bank_mask:0xf bound_ctrl:1
	v_add_f32_dpp v163, v163, v163 row_shr:4 row_mask:0xf bank_mask:0xf bound_ctrl:1
	v_add_f32_dpp v164, v164, v164 row_shr:4 row_mask:0xf bank_mask:0xf bound_ctrl:1
	v_add_f32_dpp v165, v165, v165 row_shr:4 row_mask:0xf bank_mask:0xf bound_ctrl:1
	v_add_f32_dpp v162, v162, v162 row_shr:8 row_mask:0xf bank_mask:0xf bound_ctrl:1
	v_add_f32_dpp v163, v163, v163 row_shr:8 row_mask:0xf bank_mask:0xf bound_ctrl:1
	v_add_f32_dpp v164, v164, v164 row_shr:8 row_mask:0xf bank_mask:0xf bound_ctrl:1
	v_add_f32_dpp v165, v165, v165 row_shr:8 row_mask:0xf bank_mask:0xf bound_ctrl:1
	v_add_f32_dpp v162, v162, v162 row_bcast:15 row_mask:0xa bank_mask:0xf
	v_add_f32_dpp v163, v163, v163 row_bcast:15 row_mask:0xa bank_mask:0xf
	v_add_f32_dpp v164, v164, v164 row_bcast:15 row_mask:0xa bank_mask:0xf
	v_add_f32_dpp v165, v165, v165 row_bcast:15 row_mask:0xa bank_mask:0xf
	s_mov_b64 s[98:99], exec
	s_mov_b32 exec_lo, 0x80000000
	s_mov_b32 exec_hi, 0x80000000
	ds_write_b32 v74, v162
	ds_write_b32 v74, v163 offset:8
	ds_write_b32 v74, v164 offset:16
	ds_write_b32 v74, v165 offset:24
	s_mov_b64 exec, s[98:99]
	v_readlane_b32 s54, v90, 24
	v_readlane_b32 s55, v90, 25
	s_mul_i32 s0, s54, 0x300
	s_mul_i32 s1, s55, 0x300
	v_add_u32_e32 v167, s0, v195
	s_and_saveexec_b64 s[98:99], s[40:41]
	v_add_u32_e32 v167, s1, v195
	s_mov_b64 exec, s[98:99]
	s_waitcnt vmcnt(48)
	v_cvt_scalef32_pk32_f32_fp6 v[0:31], v[196:201], 1.0
	global_load_dwordx2 v[200:201], v167, s[62:63] offset:16
	global_load_dwordx4 v[196:199], v167, s[62:63]
	v_pk_mul_f32 v[246:247], v[0:1], v[96:97]
	v_pk_mul_f32 v[254:255], v[2:3], v[98:99]
	v_pk_mul_f32 v[160:161], v[4:5], v[100:101]
	v_pk_fma_f32 v[246:247], v[6:7], v[102:103], v[246:247]
	v_pk_fma_f32 v[254:255], v[8:9], v[104:105], v[254:255]
	v_pk_fma_f32 v[160:161], v[10:11], v[106:107], v[160:161]
	v_pk_fma_f32 v[246:247], v[12:13], v[108:109], v[246:247]
	v_pk_fma_f32 v[254:255], v[14:15], v[110:111], v[254:255]
	v_pk_fma_f32 v[160:161], v[16:17], v[112:113], v[160:161]
	v_pk_fma_f32 v[246:247], v[18:19], v[114:115], v[246:247]
	v_pk_fma_f32 v[254:255], v[20:21], v[116:117], v[254:255]
	v_pk_fma_f32 v[160:161], v[22:23], v[118:119], v[160:161]
	v_pk_fma_f32 v[246:247], v[24:25], v[120:121], v[246:247]
	v_pk_fma_f32 v[254:255], v[26:27], v[122:123], v[254:255]
	v_pk_fma_f32 v[160:161], v[28:29], v[124:125], v[160:161]
	v_pk_fma_f32 v[246:247], v[30:31], v[126:127], v[246:247]
	v_pk_add_f32 v[254:255], v[254:255], v[160:161]
	s_nop 0
	v_pk_add_f32 v[246:247], v[246:247], v[254:255]
	s_nop 0
	v_add_f32_e32 v162, v246, v247
	v_readlane_b32 s54, v90, 26
	v_readlane_b32 s55, v90, 27
	s_mul_i32 s0, s54, 0x300
	s_mul_i32 s1, s55, 0x300
	v_add_u32_e32 v167, s0, v195
	s_and_saveexec_b64 s[98:99], s[40:41]
	v_add_u32_e32 v167, s1, v195
	s_mov_b64 exec, s[98:99]
	s_waitcnt vmcnt(48)
	v_cvt_scalef32_pk32_f32_fp6 v[0:31], v[228:233], 1.0
	global_load_dwordx2 v[232:233], v167, s[62:63] offset:16
	global_load_dwordx4 v[228:231], v167, s[62:63]
	v_pk_mul_f32 v[246:247], v[0:1], v[96:97]
	v_pk_mul_f32 v[254:255], v[2:3], v[98:99]
	v_pk_mul_f32 v[160:161], v[4:5], v[100:101]
	v_pk_fma_f32 v[246:247], v[6:7], v[102:103], v[246:247]
	v_pk_fma_f32 v[254:255], v[8:9], v[104:105], v[254:255]
	v_pk_fma_f32 v[160:161], v[10:11], v[106:107], v[160:161]
	v_pk_fma_f32 v[246:247], v[12:13], v[108:109], v[246:247]
	v_pk_fma_f32 v[254:255], v[14:15], v[110:111], v[254:255]
	v_pk_fma_f32 v[160:161], v[16:17], v[112:113], v[160:161]
	v_pk_fma_f32 v[246:247], v[18:19], v[114:115], v[246:247]
	v_pk_fma_f32 v[254:255], v[20:21], v[116:117], v[254:255]
	v_pk_fma_f32 v[160:161], v[22:23], v[118:119], v[160:161]
	v_pk_fma_f32 v[246:247], v[24:25], v[120:121], v[246:247]
	v_pk_fma_f32 v[254:255], v[26:27], v[122:123], v[254:255]
	v_pk_fma_f32 v[160:161], v[28:29], v[124:125], v[160:161]
	v_pk_fma_f32 v[246:247], v[30:31], v[126:127], v[246:247]
	v_pk_add_f32 v[254:255], v[254:255], v[160:161]
	s_nop 0
	v_pk_add_f32 v[246:247], v[246:247], v[254:255]
	s_nop 0
	v_add_f32_e32 v163, v246, v247
	v_readlane_b32 s54, v90, 28
	v_readlane_b32 s55, v90, 29
	s_mul_i32 s0, s54, 0x300
	s_mul_i32 s1, s55, 0x300
	v_add_u32_e32 v167, s0, v195
	s_and_saveexec_b64 s[98:99], s[40:41]
	v_add_u32_e32 v167, s1, v195
	s_mov_b64 exec, s[98:99]
	s_waitcnt vmcnt(48)
; __device__ void peer_gather_phase(const Params& P, int l, bool do_store) {
;     ...
;         v6u_t qv; qv[0] = u6[3 * pr].x; qv[1] = u6[3 * pr].y; qv[2] = u6[3 * pr + 1].x; qv[3] = u6[3 * pr + 1].y; qv[4] = u6[3 * pr + 2].x; qv[5] = u6[3 * pr + 2].y;
;         const v32f_t wv = __builtin_amdgcn_cvt_scalef32_pk32_f32_fp6(qv, 1.0f);
;         f32x2 a2 = f32x2{0.f, 0.f};
; #pragma unroll
;         for (int i = 0; i < 16; ++i) a2 += f32x2{wv[2 * i], wv[2 * i + 1]} * xu[i];
;         float hs = a2.x + a2.y;
;         hs += dpp_row_shr(hs, 1); hs += dpp_row_shr(hs, 2); hs += dpp_row_shr(hs, 4); hs += dpp_row_shr(hs, 8);
;         hs += __builtin_bit_cast(float, __builtin_amdgcn_update_dpp(0, __builtin_bit_cast(int, hs), 0x142, 0xa, 0xf, false));
;         const float da = __builtin_bit_cast(float, __builtin_amdgcn_readlane(__builtin_bit_cast(int, hs), 31));
;         const float db = __builtin_bit_cast(float, __builtin_amdgcn_readlane(__builtin_bit_cast(int, hs), 63));
;         dvec = (lane == kb + 2 * pr) ? da : dvec;
;         dvec = (lane == kb + 2 * pr + 1) ? db : dvec;
	v_cvt_scalef32_pk32_f32_fp6 v[0:31], v[234:239], 1.0
	global_load_dwordx2 v[238:239], v167, s[62:63] offset:16
	global_load_dwordx4 v[234:237], v167, s[62:63]
	v_pk_mul_f32 v[246:247], v[0:1], v[96:97]
	v_pk_mul_f32 v[254:255], v[2:3], v[98:99]
	v_pk_mul_f32 v[160:161], v[4:5], v[100:101]
	v_pk_fma_f32 v[246:247], v[6:7], v[102:103], v[246:247]
	v_pk_fma_f32 v[254:255], v[8:9], v[104:105], v[254:255]
	v_pk_fma_f32 v[160:161], v[10:11], v[106:107], v[160:161]
	v_pk_fma_f32 v[246:247], v[12:13], v[108:109], v[246:247]
	v_pk_fma_f32 v[254:255], v[14:15], v[110:111], v[254:255]
	v_pk_fma_f32 v[160:161], v[16:17], v[112:113], v[160:161]
	v_pk_fma_f32 v[246:247], v[18:19], v[114:115], v[246:247]
	v_pk_fma_f32 v[254:255], v[20:21], v[116:117], v[254:255]
	v_pk_fma_f32 v[160:161], v[22:23], v[118:119], v[160:161]
	v_pk_fma_f32 v[246:247], v[24:25], v[120:121], v[246:247]
	v_pk_fma_f32 v[254:255], v[26:27], v[122:123], v[254:255]
	v_pk_fma_f32 v[160:161], v[28:29], v[124:125], v[160:161]
	v_pk_fma_f32 v[246:247], v[30:31], v[126:127], v[246:247]
	v_pk_add_f32 v[254:255], v[254:255], v[160:161]
	s_nop 0
	v_pk_add_f32 v[246:247], v[246:247], v[254:255]
	s_nop 0
	v_add_f32_e32 v164, v246, v247
	v_readlane_b32 s54, v90, 30
	v_readlane_b32 s55, v90, 31
	s_mul_i32 s0, s54, 0x300
	s_mul_i32 s1, s55, 0x300
	v_add_u32_e32 v167, s0, v195
	s_and_saveexec_b64 s[98:99], s[40:41]
	v_add_u32_e32 v167, s1, v195
	s_mov_b64 exec, s[98:99]
	s_waitcnt vmcnt(48)
	v_cvt_scalef32_pk32_f32_fp6 v[0:31], v[240:245], 1.0
	global_load_dwordx2 v[244:245], v167, s[62:63] offset:16
	global_load_dwordx4 v[240:243], v167, s[62:63]
	v_pk_mul_f32 v[246:247], v[0:1], v[96:97]
	v_pk_mul_f32 v[254:255], v[2:3], v[98:99]
	v_pk_mul_f32 v[160:161], v[4:5], v[100:101]
	v_pk_fma_f32 v[246:247], v[6:7], v[102:103], v[246:247]
	v_pk_fma_f32 v[254:255], v[8:9], v[104:105], v[254:255]
	v_pk_fma_f32 v[160:161], v[10:11], v[106:107], v[160:161]
	v_pk_fma_f32 v[246:247], v[12:13], v[108:109], v[246:247]
	v_pk_fma_f32 v[254:255], v[14:15], v[110:111], v[254:255]
	v_pk_fma_f32 v[160:161], v[16:17], v[112:113], v[160:161]
	v_pk_fma_f32 v[246:247], v[18:19], v[114:115], v[246:247]
	v_pk_fma_f32 v[254:255], v[20:21], v[116:117], v[254:255]
	v_pk_fma_f32 v[160:161], v[22:23], v[118:119], v[160:161]
	v_pk_fma_f32 v[246:247], v[24:25], v[120:121], v[246:247]
	v_pk_fma_f32 v[254:255], v[26:27], v[122:123], v[254:255]
	v_pk_fma_f32 v[160:161], v[28:29], v[124:125], v[160:161]
	v_pk_fma_f32 v[246:247], v[30:31], v[126:127], v[246:247]
	v_pk_add_f32 v[254:255], v[254:255], v[160:161]
	s_nop 0
	v_pk_add_f32 v[246:247], v[246:247], v[254:255]
	s_nop 0
	v_add_f32_e32 v165, v246, v247
	v_add_f32_dpp v162, v162, v162 row_shr:1 row_mask:0xf bank_mask:0xf bound_ctrl:1
	v_add_f32_dpp v163, v163, v163 row_shr:1 row_mask:0xf bank_mask:0xf bound_ctrl:1
	v_add_f32_dpp v164, v164, v164 row_shr:1 row_mask:0xf bank_mask:0xf bound_ctrl:1
	v_add_f32_dpp v165, v165, v165 row_shr:1 row_mask:0xf bank_mask:0xf bound_ctrl:1
	v_add_f32_dpp v162, v162, v162 row_shr:2 row_mask:0xf bank_mask:0xf bound_ctrl:1
	v_add_f32_dpp v163, v163, v163 row_shr:2 row_mask:0xf bank_mask:0xf bound_ctrl:1
	v_add_f32_dpp v164, v164, v164 row_shr:2 row_mask:0xf bank_mask:0xf bound_ctrl:1
	v_add_f32_dpp v165, v165, v165 row_shr:2 row_mask:0xf bank_mask:0xf bound_ctrl:1
	v_add_f32_dpp v162, v162, v162 row_shr:4 row_mask:0xf bank_mask:0xf bound_ctrl:1
	v_add_f32_dpp v163, v163, v163 row_shr:4 row_mask:0xf bank_mask:0xf bound_ctrl:1
	v_add_f32_dpp v164, v164, v164 row_shr:4 row_mask:0xf bank_mask:0xf bound_ctrl:1
	v_add_f32_dpp v165, v165, v165 row_shr:4 row_mask:0xf bank_mask:0xf bound_ctrl:1
	v_add_f32_dpp v162, v162, v162 row_shr:8 row_mask:0xf bank_mask:0xf bound_ctrl:1
	v_add_f32_dpp v163, v163, v163 row_shr:8 row_mask:0xf bank_mask:0xf bound_ctrl:1
	v_add_f32_dpp v164, v164, v164 row_shr:8 row_mask:0xf bank_mask:0xf bound_ctrl:1
	v_add_f32_dpp v165, v165, v165 row_shr:8 row_mask:0xf bank_mask:0xf bound_ctrl:1
	v_add_f32_dpp v162, v162, v162 row_bcast:15 row_mask:0xa bank_mask:0xf
	v_add_f32_dpp v163, v163, v163 row_bcast:15 row_mask:0xa bank_mask:0xf
	v_add_f32_dpp v164, v164, v164 row_bcast:15 row_mask:0xa bank_mask:0xf
	v_add_f32_dpp v165, v165, v165 row_bcast:15 row_mask:0xa bank_mask:0xf
	s_mov_b64 s[98:99], exec
	s_mov_b32 exec_lo, 0x80000000
	s_mov_b32 exec_hi, 0x80000000
	ds_write_b32 v74, v162 offset:32
	ds_write_b32 v74, v163 offset:40
	ds_write_b32 v74, v164 offset:48
	ds_write_b32 v74, v165 offset:56
	s_mov_b64 exec, s[98:99]
	v_readlane_b32 s54, v90, 32
	v_readlane_b32 s55, v90, 33
	s_mul_i32 s0, s54, 0x300
	s_mul_i32 s1, s55, 0x300
	v_add_u32_e32 v167, s0, v195
	s_and_saveexec_b64 s[98:99], s[40:41]
	v_add_u32_e32 v167, s1, v195
	s_mov_b64 exec, s[98:99]
	s_waitcnt vmcnt(14)
	v_cvt_scalef32_pk32_f32_fp6 v[0:31], v[50:55], 1.0
	global_load_dwordx2 v[54:55], v167, s[62:63] offset:16
	global_load_dwordx4 v[50:53], v167, s[62:63]
	v_pk_mul_f32 v[246:247], v[0:1], v[96:97]
	v_pk_mul_f32 v[254:255], v[2:3], v[98:99]
	v_pk_mul_f32 v[160:161], v[4:5], v[100:101]
	v_pk_fma_f32 v[246:247], v[6:7], v[102:103], v[246:247]
	v_pk_fma_f32 v[254:255], v[8:9], v[104:105], v[254:255]
	v_pk_fma_f32 v[160:161], v[10:11], v[106:107], v[160:161]
	v_pk_fma_f32 v[246:247], v[12:13], v[108:109], v[246:247]
	v_pk_fma_f32 v[254:255], v[14:15], v[110:111], v[254:255]
	v_pk_fma_f32 v[160:161], v[16:17], v[112:113], v[160:161]
	v_pk_fma_f32 v[246:247], v[18:19], v[114:115], v[246:247]
	v_pk_fma_f32 v[254:255], v[20:21], v[116:117], v[254:255]
	v_pk_fma_f32 v[160:161], v[22:23], v[118:119], v[160:161]
	v_pk_fma_f32 v[246:247], v[24:25], v[120:121], v[246:247]
	v_pk_fma_f32 v[254:255], v[26:27], v[122:123], v[254:255]
	v_pk_fma_f32 v[160:161], v[28:29], v[124:125], v[160:161]
	v_pk_fma_f32 v[246:247], v[30:31], v[126:127], v[246:247]
	v_pk_add_f32 v[254:255], v[254:255], v[160:161]
	s_nop 0
	v_pk_add_f32 v[246:247], v[246:247], v[254:255]
	s_nop 0
	v_add_f32_e32 v162, v246, v247
	v_readlane_b32 s54, v90, 34
	v_readlane_b32 s55, v90, 35
	s_mul_i32 s0, s54, 0x300
	s_mul_i32 s1, s55, 0x300
	v_add_u32_e32 v167, s0, v195
	s_and_saveexec_b64 s[98:99], s[40:41]
	v_add_u32_e32 v167, s1, v195
	s_mov_b64 exec, s[98:99]
	s_waitcnt vmcnt(14)
; __device__ void peer_gather_phase(const Params& P, int l, bool do_store) {
;     ...
;         v6u_t qv; qv[0] = u6[3 * pr].x; qv[1] = u6[3 * pr].y; qv[2] = u6[3 * pr + 1].x; qv[3] = u6[3 * pr + 1].y; qv[4] = u6[3 * pr + 2].x; qv[5] = u6[3 * pr + 2].y;
;         const v32f_t wv = __builtin_amdgcn_cvt_scalef32_pk32_f32_fp6(qv, 1.0f);
;         f32x2 a2 = f32x2{0.f, 0.f};
; #pragma unroll
;         for (int i = 0; i < 16; ++i) a2 += f32x2{wv[2 * i], wv[2 * i + 1]} * xu[i];
;         float hs = a2.x + a2.y;
;         hs += dpp_row_shr(hs, 1); hs += dpp_row_shr(hs, 2); hs += dpp_row_shr(hs, 4); hs += dpp_row_shr(hs, 8);
;         hs += __builtin_bit_cast(float, __builtin_amdgcn_update_dpp(0, __builtin_bit_cast(int, hs), 0x142, 0xa, 0xf, false));
;         const float da = __builtin_bit_cast(float, __builtin_amdgcn_readlane(__builtin_bit_cast(int, hs), 31));
;         const float db = __builtin_bit_cast(float, __builtin_amdgcn_readlane(__builtin_bit_cast(int, hs), 63));
;         dvec = (lane == kb + 2 * pr) ? da : dvec;
;         dvec = (lane == kb + 2 * pr + 1) ? db : dvec;
	v_cvt_scalef32_pk32_f32_fp6 v[0:31], v[44:49], 1.0
	global_load_dwordx2 v[48:49], v167, s[62:63] offset:16
	global_load_dwordx4 v[44:47], v167, s[62:63]
	v_pk_mul_f32 v[246:247], v[0:1], v[96:97]
	v_pk_mul_f32 v[254:255], v[2:3], v[98:99]
	v_pk_mul_f32 v[160:161], v[4:5], v[100:101]
	v_pk_fma_f32 v[246:247], v[6:7], v[102:103], v[246:247]
	v_pk_fma_f32 v[254:255], v[8:9], v[104:105], v[254:255]
	v_pk_fma_f32 v[160:161], v[10:11], v[106:107], v[160:161]
	v_pk_fma_f32 v[246:247], v[12:13], v[108:109], v[246:247]
	v_pk_fma_f32 v[254:255], v[14:15], v[110:111], v[254:255]
	v_pk_fma_f32 v[160:161], v[16:17], v[112:113], v[160:161]
	v_pk_fma_f32 v[246:247], v[18:19], v[114:115], v[246:247]
	v_pk_fma_f32 v[254:255], v[20:21], v[116:117], v[254:255]
	v_pk_fma_f32 v[160:161], v[22:23], v[118:119], v[160:161]
	v_pk_fma_f32 v[246:247], v[24:25], v[120:121], v[246:247]
	v_pk_fma_f32 v[254:255], v[26:27], v[122:123], v[254:255]
	v_pk_fma_f32 v[160:161], v[28:29], v[124:125], v[160:161]
	v_pk_fma_f32 v[246:247], v[30:31], v[126:127], v[246:247]
	v_pk_add_f32 v[254:255], v[254:255], v[160:161]
	s_nop 0
	v_pk_add_f32 v[246:247], v[246:247], v[254:255]
	s_nop 0
	v_add_f32_e32 v163, v246, v247
	v_readlane_b32 s54, v90, 36
	v_readlane_b32 s55, v90, 37
	s_mul_i32 s0, s54, 0x300
	s_mul_i32 s1, s55, 0x300
	v_add_u32_e32 v167, s0, v195
	s_and_saveexec_b64 s[98:99], s[40:41]
	v_add_u32_e32 v167, s1, v195
	s_mov_b64 exec, s[98:99]
	s_waitcnt vmcnt(14)
	v_cvt_scalef32_pk32_f32_fp6 v[0:31], v[38:43], 1.0
	global_load_dwordx2 v[42:43], v167, s[62:63] offset:16
	global_load_dwordx4 v[38:41], v167, s[62:63]
	v_pk_mul_f32 v[246:247], v[0:1], v[96:97]
	v_pk_mul_f32 v[254:255], v[2:3], v[98:99]
	v_pk_mul_f32 v[160:161], v[4:5], v[100:101]
	v_pk_fma_f32 v[246:247], v[6:7], v[102:103], v[246:247]
	v_pk_fma_f32 v[254:255], v[8:9], v[104:105], v[254:255]
	v_pk_fma_f32 v[160:161], v[10:11], v[106:107], v[160:161]
	v_pk_fma_f32 v[246:247], v[12:13], v[108:109], v[246:247]
	v_pk_fma_f32 v[254:255], v[14:15], v[110:111], v[254:255]
	v_pk_fma_f32 v[160:161], v[16:17], v[112:113], v[160:161]
	v_pk_fma_f32 v[246:247], v[18:19], v[114:115], v[246:247]
	v_pk_fma_f32 v[254:255], v[20:21], v[116:117], v[254:255]
	v_pk_fma_f32 v[160:161], v[22:23], v[118:119], v[160:161]
	v_pk_fma_f32 v[246:247], v[24:25], v[120:121], v[246:247]
	v_pk_fma_f32 v[254:255], v[26:27], v[122:123], v[254:255]
	v_pk_fma_f32 v[160:161], v[28:29], v[124:125], v[160:161]
	v_pk_fma_f32 v[246:247], v[30:31], v[126:127], v[246:247]
	v_pk_add_f32 v[254:255], v[254:255], v[160:161]
	s_nop 0
	v_pk_add_f32 v[246:247], v[246:247], v[254:255]
	s_nop 0
	v_add_f32_e32 v164, v246, v247
	v_readlane_b32 s54, v90, 38
	v_readlane_b32 s55, v90, 39
	s_mul_i32 s0, s54, 0x300
	s_mul_i32 s1, s55, 0x300
	v_add_u32_e32 v167, s0, v195
	s_and_saveexec_b64 s[98:99], s[40:41]
	v_add_u32_e32 v167, s1, v195
	s_mov_b64 exec, s[98:99]
	s_waitcnt vmcnt(14)
	v_cvt_scalef32_pk32_f32_fp6 v[0:31], v[32:37], 1.0
	global_load_dwordx2 v[36:37], v167, s[62:63] offset:16
	global_load_dwordx4 v[32:35], v167, s[62:63]
	v_pk_mul_f32 v[246:247], v[0:1], v[96:97]
	v_pk_mul_f32 v[254:255], v[2:3], v[98:99]
	v_pk_mul_f32 v[160:161], v[4:5], v[100:101]
	v_pk_fma_f32 v[246:247], v[6:7], v[102:103], v[246:247]
	v_pk_fma_f32 v[254:255], v[8:9], v[104:105], v[254:255]
	v_pk_fma_f32 v[160:161], v[10:11], v[106:107], v[160:161]
	v_pk_fma_f32 v[246:247], v[12:13], v[108:109], v[246:247]
	v_pk_fma_f32 v[254:255], v[14:15], v[110:111], v[254:255]
	v_pk_fma_f32 v[160:161], v[16:17], v[112:113], v[160:161]
	v_pk_fma_f32 v[246:247], v[18:19], v[114:115], v[246:247]
	v_pk_fma_f32 v[254:255], v[20:21], v[116:117], v[254:255]
	v_pk_fma_f32 v[160:161], v[22:23], v[118:119], v[160:161]
	v_pk_fma_f32 v[246:247], v[24:25], v[120:121], v[246:247]
	v_pk_fma_f32 v[254:255], v[26:27], v[122:123], v[254:255]
	v_pk_fma_f32 v[160:161], v[28:29], v[124:125], v[160:161]
	v_pk_fma_f32 v[246:247], v[30:31], v[126:127], v[246:247]
	v_pk_add_f32 v[254:255], v[254:255], v[160:161]
	s_nop 0
	v_pk_add_f32 v[246:247], v[246:247], v[254:255]
	s_nop 0
	v_add_f32_e32 v165, v246, v247
	v_add_f32_dpp v162, v162, v162 row_shr:1 row_mask:0xf bank_mask:0xf bound_ctrl:1
	v_add_f32_dpp v163, v163, v163 row_shr:1 row_mask:0xf bank_mask:0xf bound_ctrl:1
	v_add_f32_dpp v164, v164, v164 row_shr:1 row_mask:0xf bank_mask:0xf bound_ctrl:1
	v_add_f32_dpp v165, v165, v165 row_shr:1 row_mask:0xf bank_mask:0xf bound_ctrl:1
	v_add_f32_dpp v162, v162, v162 row_shr:2 row_mask:0xf bank_mask:0xf bound_ctrl:1
	v_add_f32_dpp v163, v163, v163 row_shr:2 row_mask:0xf bank_mask:0xf bound_ctrl:1
	v_add_f32_dpp v164, v164, v164 row_shr:2 row_mask:0xf bank_mask:0xf bound_ctrl:1
	v_add_f32_dpp v165, v165, v165 row_shr:2 row_mask:0xf bank_mask:0xf bound_ctrl:1
	v_add_f32_dpp v162, v162, v162 row_shr:4 row_mask:0xf bank_mask:0xf bound_ctrl:1
	v_add_f32_dpp v163, v163, v163 row_shr:4 row_mask:0xf bank_mask:0xf bound_ctrl:1
	v_add_f32_dpp v164, v164, v164 row_shr:4 row_mask:0xf bank_mask:0xf bound_ctrl:1
	v_add_f32_dpp v165, v165, v165 row_shr:4 row_mask:0xf bank_mask:0xf bound_ctrl:1
	v_add_f32_dpp v162, v162, v162 row_shr:8 row_mask:0xf bank_mask:0xf bound_ctrl:1
	v_add_f32_dpp v163, v163, v163 row_shr:8 row_mask:0xf bank_mask:0xf bound_ctrl:1
	v_add_f32_dpp v164, v164, v164 row_shr:8 row_mask:0xf bank_mask:0xf bound_ctrl:1
	v_add_f32_dpp v165, v165, v165 row_shr:8 row_mask:0xf bank_mask:0xf bound_ctrl:1
	v_add_f32_dpp v162, v162, v162 row_bcast:15 row_mask:0xa bank_mask:0xf
	v_add_f32_dpp v163, v163, v163 row_bcast:15 row_mask:0xa bank_mask:0xf
	v_add_f32_dpp v164, v164, v164 row_bcast:15 row_mask:0xa bank_mask:0xf
	v_add_f32_dpp v165, v165, v165 row_bcast:15 row_mask:0xa bank_mask:0xf
	s_mov_b64 s[98:99], exec
	s_mov_b32 exec_lo, 0x80000000
	s_mov_b32 exec_hi, 0x80000000
	ds_write_b32 v74, v162 offset:64
	ds_write_b32 v74, v163 offset:72
	ds_write_b32 v74, v164 offset:80
	ds_write_b32 v74, v165 offset:88
	s_mov_b64 exec, s[98:99]
	v_readlane_b32 s54, v90, 40
	v_readlane_b32 s55, v90, 41
	s_mul_i32 s0, s54, 0x300
	s_mul_i32 s1, s55, 0x300
	v_add_u32_e32 v167, s0, v195
	s_and_saveexec_b64 s[98:99], s[40:41]
	v_add_u32_e32 v167, s1, v195
	s_mov_b64 exec, s[98:99]
	s_waitcnt vmcnt(14)
; __device__ void peer_gather_phase(const Params& P, int l, bool do_store) {
;     ...
;         v6u_t qv; qv[0] = u6[3 * pr].x; qv[1] = u6[3 * pr].y; qv[2] = u6[3 * pr + 1].x; qv[3] = u6[3 * pr + 1].y; qv[4] = u6[3 * pr + 2].x; qv[5] = u6[3 * pr + 2].y;
;         const v32f_t wv = __builtin_amdgcn_cvt_scalef32_pk32_f32_fp6(qv, 1.0f);
;         f32x2 a2 = f32x2{0.f, 0.f};
; #pragma unroll
;         for (int i = 0; i < 16; ++i) a2 += f32x2{wv[2 * i], wv[2 * i + 1]} * xu[i];
;         float hs = a2.x + a2.y;
;         hs += dpp_row_shr(hs, 1); hs += dpp_row_shr(hs, 2); hs += dpp_row_shr(hs, 4); hs += dpp_row_shr(hs, 8);
;         hs += __builtin_bit_cast(float, __builtin_amdgcn_update_dpp(0, __builtin_bit_cast(int, hs), 0x142, 0xa, 0xf, false));
;         const float da = __builtin_bit_cast(float, __builtin_amdgcn_readlane(__builtin_bit_cast(int, hs), 31));
;         const float db = __builtin_bit_cast(float, __builtin_amdgcn_readlane(__builtin_bit_cast(int, hs), 63));
;         dvec = (lane == kb + 2 * pr) ? da : dvec;
;         dvec = (lane == kb + 2 * pr + 1) ? db : dvec;
	v_cvt_scalef32_pk32_f32_fp6 v[0:31], v[196:201], 1.0
	global_load_dwordx2 v[200:201], v167, s[62:63] offset:16
	global_load_dwordx4 v[196:199], v167, s[62:63]
	v_pk_mul_f32 v[246:247], v[0:1], v[96:97]
	v_pk_mul_f32 v[254:255], v[2:3], v[98:99]
	v_pk_mul_f32 v[160:161], v[4:5], v[100:101]
	v_pk_fma_f32 v[246:247], v[6:7], v[102:103], v[246:247]
	v_pk_fma_f32 v[254:255], v[8:9], v[104:105], v[254:255]
	v_pk_fma_f32 v[160:161], v[10:11], v[106:107], v[160:161]
	v_pk_fma_f32 v[246:247], v[12:13], v[108:109], v[246:247]
	v_pk_fma_f32 v[254:255], v[14:15], v[110:111], v[254:255]
	v_pk_fma_f32 v[160:161], v[16:17], v[112:113], v[160:161]
	v_pk_fma_f32 v[246:247], v[18:19], v[114:115], v[246:247]
	v_pk_fma_f32 v[254:255], v[20:21], v[116:117], v[254:255]
	v_pk_fma_f32 v[160:161], v[22:23], v[118:119], v[160:161]
	v_pk_fma_f32 v[246:247], v[24:25], v[120:121], v[246:247]
	v_pk_fma_f32 v[254:255], v[26:27], v[122:123], v[254:255]
	v_pk_fma_f32 v[160:161], v[28:29], v[124:125], v[160:161]
	v_pk_fma_f32 v[246:247], v[30:31], v[126:127], v[246:247]
	v_pk_add_f32 v[254:255], v[254:255], v[160:161]
	s_nop 0
	v_pk_add_f32 v[246:247], v[246:247], v[254:255]
	s_nop 0
	v_add_f32_e32 v162, v246, v247
	v_readlane_b32 s54, v90, 42
	v_readlane_b32 s55, v90, 43
	s_mul_i32 s0, s54, 0x300
	s_mul_i32 s1, s55, 0x300
	v_add_u32_e32 v167, s0, v195
	s_and_saveexec_b64 s[98:99], s[40:41]
	v_add_u32_e32 v167, s1, v195
	s_mov_b64 exec, s[98:99]
	s_waitcnt vmcnt(14)
	v_cvt_scalef32_pk32_f32_fp6 v[0:31], v[228:233], 1.0
	global_load_dwordx2 v[232:233], v167, s[62:63] offset:16
	global_load_dwordx4 v[228:231], v167, s[62:63]
	v_pk_mul_f32 v[246:247], v[0:1], v[96:97]
	v_pk_mul_f32 v[254:255], v[2:3], v[98:99]
	v_pk_mul_f32 v[160:161], v[4:5], v[100:101]
	v_pk_fma_f32 v[246:247], v[6:7], v[102:103], v[246:247]
	v_pk_fma_f32 v[254:255], v[8:9], v[104:105], v[254:255]
	v_pk_fma_f32 v[160:161], v[10:11], v[106:107], v[160:161]
	v_pk_fma_f32 v[246:247], v[12:13], v[108:109], v[246:247]
	v_pk_fma_f32 v[254:255], v[14:15], v[110:111], v[254:255]
	v_pk_fma_f32 v[160:161], v[16:17], v[112:113], v[160:161]
	v_pk_fma_f32 v[246:247], v[18:19], v[114:115], v[246:247]
	v_pk_fma_f32 v[254:255], v[20:21], v[116:117], v[254:255]
	v_pk_fma_f32 v[160:161], v[22:23], v[118:119], v[160:161]
	v_pk_fma_f32 v[246:247], v[24:25], v[120:121], v[246:247]
	v_pk_fma_f32 v[254:255], v[26:27], v[122:123], v[254:255]
	v_pk_fma_f32 v[160:161], v[28:29], v[124:125], v[160:161]
	v_pk_fma_f32 v[246:247], v[30:31], v[126:127], v[246:247]
	v_pk_add_f32 v[254:255], v[254:255], v[160:161]
	s_nop 0
	v_pk_add_f32 v[246:247], v[246:247], v[254:255]
	s_nop 0
	v_add_f32_e32 v163, v246, v247
	v_readlane_b32 s54, v90, 44
	v_readlane_b32 s55, v90, 45
	s_mul_i32 s0, s54, 0x300
	s_mul_i32 s1, s55, 0x300
	v_add_u32_e32 v167, s0, v195
	s_and_saveexec_b64 s[98:99], s[40:41]
	v_add_u32_e32 v167, s1, v195
	s_mov_b64 exec, s[98:99]
	s_waitcnt vmcnt(14)
	v_cvt_scalef32_pk32_f32_fp6 v[0:31], v[234:239], 1.0
	global_load_dwordx2 v[238:239], v167, s[62:63] offset:16
	global_load_dwordx4 v[234:237], v167, s[62:63]
	v_pk_mul_f32 v[246:247], v[0:1], v[96:97]
	v_pk_mul_f32 v[254:255], v[2:3], v[98:99]
	v_pk_mul_f32 v[160:161], v[4:5], v[100:101]
	v_pk_fma_f32 v[246:247], v[6:7], v[102:103], v[246:247]
	v_pk_fma_f32 v[254:255], v[8:9], v[104:105], v[254:255]
	v_pk_fma_f32 v[160:161], v[10:11], v[106:107], v[160:161]
	v_pk_fma_f32 v[246:247], v[12:13], v[108:109], v[246:247]
	v_pk_fma_f32 v[254:255], v[14:15], v[110:111], v[254:255]
	v_pk_fma_f32 v[160:161], v[16:17], v[112:113], v[160:161]
	v_pk_fma_f32 v[246:247], v[18:19], v[114:115], v[246:247]
	v_pk_fma_f32 v[254:255], v[20:21], v[116:117], v[254:255]
	v_pk_fma_f32 v[160:161], v[22:23], v[118:119], v[160:161]
	v_pk_fma_f32 v[246:247], v[24:25], v[120:121], v[246:247]
	v_pk_fma_f32 v[254:255], v[26:27], v[122:123], v[254:255]
	v_pk_fma_f32 v[160:161], v[28:29], v[124:125], v[160:161]
	v_pk_fma_f32 v[246:247], v[30:31], v[126:127], v[246:247]
	v_pk_add_f32 v[254:255], v[254:255], v[160:161]
	s_nop 0
	v_pk_add_f32 v[246:247], v[246:247], v[254:255]
	s_nop 0
	v_add_f32_e32 v164, v246, v247
	v_readlane_b32 s54, v90, 46
	v_readlane_b32 s55, v90, 47
	s_mul_i32 s0, s54, 0x300
	s_mul_i32 s1, s55, 0x300
	v_add_u32_e32 v167, s0, v195
	s_and_saveexec_b64 s[98:99], s[40:41]
	v_add_u32_e32 v167, s1, v195
	s_mov_b64 exec, s[98:99]
	s_waitcnt vmcnt(14)
; __device__ void peer_gather_phase(const Params& P, int l, bool do_store) {
;     ...
;         v6u_t qv; qv[0] = u6[3 * pr].x; qv[1] = u6[3 * pr].y; qv[2] = u6[3 * pr + 1].x; qv[3] = u6[3 * pr + 1].y; qv[4] = u6[3 * pr + 2].x; qv[5] = u6[3 * pr + 2].y;
;         const v32f_t wv = __builtin_amdgcn_cvt_scalef32_pk32_f32_fp6(qv, 1.0f);
;         f32x2 a2 = f32x2{0.f, 0.f};
; #pragma unroll
;         for (int i = 0; i < 16; ++i) a2 += f32x2{wv[2 * i], wv[2 * i + 1]} * xu[i];
;         float hs = a2.x + a2.y;
;         hs += dpp_row_shr(hs, 1); hs += dpp_row_shr(hs, 2); hs += dpp_row_shr(hs, 4); hs += dpp_row_shr(hs, 8);
;         hs += __builtin_bit_cast(float, __builtin_amdgcn_update_dpp(0, __builtin_bit_cast(int, hs), 0x142, 0xa, 0xf, false));
;         const float da = __builtin_bit_cast(float, __builtin_amdgcn_readlane(__builtin_bit_cast(int, hs), 31));
;         const float db = __builtin_bit_cast(float, __builtin_amdgcn_readlane(__builtin_bit_cast(int, hs), 63));
;         dvec = (lane == kb + 2 * pr) ? da : dvec;
;         dvec = (lane == kb + 2 * pr + 1) ? db : dvec;
	v_cvt_scalef32_pk32_f32_fp6 v[0:31], v[240:245], 1.0
	global_load_dwordx2 v[244:245], v167, s[62:63] offset:16
	global_load_dwordx4 v[240:243], v167, s[62:63]
	v_pk_mul_f32 v[246:247], v[0:1], v[96:97]
	v_pk_mul_f32 v[254:255], v[2:3], v[98:99]
	v_pk_mul_f32 v[160:161], v[4:5], v[100:101]
	v_pk_fma_f32 v[246:247], v[6:7], v[102:103], v[246:247]
	v_pk_fma_f32 v[254:255], v[8:9], v[104:105], v[254:255]
	v_pk_fma_f32 v[160:161], v[10:11], v[106:107], v[160:161]
	v_pk_fma_f32 v[246:247], v[12:13], v[108:109], v[246:247]
	v_pk_fma_f32 v[254:255], v[14:15], v[110:111], v[254:255]
	v_pk_fma_f32 v[160:161], v[16:17], v[112:113], v[160:161]
	v_pk_fma_f32 v[246:247], v[18:19], v[114:115], v[246:247]
	v_pk_fma_f32 v[254:255], v[20:21], v[116:117], v[254:255]
	v_pk_fma_f32 v[160:161], v[22:23], v[118:119], v[160:161]
	v_pk_fma_f32 v[246:247], v[24:25], v[120:121], v[246:247]
	v_pk_fma_f32 v[254:255], v[26:27], v[122:123], v[254:255]
	v_pk_fma_f32 v[160:161], v[28:29], v[124:125], v[160:161]
	v_pk_fma_f32 v[246:247], v[30:31], v[126:127], v[246:247]
	v_pk_add_f32 v[254:255], v[254:255], v[160:161]
	s_nop 0
	v_pk_add_f32 v[246:247], v[246:247], v[254:255]
	s_nop 0
	v_add_f32_e32 v165, v246, v247
	v_add_f32_dpp v162, v162, v162 row_shr:1 row_mask:0xf bank_mask:0xf bound_ctrl:1
	v_add_f32_dpp v163, v163, v163 row_shr:1 row_mask:0xf bank_mask:0xf bound_ctrl:1
	v_add_f32_dpp v164, v164, v164 row_shr:1 row_mask:0xf bank_mask:0xf bound_ctrl:1
	v_add_f32_dpp v165, v165, v165 row_shr:1 row_mask:0xf bank_mask:0xf bound_ctrl:1
	v_add_f32_dpp v162, v162, v162 row_shr:2 row_mask:0xf bank_mask:0xf bound_ctrl:1
	v_add_f32_dpp v163, v163, v163 row_shr:2 row_mask:0xf bank_mask:0xf bound_ctrl:1
	v_add_f32_dpp v164, v164, v164 row_shr:2 row_mask:0xf bank_mask:0xf bound_ctrl:1
	v_add_f32_dpp v165, v165, v165 row_shr:2 row_mask:0xf bank_mask:0xf bound_ctrl:1
	v_add_f32_dpp v162, v162, v162 row_shr:4 row_mask:0xf bank_mask:0xf bound_ctrl:1
	v_add_f32_dpp v163, v163, v163 row_shr:4 row_mask:0xf bank_mask:0xf bound_ctrl:1
	v_add_f32_dpp v164, v164, v164 row_shr:4 row_mask:0xf bank_mask:0xf bound_ctrl:1
	v_add_f32_dpp v165, v165, v165 row_shr:4 row_mask:0xf bank_mask:0xf bound_ctrl:1
	v_add_f32_dpp v162, v162, v162 row_shr:8 row_mask:0xf bank_mask:0xf bound_ctrl:1
	v_add_f32_dpp v163, v163, v163 row_shr:8 row_mask:0xf bank_mask:0xf bound_ctrl:1
	v_add_f32_dpp v164, v164, v164 row_shr:8 row_mask:0xf bank_mask:0xf bound_ctrl:1
	v_add_f32_dpp v165, v165, v165 row_shr:8 row_mask:0xf bank_mask:0xf bound_ctrl:1
	v_add_f32_dpp v162, v162, v162 row_bcast:15 row_mask:0xa bank_mask:0xf
	v_add_f32_dpp v163, v163, v163 row_bcast:15 row_mask:0xa bank_mask:0xf
	v_add_f32_dpp v164, v164, v164 row_bcast:15 row_mask:0xa bank_mask:0xf
	v_add_f32_dpp v165, v165, v165 row_bcast:15 row_mask:0xa bank_mask:0xf
	s_mov_b64 s[98:99], exec
	s_mov_b32 exec_lo, 0x80000000
	s_mov_b32 exec_hi, 0x80000000
	ds_write_b32 v74, v162 offset:96
	ds_write_b32 v74, v163 offset:104
	ds_write_b32 v74, v164 offset:112
	ds_write_b32 v74, v165 offset:120
	s_mov_b64 exec, s[98:99]
	v_readlane_b32 s54, v90, 48
	v_readlane_b32 s55, v90, 49
	s_mul_i32 s0, s54, 0x300
	s_mul_i32 s1, s55, 0x300
	v_add_u32_e32 v167, s0, v195
	s_and_saveexec_b64 s[98:99], s[40:41]
	v_add_u32_e32 v167, s1, v195
	s_mov_b64 exec, s[98:99]
	s_waitcnt vmcnt(14)
	v_cvt_scalef32_pk32_f32_fp6 v[0:31], v[50:55], 1.0
	global_load_dwordx2 v[54:55], v167, s[62:63] offset:16
	global_load_dwordx4 v[50:53], v167, s[62:63]
	v_pk_mul_f32 v[246:247], v[0:1], v[96:97]
	v_pk_mul_f32 v[254:255], v[2:3], v[98:99]
	v_pk_mul_f32 v[160:161], v[4:5], v[100:101]
	v_pk_fma_f32 v[246:247], v[6:7], v[102:103], v[246:247]
	v_pk_fma_f32 v[254:255], v[8:9], v[104:105], v[254:255]
	v_pk_fma_f32 v[160:161], v[10:11], v[106:107], v[160:161]
	v_pk_fma_f32 v[246:247], v[12:13], v[108:109], v[246:247]
	v_pk_fma_f32 v[254:255], v[14:15], v[110:111], v[254:255]
	v_pk_fma_f32 v[160:161], v[16:17], v[112:113], v[160:161]
	v_pk_fma_f32 v[246:247], v[18:19], v[114:115], v[246:247]
	v_pk_fma_f32 v[254:255], v[20:21], v[116:117], v[254:255]
	v_pk_fma_f32 v[160:161], v[22:23], v[118:119], v[160:161]
	v_pk_fma_f32 v[246:247], v[24:25], v[120:121], v[246:247]
	v_pk_fma_f32 v[254:255], v[26:27], v[122:123], v[254:255]
	v_pk_fma_f32 v[160:161], v[28:29], v[124:125], v[160:161]
	v_pk_fma_f32 v[246:247], v[30:31], v[126:127], v[246:247]
	v_pk_add_f32 v[254:255], v[254:255], v[160:161]
	s_nop 0
	v_pk_add_f32 v[246:247], v[246:247], v[254:255]
	s_nop 0
	v_add_f32_e32 v162, v246, v247
	v_readlane_b32 s54, v90, 50
	v_readlane_b32 s55, v90, 51
	s_mul_i32 s0, s54, 0x300
	s_mul_i32 s1, s55, 0x300
	v_add_u32_e32 v167, s0, v195
	s_and_saveexec_b64 s[98:99], s[40:41]
	v_add_u32_e32 v167, s1, v195
	s_mov_b64 exec, s[98:99]
	s_waitcnt vmcnt(14)
	v_cvt_scalef32_pk32_f32_fp6 v[0:31], v[44:49], 1.0
	global_load_dwordx2 v[48:49], v167, s[62:63] offset:16
	global_load_dwordx4 v[44:47], v167, s[62:63]
	v_pk_mul_f32 v[246:247], v[0:1], v[96:97]
	v_pk_mul_f32 v[254:255], v[2:3], v[98:99]
	v_pk_mul_f32 v[160:161], v[4:5], v[100:101]
	v_pk_fma_f32 v[246:247], v[6:7], v[102:103], v[246:247]
	v_pk_fma_f32 v[254:255], v[8:9], v[104:105], v[254:255]
	v_pk_fma_f32 v[160:161], v[10:11], v[106:107], v[160:161]
	v_pk_fma_f32 v[246:247], v[12:13], v[108:109], v[246:247]
	v_pk_fma_f32 v[254:255], v[14:15], v[110:111], v[254:255]
	v_pk_fma_f32 v[160:161], v[16:17], v[112:113], v[160:161]
	v_pk_fma_f32 v[246:247], v[18:19], v[114:115], v[246:247]
	v_pk_fma_f32 v[254:255], v[20:21], v[116:117], v[254:255]
	v_pk_fma_f32 v[160:161], v[22:23], v[118:119], v[160:161]
	v_pk_fma_f32 v[246:247], v[24:25], v[120:121], v[246:247]
	v_pk_fma_f32 v[254:255], v[26:27], v[122:123], v[254:255]
	v_pk_fma_f32 v[160:161], v[28:29], v[124:125], v[160:161]
	v_pk_fma_f32 v[246:247], v[30:31], v[126:127], v[246:247]
	v_pk_add_f32 v[254:255], v[254:255], v[160:161]
	s_nop 0
	v_pk_add_f32 v[246:247], v[246:247], v[254:255]
	s_nop 0
	v_add_f32_e32 v163, v246, v247
	v_readlane_b32 s54, v90, 52
	v_readlane_b32 s55, v90, 53
	s_mul_i32 s0, s54, 0x300
	s_mul_i32 s1, s55, 0x300
	v_add_u32_e32 v167, s0, v195
	s_and_saveexec_b64 s[98:99], s[40:41]
	v_add_u32_e32 v167, s1, v195
	s_mov_b64 exec, s[98:99]
	s_waitcnt vmcnt(14)
; __device__ void peer_gather_phase(const Params& P, int l, bool do_store) {
;     ...
;         v6u_t qv; qv[0] = u6[3 * pr].x; qv[1] = u6[3 * pr].y; qv[2] = u6[3 * pr + 1].x; qv[3] = u6[3 * pr + 1].y; qv[4] = u6[3 * pr + 2].x; qv[5] = u6[3 * pr + 2].y;
;         const v32f_t wv = __builtin_amdgcn_cvt_scalef32_pk32_f32_fp6(qv, 1.0f);
;         f32x2 a2 = f32x2{0.f, 0.f};
; #pragma unroll
;         for (int i = 0; i < 16; ++i) a2 += f32x2{wv[2 * i], wv[2 * i + 1]} * xu[i];
;         float hs = a2.x + a2.y;
;         hs += dpp_row_shr(hs, 1); hs += dpp_row_shr(hs, 2); hs += dpp_row_shr(hs, 4); hs += dpp_row_shr(hs, 8);
;         hs += __builtin_bit_cast(float, __builtin_amdgcn_update_dpp(0, __builtin_bit_cast(int, hs), 0x142, 0xa, 0xf, false));
;         const float da = __builtin_bit_cast(float, __builtin_amdgcn_readlane(__builtin_bit_cast(int, hs), 31));
;         const float db = __builtin_bit_cast(float, __builtin_amdgcn_readlane(__builtin_bit_cast(int, hs), 63));
;         dvec = (lane == kb + 2 * pr) ? da : dvec;
;         dvec = (lane == kb + 2 * pr + 1) ? db : dvec;
	v_cvt_scalef32_pk32_f32_fp6 v[0:31], v[38:43], 1.0
	global_load_dwordx2 v[42:43], v167, s[62:63] offset:16
	global_load_dwordx4 v[38:41], v167, s[62:63]
	v_pk_mul_f32 v[246:247], v[0:1], v[96:97]
	v_pk_mul_f32 v[254:255], v[2:3], v[98:99]
	v_pk_mul_f32 v[160:161], v[4:5], v[100:101]
	v_pk_fma_f32 v[246:247], v[6:7], v[102:103], v[246:247]
	v_pk_fma_f32 v[254:255], v[8:9], v[104:105], v[254:255]
	v_pk_fma_f32 v[160:161], v[10:11], v[106:107], v[160:161]
	v_pk_fma_f32 v[246:247], v[12:13], v[108:109], v[246:247]
	v_pk_fma_f32 v[254:255], v[14:15], v[110:111], v[254:255]
	v_pk_fma_f32 v[160:161], v[16:17], v[112:113], v[160:161]
	v_pk_fma_f32 v[246:247], v[18:19], v[114:115], v[246:247]
	v_pk_fma_f32 v[254:255], v[20:21], v[116:117], v[254:255]
	v_pk_fma_f32 v[160:161], v[22:23], v[118:119], v[160:161]
	v_pk_fma_f32 v[246:247], v[24:25], v[120:121], v[246:247]
	v_pk_fma_f32 v[254:255], v[26:27], v[122:123], v[254:255]
	v_pk_fma_f32 v[160:161], v[28:29], v[124:125], v[160:161]
	v_pk_fma_f32 v[246:247], v[30:31], v[126:127], v[246:247]
	v_pk_add_f32 v[254:255], v[254:255], v[160:161]
	s_nop 0
	v_pk_add_f32 v[246:247], v[246:247], v[254:255]
	s_nop 0
	v_add_f32_e32 v164, v246, v247
	v_readlane_b32 s54, v90, 54
	v_readlane_b32 s55, v90, 55
	s_mul_i32 s0, s54, 0x300
	s_mul_i32 s1, s55, 0x300
	v_add_u32_e32 v167, s0, v195
	s_and_saveexec_b64 s[98:99], s[40:41]
	v_add_u32_e32 v167, s1, v195
	s_mov_b64 exec, s[98:99]
	s_waitcnt vmcnt(14)
	v_cvt_scalef32_pk32_f32_fp6 v[0:31], v[32:37], 1.0
	global_load_dwordx2 v[36:37], v167, s[62:63] offset:16
	global_load_dwordx4 v[32:35], v167, s[62:63]
	v_pk_mul_f32 v[246:247], v[0:1], v[96:97]
	v_pk_mul_f32 v[254:255], v[2:3], v[98:99]
	v_pk_mul_f32 v[160:161], v[4:5], v[100:101]
	v_pk_fma_f32 v[246:247], v[6:7], v[102:103], v[246:247]
	v_pk_fma_f32 v[254:255], v[8:9], v[104:105], v[254:255]
	v_pk_fma_f32 v[160:161], v[10:11], v[106:107], v[160:161]
	v_pk_fma_f32 v[246:247], v[12:13], v[108:109], v[246:247]
	v_pk_fma_f32 v[254:255], v[14:15], v[110:111], v[254:255]
	v_pk_fma_f32 v[160:161], v[16:17], v[112:113], v[160:161]
	v_pk_fma_f32 v[246:247], v[18:19], v[114:115], v[246:247]
	v_pk_fma_f32 v[254:255], v[20:21], v[116:117], v[254:255]
	v_pk_fma_f32 v[160:161], v[22:23], v[118:119], v[160:161]
	v_pk_fma_f32 v[246:247], v[24:25], v[120:121], v[246:247]
	v_pk_fma_f32 v[254:255], v[26:27], v[122:123], v[254:255]
	v_pk_fma_f32 v[160:161], v[28:29], v[124:125], v[160:161]
	v_pk_fma_f32 v[246:247], v[30:31], v[126:127], v[246:247]
	v_pk_add_f32 v[254:255], v[254:255], v[160:161]
	s_nop 0
	v_pk_add_f32 v[246:247], v[246:247], v[254:255]
	s_nop 0
	v_add_f32_e32 v165, v246, v247
	v_add_f32_dpp v162, v162, v162 row_shr:1 row_mask:0xf bank_mask:0xf bound_ctrl:1
	v_add_f32_dpp v163, v163, v163 row_shr:1 row_mask:0xf bank_mask:0xf bound_ctrl:1
	v_add_f32_dpp v164, v164, v164 row_shr:1 row_mask:0xf bank_mask:0xf bound_ctrl:1
	v_add_f32_dpp v165, v165, v165 row_shr:1 row_mask:0xf bank_mask:0xf bound_ctrl:1
	v_add_f32_dpp v162, v162, v162 row_shr:2 row_mask:0xf bank_mask:0xf bound_ctrl:1
	v_add_f32_dpp v163, v163, v163 row_shr:2 row_mask:0xf bank_mask:0xf bound_ctrl:1
	v_add_f32_dpp v164, v164, v164 row_shr:2 row_mask:0xf bank_mask:0xf bound_ctrl:1
	v_add_f32_dpp v165, v165, v165 row_shr:2 row_mask:0xf bank_mask:0xf bound_ctrl:1
	v_add_f32_dpp v162, v162, v162 row_shr:4 row_mask:0xf bank_mask:0xf bound_ctrl:1
	v_add_f32_dpp v163, v163, v163 row_shr:4 row_mask:0xf bank_mask:0xf bound_ctrl:1
	v_add_f32_dpp v164, v164, v164 row_shr:4 row_mask:0xf bank_mask:0xf bound_ctrl:1
	v_add_f32_dpp v165, v165, v165 row_shr:4 row_mask:0xf bank_mask:0xf bound_ctrl:1
	v_add_f32_dpp v162, v162, v162 row_shr:8 row_mask:0xf bank_mask:0xf bound_ctrl:1
	v_add_f32_dpp v163, v163, v163 row_shr:8 row_mask:0xf bank_mask:0xf bound_ctrl:1
	v_add_f32_dpp v164, v164, v164 row_shr:8 row_mask:0xf bank_mask:0xf bound_ctrl:1
	v_add_f32_dpp v165, v165, v165 row_shr:8 row_mask:0xf bank_mask:0xf bound_ctrl:1
	v_add_f32_dpp v162, v162, v162 row_bcast:15 row_mask:0xa bank_mask:0xf
	v_add_f32_dpp v163, v163, v163 row_bcast:15 row_mask:0xa bank_mask:0xf
	v_add_f32_dpp v164, v164, v164 row_bcast:15 row_mask:0xa bank_mask:0xf
	v_add_f32_dpp v165, v165, v165 row_bcast:15 row_mask:0xa bank_mask:0xf
	s_mov_b64 s[98:99], exec
	s_mov_b32 exec_lo, 0x80000000
	s_mov_b32 exec_hi, 0x80000000
	ds_write_b32 v74, v162 offset:128
	ds_write_b32 v74, v163 offset:136
	ds_write_b32 v74, v164 offset:144
	ds_write_b32 v74, v165 offset:152
	s_mov_b64 exec, s[98:99]
	v_readlane_b32 s54, v90, 56
	v_readlane_b32 s55, v90, 57
	s_mul_i32 s0, s54, 0x300
	s_mul_i32 s1, s55, 0x300
	v_add_u32_e32 v167, s0, v195
	s_and_saveexec_b64 s[98:99], s[40:41]
	v_add_u32_e32 v167, s1, v195
	s_mov_b64 exec, s[98:99]
	s_waitcnt vmcnt(14)
	v_cvt_scalef32_pk32_f32_fp6 v[0:31], v[196:201], 1.0
	global_load_dwordx2 v[200:201], v167, s[62:63] offset:16
	global_load_dwordx4 v[196:199], v167, s[62:63]
	v_pk_mul_f32 v[246:247], v[0:1], v[96:97]
	v_pk_mul_f32 v[254:255], v[2:3], v[98:99]
	v_pk_mul_f32 v[160:161], v[4:5], v[100:101]
	v_pk_fma_f32 v[246:247], v[6:7], v[102:103], v[246:247]
	v_pk_fma_f32 v[254:255], v[8:9], v[104:105], v[254:255]
	v_pk_fma_f32 v[160:161], v[10:11], v[106:107], v[160:161]
	v_pk_fma_f32 v[246:247], v[12:13], v[108:109], v[246:247]
	v_pk_fma_f32 v[254:255], v[14:15], v[110:111], v[254:255]
	v_pk_fma_f32 v[160:161], v[16:17], v[112:113], v[160:161]
	v_pk_fma_f32 v[246:247], v[18:19], v[114:115], v[246:247]
	v_pk_fma_f32 v[254:255], v[20:21], v[116:117], v[254:255]
	v_pk_fma_f32 v[160:161], v[22:23], v[118:119], v[160:161]
	v_pk_fma_f32 v[246:247], v[24:25], v[120:121], v[246:247]
	v_pk_fma_f32 v[254:255], v[26:27], v[122:123], v[254:255]
	v_pk_fma_f32 v[160:161], v[28:29], v[124:125], v[160:161]
	v_pk_fma_f32 v[246:247], v[30:31], v[126:127], v[246:247]
	v_pk_add_f32 v[254:255], v[254:255], v[160:161]
	s_nop 0
	v_pk_add_f32 v[246:247], v[246:247], v[254:255]
	s_nop 0
	v_add_f32_e32 v162, v246, v247
	v_readlane_b32 s54, v90, 58
	v_readlane_b32 s55, v90, 59
	s_mul_i32 s0, s54, 0x300
	s_mul_i32 s1, s55, 0x300
	v_add_u32_e32 v167, s0, v195
	s_and_saveexec_b64 s[98:99], s[40:41]
	v_add_u32_e32 v167, s1, v195
	s_mov_b64 exec, s[98:99]
	s_waitcnt vmcnt(14)
; __device__ void peer_gather_phase(const Params& P, int l, bool do_store) {
;     ...
;         v6u_t qv; qv[0] = u6[3 * pr].x; qv[1] = u6[3 * pr].y; qv[2] = u6[3 * pr + 1].x; qv[3] = u6[3 * pr + 1].y; qv[4] = u6[3 * pr + 2].x; qv[5] = u6[3 * pr + 2].y;
;         const v32f_t wv = __builtin_amdgcn_cvt_scalef32_pk32_f32_fp6(qv, 1.0f);
;         f32x2 a2 = f32x2{0.f, 0.f};
; #pragma unroll
;         for (int i = 0; i < 16; ++i) a2 += f32x2{wv[2 * i], wv[2 * i + 1]} * xu[i];
;         float hs = a2.x + a2.y;
;         hs += dpp_row_shr(hs, 1); hs += dpp_row_shr(hs, 2); hs += dpp_row_shr(hs, 4); hs += dpp_row_shr(hs, 8);
;         hs += __builtin_bit_cast(float, __builtin_amdgcn_update_dpp(0, __builtin_bit_cast(int, hs), 0x142, 0xa, 0xf, false));
;         const float da = __builtin_bit_cast(float, __builtin_amdgcn_readlane(__builtin_bit_cast(int, hs), 31));
;         const float db = __builtin_bit_cast(float, __builtin_amdgcn_readlane(__builtin_bit_cast(int, hs), 63));
;         dvec = (lane == kb + 2 * pr) ? da : dvec;
;         dvec = (lane == kb + 2 * pr + 1) ? db : dvec;
	v_cvt_scalef32_pk32_f32_fp6 v[0:31], v[228:233], 1.0
	global_load_dwordx2 v[232:233], v167, s[62:63] offset:16
	global_load_dwordx4 v[228:231], v167, s[62:63]
	v_pk_mul_f32 v[246:247], v[0:1], v[96:97]
	v_pk_mul_f32 v[254:255], v[2:3], v[98:99]
	v_pk_mul_f32 v[160:161], v[4:5], v[100:101]
	v_pk_fma_f32 v[246:247], v[6:7], v[102:103], v[246:247]
	v_pk_fma_f32 v[254:255], v[8:9], v[104:105], v[254:255]
	v_pk_fma_f32 v[160:161], v[10:11], v[106:107], v[160:161]
	v_pk_fma_f32 v[246:247], v[12:13], v[108:109], v[246:247]
	v_pk_fma_f32 v[254:255], v[14:15], v[110:111], v[254:255]
	v_pk_fma_f32 v[160:161], v[16:17], v[112:113], v[160:161]
	v_pk_fma_f32 v[246:247], v[18:19], v[114:115], v[246:247]
	v_pk_fma_f32 v[254:255], v[20:21], v[116:117], v[254:255]
	v_pk_fma_f32 v[160:161], v[22:23], v[118:119], v[160:161]
	v_pk_fma_f32 v[246:247], v[24:25], v[120:121], v[246:247]
	v_pk_fma_f32 v[254:255], v[26:27], v[122:123], v[254:255]
	v_pk_fma_f32 v[160:161], v[28:29], v[124:125], v[160:161]
	v_pk_fma_f32 v[246:247], v[30:31], v[126:127], v[246:247]
	v_pk_add_f32 v[254:255], v[254:255], v[160:161]
	s_nop 0
	v_pk_add_f32 v[246:247], v[246:247], v[254:255]
	s_nop 0
	v_add_f32_e32 v163, v246, v247
	v_readlane_b32 s54, v90, 60
	v_readlane_b32 s55, v90, 61
	s_mul_i32 s0, s54, 0x300
	s_mul_i32 s1, s55, 0x300
	v_add_u32_e32 v167, s0, v195
	s_and_saveexec_b64 s[98:99], s[40:41]
	v_add_u32_e32 v167, s1, v195
	s_mov_b64 exec, s[98:99]
	s_waitcnt vmcnt(14)
	v_cvt_scalef32_pk32_f32_fp6 v[0:31], v[234:239], 1.0
	global_load_dwordx2 v[238:239], v167, s[62:63] offset:16
	global_load_dwordx4 v[234:237], v167, s[62:63]
	v_pk_mul_f32 v[246:247], v[0:1], v[96:97]
	v_pk_mul_f32 v[254:255], v[2:3], v[98:99]
	v_pk_mul_f32 v[160:161], v[4:5], v[100:101]
	v_pk_fma_f32 v[246:247], v[6:7], v[102:103], v[246:247]
	v_pk_fma_f32 v[254:255], v[8:9], v[104:105], v[254:255]
	v_pk_fma_f32 v[160:161], v[10:11], v[106:107], v[160:161]
	v_pk_fma_f32 v[246:247], v[12:13], v[108:109], v[246:247]
	v_pk_fma_f32 v[254:255], v[14:15], v[110:111], v[254:255]
	v_pk_fma_f32 v[160:161], v[16:17], v[112:113], v[160:161]
	v_pk_fma_f32 v[246:247], v[18:19], v[114:115], v[246:247]
	v_pk_fma_f32 v[254:255], v[20:21], v[116:117], v[254:255]
	v_pk_fma_f32 v[160:161], v[22:23], v[118:119], v[160:161]
	v_pk_fma_f32 v[246:247], v[24:25], v[120:121], v[246:247]
	v_pk_fma_f32 v[254:255], v[26:27], v[122:123], v[254:255]
	v_pk_fma_f32 v[160:161], v[28:29], v[124:125], v[160:161]
	v_pk_fma_f32 v[246:247], v[30:31], v[126:127], v[246:247]
	v_pk_add_f32 v[254:255], v[254:255], v[160:161]
	s_nop 0
	v_pk_add_f32 v[246:247], v[246:247], v[254:255]
	s_nop 0
	v_add_f32_e32 v164, v246, v247
	v_readlane_b32 s54, v90, 62
	v_readlane_b32 s55, v90, 63
	s_mul_i32 s0, s54, 0x300
	s_mul_i32 s1, s55, 0x300
	v_add_u32_e32 v167, s0, v195
	s_and_saveexec_b64 s[98:99], s[40:41]
	v_add_u32_e32 v167, s1, v195
	s_mov_b64 exec, s[98:99]
	s_waitcnt vmcnt(14)
	v_cvt_scalef32_pk32_f32_fp6 v[0:31], v[240:245], 1.0
	global_load_dwordx2 v[244:245], v167, s[62:63] offset:16
	global_load_dwordx4 v[240:243], v167, s[62:63]
	v_pk_mul_f32 v[246:247], v[0:1], v[96:97]
	v_pk_mul_f32 v[254:255], v[2:3], v[98:99]
	v_pk_mul_f32 v[160:161], v[4:5], v[100:101]
	v_pk_fma_f32 v[246:247], v[6:7], v[102:103], v[246:247]
	v_pk_fma_f32 v[254:255], v[8:9], v[104:105], v[254:255]
	v_pk_fma_f32 v[160:161], v[10:11], v[106:107], v[160:161]
	v_pk_fma_f32 v[246:247], v[12:13], v[108:109], v[246:247]
	v_pk_fma_f32 v[254:255], v[14:15], v[110:111], v[254:255]
	v_pk_fma_f32 v[160:161], v[16:17], v[112:113], v[160:161]
	v_pk_fma_f32 v[246:247], v[18:19], v[114:115], v[246:247]
	v_pk_fma_f32 v[254:255], v[20:21], v[116:117], v[254:255]
	v_pk_fma_f32 v[160:161], v[22:23], v[118:119], v[160:161]
	v_pk_fma_f32 v[246:247], v[24:25], v[120:121], v[246:247]
	v_pk_fma_f32 v[254:255], v[26:27], v[122:123], v[254:255]
	v_pk_fma_f32 v[160:161], v[28:29], v[124:125], v[160:161]
	v_pk_fma_f32 v[246:247], v[30:31], v[126:127], v[246:247]
	v_pk_add_f32 v[254:255], v[254:255], v[160:161]
	s_nop 0
	v_pk_add_f32 v[246:247], v[246:247], v[254:255]
	s_nop 0
	v_add_f32_e32 v165, v246, v247
	v_add_f32_dpp v162, v162, v162 row_shr:1 row_mask:0xf bank_mask:0xf bound_ctrl:1
	v_add_f32_dpp v163, v163, v163 row_shr:1 row_mask:0xf bank_mask:0xf bound_ctrl:1
	v_add_f32_dpp v164, v164, v164 row_shr:1 row_mask:0xf bank_mask:0xf bound_ctrl:1
	v_add_f32_dpp v165, v165, v165 row_shr:1 row_mask:0xf bank_mask:0xf bound_ctrl:1
	v_add_f32_dpp v162, v162, v162 row_shr:2 row_mask:0xf bank_mask:0xf bound_ctrl:1
	v_add_f32_dpp v163, v163, v163 row_shr:2 row_mask:0xf bank_mask:0xf bound_ctrl:1
	v_add_f32_dpp v164, v164, v164 row_shr:2 row_mask:0xf bank_mask:0xf bound_ctrl:1
	v_add_f32_dpp v165, v165, v165 row_shr:2 row_mask:0xf bank_mask:0xf bound_ctrl:1
	v_add_f32_dpp v162, v162, v162 row_shr:4 row_mask:0xf bank_mask:0xf bound_ctrl:1
	v_add_f32_dpp v163, v163, v163 row_shr:4 row_mask:0xf bank_mask:0xf bound_ctrl:1
	v_add_f32_dpp v164, v164, v164 row_shr:4 row_mask:0xf bank_mask:0xf bound_ctrl:1
	v_add_f32_dpp v165, v165, v165 row_shr:4 row_mask:0xf bank_mask:0xf bound_ctrl:1
	v_add_f32_dpp v162, v162, v162 row_shr:8 row_mask:0xf bank_mask:0xf bound_ctrl:1
	v_add_f32_dpp v163, v163, v163 row_shr:8 row_mask:0xf bank_mask:0xf bound_ctrl:1
	v_add_f32_dpp v164, v164, v164 row_shr:8 row_mask:0xf bank_mask:0xf bound_ctrl:1
	v_add_f32_dpp v165, v165, v165 row_shr:8 row_mask:0xf bank_mask:0xf bound_ctrl:1
	v_add_f32_dpp v162, v162, v162 row_bcast:15 row_mask:0xa bank_mask:0xf
	v_add_f32_dpp v163, v163, v163 row_bcast:15 row_mask:0xa bank_mask:0xf
	v_add_f32_dpp v164, v164, v164 row_bcast:15 row_mask:0xa bank_mask:0xf
	v_add_f32_dpp v165, v165, v165 row_bcast:15 row_mask:0xa bank_mask:0xf
	s_mov_b64 s[98:99], exec
	s_mov_b32 exec_lo, 0x80000000
	s_mov_b32 exec_hi, 0x80000000
	ds_write_b32 v74, v162 offset:160
	ds_write_b32 v74, v163 offset:168
	ds_write_b32 v74, v164 offset:176
	ds_write_b32 v74, v165 offset:184
	s_mov_b64 exec, s[98:99]
	s_waitcnt vmcnt(14)
; __device__ void peer_gather_phase(const Params& P, int l, bool do_store) {
;     ...
;         v6u_t qv; qv[0] = u6[3 * pr].x; qv[1] = u6[3 * pr].y; qv[2] = u6[3 * pr + 1].x; qv[3] = u6[3 * pr + 1].y; qv[4] = u6[3 * pr + 2].x; qv[5] = u6[3 * pr + 2].y;
;         const v32f_t wv = __builtin_amdgcn_cvt_scalef32_pk32_f32_fp6(qv, 1.0f);
;         f32x2 a2 = f32x2{0.f, 0.f};
; #pragma unroll
;         for (int i = 0; i < 16; ++i) a2 += f32x2{wv[2 * i], wv[2 * i + 1]} * xu[i];
;         float hs = a2.x + a2.y;
;         hs += dpp_row_shr(hs, 1); hs += dpp_row_shr(hs, 2); hs += dpp_row_shr(hs, 4); hs += dpp_row_shr(hs, 8);
;         hs += __builtin_bit_cast(float, __builtin_amdgcn_update_dpp(0, __builtin_bit_cast(int, hs), 0x142, 0xa, 0xf, false));
;         const float da = __builtin_bit_cast(float, __builtin_amdgcn_readlane(__builtin_bit_cast(int, hs), 31));
;         const float db = __builtin_bit_cast(float, __builtin_amdgcn_readlane(__builtin_bit_cast(int, hs), 63));
;         dvec = (lane == kb + 2 * pr) ? da : dvec;
;         dvec = (lane == kb + 2 * pr + 1) ? db : dvec;
	v_cvt_scalef32_pk32_f32_fp6 v[0:31], v[50:55], 1.0
	v_pk_mul_f32 v[246:247], v[0:1], v[96:97]
	v_pk_mul_f32 v[254:255], v[2:3], v[98:99]
	v_pk_mul_f32 v[160:161], v[4:5], v[100:101]
	v_pk_fma_f32 v[246:247], v[6:7], v[102:103], v[246:247]
	v_pk_fma_f32 v[254:255], v[8:9], v[104:105], v[254:255]
	v_pk_fma_f32 v[160:161], v[10:11], v[106:107], v[160:161]
	v_pk_fma_f32 v[246:247], v[12:13], v[108:109], v[246:247]
	v_pk_fma_f32 v[254:255], v[14:15], v[110:111], v[254:255]
	v_pk_fma_f32 v[160:161], v[16:17], v[112:113], v[160:161]
	v_pk_fma_f32 v[246:247], v[18:19], v[114:115], v[246:247]
	v_pk_fma_f32 v[254:255], v[20:21], v[116:117], v[254:255]
	v_pk_fma_f32 v[160:161], v[22:23], v[118:119], v[160:161]
	v_pk_fma_f32 v[246:247], v[24:25], v[120:121], v[246:247]
	v_pk_fma_f32 v[254:255], v[26:27], v[122:123], v[254:255]
	v_pk_fma_f32 v[160:161], v[28:29], v[124:125], v[160:161]
	v_pk_fma_f32 v[246:247], v[30:31], v[126:127], v[246:247]
	v_pk_add_f32 v[254:255], v[254:255], v[160:161]
	s_nop 0
	v_pk_add_f32 v[246:247], v[246:247], v[254:255]
	s_nop 0
	v_add_f32_e32 v162, v246, v247
	s_waitcnt vmcnt(12)
	v_cvt_scalef32_pk32_f32_fp6 v[0:31], v[44:49], 1.0
	v_pk_mul_f32 v[246:247], v[0:1], v[96:97]
	v_pk_mul_f32 v[254:255], v[2:3], v[98:99]
	v_pk_mul_f32 v[160:161], v[4:5], v[100:101]
	v_pk_fma_f32 v[246:247], v[6:7], v[102:103], v[246:247]
	v_pk_fma_f32 v[254:255], v[8:9], v[104:105], v[254:255]
	v_pk_fma_f32 v[160:161], v[10:11], v[106:107], v[160:161]
	v_pk_fma_f32 v[246:247], v[12:13], v[108:109], v[246:247]
	v_pk_fma_f32 v[254:255], v[14:15], v[110:111], v[254:255]
	v_pk_fma_f32 v[160:161], v[16:17], v[112:113], v[160:161]
	v_pk_fma_f32 v[246:247], v[18:19], v[114:115], v[246:247]
	v_pk_fma_f32 v[254:255], v[20:21], v[116:117], v[254:255]
	v_pk_fma_f32 v[160:161], v[22:23], v[118:119], v[160:161]
	v_pk_fma_f32 v[246:247], v[24:25], v[120:121], v[246:247]
	v_pk_fma_f32 v[254:255], v[26:27], v[122:123], v[254:255]
	v_pk_fma_f32 v[160:161], v[28:29], v[124:125], v[160:161]
	v_pk_fma_f32 v[246:247], v[30:31], v[126:127], v[246:247]
	v_pk_add_f32 v[254:255], v[254:255], v[160:161]
	s_nop 0
	v_pk_add_f32 v[246:247], v[246:247], v[254:255]
	s_nop 0
	v_add_f32_e32 v163, v246, v247
	s_waitcnt vmcnt(10)
	v_cvt_scalef32_pk32_f32_fp6 v[0:31], v[38:43], 1.0
	v_pk_mul_f32 v[246:247], v[0:1], v[96:97]
	v_pk_mul_f32 v[254:255], v[2:3], v[98:99]
	v_pk_mul_f32 v[160:161], v[4:5], v[100:101]
	v_pk_fma_f32 v[246:247], v[6:7], v[102:103], v[246:247]
	v_pk_fma_f32 v[254:255], v[8:9], v[104:105], v[254:255]
	v_pk_fma_f32 v[160:161], v[10:11], v[106:107], v[160:161]
	v_pk_fma_f32 v[246:247], v[12:13], v[108:109], v[246:247]
	v_pk_fma_f32 v[254:255], v[14:15], v[110:111], v[254:255]
	v_pk_fma_f32 v[160:161], v[16:17], v[112:113], v[160:161]
	v_pk_fma_f32 v[246:247], v[18:19], v[114:115], v[246:247]
	v_pk_fma_f32 v[254:255], v[20:21], v[116:117], v[254:255]
	v_pk_fma_f32 v[160:161], v[22:23], v[118:119], v[160:161]
	v_pk_fma_f32 v[246:247], v[24:25], v[120:121], v[246:247]
	v_pk_fma_f32 v[254:255], v[26:27], v[122:123], v[254:255]
	v_pk_fma_f32 v[160:161], v[28:29], v[124:125], v[160:161]
	v_pk_fma_f32 v[246:247], v[30:31], v[126:127], v[246:247]
	v_pk_add_f32 v[254:255], v[254:255], v[160:161]
	s_nop 0
	v_pk_add_f32 v[246:247], v[246:247], v[254:255]
	s_nop 0
	v_add_f32_e32 v164, v246, v247
	s_waitcnt vmcnt(8)
	v_cvt_scalef32_pk32_f32_fp6 v[0:31], v[32:37], 1.0
	v_pk_mul_f32 v[246:247], v[0:1], v[96:97]
	v_pk_mul_f32 v[254:255], v[2:3], v[98:99]
	v_pk_mul_f32 v[160:161], v[4:5], v[100:101]
	v_pk_fma_f32 v[246:247], v[6:7], v[102:103], v[246:247]
	v_pk_fma_f32 v[254:255], v[8:9], v[104:105], v[254:255]
	v_pk_fma_f32 v[160:161], v[10:11], v[106:107], v[160:161]
	v_pk_fma_f32 v[246:247], v[12:13], v[108:109], v[246:247]
	v_pk_fma_f32 v[254:255], v[14:15], v[110:111], v[254:255]
	v_pk_fma_f32 v[160:161], v[16:17], v[112:113], v[160:161]
	v_pk_fma_f32 v[246:247], v[18:19], v[114:115], v[246:247]
	v_pk_fma_f32 v[254:255], v[20:21], v[116:117], v[254:255]
	v_pk_fma_f32 v[160:161], v[22:23], v[118:119], v[160:161]
	v_pk_fma_f32 v[246:247], v[24:25], v[120:121], v[246:247]
	v_pk_fma_f32 v[254:255], v[26:27], v[122:123], v[254:255]
	v_pk_fma_f32 v[160:161], v[28:29], v[124:125], v[160:161]
	v_pk_fma_f32 v[246:247], v[30:31], v[126:127], v[246:247]
	v_pk_add_f32 v[254:255], v[254:255], v[160:161]
	s_nop 0
	v_pk_add_f32 v[246:247], v[246:247], v[254:255]
	s_nop 0
	v_add_f32_e32 v165, v246, v247
	v_add_f32_dpp v162, v162, v162 row_shr:1 row_mask:0xf bank_mask:0xf bound_ctrl:1
	v_add_f32_dpp v163, v163, v163 row_shr:1 row_mask:0xf bank_mask:0xf bound_ctrl:1
	v_add_f32_dpp v164, v164, v164 row_shr:1 row_mask:0xf bank_mask:0xf bound_ctrl:1
	v_add_f32_dpp v165, v165, v165 row_shr:1 row_mask:0xf bank_mask:0xf bound_ctrl:1
	v_add_f32_dpp v162, v162, v162 row_shr:2 row_mask:0xf bank_mask:0xf bound_ctrl:1
	v_add_f32_dpp v163, v163, v163 row_shr:2 row_mask:0xf bank_mask:0xf bound_ctrl:1
	v_add_f32_dpp v164, v164, v164 row_shr:2 row_mask:0xf bank_mask:0xf bound_ctrl:1
	v_add_f32_dpp v165, v165, v165 row_shr:2 row_mask:0xf bank_mask:0xf bound_ctrl:1
	v_add_f32_dpp v162, v162, v162 row_shr:4 row_mask:0xf bank_mask:0xf bound_ctrl:1
	v_add_f32_dpp v163, v163, v163 row_shr:4 row_mask:0xf bank_mask:0xf bound_ctrl:1
	v_add_f32_dpp v164, v164, v164 row_shr:4 row_mask:0xf bank_mask:0xf bound_ctrl:1
	v_add_f32_dpp v165, v165, v165 row_shr:4 row_mask:0xf bank_mask:0xf bound_ctrl:1
	v_add_f32_dpp v162, v162, v162 row_shr:8 row_mask:0xf bank_mask:0xf bound_ctrl:1
	v_add_f32_dpp v163, v163, v163 row_shr:8 row_mask:0xf bank_mask:0xf bound_ctrl:1
	v_add_f32_dpp v164, v164, v164 row_shr:8 row_mask:0xf bank_mask:0xf bound_ctrl:1
	v_add_f32_dpp v165, v165, v165 row_shr:8 row_mask:0xf bank_mask:0xf bound_ctrl:1
	v_add_f32_dpp v162, v162, v162 row_bcast:15 row_mask:0xa bank_mask:0xf
	v_add_f32_dpp v163, v163, v163 row_bcast:15 row_mask:0xa bank_mask:0xf
	v_add_f32_dpp v164, v164, v164 row_bcast:15 row_mask:0xa bank_mask:0xf
	v_add_f32_dpp v165, v165, v165 row_bcast:15 row_mask:0xa bank_mask:0xf
	s_mov_b64 s[98:99], exec
	s_mov_b32 exec_lo, 0x80000000
	s_mov_b32 exec_hi, 0x80000000
	ds_write_b32 v74, v162 offset:192
	ds_write_b32 v74, v163 offset:200
	ds_write_b32 v74, v164 offset:208
	ds_write_b32 v74, v165 offset:216
	s_mov_b64 exec, s[98:99]
	s_waitcnt vmcnt(6)
; __device__ void peer_gather_phase(const Params& P, int l, bool do_store) {
;     ...
;         v6u_t qv; qv[0] = u6[3 * pr].x; qv[1] = u6[3 * pr].y; qv[2] = u6[3 * pr + 1].x; qv[3] = u6[3 * pr + 1].y; qv[4] = u6[3 * pr + 2].x; qv[5] = u6[3 * pr + 2].y;
;         const v32f_t wv = __builtin_amdgcn_cvt_scalef32_pk32_f32_fp6(qv, 1.0f);
;         f32x2 a2 = f32x2{0.f, 0.f};
; #pragma unroll
;         for (int i = 0; i < 16; ++i) a2 += f32x2{wv[2 * i], wv[2 * i + 1]} * xu[i];
;         float hs = a2.x + a2.y;
;         hs += dpp_row_shr(hs, 1); hs += dpp_row_shr(hs, 2); hs += dpp_row_shr(hs, 4); hs += dpp_row_shr(hs, 8);
;         hs += __builtin_bit_cast(float, __builtin_amdgcn_update_dpp(0, __builtin_bit_cast(int, hs), 0x142, 0xa, 0xf, false));
;         const float da = __builtin_bit_cast(float, __builtin_amdgcn_readlane(__builtin_bit_cast(int, hs), 31));
;         const float db = __builtin_bit_cast(float, __builtin_amdgcn_readlane(__builtin_bit_cast(int, hs), 63));
;         dvec = (lane == kb + 2 * pr) ? da : dvec;
;         dvec = (lane == kb + 2 * pr + 1) ? db : dvec;
;       }
	v_cvt_scalef32_pk32_f32_fp6 v[0:31], v[196:201], 1.0
	v_pk_mul_f32 v[246:247], v[0:1], v[96:97]
	v_pk_mul_f32 v[254:255], v[2:3], v[98:99]
	v_pk_mul_f32 v[160:161], v[4:5], v[100:101]
	v_pk_fma_f32 v[246:247], v[6:7], v[102:103], v[246:247]
	v_pk_fma_f32 v[254:255], v[8:9], v[104:105], v[254:255]
	v_pk_fma_f32 v[160:161], v[10:11], v[106:107], v[160:161]
	v_pk_fma_f32 v[246:247], v[12:13], v[108:109], v[246:247]
	v_pk_fma_f32 v[254:255], v[14:15], v[110:111], v[254:255]
	v_pk_fma_f32 v[160:161], v[16:17], v[112:113], v[160:161]
	v_pk_fma_f32 v[246:247], v[18:19], v[114:115], v[246:247]
	v_pk_fma_f32 v[254:255], v[20:21], v[116:117], v[254:255]
	v_pk_fma_f32 v[160:161], v[22:23], v[118:119], v[160:161]
	v_pk_fma_f32 v[246:247], v[24:25], v[120:121], v[246:247]
	v_pk_fma_f32 v[254:255], v[26:27], v[122:123], v[254:255]
	v_pk_fma_f32 v[160:161], v[28:29], v[124:125], v[160:161]
	v_pk_fma_f32 v[246:247], v[30:31], v[126:127], v[246:247]
	v_pk_add_f32 v[254:255], v[254:255], v[160:161]
	s_nop 0
	v_pk_add_f32 v[246:247], v[246:247], v[254:255]
	s_nop 0
	v_add_f32_e32 v162, v246, v247
	s_waitcnt vmcnt(4)
	v_cvt_scalef32_pk32_f32_fp6 v[0:31], v[228:233], 1.0
	v_pk_mul_f32 v[246:247], v[0:1], v[96:97]
	v_pk_mul_f32 v[254:255], v[2:3], v[98:99]
	v_pk_mul_f32 v[160:161], v[4:5], v[100:101]
	v_pk_fma_f32 v[246:247], v[6:7], v[102:103], v[246:247]
	v_pk_fma_f32 v[254:255], v[8:9], v[104:105], v[254:255]
	v_pk_fma_f32 v[160:161], v[10:11], v[106:107], v[160:161]
	v_pk_fma_f32 v[246:247], v[12:13], v[108:109], v[246:247]
	v_pk_fma_f32 v[254:255], v[14:15], v[110:111], v[254:255]
	v_pk_fma_f32 v[160:161], v[16:17], v[112:113], v[160:161]
	v_pk_fma_f32 v[246:247], v[18:19], v[114:115], v[246:247]
	v_pk_fma_f32 v[254:255], v[20:21], v[116:117], v[254:255]
	v_pk_fma_f32 v[160:161], v[22:23], v[118:119], v[160:161]
	v_pk_fma_f32 v[246:247], v[24:25], v[120:121], v[246:247]
	v_pk_fma_f32 v[254:255], v[26:27], v[122:123], v[254:255]
	v_pk_fma_f32 v[160:161], v[28:29], v[124:125], v[160:161]
	v_pk_fma_f32 v[246:247], v[30:31], v[126:127], v[246:247]
	v_pk_add_f32 v[254:255], v[254:255], v[160:161]
	s_nop 0
	v_pk_add_f32 v[246:247], v[246:247], v[254:255]
	s_nop 0
	v_add_f32_e32 v163, v246, v247
	s_waitcnt vmcnt(2)
	v_cvt_scalef32_pk32_f32_fp6 v[0:31], v[234:239], 1.0
	v_pk_mul_f32 v[246:247], v[0:1], v[96:97]
	v_pk_mul_f32 v[254:255], v[2:3], v[98:99]
	v_pk_mul_f32 v[160:161], v[4:5], v[100:101]
	v_pk_fma_f32 v[246:247], v[6:7], v[102:103], v[246:247]
	v_pk_fma_f32 v[254:255], v[8:9], v[104:105], v[254:255]
	v_pk_fma_f32 v[160:161], v[10:11], v[106:107], v[160:161]
	v_pk_fma_f32 v[246:247], v[12:13], v[108:109], v[246:247]
	v_pk_fma_f32 v[254:255], v[14:15], v[110:111], v[254:255]
	v_pk_fma_f32 v[160:161], v[16:17], v[112:113], v[160:161]
	v_pk_fma_f32 v[246:247], v[18:19], v[114:115], v[246:247]
	v_pk_fma_f32 v[254:255], v[20:21], v[116:117], v[254:255]
	v_pk_fma_f32 v[160:161], v[22:23], v[118:119], v[160:161]
	v_pk_fma_f32 v[246:247], v[24:25], v[120:121], v[246:247]
	v_pk_fma_f32 v[254:255], v[26:27], v[122:123], v[254:255]
	v_pk_fma_f32 v[160:161], v[28:29], v[124:125], v[160:161]
	v_pk_fma_f32 v[246:247], v[30:31], v[126:127], v[246:247]
	v_pk_add_f32 v[254:255], v[254:255], v[160:161]
	s_nop 0
	v_pk_add_f32 v[246:247], v[246:247], v[254:255]
	s_nop 0
	v_add_f32_e32 v164, v246, v247
	s_waitcnt vmcnt(0)
	v_cvt_scalef32_pk32_f32_fp6 v[0:31], v[240:245], 1.0
	v_pk_mul_f32 v[246:247], v[0:1], v[96:97]
	v_pk_mul_f32 v[254:255], v[2:3], v[98:99]
	v_pk_mul_f32 v[160:161], v[4:5], v[100:101]
	v_pk_fma_f32 v[246:247], v[6:7], v[102:103], v[246:247]
	v_pk_fma_f32 v[254:255], v[8:9], v[104:105], v[254:255]
	v_pk_fma_f32 v[160:161], v[10:11], v[106:107], v[160:161]
	v_pk_fma_f32 v[246:247], v[12:13], v[108:109], v[246:247]
	v_pk_fma_f32 v[254:255], v[14:15], v[110:111], v[254:255]
	v_pk_fma_f32 v[160:161], v[16:17], v[112:113], v[160:161]
	v_pk_fma_f32 v[246:247], v[18:19], v[114:115], v[246:247]
	v_pk_fma_f32 v[254:255], v[20:21], v[116:117], v[254:255]
	v_pk_fma_f32 v[160:161], v[22:23], v[118:119], v[160:161]
	v_pk_fma_f32 v[246:247], v[24:25], v[120:121], v[246:247]
	v_pk_fma_f32 v[254:255], v[26:27], v[122:123], v[254:255]
	v_pk_fma_f32 v[160:161], v[28:29], v[124:125], v[160:161]
	v_pk_fma_f32 v[246:247], v[30:31], v[126:127], v[246:247]
	v_pk_add_f32 v[254:255], v[254:255], v[160:161]
	s_nop 0
	v_pk_add_f32 v[246:247], v[246:247], v[254:255]
	s_nop 0
	v_add_f32_e32 v165, v246, v247
	v_add_f32_dpp v162, v162, v162 row_shr:1 row_mask:0xf bank_mask:0xf bound_ctrl:1
	v_add_f32_dpp v163, v163, v163 row_shr:1 row_mask:0xf bank_mask:0xf bound_ctrl:1
	v_add_f32_dpp v164, v164, v164 row_shr:1 row_mask:0xf bank_mask:0xf bound_ctrl:1
	v_add_f32_dpp v165, v165, v165 row_shr:1 row_mask:0xf bank_mask:0xf bound_ctrl:1
	v_add_f32_dpp v162, v162, v162 row_shr:2 row_mask:0xf bank_mask:0xf bound_ctrl:1
	v_add_f32_dpp v163, v163, v163 row_shr:2 row_mask:0xf bank_mask:0xf bound_ctrl:1
	v_add_f32_dpp v164, v164, v164 row_shr:2 row_mask:0xf bank_mask:0xf bound_ctrl:1
	v_add_f32_dpp v165, v165, v165 row_shr:2 row_mask:0xf bank_mask:0xf bound_ctrl:1
	v_add_f32_dpp v162, v162, v162 row_shr:4 row_mask:0xf bank_mask:0xf bound_ctrl:1
	v_add_f32_dpp v163, v163, v163 row_shr:4 row_mask:0xf bank_mask:0xf bound_ctrl:1
	v_add_f32_dpp v164, v164, v164 row_shr:4 row_mask:0xf bank_mask:0xf bound_ctrl:1
	v_add_f32_dpp v165, v165, v165 row_shr:4 row_mask:0xf bank_mask:0xf bound_ctrl:1
	v_add_f32_dpp v162, v162, v162 row_shr:8 row_mask:0xf bank_mask:0xf bound_ctrl:1
	v_add_f32_dpp v163, v163, v163 row_shr:8 row_mask:0xf bank_mask:0xf bound_ctrl:1
	v_add_f32_dpp v164, v164, v164 row_shr:8 row_mask:0xf bank_mask:0xf bound_ctrl:1
	v_add_f32_dpp v165, v165, v165 row_shr:8 row_mask:0xf bank_mask:0xf bound_ctrl:1
	v_add_f32_dpp v162, v162, v162 row_bcast:15 row_mask:0xa bank_mask:0xf
	v_add_f32_dpp v163, v163, v163 row_bcast:15 row_mask:0xa bank_mask:0xf
	v_add_f32_dpp v164, v164, v164 row_bcast:15 row_mask:0xa bank_mask:0xf
	v_add_f32_dpp v165, v165, v165 row_bcast:15 row_mask:0xa bank_mask:0xf
	s_mov_b64 s[98:99], exec
	s_mov_b32 exec_lo, 0x80000000
	s_mov_b32 exec_hi, 0x80000000
	ds_write_b32 v74, v162 offset:224
	ds_write_b32 v74, v163 offset:232
	ds_write_b32 v74, v164 offset:240
	ds_write_b32 v74, v165 offset:248
	s_mov_b64 exec, s[98:99]
	ds_read_b32 v166, v75
	s_waitcnt lgkmcnt(0)
; DEV float gelu_t(float x) {
;   float z = 0.7978845608028654f * (x + 0.044715f * x * x * x);
;   float e = __expf(2.f * z);
;   float th = 1.f - 2.f / (e + 1.f);
;   return 0.5f * x * (1.f + th);
; }
; __device__ void peer_gather_phase(const Params& P, int l, bool do_store) {
;     ...
;       const float avec = gelu_t(dvec * sux) * gsx;
;     ...
;       for (int j = 0; j < 8; ++j) {
;         const float a = __builtin_bit_cast(float, __builtin_amdgcn_readlane(__builtin_bit_cast(int, avec), kb + j));
;         const f32x2 aa = f32x2{a, a};
;         y[0] += aa * __builtin_amdgcn_cvt_scalef32_pk_f32_fp4(v8[j].x, 1.0f, 0); y[1] += aa * __builtin_amdgcn_cvt_scalef32_pk_f32_fp4(v8[j].x, 1.0f, 1);
;         y[2] += aa * __builtin_amdgcn_cvt_scalef32_pk_f32_fp4(v8[j].x, 1.0f, 2); y[3] += aa * __builtin_amdgcn_cvt_scalef32_pk_f32_fp4(v8[j].x, 1.0f, 3);
;         y[4] += aa * __builtin_amdgcn_cvt_scalef32_pk_f32_fp4(v8[j].y, 1.0f, 0); y[5] += aa * __builtin_amdgcn_cvt_scalef32_pk_f32_fp4(v8[j].y, 1.0f, 1);
;         y[6] += aa * __builtin_amdgcn_cvt_scalef32_pk_f32_fp4(v8[j].y, 1.0f, 2); y[7] += aa * __builtin_amdgcn_cvt_scalef32_pk_f32_fp4(v8[j].y, 1.0f, 3);
;       }
	v_mul_f32_e32 v0, v190, v166
	v_mul_f32_e32 v1, 0x3d372713, v0
	v_mul_f32_e32 v1, v0, v1
	v_fma_f32 v1, v0, v1, v0
	v_mul_f32_e32 v1, 0x3f4c422a, v1
	v_add_f32_e32 v1, v1, v1
	v_mul_f32_e32 v1, 0x3fb8aa3b, v1
	v_exp_f32_e32 v1, v1
	v_mul_f32_e32 v0, 0.5, v0
	v_add_f32_e32 v1, 1.0, v1
	v_div_scale_f32 v2, s[0:1], v1, v1, 2.0
	v_rcp_f32_e32 v3, v2
	s_nop 0
	v_fma_f32 v4, -v2, v3, 1.0
	v_fmac_f32_e32 v3, v4, v3
	v_div_scale_f32 v4, vcc, 2.0, v1, 2.0
	v_mul_f32_e32 v5, v4, v3
	v_fma_f32 v6, -v2, v5, v4
	v_fmac_f32_e32 v5, v6, v3
	v_fma_f32 v2, -v2, v5, v4
	v_div_fmas_f32 v2, v2, v3, v5
	v_div_fixup_f32 v1, v2, v1, 2.0
	v_sub_f32_e32 v1, 1.0, v1
	v_add_f32_e32 v1, 1.0, v1
	v_mul_f32_e32 v0, v0, v1
	v_mul_f32_e32 v167, v192, v0
	ds_write_b32 v75, v167 offset:256
	ds_read_b32 v76, v193 offset:256
	ds_read_b32 v194, v193 offset:260
	s_waitcnt vmcnt(48)
	v_cvt_scalef32_pk_f32_fp4 v[0:1], v144, 1.0
	v_cvt_scalef32_pk_f32_fp4 v[2:3], v144, 1.0 op_sel:[1,0,0]
	v_cvt_scalef32_pk_f32_fp4 v[4:5], v144, 1.0 op_sel:[0,1,0]
	v_cvt_scalef32_pk_f32_fp4 v[6:7], v144, 1.0 op_sel:[1,1,0]
	v_cvt_scalef32_pk_f32_fp4 v[8:9], v145, 1.0
	v_cvt_scalef32_pk_f32_fp4 v[10:11], v145, 1.0 op_sel:[1,0,0]
	v_cvt_scalef32_pk_f32_fp4 v[12:13], v145, 1.0 op_sel:[0,1,0]
	v_cvt_scalef32_pk_f32_fp4 v[14:15], v145, 1.0 op_sel:[1,1,0]
	v_readlane_b32 s54, v90, 16
	s_lshl_b32 s56, s54, 9
	s_add_u32 s56, s64, s56
	s_addc_u32 s57, s65, 0
	global_load_dwordx2 v[144:145], v227, s[56:57]
	s_waitcnt lgkmcnt(1)
	v_pk_fma_f32 v[130:131], v[0:1], v[76:77], v[130:131] op_sel_hi:[1,0,1]
	v_pk_fma_f32 v[138:139], v[2:3], v[76:77], v[138:139] op_sel_hi:[1,0,1]
	v_pk_fma_f32 v[140:141], v[4:5], v[76:77], v[140:141] op_sel_hi:[1,0,1]
	v_pk_fma_f32 v[142:143], v[6:7], v[76:77], v[142:143] op_sel_hi:[1,0,1]
	v_pk_fma_f32 v[128:129], v[8:9], v[76:77], v[128:129] op_sel_hi:[1,0,1]
	v_pk_fma_f32 v[132:133], v[10:11], v[76:77], v[132:133] op_sel_hi:[1,0,1]
	v_pk_fma_f32 v[134:135], v[12:13], v[76:77], v[134:135] op_sel_hi:[1,0,1]
	v_pk_fma_f32 v[136:137], v[14:15], v[76:77], v[136:137] op_sel_hi:[1,0,1]
	ds_read_b32 v76, v193 offset:264
	s_waitcnt vmcnt(48)
	v_cvt_scalef32_pk_f32_fp4 v[0:1], v146, 1.0
	v_cvt_scalef32_pk_f32_fp4 v[2:3], v146, 1.0 op_sel:[1,0,0]
	v_cvt_scalef32_pk_f32_fp4 v[4:5], v146, 1.0 op_sel:[0,1,0]
	v_cvt_scalef32_pk_f32_fp4 v[6:7], v146, 1.0 op_sel:[1,1,0]
	v_cvt_scalef32_pk_f32_fp4 v[8:9], v147, 1.0
	v_cvt_scalef32_pk_f32_fp4 v[10:11], v147, 1.0 op_sel:[1,0,0]
	v_cvt_scalef32_pk_f32_fp4 v[12:13], v147, 1.0 op_sel:[0,1,0]
	v_cvt_scalef32_pk_f32_fp4 v[14:15], v147, 1.0 op_sel:[1,1,0]
	v_readlane_b32 s54, v90, 17
	s_lshl_b32 s56, s54, 9
	s_add_u32 s56, s64, s56
	s_addc_u32 s57, s65, 0
	global_load_dwordx2 v[146:147], v227, s[56:57]
	s_waitcnt lgkmcnt(1)
	v_pk_fma_f32 v[130:131], v[0:1], v[194:195], v[130:131] op_sel_hi:[1,0,1]
	v_pk_fma_f32 v[138:139], v[2:3], v[194:195], v[138:139] op_sel_hi:[1,0,1]
	v_pk_fma_f32 v[140:141], v[4:5], v[194:195], v[140:141] op_sel_hi:[1,0,1]
	v_pk_fma_f32 v[142:143], v[6:7], v[194:195], v[142:143] op_sel_hi:[1,0,1]
	v_pk_fma_f32 v[128:129], v[8:9], v[194:195], v[128:129] op_sel_hi:[1,0,1]
	v_pk_fma_f32 v[132:133], v[10:11], v[194:195], v[132:133] op_sel_hi:[1,0,1]
	v_pk_fma_f32 v[134:135], v[12:13], v[194:195], v[134:135] op_sel_hi:[1,0,1]
	v_pk_fma_f32 v[136:137], v[14:15], v[194:195], v[136:137] op_sel_hi:[1,0,1]
	ds_read_b32 v194, v193 offset:268
	s_waitcnt vmcnt(48)
	v_cvt_scalef32_pk_f32_fp4 v[0:1], v148, 1.0
	v_cvt_scalef32_pk_f32_fp4 v[2:3], v148, 1.0 op_sel:[1,0,0]
	v_cvt_scalef32_pk_f32_fp4 v[4:5], v148, 1.0 op_sel:[0,1,0]
	v_cvt_scalef32_pk_f32_fp4 v[6:7], v148, 1.0 op_sel:[1,1,0]
	v_cvt_scalef32_pk_f32_fp4 v[8:9], v149, 1.0
	v_cvt_scalef32_pk_f32_fp4 v[10:11], v149, 1.0 op_sel:[1,0,0]
	v_cvt_scalef32_pk_f32_fp4 v[12:13], v149, 1.0 op_sel:[0,1,0]
	v_cvt_scalef32_pk_f32_fp4 v[14:15], v149, 1.0 op_sel:[1,1,0]
	v_readlane_b32 s54, v90, 18
	s_lshl_b32 s56, s54, 9
	s_add_u32 s56, s64, s56
	s_addc_u32 s57, s65, 0
	global_load_dwordx2 v[148:149], v227, s[56:57]
	s_waitcnt lgkmcnt(1)
	v_pk_fma_f32 v[130:131], v[0:1], v[76:77], v[130:131] op_sel_hi:[1,0,1]
	v_pk_fma_f32 v[138:139], v[2:3], v[76:77], v[138:139] op_sel_hi:[1,0,1]
	v_pk_fma_f32 v[140:141], v[4:5], v[76:77], v[140:141] op_sel_hi:[1,0,1]
	v_pk_fma_f32 v[142:143], v[6:7], v[76:77], v[142:143] op_sel_hi:[1,0,1]
	v_pk_fma_f32 v[128:129], v[8:9], v[76:77], v[128:129] op_sel_hi:[1,0,1]
	v_pk_fma_f32 v[132:133], v[10:11], v[76:77], v[132:133] op_sel_hi:[1,0,1]
	v_pk_fma_f32 v[134:135], v[12:13], v[76:77], v[134:135] op_sel_hi:[1,0,1]
	v_pk_fma_f32 v[136:137], v[14:15], v[76:77], v[136:137] op_sel_hi:[1,0,1]
	ds_read_b32 v76, v193 offset:272
	s_waitcnt vmcnt(48)
	v_cvt_scalef32_pk_f32_fp4 v[0:1], v150, 1.0
	v_cvt_scalef32_pk_f32_fp4 v[2:3], v150, 1.0 op_sel:[1,0,0]
	v_cvt_scalef32_pk_f32_fp4 v[4:5], v150, 1.0 op_sel:[0,1,0]
	v_cvt_scalef32_pk_f32_fp4 v[6:7], v150, 1.0 op_sel:[1,1,0]
	v_cvt_scalef32_pk_f32_fp4 v[8:9], v151, 1.0
	v_cvt_scalef32_pk_f32_fp4 v[10:11], v151, 1.0 op_sel:[1,0,0]
	v_cvt_scalef32_pk_f32_fp4 v[12:13], v151, 1.0 op_sel:[0,1,0]
	v_cvt_scalef32_pk_f32_fp4 v[14:15], v151, 1.0 op_sel:[1,1,0]
	v_readlane_b32 s54, v90, 19
	s_lshl_b32 s56, s54, 9
	s_add_u32 s56, s64, s56
	s_addc_u32 s57, s65, 0
	global_load_dwordx2 v[150:151], v227, s[56:57]
	s_waitcnt lgkmcnt(1)
; __device__ void peer_gather_phase(const Params& P, int l, bool do_store) {
;     ...
;         v8[2 * pr] = *(const uint2*)(V + (size_t)ea * 512);
;         v8[2 * pr + 1] = *(const uint2*)(V + (size_t)eb * 512);
;     ...
;       for (int j = 0; j < 8; ++j) {
;         const float a = __builtin_bit_cast(float, __builtin_amdgcn_readlane(__builtin_bit_cast(int, avec), kb + j));
;         const f32x2 aa = f32x2{a, a};
;         y[0] += aa * __builtin_amdgcn_cvt_scalef32_pk_f32_fp4(v8[j].x, 1.0f, 0); y[1] += aa * __builtin_amdgcn_cvt_scalef32_pk_f32_fp4(v8[j].x, 1.0f, 1);
;         y[2] += aa * __builtin_amdgcn_cvt_scalef32_pk_f32_fp4(v8[j].x, 1.0f, 2); y[3] += aa * __builtin_amdgcn_cvt_scalef32_pk_f32_fp4(v8[j].x, 1.0f, 3);
;         y[4] += aa * __builtin_amdgcn_cvt_scalef32_pk_f32_fp4(v8[j].y, 1.0f, 0); y[5] += aa * __builtin_amdgcn_cvt_scalef32_pk_f32_fp4(v8[j].y, 1.0f, 1);
;         y[6] += aa * __builtin_amdgcn_cvt_scalef32_pk_f32_fp4(v8[j].y, 1.0f, 2); y[7] += aa * __builtin_amdgcn_cvt_scalef32_pk_f32_fp4(v8[j].y, 1.0f, 3);
;       }
	v_pk_fma_f32 v[130:131], v[0:1], v[194:195], v[130:131] op_sel_hi:[1,0,1]
	v_pk_fma_f32 v[138:139], v[2:3], v[194:195], v[138:139] op_sel_hi:[1,0,1]
	v_pk_fma_f32 v[140:141], v[4:5], v[194:195], v[140:141] op_sel_hi:[1,0,1]
	v_pk_fma_f32 v[142:143], v[6:7], v[194:195], v[142:143] op_sel_hi:[1,0,1]
	v_pk_fma_f32 v[128:129], v[8:9], v[194:195], v[128:129] op_sel_hi:[1,0,1]
	v_pk_fma_f32 v[132:133], v[10:11], v[194:195], v[132:133] op_sel_hi:[1,0,1]
	v_pk_fma_f32 v[134:135], v[12:13], v[194:195], v[134:135] op_sel_hi:[1,0,1]
	v_pk_fma_f32 v[136:137], v[14:15], v[194:195], v[136:137] op_sel_hi:[1,0,1]
	ds_read_b32 v194, v193 offset:276
	s_waitcnt vmcnt(48)
	v_cvt_scalef32_pk_f32_fp4 v[0:1], v152, 1.0
	v_cvt_scalef32_pk_f32_fp4 v[2:3], v152, 1.0 op_sel:[1,0,0]
	v_cvt_scalef32_pk_f32_fp4 v[4:5], v152, 1.0 op_sel:[0,1,0]
	v_cvt_scalef32_pk_f32_fp4 v[6:7], v152, 1.0 op_sel:[1,1,0]
	v_cvt_scalef32_pk_f32_fp4 v[8:9], v153, 1.0
	v_cvt_scalef32_pk_f32_fp4 v[10:11], v153, 1.0 op_sel:[1,0,0]
	v_cvt_scalef32_pk_f32_fp4 v[12:13], v153, 1.0 op_sel:[0,1,0]
	v_cvt_scalef32_pk_f32_fp4 v[14:15], v153, 1.0 op_sel:[1,1,0]
	v_readlane_b32 s54, v90, 20
	s_lshl_b32 s56, s54, 9
	s_add_u32 s56, s64, s56
	s_addc_u32 s57, s65, 0
	global_load_dwordx2 v[152:153], v227, s[56:57]
	s_waitcnt lgkmcnt(1)
	v_pk_fma_f32 v[130:131], v[0:1], v[76:77], v[130:131] op_sel_hi:[1,0,1]
	v_pk_fma_f32 v[138:139], v[2:3], v[76:77], v[138:139] op_sel_hi:[1,0,1]
	v_pk_fma_f32 v[140:141], v[4:5], v[76:77], v[140:141] op_sel_hi:[1,0,1]
	v_pk_fma_f32 v[142:143], v[6:7], v[76:77], v[142:143] op_sel_hi:[1,0,1]
	v_pk_fma_f32 v[128:129], v[8:9], v[76:77], v[128:129] op_sel_hi:[1,0,1]
	v_pk_fma_f32 v[132:133], v[10:11], v[76:77], v[132:133] op_sel_hi:[1,0,1]
	v_pk_fma_f32 v[134:135], v[12:13], v[76:77], v[134:135] op_sel_hi:[1,0,1]
	v_pk_fma_f32 v[136:137], v[14:15], v[76:77], v[136:137] op_sel_hi:[1,0,1]
	ds_read_b32 v76, v193 offset:280
	s_waitcnt vmcnt(48)
	v_cvt_scalef32_pk_f32_fp4 v[0:1], v154, 1.0
	v_cvt_scalef32_pk_f32_fp4 v[2:3], v154, 1.0 op_sel:[1,0,0]
	v_cvt_scalef32_pk_f32_fp4 v[4:5], v154, 1.0 op_sel:[0,1,0]
	v_cvt_scalef32_pk_f32_fp4 v[6:7], v154, 1.0 op_sel:[1,1,0]
	v_cvt_scalef32_pk_f32_fp4 v[8:9], v155, 1.0
	v_cvt_scalef32_pk_f32_fp4 v[10:11], v155, 1.0 op_sel:[1,0,0]
	v_cvt_scalef32_pk_f32_fp4 v[12:13], v155, 1.0 op_sel:[0,1,0]
	v_cvt_scalef32_pk_f32_fp4 v[14:15], v155, 1.0 op_sel:[1,1,0]
	v_readlane_b32 s54, v90, 21
	s_lshl_b32 s56, s54, 9
	s_add_u32 s56, s64, s56
	s_addc_u32 s57, s65, 0
	global_load_dwordx2 v[154:155], v227, s[56:57]
	s_waitcnt lgkmcnt(1)
	v_pk_fma_f32 v[130:131], v[0:1], v[194:195], v[130:131] op_sel_hi:[1,0,1]
	v_pk_fma_f32 v[138:139], v[2:3], v[194:195], v[138:139] op_sel_hi:[1,0,1]
	v_pk_fma_f32 v[140:141], v[4:5], v[194:195], v[140:141] op_sel_hi:[1,0,1]
	v_pk_fma_f32 v[142:143], v[6:7], v[194:195], v[142:143] op_sel_hi:[1,0,1]
	v_pk_fma_f32 v[128:129], v[8:9], v[194:195], v[128:129] op_sel_hi:[1,0,1]
	v_pk_fma_f32 v[132:133], v[10:11], v[194:195], v[132:133] op_sel_hi:[1,0,1]
	v_pk_fma_f32 v[134:135], v[12:13], v[194:195], v[134:135] op_sel_hi:[1,0,1]
	v_pk_fma_f32 v[136:137], v[14:15], v[194:195], v[136:137] op_sel_hi:[1,0,1]
	ds_read_b32 v194, v193 offset:284
	s_waitcnt vmcnt(48)
	v_cvt_scalef32_pk_f32_fp4 v[0:1], v156, 1.0
	v_cvt_scalef32_pk_f32_fp4 v[2:3], v156, 1.0 op_sel:[1,0,0]
	v_cvt_scalef32_pk_f32_fp4 v[4:5], v156, 1.0 op_sel:[0,1,0]
	v_cvt_scalef32_pk_f32_fp4 v[6:7], v156, 1.0 op_sel:[1,1,0]
	v_cvt_scalef32_pk_f32_fp4 v[8:9], v157, 1.0
	v_cvt_scalef32_pk_f32_fp4 v[10:11], v157, 1.0 op_sel:[1,0,0]
	v_cvt_scalef32_pk_f32_fp4 v[12:13], v157, 1.0 op_sel:[0,1,0]
	v_cvt_scalef32_pk_f32_fp4 v[14:15], v157, 1.0 op_sel:[1,1,0]
	v_readlane_b32 s54, v90, 22
	s_lshl_b32 s56, s54, 9
	s_add_u32 s56, s64, s56
	s_addc_u32 s57, s65, 0
	global_load_dwordx2 v[156:157], v227, s[56:57]
	s_waitcnt lgkmcnt(1)
	v_pk_fma_f32 v[130:131], v[0:1], v[76:77], v[130:131] op_sel_hi:[1,0,1]
	v_pk_fma_f32 v[138:139], v[2:3], v[76:77], v[138:139] op_sel_hi:[1,0,1]
	v_pk_fma_f32 v[140:141], v[4:5], v[76:77], v[140:141] op_sel_hi:[1,0,1]
	v_pk_fma_f32 v[142:143], v[6:7], v[76:77], v[142:143] op_sel_hi:[1,0,1]
	v_pk_fma_f32 v[128:129], v[8:9], v[76:77], v[128:129] op_sel_hi:[1,0,1]
	v_pk_fma_f32 v[132:133], v[10:11], v[76:77], v[132:133] op_sel_hi:[1,0,1]
	v_pk_fma_f32 v[134:135], v[12:13], v[76:77], v[134:135] op_sel_hi:[1,0,1]
	v_pk_fma_f32 v[136:137], v[14:15], v[76:77], v[136:137] op_sel_hi:[1,0,1]
	ds_read_b32 v76, v193 offset:288
	s_waitcnt vmcnt(48)
	v_cvt_scalef32_pk_f32_fp4 v[0:1], v158, 1.0
	v_cvt_scalef32_pk_f32_fp4 v[2:3], v158, 1.0 op_sel:[1,0,0]
	v_cvt_scalef32_pk_f32_fp4 v[4:5], v158, 1.0 op_sel:[0,1,0]
	v_cvt_scalef32_pk_f32_fp4 v[6:7], v158, 1.0 op_sel:[1,1,0]
	v_cvt_scalef32_pk_f32_fp4 v[8:9], v159, 1.0
	v_cvt_scalef32_pk_f32_fp4 v[10:11], v159, 1.0 op_sel:[1,0,0]
	v_cvt_scalef32_pk_f32_fp4 v[12:13], v159, 1.0 op_sel:[0,1,0]
	v_cvt_scalef32_pk_f32_fp4 v[14:15], v159, 1.0 op_sel:[1,1,0]
	v_readlane_b32 s54, v90, 23
	s_lshl_b32 s56, s54, 9
	s_add_u32 s56, s64, s56
	s_addc_u32 s57, s65, 0
	global_load_dwordx2 v[158:159], v227, s[56:57]
	s_waitcnt lgkmcnt(1)
	v_pk_fma_f32 v[130:131], v[0:1], v[194:195], v[130:131] op_sel_hi:[1,0,1]
	v_pk_fma_f32 v[138:139], v[2:3], v[194:195], v[138:139] op_sel_hi:[1,0,1]
	v_pk_fma_f32 v[140:141], v[4:5], v[194:195], v[140:141] op_sel_hi:[1,0,1]
	v_pk_fma_f32 v[142:143], v[6:7], v[194:195], v[142:143] op_sel_hi:[1,0,1]
	v_pk_fma_f32 v[128:129], v[8:9], v[194:195], v[128:129] op_sel_hi:[1,0,1]
	v_pk_fma_f32 v[132:133], v[10:11], v[194:195], v[132:133] op_sel_hi:[1,0,1]
	v_pk_fma_f32 v[134:135], v[12:13], v[194:195], v[134:135] op_sel_hi:[1,0,1]
	v_pk_fma_f32 v[136:137], v[14:15], v[194:195], v[136:137] op_sel_hi:[1,0,1]
	ds_read_b32 v194, v193 offset:292
	s_waitcnt vmcnt(48)
; __device__ void peer_gather_phase(const Params& P, int l, bool do_store) {
;     ...
;         v8[2 * pr] = *(const uint2*)(V + (size_t)ea * 512);
;         v8[2 * pr + 1] = *(const uint2*)(V + (size_t)eb * 512);
;     ...
;       for (int j = 0; j < 8; ++j) {
;         const float a = __builtin_bit_cast(float, __builtin_amdgcn_readlane(__builtin_bit_cast(int, avec), kb + j));
;         const f32x2 aa = f32x2{a, a};
;         y[0] += aa * __builtin_amdgcn_cvt_scalef32_pk_f32_fp4(v8[j].x, 1.0f, 0); y[1] += aa * __builtin_amdgcn_cvt_scalef32_pk_f32_fp4(v8[j].x, 1.0f, 1);
;         y[2] += aa * __builtin_amdgcn_cvt_scalef32_pk_f32_fp4(v8[j].x, 1.0f, 2); y[3] += aa * __builtin_amdgcn_cvt_scalef32_pk_f32_fp4(v8[j].x, 1.0f, 3);
;         y[4] += aa * __builtin_amdgcn_cvt_scalef32_pk_f32_fp4(v8[j].y, 1.0f, 0); y[5] += aa * __builtin_amdgcn_cvt_scalef32_pk_f32_fp4(v8[j].y, 1.0f, 1);
;         y[6] += aa * __builtin_amdgcn_cvt_scalef32_pk_f32_fp4(v8[j].y, 1.0f, 2); y[7] += aa * __builtin_amdgcn_cvt_scalef32_pk_f32_fp4(v8[j].y, 1.0f, 3);
;       }
	v_cvt_scalef32_pk_f32_fp4 v[0:1], v168, 1.0
	v_cvt_scalef32_pk_f32_fp4 v[2:3], v168, 1.0 op_sel:[1,0,0]
	v_cvt_scalef32_pk_f32_fp4 v[4:5], v168, 1.0 op_sel:[0,1,0]
	v_cvt_scalef32_pk_f32_fp4 v[6:7], v168, 1.0 op_sel:[1,1,0]
	v_cvt_scalef32_pk_f32_fp4 v[8:9], v169, 1.0
	v_cvt_scalef32_pk_f32_fp4 v[10:11], v169, 1.0 op_sel:[1,0,0]
	v_cvt_scalef32_pk_f32_fp4 v[12:13], v169, 1.0 op_sel:[0,1,0]
	v_cvt_scalef32_pk_f32_fp4 v[14:15], v169, 1.0 op_sel:[1,1,0]
	v_readlane_b32 s54, v90, 24
	s_lshl_b32 s56, s54, 9
	s_add_u32 s56, s64, s56
	s_addc_u32 s57, s65, 0
	global_load_dwordx2 v[168:169], v227, s[56:57]
	s_waitcnt lgkmcnt(1)
	v_pk_fma_f32 v[130:131], v[0:1], v[76:77], v[130:131] op_sel_hi:[1,0,1]
	v_pk_fma_f32 v[138:139], v[2:3], v[76:77], v[138:139] op_sel_hi:[1,0,1]
	v_pk_fma_f32 v[140:141], v[4:5], v[76:77], v[140:141] op_sel_hi:[1,0,1]
	v_pk_fma_f32 v[142:143], v[6:7], v[76:77], v[142:143] op_sel_hi:[1,0,1]
	v_pk_fma_f32 v[128:129], v[8:9], v[76:77], v[128:129] op_sel_hi:[1,0,1]
	v_pk_fma_f32 v[132:133], v[10:11], v[76:77], v[132:133] op_sel_hi:[1,0,1]
	v_pk_fma_f32 v[134:135], v[12:13], v[76:77], v[134:135] op_sel_hi:[1,0,1]
	v_pk_fma_f32 v[136:137], v[14:15], v[76:77], v[136:137] op_sel_hi:[1,0,1]
	ds_read_b32 v76, v193 offset:296
	s_waitcnt vmcnt(48)
	v_cvt_scalef32_pk_f32_fp4 v[0:1], v170, 1.0
	v_cvt_scalef32_pk_f32_fp4 v[2:3], v170, 1.0 op_sel:[1,0,0]
	v_cvt_scalef32_pk_f32_fp4 v[4:5], v170, 1.0 op_sel:[0,1,0]
	v_cvt_scalef32_pk_f32_fp4 v[6:7], v170, 1.0 op_sel:[1,1,0]
	v_cvt_scalef32_pk_f32_fp4 v[8:9], v171, 1.0
	v_cvt_scalef32_pk_f32_fp4 v[10:11], v171, 1.0 op_sel:[1,0,0]
	v_cvt_scalef32_pk_f32_fp4 v[12:13], v171, 1.0 op_sel:[0,1,0]
	v_cvt_scalef32_pk_f32_fp4 v[14:15], v171, 1.0 op_sel:[1,1,0]
	v_readlane_b32 s54, v90, 25
	s_lshl_b32 s56, s54, 9
	s_add_u32 s56, s64, s56
	s_addc_u32 s57, s65, 0
	global_load_dwordx2 v[170:171], v227, s[56:57]
	s_waitcnt lgkmcnt(1)
	v_pk_fma_f32 v[130:131], v[0:1], v[194:195], v[130:131] op_sel_hi:[1,0,1]
	v_pk_fma_f32 v[138:139], v[2:3], v[194:195], v[138:139] op_sel_hi:[1,0,1]
	v_pk_fma_f32 v[140:141], v[4:5], v[194:195], v[140:141] op_sel_hi:[1,0,1]
	v_pk_fma_f32 v[142:143], v[6:7], v[194:195], v[142:143] op_sel_hi:[1,0,1]
	v_pk_fma_f32 v[128:129], v[8:9], v[194:195], v[128:129] op_sel_hi:[1,0,1]
	v_pk_fma_f32 v[132:133], v[10:11], v[194:195], v[132:133] op_sel_hi:[1,0,1]
	v_pk_fma_f32 v[134:135], v[12:13], v[194:195], v[134:135] op_sel_hi:[1,0,1]
	v_pk_fma_f32 v[136:137], v[14:15], v[194:195], v[136:137] op_sel_hi:[1,0,1]
	ds_read_b32 v194, v193 offset:300
	s_waitcnt vmcnt(48)
	v_cvt_scalef32_pk_f32_fp4 v[0:1], v172, 1.0
	v_cvt_scalef32_pk_f32_fp4 v[2:3], v172, 1.0 op_sel:[1,0,0]
	v_cvt_scalef32_pk_f32_fp4 v[4:5], v172, 1.0 op_sel:[0,1,0]
	v_cvt_scalef32_pk_f32_fp4 v[6:7], v172, 1.0 op_sel:[1,1,0]
	v_cvt_scalef32_pk_f32_fp4 v[8:9], v173, 1.0
	v_cvt_scalef32_pk_f32_fp4 v[10:11], v173, 1.0 op_sel:[1,0,0]
	v_cvt_scalef32_pk_f32_fp4 v[12:13], v173, 1.0 op_sel:[0,1,0]
	v_cvt_scalef32_pk_f32_fp4 v[14:15], v173, 1.0 op_sel:[1,1,0]
	v_readlane_b32 s54, v90, 26
	s_lshl_b32 s56, s54, 9
	s_add_u32 s56, s64, s56
	s_addc_u32 s57, s65, 0
	global_load_dwordx2 v[172:173], v227, s[56:57]
	s_waitcnt lgkmcnt(1)
	v_pk_fma_f32 v[130:131], v[0:1], v[76:77], v[130:131] op_sel_hi:[1,0,1]
	v_pk_fma_f32 v[138:139], v[2:3], v[76:77], v[138:139] op_sel_hi:[1,0,1]
	v_pk_fma_f32 v[140:141], v[4:5], v[76:77], v[140:141] op_sel_hi:[1,0,1]
	v_pk_fma_f32 v[142:143], v[6:7], v[76:77], v[142:143] op_sel_hi:[1,0,1]
	v_pk_fma_f32 v[128:129], v[8:9], v[76:77], v[128:129] op_sel_hi:[1,0,1]
	v_pk_fma_f32 v[132:133], v[10:11], v[76:77], v[132:133] op_sel_hi:[1,0,1]
	v_pk_fma_f32 v[134:135], v[12:13], v[76:77], v[134:135] op_sel_hi:[1,0,1]
	v_pk_fma_f32 v[136:137], v[14:15], v[76:77], v[136:137] op_sel_hi:[1,0,1]
	ds_read_b32 v76, v193 offset:304
	s_waitcnt vmcnt(48)
	v_cvt_scalef32_pk_f32_fp4 v[0:1], v174, 1.0
	v_cvt_scalef32_pk_f32_fp4 v[2:3], v174, 1.0 op_sel:[1,0,0]
	v_cvt_scalef32_pk_f32_fp4 v[4:5], v174, 1.0 op_sel:[0,1,0]
	v_cvt_scalef32_pk_f32_fp4 v[6:7], v174, 1.0 op_sel:[1,1,0]
	v_cvt_scalef32_pk_f32_fp4 v[8:9], v175, 1.0
	v_cvt_scalef32_pk_f32_fp4 v[10:11], v175, 1.0 op_sel:[1,0,0]
	v_cvt_scalef32_pk_f32_fp4 v[12:13], v175, 1.0 op_sel:[0,1,0]
	v_cvt_scalef32_pk_f32_fp4 v[14:15], v175, 1.0 op_sel:[1,1,0]
	v_readlane_b32 s54, v90, 27
	s_lshl_b32 s56, s54, 9
	s_add_u32 s56, s64, s56
	s_addc_u32 s57, s65, 0
	global_load_dwordx2 v[174:175], v227, s[56:57]
	s_waitcnt lgkmcnt(1)
	v_pk_fma_f32 v[130:131], v[0:1], v[194:195], v[130:131] op_sel_hi:[1,0,1]
	v_pk_fma_f32 v[138:139], v[2:3], v[194:195], v[138:139] op_sel_hi:[1,0,1]
	v_pk_fma_f32 v[140:141], v[4:5], v[194:195], v[140:141] op_sel_hi:[1,0,1]
	v_pk_fma_f32 v[142:143], v[6:7], v[194:195], v[142:143] op_sel_hi:[1,0,1]
	v_pk_fma_f32 v[128:129], v[8:9], v[194:195], v[128:129] op_sel_hi:[1,0,1]
	v_pk_fma_f32 v[132:133], v[10:11], v[194:195], v[132:133] op_sel_hi:[1,0,1]
	v_pk_fma_f32 v[134:135], v[12:13], v[194:195], v[134:135] op_sel_hi:[1,0,1]
	v_pk_fma_f32 v[136:137], v[14:15], v[194:195], v[136:137] op_sel_hi:[1,0,1]
	ds_read_b32 v194, v193 offset:308
	s_waitcnt vmcnt(48)
	v_cvt_scalef32_pk_f32_fp4 v[0:1], v180, 1.0
	v_cvt_scalef32_pk_f32_fp4 v[2:3], v180, 1.0 op_sel:[1,0,0]
	v_cvt_scalef32_pk_f32_fp4 v[4:5], v180, 1.0 op_sel:[0,1,0]
	v_cvt_scalef32_pk_f32_fp4 v[6:7], v180, 1.0 op_sel:[1,1,0]
	v_cvt_scalef32_pk_f32_fp4 v[8:9], v181, 1.0
	v_cvt_scalef32_pk_f32_fp4 v[10:11], v181, 1.0 op_sel:[1,0,0]
	v_cvt_scalef32_pk_f32_fp4 v[12:13], v181, 1.0 op_sel:[0,1,0]
	v_cvt_scalef32_pk_f32_fp4 v[14:15], v181, 1.0 op_sel:[1,1,0]
	v_readlane_b32 s54, v90, 28
	s_lshl_b32 s56, s54, 9
	s_add_u32 s56, s64, s56
	s_addc_u32 s57, s65, 0
	global_load_dwordx2 v[180:181], v227, s[56:57]
	s_waitcnt lgkmcnt(1)
; __device__ void peer_gather_phase(const Params& P, int l, bool do_store) {
;     ...
;         const int ea = __builtin_amdgcn_readlane(evs, kb + 2 * pr), eb = __builtin_amdgcn_readlane(evs, kb + 2 * pr + 1);
;         const uint2* up = (const uint2*)(U + (size_t)(uphi ? eb : ea) * 768);
;         u6[3 * pr] = up[0]; u6[3 * pr + 1] = up[1]; u6[3 * pr + 2] = up[2];
;         v8[2 * pr] = *(const uint2*)(V + (size_t)ea * 512);
;         v8[2 * pr + 1] = *(const uint2*)(V + (size_t)eb * 512);
;     ...
; #pragma unroll
;       for (int j = 0; j < 8; ++j) {
;         const float a = __builtin_bit_cast(float, __builtin_amdgcn_readlane(__builtin_bit_cast(int, avec), kb + j));
;         const f32x2 aa = f32x2{a, a};
;         y[0] += aa * __builtin_amdgcn_cvt_scalef32_pk_f32_fp4(v8[j].x, 1.0f, 0); y[1] += aa * __builtin_amdgcn_cvt_scalef32_pk_f32_fp4(v8[j].x, 1.0f, 1);
;         y[2] += aa * __builtin_amdgcn_cvt_scalef32_pk_f32_fp4(v8[j].x, 1.0f, 2); y[3] += aa * __builtin_amdgcn_cvt_scalef32_pk_f32_fp4(v8[j].x, 1.0f, 3);
;         y[4] += aa * __builtin_amdgcn_cvt_scalef32_pk_f32_fp4(v8[j].y, 1.0f, 0); y[5] += aa * __builtin_amdgcn_cvt_scalef32_pk_f32_fp4(v8[j].y, 1.0f, 1);
;         y[6] += aa * __builtin_amdgcn_cvt_scalef32_pk_f32_fp4(v8[j].y, 1.0f, 2); y[7] += aa * __builtin_amdgcn_cvt_scalef32_pk_f32_fp4(v8[j].y, 1.0f, 3);
;       }
	v_pk_fma_f32 v[130:131], v[0:1], v[76:77], v[130:131] op_sel_hi:[1,0,1]
	v_pk_fma_f32 v[138:139], v[2:3], v[76:77], v[138:139] op_sel_hi:[1,0,1]
	v_pk_fma_f32 v[140:141], v[4:5], v[76:77], v[140:141] op_sel_hi:[1,0,1]
	v_pk_fma_f32 v[142:143], v[6:7], v[76:77], v[142:143] op_sel_hi:[1,0,1]
	v_pk_fma_f32 v[128:129], v[8:9], v[76:77], v[128:129] op_sel_hi:[1,0,1]
	v_pk_fma_f32 v[132:133], v[10:11], v[76:77], v[132:133] op_sel_hi:[1,0,1]
	v_pk_fma_f32 v[134:135], v[12:13], v[76:77], v[134:135] op_sel_hi:[1,0,1]
	v_pk_fma_f32 v[136:137], v[14:15], v[76:77], v[136:137] op_sel_hi:[1,0,1]
	ds_read_b32 v76, v193 offset:312
	s_waitcnt vmcnt(48)
	v_cvt_scalef32_pk_f32_fp4 v[0:1], v182, 1.0
	v_cvt_scalef32_pk_f32_fp4 v[2:3], v182, 1.0 op_sel:[1,0,0]
	v_cvt_scalef32_pk_f32_fp4 v[4:5], v182, 1.0 op_sel:[0,1,0]
	v_cvt_scalef32_pk_f32_fp4 v[6:7], v182, 1.0 op_sel:[1,1,0]
	v_cvt_scalef32_pk_f32_fp4 v[8:9], v183, 1.0
	v_cvt_scalef32_pk_f32_fp4 v[10:11], v183, 1.0 op_sel:[1,0,0]
	v_cvt_scalef32_pk_f32_fp4 v[12:13], v183, 1.0 op_sel:[0,1,0]
	v_cvt_scalef32_pk_f32_fp4 v[14:15], v183, 1.0 op_sel:[1,1,0]
	v_readlane_b32 s54, v90, 29
	s_lshl_b32 s56, s54, 9
	s_add_u32 s56, s64, s56
	s_addc_u32 s57, s65, 0
	global_load_dwordx2 v[182:183], v227, s[56:57]
	s_waitcnt lgkmcnt(1)
	v_pk_fma_f32 v[130:131], v[0:1], v[194:195], v[130:131] op_sel_hi:[1,0,1]
	v_pk_fma_f32 v[138:139], v[2:3], v[194:195], v[138:139] op_sel_hi:[1,0,1]
	v_pk_fma_f32 v[140:141], v[4:5], v[194:195], v[140:141] op_sel_hi:[1,0,1]
	v_pk_fma_f32 v[142:143], v[6:7], v[194:195], v[142:143] op_sel_hi:[1,0,1]
	v_pk_fma_f32 v[128:129], v[8:9], v[194:195], v[128:129] op_sel_hi:[1,0,1]
	v_pk_fma_f32 v[132:133], v[10:11], v[194:195], v[132:133] op_sel_hi:[1,0,1]
	v_pk_fma_f32 v[134:135], v[12:13], v[194:195], v[134:135] op_sel_hi:[1,0,1]
	v_pk_fma_f32 v[136:137], v[14:15], v[194:195], v[136:137] op_sel_hi:[1,0,1]
	ds_read_b32 v194, v193 offset:316
	s_waitcnt vmcnt(48)
	v_cvt_scalef32_pk_f32_fp4 v[0:1], v184, 1.0
	v_cvt_scalef32_pk_f32_fp4 v[2:3], v184, 1.0 op_sel:[1,0,0]
	v_cvt_scalef32_pk_f32_fp4 v[4:5], v184, 1.0 op_sel:[0,1,0]
	v_cvt_scalef32_pk_f32_fp4 v[6:7], v184, 1.0 op_sel:[1,1,0]
	v_cvt_scalef32_pk_f32_fp4 v[8:9], v185, 1.0
	v_cvt_scalef32_pk_f32_fp4 v[10:11], v185, 1.0 op_sel:[1,0,0]
	v_cvt_scalef32_pk_f32_fp4 v[12:13], v185, 1.0 op_sel:[0,1,0]
	v_cvt_scalef32_pk_f32_fp4 v[14:15], v185, 1.0 op_sel:[1,1,0]
	v_readlane_b32 s54, v90, 30
	s_lshl_b32 s56, s54, 9
	s_add_u32 s56, s64, s56
	s_addc_u32 s57, s65, 0
	global_load_dwordx2 v[184:185], v227, s[56:57]
	s_waitcnt lgkmcnt(1)
	v_pk_fma_f32 v[130:131], v[0:1], v[76:77], v[130:131] op_sel_hi:[1,0,1]
	v_pk_fma_f32 v[138:139], v[2:3], v[76:77], v[138:139] op_sel_hi:[1,0,1]
	v_pk_fma_f32 v[140:141], v[4:5], v[76:77], v[140:141] op_sel_hi:[1,0,1]
	v_pk_fma_f32 v[142:143], v[6:7], v[76:77], v[142:143] op_sel_hi:[1,0,1]
	v_pk_fma_f32 v[128:129], v[8:9], v[76:77], v[128:129] op_sel_hi:[1,0,1]
	v_pk_fma_f32 v[132:133], v[10:11], v[76:77], v[132:133] op_sel_hi:[1,0,1]
	v_pk_fma_f32 v[134:135], v[12:13], v[76:77], v[134:135] op_sel_hi:[1,0,1]
	v_pk_fma_f32 v[136:137], v[14:15], v[76:77], v[136:137] op_sel_hi:[1,0,1]
	ds_read_b32 v76, v193 offset:320
	s_waitcnt vmcnt(48)
	v_cvt_scalef32_pk_f32_fp4 v[0:1], v186, 1.0
	v_cvt_scalef32_pk_f32_fp4 v[2:3], v186, 1.0 op_sel:[1,0,0]
	v_cvt_scalef32_pk_f32_fp4 v[4:5], v186, 1.0 op_sel:[0,1,0]
	v_cvt_scalef32_pk_f32_fp4 v[6:7], v186, 1.0 op_sel:[1,1,0]
	v_cvt_scalef32_pk_f32_fp4 v[8:9], v187, 1.0
	v_cvt_scalef32_pk_f32_fp4 v[10:11], v187, 1.0 op_sel:[1,0,0]
	v_cvt_scalef32_pk_f32_fp4 v[12:13], v187, 1.0 op_sel:[0,1,0]
	v_cvt_scalef32_pk_f32_fp4 v[14:15], v187, 1.0 op_sel:[1,1,0]
	v_readlane_b32 s54, v90, 31
	s_lshl_b32 s56, s54, 9
	s_add_u32 s56, s64, s56
	s_addc_u32 s57, s65, 0
	global_load_dwordx2 v[186:187], v227, s[56:57]
	s_waitcnt lgkmcnt(1)
	v_pk_fma_f32 v[130:131], v[0:1], v[194:195], v[130:131] op_sel_hi:[1,0,1]
	v_pk_fma_f32 v[138:139], v[2:3], v[194:195], v[138:139] op_sel_hi:[1,0,1]
	v_pk_fma_f32 v[140:141], v[4:5], v[194:195], v[140:141] op_sel_hi:[1,0,1]
	v_pk_fma_f32 v[142:143], v[6:7], v[194:195], v[142:143] op_sel_hi:[1,0,1]
	v_pk_fma_f32 v[128:129], v[8:9], v[194:195], v[128:129] op_sel_hi:[1,0,1]
	v_pk_fma_f32 v[132:133], v[10:11], v[194:195], v[132:133] op_sel_hi:[1,0,1]
	v_pk_fma_f32 v[134:135], v[12:13], v[194:195], v[134:135] op_sel_hi:[1,0,1]
	v_pk_fma_f32 v[136:137], v[14:15], v[194:195], v[136:137] op_sel_hi:[1,0,1]
	ds_read_b32 v194, v193 offset:324
	s_waitcnt vmcnt(15)
	v_cvt_scalef32_pk_f32_fp4 v[0:1], v144, 1.0
	v_cvt_scalef32_pk_f32_fp4 v[2:3], v144, 1.0 op_sel:[1,0,0]
	v_cvt_scalef32_pk_f32_fp4 v[4:5], v144, 1.0 op_sel:[0,1,0]
	v_cvt_scalef32_pk_f32_fp4 v[6:7], v144, 1.0 op_sel:[1,1,0]
	v_cvt_scalef32_pk_f32_fp4 v[8:9], v145, 1.0
	v_cvt_scalef32_pk_f32_fp4 v[10:11], v145, 1.0 op_sel:[1,0,0]
	v_cvt_scalef32_pk_f32_fp4 v[12:13], v145, 1.0 op_sel:[0,1,0]
	v_cvt_scalef32_pk_f32_fp4 v[14:15], v145, 1.0 op_sel:[1,1,0]
	v_readlane_b32 s54, v90, 32
	s_lshl_b32 s56, s54, 9
	s_add_u32 s56, s64, s56
	s_addc_u32 s57, s65, 0
	global_load_dwordx2 v[144:145], v227, s[56:57]
	s_waitcnt lgkmcnt(1)
	v_pk_fma_f32 v[130:131], v[0:1], v[76:77], v[130:131] op_sel_hi:[1,0,1]
	v_pk_fma_f32 v[138:139], v[2:3], v[76:77], v[138:139] op_sel_hi:[1,0,1]
	v_pk_fma_f32 v[140:141], v[4:5], v[76:77], v[140:141] op_sel_hi:[1,0,1]
	v_pk_fma_f32 v[142:143], v[6:7], v[76:77], v[142:143] op_sel_hi:[1,0,1]
	v_pk_fma_f32 v[128:129], v[8:9], v[76:77], v[128:129] op_sel_hi:[1,0,1]
	v_pk_fma_f32 v[132:133], v[10:11], v[76:77], v[132:133] op_sel_hi:[1,0,1]
	v_pk_fma_f32 v[134:135], v[12:13], v[76:77], v[134:135] op_sel_hi:[1,0,1]
	v_pk_fma_f32 v[136:137], v[14:15], v[76:77], v[136:137] op_sel_hi:[1,0,1]
	ds_read_b32 v76, v193 offset:328
	s_waitcnt vmcnt(15)
; __device__ void peer_gather_phase(const Params& P, int l, bool do_store) {
;     ...
;         const int ea = __builtin_amdgcn_readlane(evs, kb + 2 * pr), eb = __builtin_amdgcn_readlane(evs, kb + 2 * pr + 1);
;         const uint2* up = (const uint2*)(U + (size_t)(uphi ? eb : ea) * 768);
;         u6[3 * pr] = up[0]; u6[3 * pr + 1] = up[1]; u6[3 * pr + 2] = up[2];
;         v8[2 * pr] = *(const uint2*)(V + (size_t)ea * 512);
;         v8[2 * pr + 1] = *(const uint2*)(V + (size_t)eb * 512);
;     ...
; #pragma unroll
;       for (int j = 0; j < 8; ++j) {
;         const float a = __builtin_bit_cast(float, __builtin_amdgcn_readlane(__builtin_bit_cast(int, avec), kb + j));
;         const f32x2 aa = f32x2{a, a};
;         y[0] += aa * __builtin_amdgcn_cvt_scalef32_pk_f32_fp4(v8[j].x, 1.0f, 0); y[1] += aa * __builtin_amdgcn_cvt_scalef32_pk_f32_fp4(v8[j].x, 1.0f, 1);
;         y[2] += aa * __builtin_amdgcn_cvt_scalef32_pk_f32_fp4(v8[j].x, 1.0f, 2); y[3] += aa * __builtin_amdgcn_cvt_scalef32_pk_f32_fp4(v8[j].x, 1.0f, 3);
;         y[4] += aa * __builtin_amdgcn_cvt_scalef32_pk_f32_fp4(v8[j].y, 1.0f, 0); y[5] += aa * __builtin_amdgcn_cvt_scalef32_pk_f32_fp4(v8[j].y, 1.0f, 1);
;         y[6] += aa * __builtin_amdgcn_cvt_scalef32_pk_f32_fp4(v8[j].y, 1.0f, 2); y[7] += aa * __builtin_amdgcn_cvt_scalef32_pk_f32_fp4(v8[j].y, 1.0f, 3);
;       }
	v_cvt_scalef32_pk_f32_fp4 v[0:1], v146, 1.0
	v_cvt_scalef32_pk_f32_fp4 v[2:3], v146, 1.0 op_sel:[1,0,0]
	v_cvt_scalef32_pk_f32_fp4 v[4:5], v146, 1.0 op_sel:[0,1,0]
	v_cvt_scalef32_pk_f32_fp4 v[6:7], v146, 1.0 op_sel:[1,1,0]
	v_cvt_scalef32_pk_f32_fp4 v[8:9], v147, 1.0
	v_cvt_scalef32_pk_f32_fp4 v[10:11], v147, 1.0 op_sel:[1,0,0]
	v_cvt_scalef32_pk_f32_fp4 v[12:13], v147, 1.0 op_sel:[0,1,0]
	v_cvt_scalef32_pk_f32_fp4 v[14:15], v147, 1.0 op_sel:[1,1,0]
	v_readlane_b32 s54, v90, 33
	s_lshl_b32 s56, s54, 9
	s_add_u32 s56, s64, s56
	s_addc_u32 s57, s65, 0
	global_load_dwordx2 v[146:147], v227, s[56:57]
	s_waitcnt lgkmcnt(1)
	v_pk_fma_f32 v[130:131], v[0:1], v[194:195], v[130:131] op_sel_hi:[1,0,1]
	v_pk_fma_f32 v[138:139], v[2:3], v[194:195], v[138:139] op_sel_hi:[1,0,1]
	v_pk_fma_f32 v[140:141], v[4:5], v[194:195], v[140:141] op_sel_hi:[1,0,1]
	v_pk_fma_f32 v[142:143], v[6:7], v[194:195], v[142:143] op_sel_hi:[1,0,1]
	v_pk_fma_f32 v[128:129], v[8:9], v[194:195], v[128:129] op_sel_hi:[1,0,1]
	v_pk_fma_f32 v[132:133], v[10:11], v[194:195], v[132:133] op_sel_hi:[1,0,1]
	v_pk_fma_f32 v[134:135], v[12:13], v[194:195], v[134:135] op_sel_hi:[1,0,1]
	v_pk_fma_f32 v[136:137], v[14:15], v[194:195], v[136:137] op_sel_hi:[1,0,1]
	ds_read_b32 v194, v193 offset:332
	s_waitcnt vmcnt(15)
	v_cvt_scalef32_pk_f32_fp4 v[0:1], v148, 1.0
	v_cvt_scalef32_pk_f32_fp4 v[2:3], v148, 1.0 op_sel:[1,0,0]
	v_cvt_scalef32_pk_f32_fp4 v[4:5], v148, 1.0 op_sel:[0,1,0]
	v_cvt_scalef32_pk_f32_fp4 v[6:7], v148, 1.0 op_sel:[1,1,0]
	v_cvt_scalef32_pk_f32_fp4 v[8:9], v149, 1.0
	v_cvt_scalef32_pk_f32_fp4 v[10:11], v149, 1.0 op_sel:[1,0,0]
	v_cvt_scalef32_pk_f32_fp4 v[12:13], v149, 1.0 op_sel:[0,1,0]
	v_cvt_scalef32_pk_f32_fp4 v[14:15], v149, 1.0 op_sel:[1,1,0]
	v_readlane_b32 s54, v90, 34
	s_lshl_b32 s56, s54, 9
	s_add_u32 s56, s64, s56
	s_addc_u32 s57, s65, 0
	global_load_dwordx2 v[148:149], v227, s[56:57]
	s_waitcnt lgkmcnt(1)
	v_pk_fma_f32 v[130:131], v[0:1], v[76:77], v[130:131] op_sel_hi:[1,0,1]
	v_pk_fma_f32 v[138:139], v[2:3], v[76:77], v[138:139] op_sel_hi:[1,0,1]
	v_pk_fma_f32 v[140:141], v[4:5], v[76:77], v[140:141] op_sel_hi:[1,0,1]
	v_pk_fma_f32 v[142:143], v[6:7], v[76:77], v[142:143] op_sel_hi:[1,0,1]
	v_pk_fma_f32 v[128:129], v[8:9], v[76:77], v[128:129] op_sel_hi:[1,0,1]
	v_pk_fma_f32 v[132:133], v[10:11], v[76:77], v[132:133] op_sel_hi:[1,0,1]
	v_pk_fma_f32 v[134:135], v[12:13], v[76:77], v[134:135] op_sel_hi:[1,0,1]
	v_pk_fma_f32 v[136:137], v[14:15], v[76:77], v[136:137] op_sel_hi:[1,0,1]
	ds_read_b32 v76, v193 offset:336
	s_waitcnt vmcnt(15)
	v_cvt_scalef32_pk_f32_fp4 v[0:1], v150, 1.0
	v_cvt_scalef32_pk_f32_fp4 v[2:3], v150, 1.0 op_sel:[1,0,0]
	v_cvt_scalef32_pk_f32_fp4 v[4:5], v150, 1.0 op_sel:[0,1,0]
	v_cvt_scalef32_pk_f32_fp4 v[6:7], v150, 1.0 op_sel:[1,1,0]
	v_cvt_scalef32_pk_f32_fp4 v[8:9], v151, 1.0
	v_cvt_scalef32_pk_f32_fp4 v[10:11], v151, 1.0 op_sel:[1,0,0]
	v_cvt_scalef32_pk_f32_fp4 v[12:13], v151, 1.0 op_sel:[0,1,0]
	v_cvt_scalef32_pk_f32_fp4 v[14:15], v151, 1.0 op_sel:[1,1,0]
	v_readlane_b32 s54, v90, 35
	s_lshl_b32 s56, s54, 9
	s_add_u32 s56, s64, s56
	s_addc_u32 s57, s65, 0
	global_load_dwordx2 v[150:151], v227, s[56:57]
	s_waitcnt lgkmcnt(1)
	v_pk_fma_f32 v[130:131], v[0:1], v[194:195], v[130:131] op_sel_hi:[1,0,1]
	v_pk_fma_f32 v[138:139], v[2:3], v[194:195], v[138:139] op_sel_hi:[1,0,1]
	v_pk_fma_f32 v[140:141], v[4:5], v[194:195], v[140:141] op_sel_hi:[1,0,1]
	v_pk_fma_f32 v[142:143], v[6:7], v[194:195], v[142:143] op_sel_hi:[1,0,1]
	v_pk_fma_f32 v[128:129], v[8:9], v[194:195], v[128:129] op_sel_hi:[1,0,1]
	v_pk_fma_f32 v[132:133], v[10:11], v[194:195], v[132:133] op_sel_hi:[1,0,1]
	v_pk_fma_f32 v[134:135], v[12:13], v[194:195], v[134:135] op_sel_hi:[1,0,1]
	v_pk_fma_f32 v[136:137], v[14:15], v[194:195], v[136:137] op_sel_hi:[1,0,1]
	ds_read_b32 v194, v193 offset:340
	s_waitcnt vmcnt(15)
	v_cvt_scalef32_pk_f32_fp4 v[0:1], v152, 1.0
	v_cvt_scalef32_pk_f32_fp4 v[2:3], v152, 1.0 op_sel:[1,0,0]
	v_cvt_scalef32_pk_f32_fp4 v[4:5], v152, 1.0 op_sel:[0,1,0]
	v_cvt_scalef32_pk_f32_fp4 v[6:7], v152, 1.0 op_sel:[1,1,0]
	v_cvt_scalef32_pk_f32_fp4 v[8:9], v153, 1.0
	v_cvt_scalef32_pk_f32_fp4 v[10:11], v153, 1.0 op_sel:[1,0,0]
	v_cvt_scalef32_pk_f32_fp4 v[12:13], v153, 1.0 op_sel:[0,1,0]
	v_cvt_scalef32_pk_f32_fp4 v[14:15], v153, 1.0 op_sel:[1,1,0]
	v_readlane_b32 s54, v90, 36
	s_lshl_b32 s56, s54, 9
	s_add_u32 s56, s64, s56
	s_addc_u32 s57, s65, 0
	global_load_dwordx2 v[152:153], v227, s[56:57]
	s_waitcnt lgkmcnt(1)
	v_pk_fma_f32 v[130:131], v[0:1], v[76:77], v[130:131] op_sel_hi:[1,0,1]
	v_pk_fma_f32 v[138:139], v[2:3], v[76:77], v[138:139] op_sel_hi:[1,0,1]
	v_pk_fma_f32 v[140:141], v[4:5], v[76:77], v[140:141] op_sel_hi:[1,0,1]
	v_pk_fma_f32 v[142:143], v[6:7], v[76:77], v[142:143] op_sel_hi:[1,0,1]
	v_pk_fma_f32 v[128:129], v[8:9], v[76:77], v[128:129] op_sel_hi:[1,0,1]
	v_pk_fma_f32 v[132:133], v[10:11], v[76:77], v[132:133] op_sel_hi:[1,0,1]
	v_pk_fma_f32 v[134:135], v[12:13], v[76:77], v[134:135] op_sel_hi:[1,0,1]
	v_pk_fma_f32 v[136:137], v[14:15], v[76:77], v[136:137] op_sel_hi:[1,0,1]
	ds_read_b32 v76, v193 offset:344
	s_waitcnt vmcnt(15)
	v_cvt_scalef32_pk_f32_fp4 v[0:1], v154, 1.0
	v_cvt_scalef32_pk_f32_fp4 v[2:3], v154, 1.0 op_sel:[1,0,0]
	v_cvt_scalef32_pk_f32_fp4 v[4:5], v154, 1.0 op_sel:[0,1,0]
	v_cvt_scalef32_pk_f32_fp4 v[6:7], v154, 1.0 op_sel:[1,1,0]
	v_cvt_scalef32_pk_f32_fp4 v[8:9], v155, 1.0
	v_cvt_scalef32_pk_f32_fp4 v[10:11], v155, 1.0 op_sel:[1,0,0]
	v_cvt_scalef32_pk_f32_fp4 v[12:13], v155, 1.0 op_sel:[0,1,0]
	v_cvt_scalef32_pk_f32_fp4 v[14:15], v155, 1.0 op_sel:[1,1,0]
	v_readlane_b32 s54, v90, 37
	s_lshl_b32 s56, s54, 9
	s_add_u32 s56, s64, s56
	s_addc_u32 s57, s65, 0
	global_load_dwordx2 v[154:155], v227, s[56:57]
	s_waitcnt lgkmcnt(1)
; __device__ void peer_gather_phase(const Params& P, int l, bool do_store) {
;     ...
;         const int ea = __builtin_amdgcn_readlane(evs, kb + 2 * pr), eb = __builtin_amdgcn_readlane(evs, kb + 2 * pr + 1);
;         const uint2* up = (const uint2*)(U + (size_t)(uphi ? eb : ea) * 768);
;         u6[3 * pr] = up[0]; u6[3 * pr + 1] = up[1]; u6[3 * pr + 2] = up[2];
;         v8[2 * pr] = *(const uint2*)(V + (size_t)ea * 512);
;         v8[2 * pr + 1] = *(const uint2*)(V + (size_t)eb * 512);
;     ...
; #pragma unroll
;       for (int j = 0; j < 8; ++j) {
;         const float a = __builtin_bit_cast(float, __builtin_amdgcn_readlane(__builtin_bit_cast(int, avec), kb + j));
;         const f32x2 aa = f32x2{a, a};
;         y[0] += aa * __builtin_amdgcn_cvt_scalef32_pk_f32_fp4(v8[j].x, 1.0f, 0); y[1] += aa * __builtin_amdgcn_cvt_scalef32_pk_f32_fp4(v8[j].x, 1.0f, 1);
;         y[2] += aa * __builtin_amdgcn_cvt_scalef32_pk_f32_fp4(v8[j].x, 1.0f, 2); y[3] += aa * __builtin_amdgcn_cvt_scalef32_pk_f32_fp4(v8[j].x, 1.0f, 3);
;         y[4] += aa * __builtin_amdgcn_cvt_scalef32_pk_f32_fp4(v8[j].y, 1.0f, 0); y[5] += aa * __builtin_amdgcn_cvt_scalef32_pk_f32_fp4(v8[j].y, 1.0f, 1);
;         y[6] += aa * __builtin_amdgcn_cvt_scalef32_pk_f32_fp4(v8[j].y, 1.0f, 2); y[7] += aa * __builtin_amdgcn_cvt_scalef32_pk_f32_fp4(v8[j].y, 1.0f, 3);
;       }
	v_pk_fma_f32 v[130:131], v[0:1], v[194:195], v[130:131] op_sel_hi:[1,0,1]
	v_pk_fma_f32 v[138:139], v[2:3], v[194:195], v[138:139] op_sel_hi:[1,0,1]
	v_pk_fma_f32 v[140:141], v[4:5], v[194:195], v[140:141] op_sel_hi:[1,0,1]
	v_pk_fma_f32 v[142:143], v[6:7], v[194:195], v[142:143] op_sel_hi:[1,0,1]
	v_pk_fma_f32 v[128:129], v[8:9], v[194:195], v[128:129] op_sel_hi:[1,0,1]
	v_pk_fma_f32 v[132:133], v[10:11], v[194:195], v[132:133] op_sel_hi:[1,0,1]
	v_pk_fma_f32 v[134:135], v[12:13], v[194:195], v[134:135] op_sel_hi:[1,0,1]
	v_pk_fma_f32 v[136:137], v[14:15], v[194:195], v[136:137] op_sel_hi:[1,0,1]
	ds_read_b32 v194, v193 offset:348
	s_waitcnt vmcnt(15)
	v_cvt_scalef32_pk_f32_fp4 v[0:1], v156, 1.0
	v_cvt_scalef32_pk_f32_fp4 v[2:3], v156, 1.0 op_sel:[1,0,0]
	v_cvt_scalef32_pk_f32_fp4 v[4:5], v156, 1.0 op_sel:[0,1,0]
	v_cvt_scalef32_pk_f32_fp4 v[6:7], v156, 1.0 op_sel:[1,1,0]
	v_cvt_scalef32_pk_f32_fp4 v[8:9], v157, 1.0
	v_cvt_scalef32_pk_f32_fp4 v[10:11], v157, 1.0 op_sel:[1,0,0]
	v_cvt_scalef32_pk_f32_fp4 v[12:13], v157, 1.0 op_sel:[0,1,0]
	v_cvt_scalef32_pk_f32_fp4 v[14:15], v157, 1.0 op_sel:[1,1,0]
	v_readlane_b32 s54, v90, 38
	s_lshl_b32 s56, s54, 9
	s_add_u32 s56, s64, s56
	s_addc_u32 s57, s65, 0
	global_load_dwordx2 v[156:157], v227, s[56:57]
	s_waitcnt lgkmcnt(1)
	v_pk_fma_f32 v[130:131], v[0:1], v[76:77], v[130:131] op_sel_hi:[1,0,1]
	v_pk_fma_f32 v[138:139], v[2:3], v[76:77], v[138:139] op_sel_hi:[1,0,1]
	v_pk_fma_f32 v[140:141], v[4:5], v[76:77], v[140:141] op_sel_hi:[1,0,1]
	v_pk_fma_f32 v[142:143], v[6:7], v[76:77], v[142:143] op_sel_hi:[1,0,1]
	v_pk_fma_f32 v[128:129], v[8:9], v[76:77], v[128:129] op_sel_hi:[1,0,1]
	v_pk_fma_f32 v[132:133], v[10:11], v[76:77], v[132:133] op_sel_hi:[1,0,1]
	v_pk_fma_f32 v[134:135], v[12:13], v[76:77], v[134:135] op_sel_hi:[1,0,1]
	v_pk_fma_f32 v[136:137], v[14:15], v[76:77], v[136:137] op_sel_hi:[1,0,1]
	ds_read_b32 v76, v193 offset:352
	s_waitcnt vmcnt(15)
	v_cvt_scalef32_pk_f32_fp4 v[0:1], v158, 1.0
	v_cvt_scalef32_pk_f32_fp4 v[2:3], v158, 1.0 op_sel:[1,0,0]
	v_cvt_scalef32_pk_f32_fp4 v[4:5], v158, 1.0 op_sel:[0,1,0]
	v_cvt_scalef32_pk_f32_fp4 v[6:7], v158, 1.0 op_sel:[1,1,0]
	v_cvt_scalef32_pk_f32_fp4 v[8:9], v159, 1.0
	v_cvt_scalef32_pk_f32_fp4 v[10:11], v159, 1.0 op_sel:[1,0,0]
	v_cvt_scalef32_pk_f32_fp4 v[12:13], v159, 1.0 op_sel:[0,1,0]
	v_cvt_scalef32_pk_f32_fp4 v[14:15], v159, 1.0 op_sel:[1,1,0]
	v_readlane_b32 s54, v90, 39
	s_lshl_b32 s56, s54, 9
	s_add_u32 s56, s64, s56
	s_addc_u32 s57, s65, 0
	global_load_dwordx2 v[158:159], v227, s[56:57]
	s_waitcnt lgkmcnt(1)
	v_pk_fma_f32 v[130:131], v[0:1], v[194:195], v[130:131] op_sel_hi:[1,0,1]
	v_pk_fma_f32 v[138:139], v[2:3], v[194:195], v[138:139] op_sel_hi:[1,0,1]
	v_pk_fma_f32 v[140:141], v[4:5], v[194:195], v[140:141] op_sel_hi:[1,0,1]
	v_pk_fma_f32 v[142:143], v[6:7], v[194:195], v[142:143] op_sel_hi:[1,0,1]
	v_pk_fma_f32 v[128:129], v[8:9], v[194:195], v[128:129] op_sel_hi:[1,0,1]
	v_pk_fma_f32 v[132:133], v[10:11], v[194:195], v[132:133] op_sel_hi:[1,0,1]
	v_pk_fma_f32 v[134:135], v[12:13], v[194:195], v[134:135] op_sel_hi:[1,0,1]
	v_pk_fma_f32 v[136:137], v[14:15], v[194:195], v[136:137] op_sel_hi:[1,0,1]
	ds_read_b32 v194, v193 offset:356
	s_waitcnt vmcnt(15)
	v_cvt_scalef32_pk_f32_fp4 v[0:1], v168, 1.0
	v_cvt_scalef32_pk_f32_fp4 v[2:3], v168, 1.0 op_sel:[1,0,0]
	v_cvt_scalef32_pk_f32_fp4 v[4:5], v168, 1.0 op_sel:[0,1,0]
	v_cvt_scalef32_pk_f32_fp4 v[6:7], v168, 1.0 op_sel:[1,1,0]
	v_cvt_scalef32_pk_f32_fp4 v[8:9], v169, 1.0
	v_cvt_scalef32_pk_f32_fp4 v[10:11], v169, 1.0 op_sel:[1,0,0]
	v_cvt_scalef32_pk_f32_fp4 v[12:13], v169, 1.0 op_sel:[0,1,0]
	v_cvt_scalef32_pk_f32_fp4 v[14:15], v169, 1.0 op_sel:[1,1,0]
	v_readlane_b32 s54, v90, 40
	s_lshl_b32 s56, s54, 9
	s_add_u32 s56, s64, s56
	s_addc_u32 s57, s65, 0
	global_load_dwordx2 v[168:169], v227, s[56:57]
	s_waitcnt lgkmcnt(1)
	v_pk_fma_f32 v[130:131], v[0:1], v[76:77], v[130:131] op_sel_hi:[1,0,1]
	v_pk_fma_f32 v[138:139], v[2:3], v[76:77], v[138:139] op_sel_hi:[1,0,1]
	v_pk_fma_f32 v[140:141], v[4:5], v[76:77], v[140:141] op_sel_hi:[1,0,1]
	v_pk_fma_f32 v[142:143], v[6:7], v[76:77], v[142:143] op_sel_hi:[1,0,1]
	v_pk_fma_f32 v[128:129], v[8:9], v[76:77], v[128:129] op_sel_hi:[1,0,1]
	v_pk_fma_f32 v[132:133], v[10:11], v[76:77], v[132:133] op_sel_hi:[1,0,1]
	v_pk_fma_f32 v[134:135], v[12:13], v[76:77], v[134:135] op_sel_hi:[1,0,1]
	v_pk_fma_f32 v[136:137], v[14:15], v[76:77], v[136:137] op_sel_hi:[1,0,1]
	ds_read_b32 v76, v193 offset:360
	s_waitcnt vmcnt(15)
	v_cvt_scalef32_pk_f32_fp4 v[0:1], v170, 1.0
	v_cvt_scalef32_pk_f32_fp4 v[2:3], v170, 1.0 op_sel:[1,0,0]
	v_cvt_scalef32_pk_f32_fp4 v[4:5], v170, 1.0 op_sel:[0,1,0]
	v_cvt_scalef32_pk_f32_fp4 v[6:7], v170, 1.0 op_sel:[1,1,0]
	v_cvt_scalef32_pk_f32_fp4 v[8:9], v171, 1.0
	v_cvt_scalef32_pk_f32_fp4 v[10:11], v171, 1.0 op_sel:[1,0,0]
	v_cvt_scalef32_pk_f32_fp4 v[12:13], v171, 1.0 op_sel:[0,1,0]
	v_cvt_scalef32_pk_f32_fp4 v[14:15], v171, 1.0 op_sel:[1,1,0]
	v_readlane_b32 s54, v90, 41
	s_lshl_b32 s56, s54, 9
	s_add_u32 s56, s64, s56
	s_addc_u32 s57, s65, 0
	global_load_dwordx2 v[170:171], v227, s[56:57]
	s_waitcnt lgkmcnt(1)
	v_pk_fma_f32 v[130:131], v[0:1], v[194:195], v[130:131] op_sel_hi:[1,0,1]
	v_pk_fma_f32 v[138:139], v[2:3], v[194:195], v[138:139] op_sel_hi:[1,0,1]
	v_pk_fma_f32 v[140:141], v[4:5], v[194:195], v[140:141] op_sel_hi:[1,0,1]
	v_pk_fma_f32 v[142:143], v[6:7], v[194:195], v[142:143] op_sel_hi:[1,0,1]
	v_pk_fma_f32 v[128:129], v[8:9], v[194:195], v[128:129] op_sel_hi:[1,0,1]
	v_pk_fma_f32 v[132:133], v[10:11], v[194:195], v[132:133] op_sel_hi:[1,0,1]
	v_pk_fma_f32 v[134:135], v[12:13], v[194:195], v[134:135] op_sel_hi:[1,0,1]
	v_pk_fma_f32 v[136:137], v[14:15], v[194:195], v[136:137] op_sel_hi:[1,0,1]
	ds_read_b32 v194, v193 offset:364
	s_waitcnt vmcnt(15)
; __device__ void peer_gather_phase(const Params& P, int l, bool do_store) {
;     ...
;         const int ea = __builtin_amdgcn_readlane(evs, kb + 2 * pr), eb = __builtin_amdgcn_readlane(evs, kb + 2 * pr + 1);
;         const uint2* up = (const uint2*)(U + (size_t)(uphi ? eb : ea) * 768);
;         u6[3 * pr] = up[0]; u6[3 * pr + 1] = up[1]; u6[3 * pr + 2] = up[2];
;         v8[2 * pr] = *(const uint2*)(V + (size_t)ea * 512);
;         v8[2 * pr + 1] = *(const uint2*)(V + (size_t)eb * 512);
;     ...
; #pragma unroll
;       for (int j = 0; j < 8; ++j) {
;         const float a = __builtin_bit_cast(float, __builtin_amdgcn_readlane(__builtin_bit_cast(int, avec), kb + j));
;         const f32x2 aa = f32x2{a, a};
;         y[0] += aa * __builtin_amdgcn_cvt_scalef32_pk_f32_fp4(v8[j].x, 1.0f, 0); y[1] += aa * __builtin_amdgcn_cvt_scalef32_pk_f32_fp4(v8[j].x, 1.0f, 1);
;         y[2] += aa * __builtin_amdgcn_cvt_scalef32_pk_f32_fp4(v8[j].x, 1.0f, 2); y[3] += aa * __builtin_amdgcn_cvt_scalef32_pk_f32_fp4(v8[j].x, 1.0f, 3);
;         y[4] += aa * __builtin_amdgcn_cvt_scalef32_pk_f32_fp4(v8[j].y, 1.0f, 0); y[5] += aa * __builtin_amdgcn_cvt_scalef32_pk_f32_fp4(v8[j].y, 1.0f, 1);
;         y[6] += aa * __builtin_amdgcn_cvt_scalef32_pk_f32_fp4(v8[j].y, 1.0f, 2); y[7] += aa * __builtin_amdgcn_cvt_scalef32_pk_f32_fp4(v8[j].y, 1.0f, 3);
;       }
	v_cvt_scalef32_pk_f32_fp4 v[0:1], v172, 1.0
	v_cvt_scalef32_pk_f32_fp4 v[2:3], v172, 1.0 op_sel:[1,0,0]
	v_cvt_scalef32_pk_f32_fp4 v[4:5], v172, 1.0 op_sel:[0,1,0]
	v_cvt_scalef32_pk_f32_fp4 v[6:7], v172, 1.0 op_sel:[1,1,0]
	v_cvt_scalef32_pk_f32_fp4 v[8:9], v173, 1.0
	v_cvt_scalef32_pk_f32_fp4 v[10:11], v173, 1.0 op_sel:[1,0,0]
	v_cvt_scalef32_pk_f32_fp4 v[12:13], v173, 1.0 op_sel:[0,1,0]
	v_cvt_scalef32_pk_f32_fp4 v[14:15], v173, 1.0 op_sel:[1,1,0]
	v_readlane_b32 s54, v90, 42
	s_lshl_b32 s56, s54, 9
	s_add_u32 s56, s64, s56
	s_addc_u32 s57, s65, 0
	global_load_dwordx2 v[172:173], v227, s[56:57]
	s_waitcnt lgkmcnt(1)
	v_pk_fma_f32 v[130:131], v[0:1], v[76:77], v[130:131] op_sel_hi:[1,0,1]
	v_pk_fma_f32 v[138:139], v[2:3], v[76:77], v[138:139] op_sel_hi:[1,0,1]
	v_pk_fma_f32 v[140:141], v[4:5], v[76:77], v[140:141] op_sel_hi:[1,0,1]
	v_pk_fma_f32 v[142:143], v[6:7], v[76:77], v[142:143] op_sel_hi:[1,0,1]
	v_pk_fma_f32 v[128:129], v[8:9], v[76:77], v[128:129] op_sel_hi:[1,0,1]
	v_pk_fma_f32 v[132:133], v[10:11], v[76:77], v[132:133] op_sel_hi:[1,0,1]
	v_pk_fma_f32 v[134:135], v[12:13], v[76:77], v[134:135] op_sel_hi:[1,0,1]
	v_pk_fma_f32 v[136:137], v[14:15], v[76:77], v[136:137] op_sel_hi:[1,0,1]
	ds_read_b32 v76, v193 offset:368
	s_waitcnt vmcnt(15)
	v_cvt_scalef32_pk_f32_fp4 v[0:1], v174, 1.0
	v_cvt_scalef32_pk_f32_fp4 v[2:3], v174, 1.0 op_sel:[1,0,0]
	v_cvt_scalef32_pk_f32_fp4 v[4:5], v174, 1.0 op_sel:[0,1,0]
	v_cvt_scalef32_pk_f32_fp4 v[6:7], v174, 1.0 op_sel:[1,1,0]
	v_cvt_scalef32_pk_f32_fp4 v[8:9], v175, 1.0
	v_cvt_scalef32_pk_f32_fp4 v[10:11], v175, 1.0 op_sel:[1,0,0]
	v_cvt_scalef32_pk_f32_fp4 v[12:13], v175, 1.0 op_sel:[0,1,0]
	v_cvt_scalef32_pk_f32_fp4 v[14:15], v175, 1.0 op_sel:[1,1,0]
	v_readlane_b32 s54, v90, 43
	s_lshl_b32 s56, s54, 9
	s_add_u32 s56, s64, s56
	s_addc_u32 s57, s65, 0
	global_load_dwordx2 v[174:175], v227, s[56:57]
	s_waitcnt lgkmcnt(1)
	v_pk_fma_f32 v[130:131], v[0:1], v[194:195], v[130:131] op_sel_hi:[1,0,1]
	v_pk_fma_f32 v[138:139], v[2:3], v[194:195], v[138:139] op_sel_hi:[1,0,1]
	v_pk_fma_f32 v[140:141], v[4:5], v[194:195], v[140:141] op_sel_hi:[1,0,1]
	v_pk_fma_f32 v[142:143], v[6:7], v[194:195], v[142:143] op_sel_hi:[1,0,1]
	v_pk_fma_f32 v[128:129], v[8:9], v[194:195], v[128:129] op_sel_hi:[1,0,1]
	v_pk_fma_f32 v[132:133], v[10:11], v[194:195], v[132:133] op_sel_hi:[1,0,1]
	v_pk_fma_f32 v[134:135], v[12:13], v[194:195], v[134:135] op_sel_hi:[1,0,1]
	v_pk_fma_f32 v[136:137], v[14:15], v[194:195], v[136:137] op_sel_hi:[1,0,1]
	ds_read_b32 v194, v193 offset:372
	s_waitcnt vmcnt(15)
	v_cvt_scalef32_pk_f32_fp4 v[0:1], v180, 1.0
	v_cvt_scalef32_pk_f32_fp4 v[2:3], v180, 1.0 op_sel:[1,0,0]
	v_cvt_scalef32_pk_f32_fp4 v[4:5], v180, 1.0 op_sel:[0,1,0]
	v_cvt_scalef32_pk_f32_fp4 v[6:7], v180, 1.0 op_sel:[1,1,0]
	v_cvt_scalef32_pk_f32_fp4 v[8:9], v181, 1.0
	v_cvt_scalef32_pk_f32_fp4 v[10:11], v181, 1.0 op_sel:[1,0,0]
	v_cvt_scalef32_pk_f32_fp4 v[12:13], v181, 1.0 op_sel:[0,1,0]
	v_cvt_scalef32_pk_f32_fp4 v[14:15], v181, 1.0 op_sel:[1,1,0]
	v_readlane_b32 s54, v90, 44
	s_lshl_b32 s56, s54, 9
	s_add_u32 s56, s64, s56
	s_addc_u32 s57, s65, 0
	global_load_dwordx2 v[180:181], v227, s[56:57]
	s_waitcnt lgkmcnt(1)
	v_pk_fma_f32 v[130:131], v[0:1], v[76:77], v[130:131] op_sel_hi:[1,0,1]
	v_pk_fma_f32 v[138:139], v[2:3], v[76:77], v[138:139] op_sel_hi:[1,0,1]
	v_pk_fma_f32 v[140:141], v[4:5], v[76:77], v[140:141] op_sel_hi:[1,0,1]
	v_pk_fma_f32 v[142:143], v[6:7], v[76:77], v[142:143] op_sel_hi:[1,0,1]
	v_pk_fma_f32 v[128:129], v[8:9], v[76:77], v[128:129] op_sel_hi:[1,0,1]
	v_pk_fma_f32 v[132:133], v[10:11], v[76:77], v[132:133] op_sel_hi:[1,0,1]
	v_pk_fma_f32 v[134:135], v[12:13], v[76:77], v[134:135] op_sel_hi:[1,0,1]
	v_pk_fma_f32 v[136:137], v[14:15], v[76:77], v[136:137] op_sel_hi:[1,0,1]
	ds_read_b32 v76, v193 offset:376
	s_waitcnt vmcnt(15)
	v_cvt_scalef32_pk_f32_fp4 v[0:1], v182, 1.0
	v_cvt_scalef32_pk_f32_fp4 v[2:3], v182, 1.0 op_sel:[1,0,0]
	v_cvt_scalef32_pk_f32_fp4 v[4:5], v182, 1.0 op_sel:[0,1,0]
	v_cvt_scalef32_pk_f32_fp4 v[6:7], v182, 1.0 op_sel:[1,1,0]
	v_cvt_scalef32_pk_f32_fp4 v[8:9], v183, 1.0
	v_cvt_scalef32_pk_f32_fp4 v[10:11], v183, 1.0 op_sel:[1,0,0]
	v_cvt_scalef32_pk_f32_fp4 v[12:13], v183, 1.0 op_sel:[0,1,0]
	v_cvt_scalef32_pk_f32_fp4 v[14:15], v183, 1.0 op_sel:[1,1,0]
	v_readlane_b32 s54, v90, 45
	s_lshl_b32 s56, s54, 9
	s_add_u32 s56, s64, s56
	s_addc_u32 s57, s65, 0
	global_load_dwordx2 v[182:183], v227, s[56:57]
	s_waitcnt lgkmcnt(1)
	v_pk_fma_f32 v[130:131], v[0:1], v[194:195], v[130:131] op_sel_hi:[1,0,1]
	v_pk_fma_f32 v[138:139], v[2:3], v[194:195], v[138:139] op_sel_hi:[1,0,1]
	v_pk_fma_f32 v[140:141], v[4:5], v[194:195], v[140:141] op_sel_hi:[1,0,1]
	v_pk_fma_f32 v[142:143], v[6:7], v[194:195], v[142:143] op_sel_hi:[1,0,1]
	v_pk_fma_f32 v[128:129], v[8:9], v[194:195], v[128:129] op_sel_hi:[1,0,1]
	v_pk_fma_f32 v[132:133], v[10:11], v[194:195], v[132:133] op_sel_hi:[1,0,1]
	v_pk_fma_f32 v[134:135], v[12:13], v[194:195], v[134:135] op_sel_hi:[1,0,1]
	v_pk_fma_f32 v[136:137], v[14:15], v[194:195], v[136:137] op_sel_hi:[1,0,1]
	ds_read_b32 v194, v193 offset:380
	s_waitcnt vmcnt(15)
	v_cvt_scalef32_pk_f32_fp4 v[0:1], v184, 1.0
	v_cvt_scalef32_pk_f32_fp4 v[2:3], v184, 1.0 op_sel:[1,0,0]
	v_cvt_scalef32_pk_f32_fp4 v[4:5], v184, 1.0 op_sel:[0,1,0]
	v_cvt_scalef32_pk_f32_fp4 v[6:7], v184, 1.0 op_sel:[1,1,0]
	v_cvt_scalef32_pk_f32_fp4 v[8:9], v185, 1.0
	v_cvt_scalef32_pk_f32_fp4 v[10:11], v185, 1.0 op_sel:[1,0,0]
	v_cvt_scalef32_pk_f32_fp4 v[12:13], v185, 1.0 op_sel:[0,1,0]
	v_cvt_scalef32_pk_f32_fp4 v[14:15], v185, 1.0 op_sel:[1,1,0]
	v_readlane_b32 s54, v90, 46
	s_lshl_b32 s56, s54, 9
	s_add_u32 s56, s64, s56
	s_addc_u32 s57, s65, 0
	global_load_dwordx2 v[184:185], v227, s[56:57]
	s_waitcnt lgkmcnt(1)
; __device__ void peer_gather_phase(const Params& P, int l, bool do_store) {
;     ...
;         const int ea = __builtin_amdgcn_readlane(evs, kb + 2 * pr), eb = __builtin_amdgcn_readlane(evs, kb + 2 * pr + 1);
;         const uint2* up = (const uint2*)(U + (size_t)(uphi ? eb : ea) * 768);
;         u6[3 * pr] = up[0]; u6[3 * pr + 1] = up[1]; u6[3 * pr + 2] = up[2];
;         v8[2 * pr] = *(const uint2*)(V + (size_t)ea * 512);
;         v8[2 * pr + 1] = *(const uint2*)(V + (size_t)eb * 512);
;     ...
; #pragma unroll
;       for (int j = 0; j < 8; ++j) {
;         const float a = __builtin_bit_cast(float, __builtin_amdgcn_readlane(__builtin_bit_cast(int, avec), kb + j));
;         const f32x2 aa = f32x2{a, a};
;         y[0] += aa * __builtin_amdgcn_cvt_scalef32_pk_f32_fp4(v8[j].x, 1.0f, 0); y[1] += aa * __builtin_amdgcn_cvt_scalef32_pk_f32_fp4(v8[j].x, 1.0f, 1);
;         y[2] += aa * __builtin_amdgcn_cvt_scalef32_pk_f32_fp4(v8[j].x, 1.0f, 2); y[3] += aa * __builtin_amdgcn_cvt_scalef32_pk_f32_fp4(v8[j].x, 1.0f, 3);
;         y[4] += aa * __builtin_amdgcn_cvt_scalef32_pk_f32_fp4(v8[j].y, 1.0f, 0); y[5] += aa * __builtin_amdgcn_cvt_scalef32_pk_f32_fp4(v8[j].y, 1.0f, 1);
;         y[6] += aa * __builtin_amdgcn_cvt_scalef32_pk_f32_fp4(v8[j].y, 1.0f, 2); y[7] += aa * __builtin_amdgcn_cvt_scalef32_pk_f32_fp4(v8[j].y, 1.0f, 3);
;       }
	v_pk_fma_f32 v[130:131], v[0:1], v[76:77], v[130:131] op_sel_hi:[1,0,1]
	v_pk_fma_f32 v[138:139], v[2:3], v[76:77], v[138:139] op_sel_hi:[1,0,1]
	v_pk_fma_f32 v[140:141], v[4:5], v[76:77], v[140:141] op_sel_hi:[1,0,1]
	v_pk_fma_f32 v[142:143], v[6:7], v[76:77], v[142:143] op_sel_hi:[1,0,1]
	v_pk_fma_f32 v[128:129], v[8:9], v[76:77], v[128:129] op_sel_hi:[1,0,1]
	v_pk_fma_f32 v[132:133], v[10:11], v[76:77], v[132:133] op_sel_hi:[1,0,1]
	v_pk_fma_f32 v[134:135], v[12:13], v[76:77], v[134:135] op_sel_hi:[1,0,1]
	v_pk_fma_f32 v[136:137], v[14:15], v[76:77], v[136:137] op_sel_hi:[1,0,1]
	ds_read_b32 v76, v193 offset:384
	s_waitcnt vmcnt(15)
	v_cvt_scalef32_pk_f32_fp4 v[0:1], v186, 1.0
	v_cvt_scalef32_pk_f32_fp4 v[2:3], v186, 1.0 op_sel:[1,0,0]
	v_cvt_scalef32_pk_f32_fp4 v[4:5], v186, 1.0 op_sel:[0,1,0]
	v_cvt_scalef32_pk_f32_fp4 v[6:7], v186, 1.0 op_sel:[1,1,0]
	v_cvt_scalef32_pk_f32_fp4 v[8:9], v187, 1.0
	v_cvt_scalef32_pk_f32_fp4 v[10:11], v187, 1.0 op_sel:[1,0,0]
	v_cvt_scalef32_pk_f32_fp4 v[12:13], v187, 1.0 op_sel:[0,1,0]
	v_cvt_scalef32_pk_f32_fp4 v[14:15], v187, 1.0 op_sel:[1,1,0]
	v_readlane_b32 s54, v90, 47
	s_lshl_b32 s56, s54, 9
	s_add_u32 s56, s64, s56
	s_addc_u32 s57, s65, 0
	global_load_dwordx2 v[186:187], v227, s[56:57]
	s_waitcnt lgkmcnt(1)
	v_pk_fma_f32 v[130:131], v[0:1], v[194:195], v[130:131] op_sel_hi:[1,0,1]
	v_pk_fma_f32 v[138:139], v[2:3], v[194:195], v[138:139] op_sel_hi:[1,0,1]
	v_pk_fma_f32 v[140:141], v[4:5], v[194:195], v[140:141] op_sel_hi:[1,0,1]
	v_pk_fma_f32 v[142:143], v[6:7], v[194:195], v[142:143] op_sel_hi:[1,0,1]
	v_pk_fma_f32 v[128:129], v[8:9], v[194:195], v[128:129] op_sel_hi:[1,0,1]
	v_pk_fma_f32 v[132:133], v[10:11], v[194:195], v[132:133] op_sel_hi:[1,0,1]
	v_pk_fma_f32 v[134:135], v[12:13], v[194:195], v[134:135] op_sel_hi:[1,0,1]
	v_pk_fma_f32 v[136:137], v[14:15], v[194:195], v[136:137] op_sel_hi:[1,0,1]
	ds_read_b32 v194, v193 offset:388
	s_waitcnt vmcnt(15)
	v_cvt_scalef32_pk_f32_fp4 v[0:1], v144, 1.0
	v_cvt_scalef32_pk_f32_fp4 v[2:3], v144, 1.0 op_sel:[1,0,0]
	v_cvt_scalef32_pk_f32_fp4 v[4:5], v144, 1.0 op_sel:[0,1,0]
	v_cvt_scalef32_pk_f32_fp4 v[6:7], v144, 1.0 op_sel:[1,1,0]
	v_cvt_scalef32_pk_f32_fp4 v[8:9], v145, 1.0
	v_cvt_scalef32_pk_f32_fp4 v[10:11], v145, 1.0 op_sel:[1,0,0]
	v_cvt_scalef32_pk_f32_fp4 v[12:13], v145, 1.0 op_sel:[0,1,0]
	v_cvt_scalef32_pk_f32_fp4 v[14:15], v145, 1.0 op_sel:[1,1,0]
	v_readlane_b32 s54, v90, 48
	s_lshl_b32 s56, s54, 9
	s_add_u32 s56, s64, s56
	s_addc_u32 s57, s65, 0
	global_load_dwordx2 v[144:145], v227, s[56:57]
	s_waitcnt lgkmcnt(1)
	v_pk_fma_f32 v[130:131], v[0:1], v[76:77], v[130:131] op_sel_hi:[1,0,1]
	v_pk_fma_f32 v[138:139], v[2:3], v[76:77], v[138:139] op_sel_hi:[1,0,1]
	v_pk_fma_f32 v[140:141], v[4:5], v[76:77], v[140:141] op_sel_hi:[1,0,1]
	v_pk_fma_f32 v[142:143], v[6:7], v[76:77], v[142:143] op_sel_hi:[1,0,1]
	v_pk_fma_f32 v[128:129], v[8:9], v[76:77], v[128:129] op_sel_hi:[1,0,1]
	v_pk_fma_f32 v[132:133], v[10:11], v[76:77], v[132:133] op_sel_hi:[1,0,1]
	v_pk_fma_f32 v[134:135], v[12:13], v[76:77], v[134:135] op_sel_hi:[1,0,1]
	v_pk_fma_f32 v[136:137], v[14:15], v[76:77], v[136:137] op_sel_hi:[1,0,1]
	ds_read_b32 v76, v193 offset:392
	s_waitcnt vmcnt(15)
	v_cvt_scalef32_pk_f32_fp4 v[0:1], v146, 1.0
	v_cvt_scalef32_pk_f32_fp4 v[2:3], v146, 1.0 op_sel:[1,0,0]
	v_cvt_scalef32_pk_f32_fp4 v[4:5], v146, 1.0 op_sel:[0,1,0]
	v_cvt_scalef32_pk_f32_fp4 v[6:7], v146, 1.0 op_sel:[1,1,0]
	v_cvt_scalef32_pk_f32_fp4 v[8:9], v147, 1.0
	v_cvt_scalef32_pk_f32_fp4 v[10:11], v147, 1.0 op_sel:[1,0,0]
	v_cvt_scalef32_pk_f32_fp4 v[12:13], v147, 1.0 op_sel:[0,1,0]
	v_cvt_scalef32_pk_f32_fp4 v[14:15], v147, 1.0 op_sel:[1,1,0]
	v_readlane_b32 s54, v90, 49
	s_lshl_b32 s56, s54, 9
	s_add_u32 s56, s64, s56
	s_addc_u32 s57, s65, 0
	global_load_dwordx2 v[146:147], v227, s[56:57]
	s_waitcnt lgkmcnt(1)
	v_pk_fma_f32 v[130:131], v[0:1], v[194:195], v[130:131] op_sel_hi:[1,0,1]
	v_pk_fma_f32 v[138:139], v[2:3], v[194:195], v[138:139] op_sel_hi:[1,0,1]
	v_pk_fma_f32 v[140:141], v[4:5], v[194:195], v[140:141] op_sel_hi:[1,0,1]
	v_pk_fma_f32 v[142:143], v[6:7], v[194:195], v[142:143] op_sel_hi:[1,0,1]
	v_pk_fma_f32 v[128:129], v[8:9], v[194:195], v[128:129] op_sel_hi:[1,0,1]
	v_pk_fma_f32 v[132:133], v[10:11], v[194:195], v[132:133] op_sel_hi:[1,0,1]
	v_pk_fma_f32 v[134:135], v[12:13], v[194:195], v[134:135] op_sel_hi:[1,0,1]
	v_pk_fma_f32 v[136:137], v[14:15], v[194:195], v[136:137] op_sel_hi:[1,0,1]
	ds_read_b32 v194, v193 offset:396
	s_waitcnt vmcnt(15)
	v_cvt_scalef32_pk_f32_fp4 v[0:1], v148, 1.0
	v_cvt_scalef32_pk_f32_fp4 v[2:3], v148, 1.0 op_sel:[1,0,0]
	v_cvt_scalef32_pk_f32_fp4 v[4:5], v148, 1.0 op_sel:[0,1,0]
	v_cvt_scalef32_pk_f32_fp4 v[6:7], v148, 1.0 op_sel:[1,1,0]
	v_cvt_scalef32_pk_f32_fp4 v[8:9], v149, 1.0
	v_cvt_scalef32_pk_f32_fp4 v[10:11], v149, 1.0 op_sel:[1,0,0]
	v_cvt_scalef32_pk_f32_fp4 v[12:13], v149, 1.0 op_sel:[0,1,0]
	v_cvt_scalef32_pk_f32_fp4 v[14:15], v149, 1.0 op_sel:[1,1,0]
	v_readlane_b32 s54, v90, 50
	s_lshl_b32 s56, s54, 9
	s_add_u32 s56, s64, s56
	s_addc_u32 s57, s65, 0
	global_load_dwordx2 v[148:149], v227, s[56:57]
	s_waitcnt lgkmcnt(1)
	v_pk_fma_f32 v[130:131], v[0:1], v[76:77], v[130:131] op_sel_hi:[1,0,1]
	v_pk_fma_f32 v[138:139], v[2:3], v[76:77], v[138:139] op_sel_hi:[1,0,1]
	v_pk_fma_f32 v[140:141], v[4:5], v[76:77], v[140:141] op_sel_hi:[1,0,1]
	v_pk_fma_f32 v[142:143], v[6:7], v[76:77], v[142:143] op_sel_hi:[1,0,1]
	v_pk_fma_f32 v[128:129], v[8:9], v[76:77], v[128:129] op_sel_hi:[1,0,1]
	v_pk_fma_f32 v[132:133], v[10:11], v[76:77], v[132:133] op_sel_hi:[1,0,1]
	v_pk_fma_f32 v[134:135], v[12:13], v[76:77], v[134:135] op_sel_hi:[1,0,1]
	v_pk_fma_f32 v[136:137], v[14:15], v[76:77], v[136:137] op_sel_hi:[1,0,1]
	ds_read_b32 v76, v193 offset:400
	s_waitcnt vmcnt(15)
; __device__ void peer_gather_phase(const Params& P, int l, bool do_store) {
;     ...
;         const int ea = __builtin_amdgcn_readlane(evs, kb + 2 * pr), eb = __builtin_amdgcn_readlane(evs, kb + 2 * pr + 1);
;         const uint2* up = (const uint2*)(U + (size_t)(uphi ? eb : ea) * 768);
;         u6[3 * pr] = up[0]; u6[3 * pr + 1] = up[1]; u6[3 * pr + 2] = up[2];
;         v8[2 * pr] = *(const uint2*)(V + (size_t)ea * 512);
;         v8[2 * pr + 1] = *(const uint2*)(V + (size_t)eb * 512);
;     ...
; #pragma unroll
;       for (int j = 0; j < 8; ++j) {
;         const float a = __builtin_bit_cast(float, __builtin_amdgcn_readlane(__builtin_bit_cast(int, avec), kb + j));
;         const f32x2 aa = f32x2{a, a};
;         y[0] += aa * __builtin_amdgcn_cvt_scalef32_pk_f32_fp4(v8[j].x, 1.0f, 0); y[1] += aa * __builtin_amdgcn_cvt_scalef32_pk_f32_fp4(v8[j].x, 1.0f, 1);
;         y[2] += aa * __builtin_amdgcn_cvt_scalef32_pk_f32_fp4(v8[j].x, 1.0f, 2); y[3] += aa * __builtin_amdgcn_cvt_scalef32_pk_f32_fp4(v8[j].x, 1.0f, 3);
;         y[4] += aa * __builtin_amdgcn_cvt_scalef32_pk_f32_fp4(v8[j].y, 1.0f, 0); y[5] += aa * __builtin_amdgcn_cvt_scalef32_pk_f32_fp4(v8[j].y, 1.0f, 1);
;         y[6] += aa * __builtin_amdgcn_cvt_scalef32_pk_f32_fp4(v8[j].y, 1.0f, 2); y[7] += aa * __builtin_amdgcn_cvt_scalef32_pk_f32_fp4(v8[j].y, 1.0f, 3);
;       }
	v_cvt_scalef32_pk_f32_fp4 v[0:1], v150, 1.0
	v_cvt_scalef32_pk_f32_fp4 v[2:3], v150, 1.0 op_sel:[1,0,0]
	v_cvt_scalef32_pk_f32_fp4 v[4:5], v150, 1.0 op_sel:[0,1,0]
	v_cvt_scalef32_pk_f32_fp4 v[6:7], v150, 1.0 op_sel:[1,1,0]
	v_cvt_scalef32_pk_f32_fp4 v[8:9], v151, 1.0
	v_cvt_scalef32_pk_f32_fp4 v[10:11], v151, 1.0 op_sel:[1,0,0]
	v_cvt_scalef32_pk_f32_fp4 v[12:13], v151, 1.0 op_sel:[0,1,0]
	v_cvt_scalef32_pk_f32_fp4 v[14:15], v151, 1.0 op_sel:[1,1,0]
	v_readlane_b32 s54, v90, 51
	s_lshl_b32 s56, s54, 9
	s_add_u32 s56, s64, s56
	s_addc_u32 s57, s65, 0
	global_load_dwordx2 v[150:151], v227, s[56:57]
	s_waitcnt lgkmcnt(1)
	v_pk_fma_f32 v[130:131], v[0:1], v[194:195], v[130:131] op_sel_hi:[1,0,1]
	v_pk_fma_f32 v[138:139], v[2:3], v[194:195], v[138:139] op_sel_hi:[1,0,1]
	v_pk_fma_f32 v[140:141], v[4:5], v[194:195], v[140:141] op_sel_hi:[1,0,1]
	v_pk_fma_f32 v[142:143], v[6:7], v[194:195], v[142:143] op_sel_hi:[1,0,1]
	v_pk_fma_f32 v[128:129], v[8:9], v[194:195], v[128:129] op_sel_hi:[1,0,1]
	v_pk_fma_f32 v[132:133], v[10:11], v[194:195], v[132:133] op_sel_hi:[1,0,1]
	v_pk_fma_f32 v[134:135], v[12:13], v[194:195], v[134:135] op_sel_hi:[1,0,1]
	v_pk_fma_f32 v[136:137], v[14:15], v[194:195], v[136:137] op_sel_hi:[1,0,1]
	ds_read_b32 v194, v193 offset:404
	s_waitcnt vmcnt(15)
	v_cvt_scalef32_pk_f32_fp4 v[0:1], v152, 1.0
	v_cvt_scalef32_pk_f32_fp4 v[2:3], v152, 1.0 op_sel:[1,0,0]
	v_cvt_scalef32_pk_f32_fp4 v[4:5], v152, 1.0 op_sel:[0,1,0]
	v_cvt_scalef32_pk_f32_fp4 v[6:7], v152, 1.0 op_sel:[1,1,0]
	v_cvt_scalef32_pk_f32_fp4 v[8:9], v153, 1.0
	v_cvt_scalef32_pk_f32_fp4 v[10:11], v153, 1.0 op_sel:[1,0,0]
	v_cvt_scalef32_pk_f32_fp4 v[12:13], v153, 1.0 op_sel:[0,1,0]
	v_cvt_scalef32_pk_f32_fp4 v[14:15], v153, 1.0 op_sel:[1,1,0]
	v_readlane_b32 s54, v90, 52
	s_lshl_b32 s56, s54, 9
	s_add_u32 s56, s64, s56
	s_addc_u32 s57, s65, 0
	global_load_dwordx2 v[152:153], v227, s[56:57]
	s_waitcnt lgkmcnt(1)
	v_pk_fma_f32 v[130:131], v[0:1], v[76:77], v[130:131] op_sel_hi:[1,0,1]
	v_pk_fma_f32 v[138:139], v[2:3], v[76:77], v[138:139] op_sel_hi:[1,0,1]
	v_pk_fma_f32 v[140:141], v[4:5], v[76:77], v[140:141] op_sel_hi:[1,0,1]
	v_pk_fma_f32 v[142:143], v[6:7], v[76:77], v[142:143] op_sel_hi:[1,0,1]
	v_pk_fma_f32 v[128:129], v[8:9], v[76:77], v[128:129] op_sel_hi:[1,0,1]
	v_pk_fma_f32 v[132:133], v[10:11], v[76:77], v[132:133] op_sel_hi:[1,0,1]
	v_pk_fma_f32 v[134:135], v[12:13], v[76:77], v[134:135] op_sel_hi:[1,0,1]
	v_pk_fma_f32 v[136:137], v[14:15], v[76:77], v[136:137] op_sel_hi:[1,0,1]
	ds_read_b32 v76, v193 offset:408
	s_waitcnt vmcnt(15)
	v_cvt_scalef32_pk_f32_fp4 v[0:1], v154, 1.0
	v_cvt_scalef32_pk_f32_fp4 v[2:3], v154, 1.0 op_sel:[1,0,0]
	v_cvt_scalef32_pk_f32_fp4 v[4:5], v154, 1.0 op_sel:[0,1,0]
	v_cvt_scalef32_pk_f32_fp4 v[6:7], v154, 1.0 op_sel:[1,1,0]
	v_cvt_scalef32_pk_f32_fp4 v[8:9], v155, 1.0
	v_cvt_scalef32_pk_f32_fp4 v[10:11], v155, 1.0 op_sel:[1,0,0]
	v_cvt_scalef32_pk_f32_fp4 v[12:13], v155, 1.0 op_sel:[0,1,0]
	v_cvt_scalef32_pk_f32_fp4 v[14:15], v155, 1.0 op_sel:[1,1,0]
	v_readlane_b32 s54, v90, 53
	s_lshl_b32 s56, s54, 9
	s_add_u32 s56, s64, s56
	s_addc_u32 s57, s65, 0
	global_load_dwordx2 v[154:155], v227, s[56:57]
	s_waitcnt lgkmcnt(1)
	v_pk_fma_f32 v[130:131], v[0:1], v[194:195], v[130:131] op_sel_hi:[1,0,1]
	v_pk_fma_f32 v[138:139], v[2:3], v[194:195], v[138:139] op_sel_hi:[1,0,1]
	v_pk_fma_f32 v[140:141], v[4:5], v[194:195], v[140:141] op_sel_hi:[1,0,1]
	v_pk_fma_f32 v[142:143], v[6:7], v[194:195], v[142:143] op_sel_hi:[1,0,1]
	v_pk_fma_f32 v[128:129], v[8:9], v[194:195], v[128:129] op_sel_hi:[1,0,1]
	v_pk_fma_f32 v[132:133], v[10:11], v[194:195], v[132:133] op_sel_hi:[1,0,1]
	v_pk_fma_f32 v[134:135], v[12:13], v[194:195], v[134:135] op_sel_hi:[1,0,1]
	v_pk_fma_f32 v[136:137], v[14:15], v[194:195], v[136:137] op_sel_hi:[1,0,1]
	ds_read_b32 v194, v193 offset:412
	s_waitcnt vmcnt(15)
	v_cvt_scalef32_pk_f32_fp4 v[0:1], v156, 1.0
	v_cvt_scalef32_pk_f32_fp4 v[2:3], v156, 1.0 op_sel:[1,0,0]
	v_cvt_scalef32_pk_f32_fp4 v[4:5], v156, 1.0 op_sel:[0,1,0]
	v_cvt_scalef32_pk_f32_fp4 v[6:7], v156, 1.0 op_sel:[1,1,0]
	v_cvt_scalef32_pk_f32_fp4 v[8:9], v157, 1.0
	v_cvt_scalef32_pk_f32_fp4 v[10:11], v157, 1.0 op_sel:[1,0,0]
	v_cvt_scalef32_pk_f32_fp4 v[12:13], v157, 1.0 op_sel:[0,1,0]
	v_cvt_scalef32_pk_f32_fp4 v[14:15], v157, 1.0 op_sel:[1,1,0]
	v_readlane_b32 s54, v90, 54
	s_lshl_b32 s56, s54, 9
	s_add_u32 s56, s64, s56
	s_addc_u32 s57, s65, 0
	global_load_dwordx2 v[156:157], v227, s[56:57]
	s_waitcnt lgkmcnt(1)
	v_pk_fma_f32 v[130:131], v[0:1], v[76:77], v[130:131] op_sel_hi:[1,0,1]
	v_pk_fma_f32 v[138:139], v[2:3], v[76:77], v[138:139] op_sel_hi:[1,0,1]
	v_pk_fma_f32 v[140:141], v[4:5], v[76:77], v[140:141] op_sel_hi:[1,0,1]
	v_pk_fma_f32 v[142:143], v[6:7], v[76:77], v[142:143] op_sel_hi:[1,0,1]
	v_pk_fma_f32 v[128:129], v[8:9], v[76:77], v[128:129] op_sel_hi:[1,0,1]
	v_pk_fma_f32 v[132:133], v[10:11], v[76:77], v[132:133] op_sel_hi:[1,0,1]
	v_pk_fma_f32 v[134:135], v[12:13], v[76:77], v[134:135] op_sel_hi:[1,0,1]
	v_pk_fma_f32 v[136:137], v[14:15], v[76:77], v[136:137] op_sel_hi:[1,0,1]
	ds_read_b32 v76, v193 offset:416
	s_waitcnt vmcnt(15)
	v_cvt_scalef32_pk_f32_fp4 v[0:1], v158, 1.0
	v_cvt_scalef32_pk_f32_fp4 v[2:3], v158, 1.0 op_sel:[1,0,0]
	v_cvt_scalef32_pk_f32_fp4 v[4:5], v158, 1.0 op_sel:[0,1,0]
	v_cvt_scalef32_pk_f32_fp4 v[6:7], v158, 1.0 op_sel:[1,1,0]
	v_cvt_scalef32_pk_f32_fp4 v[8:9], v159, 1.0
	v_cvt_scalef32_pk_f32_fp4 v[10:11], v159, 1.0 op_sel:[1,0,0]
	v_cvt_scalef32_pk_f32_fp4 v[12:13], v159, 1.0 op_sel:[0,1,0]
	v_cvt_scalef32_pk_f32_fp4 v[14:15], v159, 1.0 op_sel:[1,1,0]
	v_readlane_b32 s54, v90, 55
	s_lshl_b32 s56, s54, 9
	s_add_u32 s56, s64, s56
	s_addc_u32 s57, s65, 0
	global_load_dwordx2 v[158:159], v227, s[56:57]
	s_waitcnt lgkmcnt(1)
; __device__ void peer_gather_phase(const Params& P, int l, bool do_store) {
;     ...
;         const int ea = __builtin_amdgcn_readlane(evs, kb + 2 * pr), eb = __builtin_amdgcn_readlane(evs, kb + 2 * pr + 1);
;         const uint2* up = (const uint2*)(U + (size_t)(uphi ? eb : ea) * 768);
;         u6[3 * pr] = up[0]; u6[3 * pr + 1] = up[1]; u6[3 * pr + 2] = up[2];
;         v8[2 * pr] = *(const uint2*)(V + (size_t)ea * 512);
;         v8[2 * pr + 1] = *(const uint2*)(V + (size_t)eb * 512);
;     ...
; #pragma unroll
;       for (int j = 0; j < 8; ++j) {
;         const float a = __builtin_bit_cast(float, __builtin_amdgcn_readlane(__builtin_bit_cast(int, avec), kb + j));
;         const f32x2 aa = f32x2{a, a};
;         y[0] += aa * __builtin_amdgcn_cvt_scalef32_pk_f32_fp4(v8[j].x, 1.0f, 0); y[1] += aa * __builtin_amdgcn_cvt_scalef32_pk_f32_fp4(v8[j].x, 1.0f, 1);
;         y[2] += aa * __builtin_amdgcn_cvt_scalef32_pk_f32_fp4(v8[j].x, 1.0f, 2); y[3] += aa * __builtin_amdgcn_cvt_scalef32_pk_f32_fp4(v8[j].x, 1.0f, 3);
;         y[4] += aa * __builtin_amdgcn_cvt_scalef32_pk_f32_fp4(v8[j].y, 1.0f, 0); y[5] += aa * __builtin_amdgcn_cvt_scalef32_pk_f32_fp4(v8[j].y, 1.0f, 1);
;         y[6] += aa * __builtin_amdgcn_cvt_scalef32_pk_f32_fp4(v8[j].y, 1.0f, 2); y[7] += aa * __builtin_amdgcn_cvt_scalef32_pk_f32_fp4(v8[j].y, 1.0f, 3);
;       }
	v_pk_fma_f32 v[130:131], v[0:1], v[194:195], v[130:131] op_sel_hi:[1,0,1]
	v_pk_fma_f32 v[138:139], v[2:3], v[194:195], v[138:139] op_sel_hi:[1,0,1]
	v_pk_fma_f32 v[140:141], v[4:5], v[194:195], v[140:141] op_sel_hi:[1,0,1]
	v_pk_fma_f32 v[142:143], v[6:7], v[194:195], v[142:143] op_sel_hi:[1,0,1]
	v_pk_fma_f32 v[128:129], v[8:9], v[194:195], v[128:129] op_sel_hi:[1,0,1]
	v_pk_fma_f32 v[132:133], v[10:11], v[194:195], v[132:133] op_sel_hi:[1,0,1]
	v_pk_fma_f32 v[134:135], v[12:13], v[194:195], v[134:135] op_sel_hi:[1,0,1]
	v_pk_fma_f32 v[136:137], v[14:15], v[194:195], v[136:137] op_sel_hi:[1,0,1]
	ds_read_b32 v194, v193 offset:420
	s_waitcnt vmcnt(15)
	v_cvt_scalef32_pk_f32_fp4 v[0:1], v168, 1.0
	v_cvt_scalef32_pk_f32_fp4 v[2:3], v168, 1.0 op_sel:[1,0,0]
	v_cvt_scalef32_pk_f32_fp4 v[4:5], v168, 1.0 op_sel:[0,1,0]
	v_cvt_scalef32_pk_f32_fp4 v[6:7], v168, 1.0 op_sel:[1,1,0]
	v_cvt_scalef32_pk_f32_fp4 v[8:9], v169, 1.0
	v_cvt_scalef32_pk_f32_fp4 v[10:11], v169, 1.0 op_sel:[1,0,0]
	v_cvt_scalef32_pk_f32_fp4 v[12:13], v169, 1.0 op_sel:[0,1,0]
	v_cvt_scalef32_pk_f32_fp4 v[14:15], v169, 1.0 op_sel:[1,1,0]
	v_readlane_b32 s54, v90, 56
	s_lshl_b32 s56, s54, 9
	s_add_u32 s56, s64, s56
	s_addc_u32 s57, s65, 0
	global_load_dwordx2 v[168:169], v227, s[56:57]
	s_waitcnt lgkmcnt(1)
	v_pk_fma_f32 v[130:131], v[0:1], v[76:77], v[130:131] op_sel_hi:[1,0,1]
	v_pk_fma_f32 v[138:139], v[2:3], v[76:77], v[138:139] op_sel_hi:[1,0,1]
	v_pk_fma_f32 v[140:141], v[4:5], v[76:77], v[140:141] op_sel_hi:[1,0,1]
	v_pk_fma_f32 v[142:143], v[6:7], v[76:77], v[142:143] op_sel_hi:[1,0,1]
	v_pk_fma_f32 v[128:129], v[8:9], v[76:77], v[128:129] op_sel_hi:[1,0,1]
	v_pk_fma_f32 v[132:133], v[10:11], v[76:77], v[132:133] op_sel_hi:[1,0,1]
	v_pk_fma_f32 v[134:135], v[12:13], v[76:77], v[134:135] op_sel_hi:[1,0,1]
	v_pk_fma_f32 v[136:137], v[14:15], v[76:77], v[136:137] op_sel_hi:[1,0,1]
	ds_read_b32 v76, v193 offset:424
	s_waitcnt vmcnt(15)
	v_cvt_scalef32_pk_f32_fp4 v[0:1], v170, 1.0
	v_cvt_scalef32_pk_f32_fp4 v[2:3], v170, 1.0 op_sel:[1,0,0]
	v_cvt_scalef32_pk_f32_fp4 v[4:5], v170, 1.0 op_sel:[0,1,0]
	v_cvt_scalef32_pk_f32_fp4 v[6:7], v170, 1.0 op_sel:[1,1,0]
	v_cvt_scalef32_pk_f32_fp4 v[8:9], v171, 1.0
	v_cvt_scalef32_pk_f32_fp4 v[10:11], v171, 1.0 op_sel:[1,0,0]
	v_cvt_scalef32_pk_f32_fp4 v[12:13], v171, 1.0 op_sel:[0,1,0]
	v_cvt_scalef32_pk_f32_fp4 v[14:15], v171, 1.0 op_sel:[1,1,0]
	v_readlane_b32 s54, v90, 57
	s_lshl_b32 s56, s54, 9
	s_add_u32 s56, s64, s56
	s_addc_u32 s57, s65, 0
	global_load_dwordx2 v[170:171], v227, s[56:57]
	s_waitcnt lgkmcnt(1)
	v_pk_fma_f32 v[130:131], v[0:1], v[194:195], v[130:131] op_sel_hi:[1,0,1]
	v_pk_fma_f32 v[138:139], v[2:3], v[194:195], v[138:139] op_sel_hi:[1,0,1]
	v_pk_fma_f32 v[140:141], v[4:5], v[194:195], v[140:141] op_sel_hi:[1,0,1]
	v_pk_fma_f32 v[142:143], v[6:7], v[194:195], v[142:143] op_sel_hi:[1,0,1]
	v_pk_fma_f32 v[128:129], v[8:9], v[194:195], v[128:129] op_sel_hi:[1,0,1]
	v_pk_fma_f32 v[132:133], v[10:11], v[194:195], v[132:133] op_sel_hi:[1,0,1]
	v_pk_fma_f32 v[134:135], v[12:13], v[194:195], v[134:135] op_sel_hi:[1,0,1]
	v_pk_fma_f32 v[136:137], v[14:15], v[194:195], v[136:137] op_sel_hi:[1,0,1]
	ds_read_b32 v194, v193 offset:428
	s_waitcnt vmcnt(15)
	v_cvt_scalef32_pk_f32_fp4 v[0:1], v172, 1.0
	v_cvt_scalef32_pk_f32_fp4 v[2:3], v172, 1.0 op_sel:[1,0,0]
	v_cvt_scalef32_pk_f32_fp4 v[4:5], v172, 1.0 op_sel:[0,1,0]
	v_cvt_scalef32_pk_f32_fp4 v[6:7], v172, 1.0 op_sel:[1,1,0]
	v_cvt_scalef32_pk_f32_fp4 v[8:9], v173, 1.0
	v_cvt_scalef32_pk_f32_fp4 v[10:11], v173, 1.0 op_sel:[1,0,0]
	v_cvt_scalef32_pk_f32_fp4 v[12:13], v173, 1.0 op_sel:[0,1,0]
	v_cvt_scalef32_pk_f32_fp4 v[14:15], v173, 1.0 op_sel:[1,1,0]
	v_readlane_b32 s54, v90, 58
	s_lshl_b32 s56, s54, 9
	s_add_u32 s56, s64, s56
	s_addc_u32 s57, s65, 0
	global_load_dwordx2 v[172:173], v227, s[56:57]
	s_waitcnt lgkmcnt(1)
	v_pk_fma_f32 v[130:131], v[0:1], v[76:77], v[130:131] op_sel_hi:[1,0,1]
	v_pk_fma_f32 v[138:139], v[2:3], v[76:77], v[138:139] op_sel_hi:[1,0,1]
	v_pk_fma_f32 v[140:141], v[4:5], v[76:77], v[140:141] op_sel_hi:[1,0,1]
	v_pk_fma_f32 v[142:143], v[6:7], v[76:77], v[142:143] op_sel_hi:[1,0,1]
	v_pk_fma_f32 v[128:129], v[8:9], v[76:77], v[128:129] op_sel_hi:[1,0,1]
	v_pk_fma_f32 v[132:133], v[10:11], v[76:77], v[132:133] op_sel_hi:[1,0,1]
	v_pk_fma_f32 v[134:135], v[12:13], v[76:77], v[134:135] op_sel_hi:[1,0,1]
	v_pk_fma_f32 v[136:137], v[14:15], v[76:77], v[136:137] op_sel_hi:[1,0,1]
	ds_read_b32 v76, v193 offset:432
	s_waitcnt vmcnt(15)
	v_cvt_scalef32_pk_f32_fp4 v[0:1], v174, 1.0
	v_cvt_scalef32_pk_f32_fp4 v[2:3], v174, 1.0 op_sel:[1,0,0]
	v_cvt_scalef32_pk_f32_fp4 v[4:5], v174, 1.0 op_sel:[0,1,0]
	v_cvt_scalef32_pk_f32_fp4 v[6:7], v174, 1.0 op_sel:[1,1,0]
	v_cvt_scalef32_pk_f32_fp4 v[8:9], v175, 1.0
	v_cvt_scalef32_pk_f32_fp4 v[10:11], v175, 1.0 op_sel:[1,0,0]
	v_cvt_scalef32_pk_f32_fp4 v[12:13], v175, 1.0 op_sel:[0,1,0]
	v_cvt_scalef32_pk_f32_fp4 v[14:15], v175, 1.0 op_sel:[1,1,0]
	v_readlane_b32 s54, v90, 59
	s_lshl_b32 s56, s54, 9
	s_add_u32 s56, s64, s56
	s_addc_u32 s57, s65, 0
	global_load_dwordx2 v[174:175], v227, s[56:57]
	s_waitcnt lgkmcnt(1)
	v_pk_fma_f32 v[130:131], v[0:1], v[194:195], v[130:131] op_sel_hi:[1,0,1]
	v_pk_fma_f32 v[138:139], v[2:3], v[194:195], v[138:139] op_sel_hi:[1,0,1]
	v_pk_fma_f32 v[140:141], v[4:5], v[194:195], v[140:141] op_sel_hi:[1,0,1]
	v_pk_fma_f32 v[142:143], v[6:7], v[194:195], v[142:143] op_sel_hi:[1,0,1]
	v_pk_fma_f32 v[128:129], v[8:9], v[194:195], v[128:129] op_sel_hi:[1,0,1]
	v_pk_fma_f32 v[132:133], v[10:11], v[194:195], v[132:133] op_sel_hi:[1,0,1]
	v_pk_fma_f32 v[134:135], v[12:13], v[194:195], v[134:135] op_sel_hi:[1,0,1]
	v_pk_fma_f32 v[136:137], v[14:15], v[194:195], v[136:137] op_sel_hi:[1,0,1]
	ds_read_b32 v194, v193 offset:436
	s_waitcnt vmcnt(15)
; __device__ void peer_gather_phase(const Params& P, int l, bool do_store) {
;     ...
;         const int ea = __builtin_amdgcn_readlane(evs, kb + 2 * pr), eb = __builtin_amdgcn_readlane(evs, kb + 2 * pr + 1);
;         const uint2* up = (const uint2*)(U + (size_t)(uphi ? eb : ea) * 768);
;         u6[3 * pr] = up[0]; u6[3 * pr + 1] = up[1]; u6[3 * pr + 2] = up[2];
;         v8[2 * pr] = *(const uint2*)(V + (size_t)ea * 512);
;         v8[2 * pr + 1] = *(const uint2*)(V + (size_t)eb * 512);
;     ...
; #pragma unroll
;       for (int j = 0; j < 8; ++j) {
;         const float a = __builtin_bit_cast(float, __builtin_amdgcn_readlane(__builtin_bit_cast(int, avec), kb + j));
;         const f32x2 aa = f32x2{a, a};
;         y[0] += aa * __builtin_amdgcn_cvt_scalef32_pk_f32_fp4(v8[j].x, 1.0f, 0); y[1] += aa * __builtin_amdgcn_cvt_scalef32_pk_f32_fp4(v8[j].x, 1.0f, 1);
;         y[2] += aa * __builtin_amdgcn_cvt_scalef32_pk_f32_fp4(v8[j].x, 1.0f, 2); y[3] += aa * __builtin_amdgcn_cvt_scalef32_pk_f32_fp4(v8[j].x, 1.0f, 3);
;         y[4] += aa * __builtin_amdgcn_cvt_scalef32_pk_f32_fp4(v8[j].y, 1.0f, 0); y[5] += aa * __builtin_amdgcn_cvt_scalef32_pk_f32_fp4(v8[j].y, 1.0f, 1);
;         y[6] += aa * __builtin_amdgcn_cvt_scalef32_pk_f32_fp4(v8[j].y, 1.0f, 2); y[7] += aa * __builtin_amdgcn_cvt_scalef32_pk_f32_fp4(v8[j].y, 1.0f, 3);
;       }
	v_cvt_scalef32_pk_f32_fp4 v[0:1], v180, 1.0
	v_cvt_scalef32_pk_f32_fp4 v[2:3], v180, 1.0 op_sel:[1,0,0]
	v_cvt_scalef32_pk_f32_fp4 v[4:5], v180, 1.0 op_sel:[0,1,0]
	v_cvt_scalef32_pk_f32_fp4 v[6:7], v180, 1.0 op_sel:[1,1,0]
	v_cvt_scalef32_pk_f32_fp4 v[8:9], v181, 1.0
	v_cvt_scalef32_pk_f32_fp4 v[10:11], v181, 1.0 op_sel:[1,0,0]
	v_cvt_scalef32_pk_f32_fp4 v[12:13], v181, 1.0 op_sel:[0,1,0]
	v_cvt_scalef32_pk_f32_fp4 v[14:15], v181, 1.0 op_sel:[1,1,0]
	v_readlane_b32 s54, v90, 60
	s_lshl_b32 s56, s54, 9
	s_add_u32 s56, s64, s56
	s_addc_u32 s57, s65, 0
	global_load_dwordx2 v[180:181], v227, s[56:57]
	s_waitcnt lgkmcnt(1)
	v_pk_fma_f32 v[130:131], v[0:1], v[76:77], v[130:131] op_sel_hi:[1,0,1]
	v_pk_fma_f32 v[138:139], v[2:3], v[76:77], v[138:139] op_sel_hi:[1,0,1]
	v_pk_fma_f32 v[140:141], v[4:5], v[76:77], v[140:141] op_sel_hi:[1,0,1]
	v_pk_fma_f32 v[142:143], v[6:7], v[76:77], v[142:143] op_sel_hi:[1,0,1]
	v_pk_fma_f32 v[128:129], v[8:9], v[76:77], v[128:129] op_sel_hi:[1,0,1]
	v_pk_fma_f32 v[132:133], v[10:11], v[76:77], v[132:133] op_sel_hi:[1,0,1]
	v_pk_fma_f32 v[134:135], v[12:13], v[76:77], v[134:135] op_sel_hi:[1,0,1]
	v_pk_fma_f32 v[136:137], v[14:15], v[76:77], v[136:137] op_sel_hi:[1,0,1]
	ds_read_b32 v76, v193 offset:440
	s_waitcnt vmcnt(15)
	v_cvt_scalef32_pk_f32_fp4 v[0:1], v182, 1.0
	v_cvt_scalef32_pk_f32_fp4 v[2:3], v182, 1.0 op_sel:[1,0,0]
	v_cvt_scalef32_pk_f32_fp4 v[4:5], v182, 1.0 op_sel:[0,1,0]
	v_cvt_scalef32_pk_f32_fp4 v[6:7], v182, 1.0 op_sel:[1,1,0]
	v_cvt_scalef32_pk_f32_fp4 v[8:9], v183, 1.0
	v_cvt_scalef32_pk_f32_fp4 v[10:11], v183, 1.0 op_sel:[1,0,0]
	v_cvt_scalef32_pk_f32_fp4 v[12:13], v183, 1.0 op_sel:[0,1,0]
	v_cvt_scalef32_pk_f32_fp4 v[14:15], v183, 1.0 op_sel:[1,1,0]
	v_readlane_b32 s54, v90, 61
	s_lshl_b32 s56, s54, 9
	s_add_u32 s56, s64, s56
	s_addc_u32 s57, s65, 0
	global_load_dwordx2 v[182:183], v227, s[56:57]
	s_waitcnt lgkmcnt(1)
	v_pk_fma_f32 v[130:131], v[0:1], v[194:195], v[130:131] op_sel_hi:[1,0,1]
	v_pk_fma_f32 v[138:139], v[2:3], v[194:195], v[138:139] op_sel_hi:[1,0,1]
	v_pk_fma_f32 v[140:141], v[4:5], v[194:195], v[140:141] op_sel_hi:[1,0,1]
	v_pk_fma_f32 v[142:143], v[6:7], v[194:195], v[142:143] op_sel_hi:[1,0,1]
	v_pk_fma_f32 v[128:129], v[8:9], v[194:195], v[128:129] op_sel_hi:[1,0,1]
	v_pk_fma_f32 v[132:133], v[10:11], v[194:195], v[132:133] op_sel_hi:[1,0,1]
	v_pk_fma_f32 v[134:135], v[12:13], v[194:195], v[134:135] op_sel_hi:[1,0,1]
	v_pk_fma_f32 v[136:137], v[14:15], v[194:195], v[136:137] op_sel_hi:[1,0,1]
	ds_read_b32 v194, v193 offset:444
	s_waitcnt vmcnt(15)
	v_cvt_scalef32_pk_f32_fp4 v[0:1], v184, 1.0
	v_cvt_scalef32_pk_f32_fp4 v[2:3], v184, 1.0 op_sel:[1,0,0]
	v_cvt_scalef32_pk_f32_fp4 v[4:5], v184, 1.0 op_sel:[0,1,0]
	v_cvt_scalef32_pk_f32_fp4 v[6:7], v184, 1.0 op_sel:[1,1,0]
	v_cvt_scalef32_pk_f32_fp4 v[8:9], v185, 1.0
	v_cvt_scalef32_pk_f32_fp4 v[10:11], v185, 1.0 op_sel:[1,0,0]
	v_cvt_scalef32_pk_f32_fp4 v[12:13], v185, 1.0 op_sel:[0,1,0]
	v_cvt_scalef32_pk_f32_fp4 v[14:15], v185, 1.0 op_sel:[1,1,0]
	v_readlane_b32 s54, v90, 62
	s_lshl_b32 s56, s54, 9
	s_add_u32 s56, s64, s56
	s_addc_u32 s57, s65, 0
	global_load_dwordx2 v[184:185], v227, s[56:57]
	s_waitcnt lgkmcnt(1)
	v_pk_fma_f32 v[130:131], v[0:1], v[76:77], v[130:131] op_sel_hi:[1,0,1]
	v_pk_fma_f32 v[138:139], v[2:3], v[76:77], v[138:139] op_sel_hi:[1,0,1]
	v_pk_fma_f32 v[140:141], v[4:5], v[76:77], v[140:141] op_sel_hi:[1,0,1]
	v_pk_fma_f32 v[142:143], v[6:7], v[76:77], v[142:143] op_sel_hi:[1,0,1]
	v_pk_fma_f32 v[128:129], v[8:9], v[76:77], v[128:129] op_sel_hi:[1,0,1]
	v_pk_fma_f32 v[132:133], v[10:11], v[76:77], v[132:133] op_sel_hi:[1,0,1]
	v_pk_fma_f32 v[134:135], v[12:13], v[76:77], v[134:135] op_sel_hi:[1,0,1]
	v_pk_fma_f32 v[136:137], v[14:15], v[76:77], v[136:137] op_sel_hi:[1,0,1]
	ds_read_b32 v76, v193 offset:448
	s_waitcnt vmcnt(15)
	v_cvt_scalef32_pk_f32_fp4 v[0:1], v186, 1.0
	v_cvt_scalef32_pk_f32_fp4 v[2:3], v186, 1.0 op_sel:[1,0,0]
	v_cvt_scalef32_pk_f32_fp4 v[4:5], v186, 1.0 op_sel:[0,1,0]
	v_cvt_scalef32_pk_f32_fp4 v[6:7], v186, 1.0 op_sel:[1,1,0]
	v_cvt_scalef32_pk_f32_fp4 v[8:9], v187, 1.0
	v_cvt_scalef32_pk_f32_fp4 v[10:11], v187, 1.0 op_sel:[1,0,0]
	v_cvt_scalef32_pk_f32_fp4 v[12:13], v187, 1.0 op_sel:[0,1,0]
	v_cvt_scalef32_pk_f32_fp4 v[14:15], v187, 1.0 op_sel:[1,1,0]
	v_readlane_b32 s54, v90, 63
	s_lshl_b32 s56, s54, 9
	s_add_u32 s56, s64, s56
	s_addc_u32 s57, s65, 0
	global_load_dwordx2 v[186:187], v227, s[56:57]
	s_waitcnt lgkmcnt(1)
	v_pk_fma_f32 v[130:131], v[0:1], v[194:195], v[130:131] op_sel_hi:[1,0,1]
	v_pk_fma_f32 v[138:139], v[2:3], v[194:195], v[138:139] op_sel_hi:[1,0,1]
	v_pk_fma_f32 v[140:141], v[4:5], v[194:195], v[140:141] op_sel_hi:[1,0,1]
	v_pk_fma_f32 v[142:143], v[6:7], v[194:195], v[142:143] op_sel_hi:[1,0,1]
	v_pk_fma_f32 v[128:129], v[8:9], v[194:195], v[128:129] op_sel_hi:[1,0,1]
	v_pk_fma_f32 v[132:133], v[10:11], v[194:195], v[132:133] op_sel_hi:[1,0,1]
	v_pk_fma_f32 v[134:135], v[12:13], v[194:195], v[134:135] op_sel_hi:[1,0,1]
	v_pk_fma_f32 v[136:137], v[14:15], v[194:195], v[136:137] op_sel_hi:[1,0,1]
	ds_read_b32 v194, v193 offset:452
	s_waitcnt vmcnt(15)
	v_cvt_scalef32_pk_f32_fp4 v[0:1], v144, 1.0
	v_cvt_scalef32_pk_f32_fp4 v[2:3], v144, 1.0 op_sel:[1,0,0]
	v_cvt_scalef32_pk_f32_fp4 v[4:5], v144, 1.0 op_sel:[0,1,0]
	v_cvt_scalef32_pk_f32_fp4 v[6:7], v144, 1.0 op_sel:[1,1,0]
	v_cvt_scalef32_pk_f32_fp4 v[8:9], v145, 1.0
	v_cvt_scalef32_pk_f32_fp4 v[10:11], v145, 1.0 op_sel:[1,0,0]
	v_cvt_scalef32_pk_f32_fp4 v[12:13], v145, 1.0 op_sel:[0,1,0]
	v_cvt_scalef32_pk_f32_fp4 v[14:15], v145, 1.0 op_sel:[1,1,0]
	s_waitcnt lgkmcnt(1)
; __device__ void peer_gather_phase(const Params& P, int l, bool do_store) {
;     ...
; #pragma unroll
;       for (int j = 0; j < 8; ++j) {
;         const float a = __builtin_bit_cast(float, __builtin_amdgcn_readlane(__builtin_bit_cast(int, avec), kb + j));
;         const f32x2 aa = f32x2{a, a};
;         y[0] += aa * __builtin_amdgcn_cvt_scalef32_pk_f32_fp4(v8[j].x, 1.0f, 0); y[1] += aa * __builtin_amdgcn_cvt_scalef32_pk_f32_fp4(v8[j].x, 1.0f, 1);
;         y[2] += aa * __builtin_amdgcn_cvt_scalef32_pk_f32_fp4(v8[j].x, 1.0f, 2); y[3] += aa * __builtin_amdgcn_cvt_scalef32_pk_f32_fp4(v8[j].x, 1.0f, 3);
;         y[4] += aa * __builtin_amdgcn_cvt_scalef32_pk_f32_fp4(v8[j].y, 1.0f, 0); y[5] += aa * __builtin_amdgcn_cvt_scalef32_pk_f32_fp4(v8[j].y, 1.0f, 1);
;         y[6] += aa * __builtin_amdgcn_cvt_scalef32_pk_f32_fp4(v8[j].y, 1.0f, 2); y[7] += aa * __builtin_amdgcn_cvt_scalef32_pk_f32_fp4(v8[j].y, 1.0f, 3);
;       }
	v_pk_fma_f32 v[130:131], v[0:1], v[76:77], v[130:131] op_sel_hi:[1,0,1]
	v_pk_fma_f32 v[138:139], v[2:3], v[76:77], v[138:139] op_sel_hi:[1,0,1]
	v_pk_fma_f32 v[140:141], v[4:5], v[76:77], v[140:141] op_sel_hi:[1,0,1]
	v_pk_fma_f32 v[142:143], v[6:7], v[76:77], v[142:143] op_sel_hi:[1,0,1]
	v_pk_fma_f32 v[128:129], v[8:9], v[76:77], v[128:129] op_sel_hi:[1,0,1]
	v_pk_fma_f32 v[132:133], v[10:11], v[76:77], v[132:133] op_sel_hi:[1,0,1]
	v_pk_fma_f32 v[134:135], v[12:13], v[76:77], v[134:135] op_sel_hi:[1,0,1]
	v_pk_fma_f32 v[136:137], v[14:15], v[76:77], v[136:137] op_sel_hi:[1,0,1]
	ds_read_b32 v76, v193 offset:456
	s_waitcnt vmcnt(14)
	v_cvt_scalef32_pk_f32_fp4 v[0:1], v146, 1.0
	v_cvt_scalef32_pk_f32_fp4 v[2:3], v146, 1.0 op_sel:[1,0,0]
	v_cvt_scalef32_pk_f32_fp4 v[4:5], v146, 1.0 op_sel:[0,1,0]
	v_cvt_scalef32_pk_f32_fp4 v[6:7], v146, 1.0 op_sel:[1,1,0]
	v_cvt_scalef32_pk_f32_fp4 v[8:9], v147, 1.0
	v_cvt_scalef32_pk_f32_fp4 v[10:11], v147, 1.0 op_sel:[1,0,0]
	v_cvt_scalef32_pk_f32_fp4 v[12:13], v147, 1.0 op_sel:[0,1,0]
	v_cvt_scalef32_pk_f32_fp4 v[14:15], v147, 1.0 op_sel:[1,1,0]
	s_waitcnt lgkmcnt(1)
	v_pk_fma_f32 v[130:131], v[0:1], v[194:195], v[130:131] op_sel_hi:[1,0,1]
	v_pk_fma_f32 v[138:139], v[2:3], v[194:195], v[138:139] op_sel_hi:[1,0,1]
	v_pk_fma_f32 v[140:141], v[4:5], v[194:195], v[140:141] op_sel_hi:[1,0,1]
	v_pk_fma_f32 v[142:143], v[6:7], v[194:195], v[142:143] op_sel_hi:[1,0,1]
	v_pk_fma_f32 v[128:129], v[8:9], v[194:195], v[128:129] op_sel_hi:[1,0,1]
	v_pk_fma_f32 v[132:133], v[10:11], v[194:195], v[132:133] op_sel_hi:[1,0,1]
	v_pk_fma_f32 v[134:135], v[12:13], v[194:195], v[134:135] op_sel_hi:[1,0,1]
	v_pk_fma_f32 v[136:137], v[14:15], v[194:195], v[136:137] op_sel_hi:[1,0,1]
	ds_read_b32 v194, v193 offset:460
	s_waitcnt vmcnt(13)
	v_cvt_scalef32_pk_f32_fp4 v[0:1], v148, 1.0
	v_cvt_scalef32_pk_f32_fp4 v[2:3], v148, 1.0 op_sel:[1,0,0]
	v_cvt_scalef32_pk_f32_fp4 v[4:5], v148, 1.0 op_sel:[0,1,0]
	v_cvt_scalef32_pk_f32_fp4 v[6:7], v148, 1.0 op_sel:[1,1,0]
	v_cvt_scalef32_pk_f32_fp4 v[8:9], v149, 1.0
	v_cvt_scalef32_pk_f32_fp4 v[10:11], v149, 1.0 op_sel:[1,0,0]
	v_cvt_scalef32_pk_f32_fp4 v[12:13], v149, 1.0 op_sel:[0,1,0]
	v_cvt_scalef32_pk_f32_fp4 v[14:15], v149, 1.0 op_sel:[1,1,0]
	s_waitcnt lgkmcnt(1)
	v_pk_fma_f32 v[130:131], v[0:1], v[76:77], v[130:131] op_sel_hi:[1,0,1]
	v_pk_fma_f32 v[138:139], v[2:3], v[76:77], v[138:139] op_sel_hi:[1,0,1]
	v_pk_fma_f32 v[140:141], v[4:5], v[76:77], v[140:141] op_sel_hi:[1,0,1]
	v_pk_fma_f32 v[142:143], v[6:7], v[76:77], v[142:143] op_sel_hi:[1,0,1]
	v_pk_fma_f32 v[128:129], v[8:9], v[76:77], v[128:129] op_sel_hi:[1,0,1]
	v_pk_fma_f32 v[132:133], v[10:11], v[76:77], v[132:133] op_sel_hi:[1,0,1]
	v_pk_fma_f32 v[134:135], v[12:13], v[76:77], v[134:135] op_sel_hi:[1,0,1]
	v_pk_fma_f32 v[136:137], v[14:15], v[76:77], v[136:137] op_sel_hi:[1,0,1]
	ds_read_b32 v76, v193 offset:464
	s_waitcnt vmcnt(12)
	v_cvt_scalef32_pk_f32_fp4 v[0:1], v150, 1.0
	v_cvt_scalef32_pk_f32_fp4 v[2:3], v150, 1.0 op_sel:[1,0,0]
	v_cvt_scalef32_pk_f32_fp4 v[4:5], v150, 1.0 op_sel:[0,1,0]
	v_cvt_scalef32_pk_f32_fp4 v[6:7], v150, 1.0 op_sel:[1,1,0]
	v_cvt_scalef32_pk_f32_fp4 v[8:9], v151, 1.0
	v_cvt_scalef32_pk_f32_fp4 v[10:11], v151, 1.0 op_sel:[1,0,0]
	v_cvt_scalef32_pk_f32_fp4 v[12:13], v151, 1.0 op_sel:[0,1,0]
	v_cvt_scalef32_pk_f32_fp4 v[14:15], v151, 1.0 op_sel:[1,1,0]
	s_waitcnt lgkmcnt(1)
	v_pk_fma_f32 v[130:131], v[0:1], v[194:195], v[130:131] op_sel_hi:[1,0,1]
	v_pk_fma_f32 v[138:139], v[2:3], v[194:195], v[138:139] op_sel_hi:[1,0,1]
	v_pk_fma_f32 v[140:141], v[4:5], v[194:195], v[140:141] op_sel_hi:[1,0,1]
	v_pk_fma_f32 v[142:143], v[6:7], v[194:195], v[142:143] op_sel_hi:[1,0,1]
	v_pk_fma_f32 v[128:129], v[8:9], v[194:195], v[128:129] op_sel_hi:[1,0,1]
	v_pk_fma_f32 v[132:133], v[10:11], v[194:195], v[132:133] op_sel_hi:[1,0,1]
	v_pk_fma_f32 v[134:135], v[12:13], v[194:195], v[134:135] op_sel_hi:[1,0,1]
	v_pk_fma_f32 v[136:137], v[14:15], v[194:195], v[136:137] op_sel_hi:[1,0,1]
	ds_read_b32 v194, v193 offset:468
	s_waitcnt vmcnt(11)
	v_cvt_scalef32_pk_f32_fp4 v[0:1], v152, 1.0
	v_cvt_scalef32_pk_f32_fp4 v[2:3], v152, 1.0 op_sel:[1,0,0]
	v_cvt_scalef32_pk_f32_fp4 v[4:5], v152, 1.0 op_sel:[0,1,0]
	v_cvt_scalef32_pk_f32_fp4 v[6:7], v152, 1.0 op_sel:[1,1,0]
	v_cvt_scalef32_pk_f32_fp4 v[8:9], v153, 1.0
	v_cvt_scalef32_pk_f32_fp4 v[10:11], v153, 1.0 op_sel:[1,0,0]
	v_cvt_scalef32_pk_f32_fp4 v[12:13], v153, 1.0 op_sel:[0,1,0]
	v_cvt_scalef32_pk_f32_fp4 v[14:15], v153, 1.0 op_sel:[1,1,0]
	s_waitcnt lgkmcnt(1)
	v_pk_fma_f32 v[130:131], v[0:1], v[76:77], v[130:131] op_sel_hi:[1,0,1]
	v_pk_fma_f32 v[138:139], v[2:3], v[76:77], v[138:139] op_sel_hi:[1,0,1]
	v_pk_fma_f32 v[140:141], v[4:5], v[76:77], v[140:141] op_sel_hi:[1,0,1]
	v_pk_fma_f32 v[142:143], v[6:7], v[76:77], v[142:143] op_sel_hi:[1,0,1]
	v_pk_fma_f32 v[128:129], v[8:9], v[76:77], v[128:129] op_sel_hi:[1,0,1]
	v_pk_fma_f32 v[132:133], v[10:11], v[76:77], v[132:133] op_sel_hi:[1,0,1]
	v_pk_fma_f32 v[134:135], v[12:13], v[76:77], v[134:135] op_sel_hi:[1,0,1]
	v_pk_fma_f32 v[136:137], v[14:15], v[76:77], v[136:137] op_sel_hi:[1,0,1]
	ds_read_b32 v76, v193 offset:472
	s_waitcnt vmcnt(10)
	v_cvt_scalef32_pk_f32_fp4 v[0:1], v154, 1.0
	v_cvt_scalef32_pk_f32_fp4 v[2:3], v154, 1.0 op_sel:[1,0,0]
	v_cvt_scalef32_pk_f32_fp4 v[4:5], v154, 1.0 op_sel:[0,1,0]
	v_cvt_scalef32_pk_f32_fp4 v[6:7], v154, 1.0 op_sel:[1,1,0]
	v_cvt_scalef32_pk_f32_fp4 v[8:9], v155, 1.0
	v_cvt_scalef32_pk_f32_fp4 v[10:11], v155, 1.0 op_sel:[1,0,0]
	v_cvt_scalef32_pk_f32_fp4 v[12:13], v155, 1.0 op_sel:[0,1,0]
	v_cvt_scalef32_pk_f32_fp4 v[14:15], v155, 1.0 op_sel:[1,1,0]
	s_waitcnt lgkmcnt(1)
; __device__ void peer_gather_phase(const Params& P, int l, bool do_store) {
;     ...
; #pragma unroll
;       for (int j = 0; j < 8; ++j) {
;         const float a = __builtin_bit_cast(float, __builtin_amdgcn_readlane(__builtin_bit_cast(int, avec), kb + j));
;         const f32x2 aa = f32x2{a, a};
;         y[0] += aa * __builtin_amdgcn_cvt_scalef32_pk_f32_fp4(v8[j].x, 1.0f, 0); y[1] += aa * __builtin_amdgcn_cvt_scalef32_pk_f32_fp4(v8[j].x, 1.0f, 1);
;         y[2] += aa * __builtin_amdgcn_cvt_scalef32_pk_f32_fp4(v8[j].x, 1.0f, 2); y[3] += aa * __builtin_amdgcn_cvt_scalef32_pk_f32_fp4(v8[j].x, 1.0f, 3);
;         y[4] += aa * __builtin_amdgcn_cvt_scalef32_pk_f32_fp4(v8[j].y, 1.0f, 0); y[5] += aa * __builtin_amdgcn_cvt_scalef32_pk_f32_fp4(v8[j].y, 1.0f, 1);
;         y[6] += aa * __builtin_amdgcn_cvt_scalef32_pk_f32_fp4(v8[j].y, 1.0f, 2); y[7] += aa * __builtin_amdgcn_cvt_scalef32_pk_f32_fp4(v8[j].y, 1.0f, 3);
;       }
	v_pk_fma_f32 v[130:131], v[0:1], v[194:195], v[130:131] op_sel_hi:[1,0,1]
	v_pk_fma_f32 v[138:139], v[2:3], v[194:195], v[138:139] op_sel_hi:[1,0,1]
	v_pk_fma_f32 v[140:141], v[4:5], v[194:195], v[140:141] op_sel_hi:[1,0,1]
	v_pk_fma_f32 v[142:143], v[6:7], v[194:195], v[142:143] op_sel_hi:[1,0,1]
	v_pk_fma_f32 v[128:129], v[8:9], v[194:195], v[128:129] op_sel_hi:[1,0,1]
	v_pk_fma_f32 v[132:133], v[10:11], v[194:195], v[132:133] op_sel_hi:[1,0,1]
	v_pk_fma_f32 v[134:135], v[12:13], v[194:195], v[134:135] op_sel_hi:[1,0,1]
	v_pk_fma_f32 v[136:137], v[14:15], v[194:195], v[136:137] op_sel_hi:[1,0,1]
	ds_read_b32 v194, v193 offset:476
	s_waitcnt vmcnt(9)
	v_cvt_scalef32_pk_f32_fp4 v[0:1], v156, 1.0
	v_cvt_scalef32_pk_f32_fp4 v[2:3], v156, 1.0 op_sel:[1,0,0]
	v_cvt_scalef32_pk_f32_fp4 v[4:5], v156, 1.0 op_sel:[0,1,0]
	v_cvt_scalef32_pk_f32_fp4 v[6:7], v156, 1.0 op_sel:[1,1,0]
	v_cvt_scalef32_pk_f32_fp4 v[8:9], v157, 1.0
	v_cvt_scalef32_pk_f32_fp4 v[10:11], v157, 1.0 op_sel:[1,0,0]
	v_cvt_scalef32_pk_f32_fp4 v[12:13], v157, 1.0 op_sel:[0,1,0]
	v_cvt_scalef32_pk_f32_fp4 v[14:15], v157, 1.0 op_sel:[1,1,0]
	s_waitcnt lgkmcnt(1)
	v_pk_fma_f32 v[130:131], v[0:1], v[76:77], v[130:131] op_sel_hi:[1,0,1]
	v_pk_fma_f32 v[138:139], v[2:3], v[76:77], v[138:139] op_sel_hi:[1,0,1]
	v_pk_fma_f32 v[140:141], v[4:5], v[76:77], v[140:141] op_sel_hi:[1,0,1]
	v_pk_fma_f32 v[142:143], v[6:7], v[76:77], v[142:143] op_sel_hi:[1,0,1]
	v_pk_fma_f32 v[128:129], v[8:9], v[76:77], v[128:129] op_sel_hi:[1,0,1]
	v_pk_fma_f32 v[132:133], v[10:11], v[76:77], v[132:133] op_sel_hi:[1,0,1]
	v_pk_fma_f32 v[134:135], v[12:13], v[76:77], v[134:135] op_sel_hi:[1,0,1]
	v_pk_fma_f32 v[136:137], v[14:15], v[76:77], v[136:137] op_sel_hi:[1,0,1]
	ds_read_b32 v76, v193 offset:480
	s_waitcnt vmcnt(8)
	v_cvt_scalef32_pk_f32_fp4 v[0:1], v158, 1.0
	v_cvt_scalef32_pk_f32_fp4 v[2:3], v158, 1.0 op_sel:[1,0,0]
	v_cvt_scalef32_pk_f32_fp4 v[4:5], v158, 1.0 op_sel:[0,1,0]
	v_cvt_scalef32_pk_f32_fp4 v[6:7], v158, 1.0 op_sel:[1,1,0]
	v_cvt_scalef32_pk_f32_fp4 v[8:9], v159, 1.0
	v_cvt_scalef32_pk_f32_fp4 v[10:11], v159, 1.0 op_sel:[1,0,0]
	v_cvt_scalef32_pk_f32_fp4 v[12:13], v159, 1.0 op_sel:[0,1,0]
	v_cvt_scalef32_pk_f32_fp4 v[14:15], v159, 1.0 op_sel:[1,1,0]
	s_waitcnt lgkmcnt(1)
	v_pk_fma_f32 v[130:131], v[0:1], v[194:195], v[130:131] op_sel_hi:[1,0,1]
	v_pk_fma_f32 v[138:139], v[2:3], v[194:195], v[138:139] op_sel_hi:[1,0,1]
	v_pk_fma_f32 v[140:141], v[4:5], v[194:195], v[140:141] op_sel_hi:[1,0,1]
	v_pk_fma_f32 v[142:143], v[6:7], v[194:195], v[142:143] op_sel_hi:[1,0,1]
	v_pk_fma_f32 v[128:129], v[8:9], v[194:195], v[128:129] op_sel_hi:[1,0,1]
	v_pk_fma_f32 v[132:133], v[10:11], v[194:195], v[132:133] op_sel_hi:[1,0,1]
	v_pk_fma_f32 v[134:135], v[12:13], v[194:195], v[134:135] op_sel_hi:[1,0,1]
	v_pk_fma_f32 v[136:137], v[14:15], v[194:195], v[136:137] op_sel_hi:[1,0,1]
	ds_read_b32 v194, v193 offset:484
	s_waitcnt vmcnt(7)
	v_cvt_scalef32_pk_f32_fp4 v[0:1], v168, 1.0
	v_cvt_scalef32_pk_f32_fp4 v[2:3], v168, 1.0 op_sel:[1,0,0]
	v_cvt_scalef32_pk_f32_fp4 v[4:5], v168, 1.0 op_sel:[0,1,0]
	v_cvt_scalef32_pk_f32_fp4 v[6:7], v168, 1.0 op_sel:[1,1,0]
	v_cvt_scalef32_pk_f32_fp4 v[8:9], v169, 1.0
	v_cvt_scalef32_pk_f32_fp4 v[10:11], v169, 1.0 op_sel:[1,0,0]
	v_cvt_scalef32_pk_f32_fp4 v[12:13], v169, 1.0 op_sel:[0,1,0]
	v_cvt_scalef32_pk_f32_fp4 v[14:15], v169, 1.0 op_sel:[1,1,0]
	s_waitcnt lgkmcnt(1)
	v_pk_fma_f32 v[130:131], v[0:1], v[76:77], v[130:131] op_sel_hi:[1,0,1]
	v_pk_fma_f32 v[138:139], v[2:3], v[76:77], v[138:139] op_sel_hi:[1,0,1]
	v_pk_fma_f32 v[140:141], v[4:5], v[76:77], v[140:141] op_sel_hi:[1,0,1]
	v_pk_fma_f32 v[142:143], v[6:7], v[76:77], v[142:143] op_sel_hi:[1,0,1]
	v_pk_fma_f32 v[128:129], v[8:9], v[76:77], v[128:129] op_sel_hi:[1,0,1]
	v_pk_fma_f32 v[132:133], v[10:11], v[76:77], v[132:133] op_sel_hi:[1,0,1]
	v_pk_fma_f32 v[134:135], v[12:13], v[76:77], v[134:135] op_sel_hi:[1,0,1]
	v_pk_fma_f32 v[136:137], v[14:15], v[76:77], v[136:137] op_sel_hi:[1,0,1]
	ds_read_b32 v76, v193 offset:488
	s_waitcnt vmcnt(6)
	v_cvt_scalef32_pk_f32_fp4 v[0:1], v170, 1.0
	v_cvt_scalef32_pk_f32_fp4 v[2:3], v170, 1.0 op_sel:[1,0,0]
	v_cvt_scalef32_pk_f32_fp4 v[4:5], v170, 1.0 op_sel:[0,1,0]
	v_cvt_scalef32_pk_f32_fp4 v[6:7], v170, 1.0 op_sel:[1,1,0]
	v_cvt_scalef32_pk_f32_fp4 v[8:9], v171, 1.0
	v_cvt_scalef32_pk_f32_fp4 v[10:11], v171, 1.0 op_sel:[1,0,0]
	v_cvt_scalef32_pk_f32_fp4 v[12:13], v171, 1.0 op_sel:[0,1,0]
	v_cvt_scalef32_pk_f32_fp4 v[14:15], v171, 1.0 op_sel:[1,1,0]
	s_waitcnt lgkmcnt(1)
	v_pk_fma_f32 v[130:131], v[0:1], v[194:195], v[130:131] op_sel_hi:[1,0,1]
	v_pk_fma_f32 v[138:139], v[2:3], v[194:195], v[138:139] op_sel_hi:[1,0,1]
	v_pk_fma_f32 v[140:141], v[4:5], v[194:195], v[140:141] op_sel_hi:[1,0,1]
	v_pk_fma_f32 v[142:143], v[6:7], v[194:195], v[142:143] op_sel_hi:[1,0,1]
	v_pk_fma_f32 v[128:129], v[8:9], v[194:195], v[128:129] op_sel_hi:[1,0,1]
	v_pk_fma_f32 v[132:133], v[10:11], v[194:195], v[132:133] op_sel_hi:[1,0,1]
	v_pk_fma_f32 v[134:135], v[12:13], v[194:195], v[134:135] op_sel_hi:[1,0,1]
	v_pk_fma_f32 v[136:137], v[14:15], v[194:195], v[136:137] op_sel_hi:[1,0,1]
	ds_read_b32 v194, v193 offset:492
	s_waitcnt vmcnt(5)
	v_cvt_scalef32_pk_f32_fp4 v[0:1], v172, 1.0
	v_cvt_scalef32_pk_f32_fp4 v[2:3], v172, 1.0 op_sel:[1,0,0]
	v_cvt_scalef32_pk_f32_fp4 v[4:5], v172, 1.0 op_sel:[0,1,0]
	v_cvt_scalef32_pk_f32_fp4 v[6:7], v172, 1.0 op_sel:[1,1,0]
	v_cvt_scalef32_pk_f32_fp4 v[8:9], v173, 1.0
	v_cvt_scalef32_pk_f32_fp4 v[10:11], v173, 1.0 op_sel:[1,0,0]
	v_cvt_scalef32_pk_f32_fp4 v[12:13], v173, 1.0 op_sel:[0,1,0]
	v_cvt_scalef32_pk_f32_fp4 v[14:15], v173, 1.0 op_sel:[1,1,0]
	s_waitcnt lgkmcnt(1)
; __device__ void peer_gather_phase(const Params& P, int l, bool do_store) {
;     ...
; #pragma unroll
;       for (int j = 0; j < 8; ++j) {
;         const float a = __builtin_bit_cast(float, __builtin_amdgcn_readlane(__builtin_bit_cast(int, avec), kb + j));
;         const f32x2 aa = f32x2{a, a};
;         y[0] += aa * __builtin_amdgcn_cvt_scalef32_pk_f32_fp4(v8[j].x, 1.0f, 0); y[1] += aa * __builtin_amdgcn_cvt_scalef32_pk_f32_fp4(v8[j].x, 1.0f, 1);
;         y[2] += aa * __builtin_amdgcn_cvt_scalef32_pk_f32_fp4(v8[j].x, 1.0f, 2); y[3] += aa * __builtin_amdgcn_cvt_scalef32_pk_f32_fp4(v8[j].x, 1.0f, 3);
;         y[4] += aa * __builtin_amdgcn_cvt_scalef32_pk_f32_fp4(v8[j].y, 1.0f, 0); y[5] += aa * __builtin_amdgcn_cvt_scalef32_pk_f32_fp4(v8[j].y, 1.0f, 1);
;         y[6] += aa * __builtin_amdgcn_cvt_scalef32_pk_f32_fp4(v8[j].y, 1.0f, 2); y[7] += aa * __builtin_amdgcn_cvt_scalef32_pk_f32_fp4(v8[j].y, 1.0f, 3);
;       }
	v_pk_fma_f32 v[130:131], v[0:1], v[76:77], v[130:131] op_sel_hi:[1,0,1]
	v_pk_fma_f32 v[138:139], v[2:3], v[76:77], v[138:139] op_sel_hi:[1,0,1]
	v_pk_fma_f32 v[140:141], v[4:5], v[76:77], v[140:141] op_sel_hi:[1,0,1]
	v_pk_fma_f32 v[142:143], v[6:7], v[76:77], v[142:143] op_sel_hi:[1,0,1]
	v_pk_fma_f32 v[128:129], v[8:9], v[76:77], v[128:129] op_sel_hi:[1,0,1]
	v_pk_fma_f32 v[132:133], v[10:11], v[76:77], v[132:133] op_sel_hi:[1,0,1]
	v_pk_fma_f32 v[134:135], v[12:13], v[76:77], v[134:135] op_sel_hi:[1,0,1]
	v_pk_fma_f32 v[136:137], v[14:15], v[76:77], v[136:137] op_sel_hi:[1,0,1]
	ds_read_b32 v76, v193 offset:496
	s_waitcnt vmcnt(4)
	v_cvt_scalef32_pk_f32_fp4 v[0:1], v174, 1.0
	v_cvt_scalef32_pk_f32_fp4 v[2:3], v174, 1.0 op_sel:[1,0,0]
	v_cvt_scalef32_pk_f32_fp4 v[4:5], v174, 1.0 op_sel:[0,1,0]
	v_cvt_scalef32_pk_f32_fp4 v[6:7], v174, 1.0 op_sel:[1,1,0]
	v_cvt_scalef32_pk_f32_fp4 v[8:9], v175, 1.0
	v_cvt_scalef32_pk_f32_fp4 v[10:11], v175, 1.0 op_sel:[1,0,0]
	v_cvt_scalef32_pk_f32_fp4 v[12:13], v175, 1.0 op_sel:[0,1,0]
	v_cvt_scalef32_pk_f32_fp4 v[14:15], v175, 1.0 op_sel:[1,1,0]
	s_waitcnt lgkmcnt(1)
	v_pk_fma_f32 v[130:131], v[0:1], v[194:195], v[130:131] op_sel_hi:[1,0,1]
	v_pk_fma_f32 v[138:139], v[2:3], v[194:195], v[138:139] op_sel_hi:[1,0,1]
	v_pk_fma_f32 v[140:141], v[4:5], v[194:195], v[140:141] op_sel_hi:[1,0,1]
	v_pk_fma_f32 v[142:143], v[6:7], v[194:195], v[142:143] op_sel_hi:[1,0,1]
	v_pk_fma_f32 v[128:129], v[8:9], v[194:195], v[128:129] op_sel_hi:[1,0,1]
	v_pk_fma_f32 v[132:133], v[10:11], v[194:195], v[132:133] op_sel_hi:[1,0,1]
	v_pk_fma_f32 v[134:135], v[12:13], v[194:195], v[134:135] op_sel_hi:[1,0,1]
	v_pk_fma_f32 v[136:137], v[14:15], v[194:195], v[136:137] op_sel_hi:[1,0,1]
	ds_read_b32 v194, v193 offset:500
	s_waitcnt vmcnt(3)
	v_cvt_scalef32_pk_f32_fp4 v[0:1], v180, 1.0
	v_cvt_scalef32_pk_f32_fp4 v[2:3], v180, 1.0 op_sel:[1,0,0]
	v_cvt_scalef32_pk_f32_fp4 v[4:5], v180, 1.0 op_sel:[0,1,0]
	v_cvt_scalef32_pk_f32_fp4 v[6:7], v180, 1.0 op_sel:[1,1,0]
	v_cvt_scalef32_pk_f32_fp4 v[8:9], v181, 1.0
	v_cvt_scalef32_pk_f32_fp4 v[10:11], v181, 1.0 op_sel:[1,0,0]
	v_cvt_scalef32_pk_f32_fp4 v[12:13], v181, 1.0 op_sel:[0,1,0]
	v_cvt_scalef32_pk_f32_fp4 v[14:15], v181, 1.0 op_sel:[1,1,0]
	s_waitcnt lgkmcnt(1)
	v_pk_fma_f32 v[130:131], v[0:1], v[76:77], v[130:131] op_sel_hi:[1,0,1]
	v_pk_fma_f32 v[138:139], v[2:3], v[76:77], v[138:139] op_sel_hi:[1,0,1]
	v_pk_fma_f32 v[140:141], v[4:5], v[76:77], v[140:141] op_sel_hi:[1,0,1]
	v_pk_fma_f32 v[142:143], v[6:7], v[76:77], v[142:143] op_sel_hi:[1,0,1]
	v_pk_fma_f32 v[128:129], v[8:9], v[76:77], v[128:129] op_sel_hi:[1,0,1]
	v_pk_fma_f32 v[132:133], v[10:11], v[76:77], v[132:133] op_sel_hi:[1,0,1]
	v_pk_fma_f32 v[134:135], v[12:13], v[76:77], v[134:135] op_sel_hi:[1,0,1]
	v_pk_fma_f32 v[136:137], v[14:15], v[76:77], v[136:137] op_sel_hi:[1,0,1]
	ds_read_b32 v76, v193 offset:504
	s_waitcnt vmcnt(2)
	v_cvt_scalef32_pk_f32_fp4 v[0:1], v182, 1.0
	v_cvt_scalef32_pk_f32_fp4 v[2:3], v182, 1.0 op_sel:[1,0,0]
	v_cvt_scalef32_pk_f32_fp4 v[4:5], v182, 1.0 op_sel:[0,1,0]
	v_cvt_scalef32_pk_f32_fp4 v[6:7], v182, 1.0 op_sel:[1,1,0]
	v_cvt_scalef32_pk_f32_fp4 v[8:9], v183, 1.0
	v_cvt_scalef32_pk_f32_fp4 v[10:11], v183, 1.0 op_sel:[1,0,0]
	v_cvt_scalef32_pk_f32_fp4 v[12:13], v183, 1.0 op_sel:[0,1,0]
	v_cvt_scalef32_pk_f32_fp4 v[14:15], v183, 1.0 op_sel:[1,1,0]
	s_waitcnt lgkmcnt(1)
	v_pk_fma_f32 v[130:131], v[0:1], v[194:195], v[130:131] op_sel_hi:[1,0,1]
	v_pk_fma_f32 v[138:139], v[2:3], v[194:195], v[138:139] op_sel_hi:[1,0,1]
	v_pk_fma_f32 v[140:141], v[4:5], v[194:195], v[140:141] op_sel_hi:[1,0,1]
	v_pk_fma_f32 v[142:143], v[6:7], v[194:195], v[142:143] op_sel_hi:[1,0,1]
	v_pk_fma_f32 v[128:129], v[8:9], v[194:195], v[128:129] op_sel_hi:[1,0,1]
	v_pk_fma_f32 v[132:133], v[10:11], v[194:195], v[132:133] op_sel_hi:[1,0,1]
	v_pk_fma_f32 v[134:135], v[12:13], v[194:195], v[134:135] op_sel_hi:[1,0,1]
	v_pk_fma_f32 v[136:137], v[14:15], v[194:195], v[136:137] op_sel_hi:[1,0,1]
	ds_read_b32 v194, v193 offset:508
	s_waitcnt vmcnt(1)
	v_cvt_scalef32_pk_f32_fp4 v[0:1], v184, 1.0
	v_cvt_scalef32_pk_f32_fp4 v[2:3], v184, 1.0 op_sel:[1,0,0]
	v_cvt_scalef32_pk_f32_fp4 v[4:5], v184, 1.0 op_sel:[0,1,0]
	v_cvt_scalef32_pk_f32_fp4 v[6:7], v184, 1.0 op_sel:[1,1,0]
	v_cvt_scalef32_pk_f32_fp4 v[8:9], v185, 1.0
	v_cvt_scalef32_pk_f32_fp4 v[10:11], v185, 1.0 op_sel:[1,0,0]
	v_cvt_scalef32_pk_f32_fp4 v[12:13], v185, 1.0 op_sel:[0,1,0]
	v_cvt_scalef32_pk_f32_fp4 v[14:15], v185, 1.0 op_sel:[1,1,0]
	s_waitcnt lgkmcnt(1)
	v_pk_fma_f32 v[130:131], v[0:1], v[76:77], v[130:131] op_sel_hi:[1,0,1]
	v_pk_fma_f32 v[138:139], v[2:3], v[76:77], v[138:139] op_sel_hi:[1,0,1]
	v_pk_fma_f32 v[140:141], v[4:5], v[76:77], v[140:141] op_sel_hi:[1,0,1]
	v_pk_fma_f32 v[142:143], v[6:7], v[76:77], v[142:143] op_sel_hi:[1,0,1]
	v_pk_fma_f32 v[128:129], v[8:9], v[76:77], v[128:129] op_sel_hi:[1,0,1]
	v_pk_fma_f32 v[132:133], v[10:11], v[76:77], v[132:133] op_sel_hi:[1,0,1]
	v_pk_fma_f32 v[134:135], v[12:13], v[76:77], v[134:135] op_sel_hi:[1,0,1]
	v_pk_fma_f32 v[136:137], v[14:15], v[76:77], v[136:137] op_sel_hi:[1,0,1]
	s_waitcnt vmcnt(0)
	v_cvt_scalef32_pk_f32_fp4 v[0:1], v186, 1.0
	v_cvt_scalef32_pk_f32_fp4 v[2:3], v186, 1.0 op_sel:[1,0,0]
	v_cvt_scalef32_pk_f32_fp4 v[4:5], v186, 1.0 op_sel:[0,1,0]
	v_cvt_scalef32_pk_f32_fp4 v[6:7], v186, 1.0 op_sel:[1,1,0]
	v_cvt_scalef32_pk_f32_fp4 v[8:9], v187, 1.0
	v_cvt_scalef32_pk_f32_fp4 v[10:11], v187, 1.0 op_sel:[1,0,0]
	v_cvt_scalef32_pk_f32_fp4 v[12:13], v187, 1.0 op_sel:[0,1,0]
	v_cvt_scalef32_pk_f32_fp4 v[14:15], v187, 1.0 op_sel:[1,1,0]
	s_waitcnt lgkmcnt(0)
; __device__ void peer_gather_phase(const Params& P, int l, bool do_store) {
;     ...
; #pragma unroll
;       for (int j = 0; j < 8; ++j) {
;         const float a = __builtin_bit_cast(float, __builtin_amdgcn_readlane(__builtin_bit_cast(int, avec), kb + j));
;         const f32x2 aa = f32x2{a, a};
;         y[0] += aa * __builtin_amdgcn_cvt_scalef32_pk_f32_fp4(v8[j].x, 1.0f, 0); y[1] += aa * __builtin_amdgcn_cvt_scalef32_pk_f32_fp4(v8[j].x, 1.0f, 1);
;         y[2] += aa * __builtin_amdgcn_cvt_scalef32_pk_f32_fp4(v8[j].x, 1.0f, 2); y[3] += aa * __builtin_amdgcn_cvt_scalef32_pk_f32_fp4(v8[j].x, 1.0f, 3);
;         y[4] += aa * __builtin_amdgcn_cvt_scalef32_pk_f32_fp4(v8[j].y, 1.0f, 0); y[5] += aa * __builtin_amdgcn_cvt_scalef32_pk_f32_fp4(v8[j].y, 1.0f, 1);
;         y[6] += aa * __builtin_amdgcn_cvt_scalef32_pk_f32_fp4(v8[j].y, 1.0f, 2); y[7] += aa * __builtin_amdgcn_cvt_scalef32_pk_f32_fp4(v8[j].y, 1.0f, 3);
;       }
;     ...
;     float* xfp = P.out + (size_t)t * 1024 + lane * 16;
;     float pre[16];
; #pragma unroll
;     for (int k2 = 0; k2 < 8; ++k2) {
;       pre[2 * k2 + 0] = ALPHA_C * xf[k2].x + y[k2].x;
;       pre[2 * k2 + 1] = ALPHA_C * xf[k2].y + y[k2].y;
;     }
;     float sm = 0.f;
; #pragma unroll
;     for (int k = 0; k < 16; ++k) sm += pre[k];
;     const float mean = wave_sum(sm) * (1.f / 1024.f);
;     float vs = 0.f;
; #pragma unroll
;     for (int k = 0; k < 16; ++k) { const float dd = pre[k] - mean; vs += dd * dd; }
;     const float rstd = rsqrtf(wave_sum(vs) * (1.f / 1024.f) + EPS_C);
;     const float* g2 = P.ln2_g + l * 1024 + lane * 16;
;     const float* b2 = P.ln2_b + l * 1024 + lane * 16;
;     float o[16];
; #pragma unroll
;     for (int k4 = 0; k4 < 4; ++k4) {
;       const float4 gg = *(const float4*)(g2 + 4 * k4), bb = *(const float4*)(b2 + 4 * k4);
;       o[4 * k4 + 0] = (pre[4 * k4 + 0] - mean) * rstd * gg.x + bb.x; o[4 * k4 + 1] = (pre[4 * k4 + 1] - mean) * rstd * gg.y + bb.y;
;       o[4 * k4 + 2] = (pre[4 * k4 + 2] - mean) * rstd * gg.z + bb.z; o[4 * k4 + 3] = (pre[4 * k4 + 3] - mean) * rstd * gg.w + bb.w;
;       float4 ov; ov.x = o[4 * k4]; ov.y = o[4 * k4 + 1]; ov.z = o[4 * k4 + 2]; ov.w = o[4 * k4 + 3];
;       if (do_store && l == 1) *(float4*)(xfp + 4 * k4) = ov;
	v_pk_fma_f32 v[130:131], v[0:1], v[194:195], v[130:131] op_sel_hi:[1,0,1]
	v_pk_fma_f32 v[138:139], v[2:3], v[194:195], v[138:139] op_sel_hi:[1,0,1]
	v_pk_fma_f32 v[140:141], v[4:5], v[194:195], v[140:141] op_sel_hi:[1,0,1]
	v_pk_fma_f32 v[142:143], v[6:7], v[194:195], v[142:143] op_sel_hi:[1,0,1]
	v_pk_fma_f32 v[128:129], v[8:9], v[194:195], v[128:129] op_sel_hi:[1,0,1]
	v_pk_fma_f32 v[132:133], v[10:11], v[194:195], v[132:133] op_sel_hi:[1,0,1]
	v_pk_fma_f32 v[134:135], v[12:13], v[194:195], v[134:135] op_sel_hi:[1,0,1]
	v_pk_fma_f32 v[136:137], v[14:15], v[194:195], v[136:137] op_sel_hi:[1,0,1]
	v_lshlrev_b32_e32 v0, 16, v70
	v_lshlrev_b32_e32 v2, 16, v69
	v_and_b32_e32 v3, 0xffff0000, v69
	v_and_b32_e32 v1, 0xffff0000, v70
	s_mov_b32 s0, 0x3fb504f3
	v_pk_fma_f32 v[16:17], v[0:1], s[0:1], v[140:141] op_sel_hi:[1,0,1]
	v_pk_fma_f32 v[18:19], v[2:3], s[0:1], v[138:139] op_sel_hi:[1,0,1]
	global_load_dwordx4 v[0:3], v[82:83], off
	global_load_dwordx4 v[20:23], v[84:85], off
	global_load_dwordx4 v[44:47], v[82:83], off offset:16
	global_load_dwordx4 v[48:51], v[84:85], off offset:16
	global_load_dwordx4 v[52:55], v[82:83], off offset:32
	global_load_dwordx4 v[228:231], v[84:85], off offset:32
	global_load_dwordx4 v[232:235], v[82:83], off offset:48
	global_load_dwordx4 v[236:239], v[84:85], off offset:48
	v_lshlrev_b32_e32 v4, 16, v68
	v_and_b32_e32 v5, 0xffff0000, v68
	v_pk_fma_f32 v[4:5], v[4:5], s[0:1], v[130:131] op_sel_hi:[1,0,1]
	v_lshlrev_b32_e32 v10, 16, v71
	v_add_f32_e32 v24, 0, v4
	v_add_f32_e32 v24, v5, v24
	v_add_f32_e32 v24, v18, v24
	v_add_f32_e32 v24, v19, v24
	v_and_b32_e32 v11, 0xffff0000, v71
	v_add_f32_e32 v24, v16, v24
	v_pk_fma_f32 v[10:11], v[10:11], s[0:1], v[142:143] op_sel_hi:[1,0,1]
	v_add_f32_e32 v24, v17, v24
	v_lshlrev_b32_e32 v6, 16, v64
	v_lshlrev_b32_e32 v8, 16, v66
	v_lshlrev_b32_e32 v12, 16, v65
	v_lshlrev_b32_e32 v14, 16, v67
	v_and_b32_e32 v7, 0xffff0000, v64
	v_and_b32_e32 v13, 0xffff0000, v65
	v_and_b32_e32 v9, 0xffff0000, v66
	v_and_b32_e32 v15, 0xffff0000, v67
	v_add_f32_e32 v24, v10, v24
	v_add_f32_e32 v26, v11, v24
	v_pk_fma_f32 v[24:25], v[14:15], s[0:1], v[136:137] op_sel_hi:[1,0,1]
	v_pk_fma_f32 v[14:15], v[8:9], s[0:1], v[134:135] op_sel_hi:[1,0,1]
	v_pk_fma_f32 v[8:9], v[12:13], s[0:1], v[132:133] op_sel_hi:[1,0,1]
	v_pk_fma_f32 v[12:13], v[6:7], s[0:1], v[128:129] op_sel_hi:[1,0,1]
	v_mov_b32_e32 v7, v177
	v_add_f32_e32 v6, v12, v26
	v_add_f32_e32 v6, v13, v6
	v_add_f32_e32 v6, v8, v6
	v_add_f32_e32 v6, v9, v6
	v_add_f32_e32 v6, v14, v6
	v_add_f32_e32 v6, v15, v6
	v_add_f32_e32 v6, v24, v6
	v_add_f32_e32 v6, v25, v6
	s_nop 1
	v_add_f32_dpp v6, v6, v6 row_shr:1 row_mask:0xf bank_mask:0xf bound_ctrl:1
	s_nop 1
	v_add_f32_dpp v6, v6, v6 row_shr:2 row_mask:0xf bank_mask:0xf bound_ctrl:1
	s_nop 1
	v_add_f32_dpp v6, v6, v6 row_shr:4 row_mask:0xf bank_mask:0xf bound_ctrl:1
	s_nop 1
	v_add_f32_dpp v6, v6, v6 row_shr:8 row_mask:0xf bank_mask:0xf bound_ctrl:1
	s_nop 1
	v_mov_b32_dpp v7, v6 row_bcast:15 row_mask:0xa bank_mask:0xf
	v_add_f32_e32 v6, v6, v7
	v_mov_b32_e32 v7, v177
	s_nop 1
	v_mov_b32_dpp v7, v6 row_bcast:31 row_mask:0xc bank_mask:0xf
	v_add_f32_e32 v6, v6, v7
	s_nop 0
	v_readlane_b32 s0, v6, 63
	s_nop 1
	v_mul_f32_e32 v26, s0, v210
	v_pk_add_f32 v[28:29], v[4:5], v[26:27] op_sel_hi:[1,0] neg_lo:[0,1] neg_hi:[0,1]
	v_pk_add_f32 v[32:33], v[18:19], v[26:27] op_sel_hi:[1,0] neg_lo:[0,1] neg_hi:[0,1]
	v_pk_mul_f32 v[30:31], v[28:29], v[28:29]
	v_pk_mul_f32 v[18:19], v[32:33], v[32:33]
	v_pk_add_f32 v[4:5], v[16:17], v[26:27] op_sel_hi:[1,0] neg_lo:[0,1] neg_hi:[0,1]
	v_pk_add_f32 v[6:7], v[10:11], v[26:27] op_sel_hi:[1,0] neg_lo:[0,1] neg_hi:[0,1]
	v_pk_add_f32 v[10:11], v[12:13], v[26:27] op_sel_hi:[1,0] neg_lo:[0,1] neg_hi:[0,1]
	v_pk_add_f32 v[8:9], v[8:9], v[26:27] op_sel_hi:[1,0] neg_lo:[0,1] neg_hi:[0,1]
	v_pk_add_f32 v[14:15], v[14:15], v[26:27] op_sel_hi:[1,0] neg_lo:[0,1] neg_hi:[0,1]
	v_pk_add_f32 v[12:13], v[24:25], v[26:27] op_sel_hi:[1,0] neg_lo:[0,1] neg_hi:[0,1]
	v_add_f32_e32 v26, v30, v31
	v_add_f32_e32 v18, v18, v26
	v_pk_mul_f32 v[16:17], v[4:5], v[4:5]
	v_add_f32_e32 v18, v19, v18
	v_add_f32_e32 v16, v16, v18
	v_pk_mul_f32 v[34:35], v[6:7], v[6:7]
	v_add_f32_e32 v16, v17, v16
	v_add_f32_e32 v16, v34, v16
	v_pk_mul_f32 v[36:37], v[10:11], v[10:11]
	v_add_f32_e32 v16, v35, v16
	v_add_f32_e32 v16, v36, v16
	v_pk_mul_f32 v[38:39], v[8:9], v[8:9]
	v_add_f32_e32 v16, v37, v16
	v_add_f32_e32 v16, v38, v16
	v_pk_mul_f32 v[40:41], v[14:15], v[14:15]
	v_add_f32_e32 v16, v39, v16
	v_add_f32_e32 v16, v40, v16
	v_pk_mul_f32 v[24:25], v[12:13], v[12:13]
	v_add_f32_e32 v16, v41, v16
	v_add_f32_e32 v16, v24, v16
	v_add_f32_e32 v16, v25, v16
	v_mov_b32_e32 v17, v177
	s_nop 0
	v_add_f32_dpp v16, v16, v16 row_shr:1 row_mask:0xf bank_mask:0xf bound_ctrl:1
	s_nop 1
	v_add_f32_dpp v16, v16, v16 row_shr:2 row_mask:0xf bank_mask:0xf bound_ctrl:1
	s_nop 1
	v_add_f32_dpp v16, v16, v16 row_shr:4 row_mask:0xf bank_mask:0xf bound_ctrl:1
	s_nop 1
	v_add_f32_dpp v16, v16, v16 row_shr:8 row_mask:0xf bank_mask:0xf bound_ctrl:1
	s_nop 1
	v_mov_b32_dpp v17, v16 row_bcast:15 row_mask:0xa bank_mask:0xf
	v_add_f32_e32 v16, v16, v17
	v_mov_b32_e32 v17, v177
	s_nop 1
	v_mov_b32_dpp v17, v16 row_bcast:31 row_mask:0xc bank_mask:0xf
	v_add_f32_e32 v16, v16, v17
	s_nop 0
	v_readlane_b32 s0, v16, 63
	s_nop 1
	v_fma_f32 v16, s0, v210, v203
	s_mov_b32 s0, 0x800000
	v_mul_f32_e32 v17, 0x4b800000, v16
	v_cmp_gt_f32_e32 vcc, s0, v16
	s_nop 1
	v_cndmask_b32_e32 v16, v16, v17, vcc
	v_rsq_f32_e32 v18, v16
	v_lshl_add_u64 v[16:17], v[94:95], 2, v[80:81]
	v_mul_f32_e32 v19, 0x45800000, v18
	v_cndmask_b32_e32 v18, v18, v19, vcc
	v_pk_mul_f32 v[24:25], v[28:29], v[18:19] op_sel_hi:[1,0]
	s_and_b64 vcc, exec, s[38:39]
	s_waitcnt vmcnt(0)
	v_pk_fma_f32 v[0:1], v[0:1], v[24:25], v[20:21]
	v_pk_mul_f32 v[20:21], v[32:33], v[18:19] op_sel_hi:[1,0]
	s_nop 0
	v_pk_fma_f32 v[2:3], v[2:3], v[20:21], v[22:23]
	s_cbranch_vccz .LBB0_25
	global_store_dwordx4 v[16:17], v[0:3], off
